# v9 + static s_setprio 3 for the rwkv scan consumer waves inside the chunk loop
# baseline (speedup 1.0000x reference)
;     ...
;         const int i0 = w * 16 + (lane >> 3), i1 = i0 + 8, js = (lane & 7) * 8;
;         f32x2 S0, S1, S2, S3, T0, T1, T2, T3;
;         if (samp) {
;             const float* s0 = P.in[4] + ((size_t)(l * 16 + b) * 16 + h) * 4096 + js;
;             const f32x4 a0 = *(const f32x4*)(s0 + i0 * 64), a1 = *(const f32x4*)(s0 + i0 * 64 + 4), c0 = *(const f32x4*)(s0 + i1 * 64), c1 = *(const f32x4*)(s0 + i1 * 64 + 4);
;             S0 = a0.xy; S1 = a0.zw; S2 = a1.xy; S3 = a1.zw; T0 = c0.xy; T1 = c0.zw; T2 = c1.xy; T3 = c1.zw;
;         } else if (resume) {
;             const float* s0 = P.out + O_RP + ((size_t)(l * 4 + b) * 16 + h) * 4096 + js;
;             const f32x4 a0 = *(const f32x4*)(s0 + i0 * 64), a1 = *(const f32x4*)(s0 + i0 * 64 + 4), c0v = *(const f32x4*)(s0 + i1 * 64), c1v = *(const f32x4*)(s0 + i1 * 64 + 4);
;             S0 = a0.xy; S1 = a0.zw; S2 = a1.xy; S3 = a1.zw; T0 = c0v.xy; T1 = c0v.zw; T2 = c1v.xy; T3 = c1v.zw;
;         } else { S0 = (f32x2){0.f, 0.f}; S1 = S0; S2 = S0; S3 = S0; T0 = S0; T1 = S0; T2 = S0; T3 = S0; }
;         __syncthreads();
;         for (int c = c0; c < nch; ++c) {
;             const float* bb = bufs + (c & 1) * (16 * 384) + js;
;             const float* bv = bufs + (c & 1) * (16 * 384) + 320 + i0;
;             float* yb = ybuf + (c & 1) * 8192 + w * 64 + lane;
;             f32x4 w0, w1, a0, a1, b0, b1, k0, k1, r0, r1; float vi, vj;
;             f32x4 W0, W1, A0, A1, B0, B1, K0, K1, R0, R1; float VI, VJ;
.LBB0_1393:
	s_andn2_saveexec_b64 s[2:3], s[8:9]
	s_cbranch_execz .LBB0_1397
	v_lshrrev_b32_e32 v0, 3, v22
	v_lshl_or_b32 v16, v10, 4, v0
	v_lshlrev_b32_e32 v0, 3, v22
	v_and_b32_e32 v17, 56, v0
	v_and_b32_e32 v0, 0x3fffffc0, v18
	v_lshlrev_b32_e32 v0, 2, v0
	v_lshlrev_b32_e32 v1, 2, v22
	v_mov_b32_e32 v8, 0
	s_mov_b32 s1, 0
	v_add3_u32 v18, 0, v0, v1
	v_mov_b32_e32 v9, v8
	v_mov_b32_e32 v10, v8
	v_mov_b32_e32 v11, v8
	v_mov_b32_e32 v12, v8
	v_mov_b32_e32 v13, v8
	v_mov_b32_e32 v14, v8
	v_mov_b32_e32 v15, v8
	v_mov_b32_e32 v4, v8
	v_mov_b32_e32 v5, v8
	v_mov_b32_e32 v6, v8
	v_mov_b32_e32 v7, v8
	v_mov_b32_e32 v0, v8
	v_mov_b32_e32 v1, v8
	v_mov_b32_e32 v2, v8
	v_mov_b32_e32 v3, v8
	s_barrier
	s_setprio 3
.LBB0_1395:
	s_and_b32 s8, s1, 1
	s_mul_i32 s9, s8, 0x6000
	v_lshl_add_u32 v27, s8, 15, v18
	s_add_i32 s8, s9, 0
	v_lshl_add_u32 v21, v16, 2, s8
	v_lshl_add_u32 v20, v17, 2, s8
	v_add_u32_e32 v29, 0x400, v21
	v_add_u32_e32 v112, 0x800, v21
	ds_read_b128 v[30:33], v20
	ds_read_b128 v[34:37], v20 offset:16
	ds_read_b128 v[38:41], v20 offset:256
	ds_read_b128 v[42:45], v20 offset:272
	ds_read_b128 v[46:49], v20 offset:512
	ds_read_b128 v[50:53], v20 offset:528
	ds_read_b128 v[54:57], v20 offset:768
	ds_read_b128 v[58:61], v20 offset:784
	ds_read_b128 v[62:65], v20 offset:1024
	ds_read_b128 v[66:69], v20 offset:1040
	ds_read_b128 v[70:73], v20 offset:1536
	ds_read_b128 v[74:77], v20 offset:1552
	ds_read_b128 v[78:81], v20 offset:1792
	ds_read_b128 v[82:85], v20 offset:1808
	s_waitcnt vmcnt(3)
	ds_read_b128 v[86:89], v20 offset:2048
	ds_read_b128 v[90:93], v20 offset:2064
	s_waitcnt vmcnt(2)
	ds_read_b128 v[94:97], v20 offset:2304
	ds_read_b128 v[98:101], v20 offset:2320
	ds_read_b128 v[102:105], v20 offset:2560
	ds_read_b128 v[106:109], v20 offset:2576
	ds_read2_b32 v[110:111], v29 offset0:64 offset1:72
	ds_read2_b32 v[112:113], v112 offset0:192 offset1:200
	s_waitcnt lgkmcnt(14)
	v_pk_mul_f32 v[114:115], v[8:9], v[38:39]
	v_pk_mul_f32 v[116:117], v[12:13], v[42:43]
	v_pk_mul_f32 v[38:39], v[4:5], v[38:39]
	v_pk_mul_f32 v[42:43], v[0:1], v[42:43]
	v_pk_fma_f32 v[114:115], v[10:11], v[40:41], v[114:115]
	v_pk_fma_f32 v[116:117], v[14:15], v[44:45], v[116:117]
	s_waitcnt lgkmcnt(1)
	v_pk_mul_f32 v[118:119], v[54:55], v[110:111] op_sel_hi:[1,0]
	v_pk_mul_f32 v[120:121], v[56:57], v[110:111] op_sel_hi:[1,0]
	v_pk_mul_f32 v[122:123], v[58:59], v[110:111] op_sel_hi:[1,0]
	v_pk_mul_f32 v[124:125], v[60:61], v[110:111] op_sel_hi:[1,0]
	v_mov_b32_e32 v110, v111
	v_pk_fma_f32 v[38:39], v[6:7], v[40:41], v[38:39]
	v_pk_fma_f32 v[40:41], v[2:3], v[44:45], v[42:43]
	v_pk_add_f32 v[44:45], v[114:115], v[116:117]
	v_pk_mul_f32 v[54:55], v[54:55], v[110:111] op_sel_hi:[1,0]
	v_pk_add_f32 v[38:39], v[38:39], v[40:41]
	v_pk_fma_f32 v[8:9], v[8:9], v[30:31], v[118:119]
	v_add_f32_e32 v29, v44, v45
	v_pk_fma_f32 v[4:5], v[4:5], v[30:31], v[54:55]
	v_add_f32_e32 v30, v38, v39
	v_add_f32_dpp v29, v29, v29 quad_perm:[1,0,3,2] row_mask:0xf bank_mask:0xf bound_ctrl:1
	v_pk_mul_f32 v[56:57], v[56:57], v[110:111] op_sel_hi:[1,0]
	v_add_f32_dpp v30, v30, v30 quad_perm:[1,0,3,2] row_mask:0xf bank_mask:0xf bound_ctrl:1
	v_pk_mul_f32 v[58:59], v[58:59], v[110:111] op_sel_hi:[1,0]
	v_add_f32_dpp v29, v29, v29 quad_perm:[2,3,0,1] row_mask:0xf bank_mask:0xf bound_ctrl:1
	v_add_f32_dpp v31, v30, v30 quad_perm:[2,3,0,1] row_mask:0xf bank_mask:0xf bound_ctrl:1
	v_pk_fma_f32 v[10:11], v[10:11], v[32:33], v[120:121]
	v_pk_fma_f32 v[12:13], v[12:13], v[34:35], v[122:123]
	v_pk_mul_f32 v[60:61], v[60:61], v[110:111] op_sel_hi:[1,0]
	v_pk_fma_f32 v[6:7], v[6:7], v[32:33], v[56:57]
	v_pk_fma_f32 v[0:1], v[0:1], v[34:35], v[58:59]
	v_add_f32_dpp v30, v29, v29 row_half_mirror row_mask:0xf bank_mask:0xf bound_ctrl:1
	v_add_f32_dpp v32, v31, v31 row_half_mirror row_mask:0xf bank_mask:0xf bound_ctrl:1
	v_pk_fma_f32 v[14:15], v[14:15], v[36:37], v[124:125]
	v_pk_fma_f32 v[2:3], v[2:3], v[36:37], v[60:61]
	v_pk_fma_f32 v[8:9], v[46:47], v[30:31], v[8:9] op_sel_hi:[1,0,1]
	v_pk_fma_f32 v[12:13], v[50:51], v[30:31], v[12:13] op_sel_hi:[1,0,1]
	v_pk_fma_f32 v[4:5], v[46:47], v[32:33], v[4:5] op_sel_hi:[1,0,1]
	v_pk_fma_f32 v[0:1], v[50:51], v[32:33], v[0:1] op_sel_hi:[1,0,1]
	v_pk_fma_f32 v[10:11], v[48:49], v[30:31], v[10:11] op_sel_hi:[1,0,1]
	v_pk_fma_f32 v[14:15], v[52:53], v[30:31], v[14:15] op_sel_hi:[1,0,1]
	v_pk_fma_f32 v[6:7], v[48:49], v[32:33], v[6:7] op_sel_hi:[1,0,1]
	v_pk_fma_f32 v[2:3], v[52:53], v[32:33], v[2:3] op_sel_hi:[1,0,1]
	v_pk_mul_f32 v[30:31], v[62:63], v[8:9]
	v_pk_mul_f32 v[32:33], v[66:67], v[12:13]
	v_pk_mul_f32 v[34:35], v[62:63], v[4:5]
	v_pk_mul_f32 v[36:37], v[66:67], v[0:1]
	v_pk_mul_f32 v[38:39], v[78:79], v[8:9]
	v_pk_mul_f32 v[40:41], v[82:83], v[12:13]
	v_pk_mul_f32 v[48:49], v[78:79], v[4:5]
	v_pk_mul_f32 v[50:51], v[82:83], v[0:1]
	s_waitcnt lgkmcnt(0)
; #define SCAN_STEP(w0, w1, a0, a1, b0, b1, k0, k1, r0, r1, vi, vj, t) do { \
;                 SCAN_ROW(S0, S1, S2, S3, w0, w1, a0, a1, b0, b1, k0, k1, r0, r1, vi, (t) * 512); \
;                 SCAN_ROW(T0, T1, T2, T3, w0, w1, a0, a1, b0, b1, k0, k1, r0, r1, vj, (t) * 512 + 256); } while (0)
;     ...
;             SCAN_LOAD(w0, w1, a0, a1, b0, b1, k0, k1, r0, r1, vi, vj, 0);
; #pragma unroll
;             for (int t = 0; t < 16; t += 2) {
;                 SCAN_LOAD(W0, W1, A0, A1, B0, B1, K0, K1, R0, R1, VI, VJ, t + 1);
;                 SCAN_STEP(w0, w1, a0, a1, b0, b1, k0, k1, r0, r1, vi, vj, t);
;                 if (t + 2 < 16) SCAN_LOAD(w0, w1, a0, a1, b0, b1, k0, k1, r0, r1, vi, vj, t + 2);
;                 SCAN_STEP(W0, W1, A0, A1, B0, B1, K0, K1, R0, R1, VI, VJ, t + 1);
	v_mov_b32_e32 v42, v113
	v_pk_mul_f32 v[8:9], v[70:71], v[8:9]
	v_pk_mul_f32 v[44:45], v[72:73], v[10:11]
	v_pk_mul_f32 v[46:47], v[76:77], v[14:15]
	v_pk_mul_f32 v[4:5], v[70:71], v[4:5]
	v_pk_mul_f32 v[52:53], v[72:73], v[6:7]
	v_pk_mul_f32 v[0:1], v[74:75], v[0:1]
	v_pk_mul_f32 v[54:55], v[76:77], v[2:3]
	v_pk_fma_f32 v[30:31], v[64:65], v[10:11], v[30:31]
	v_pk_fma_f32 v[32:33], v[68:69], v[14:15], v[32:33]
	v_pk_fma_f32 v[34:35], v[64:65], v[6:7], v[34:35]
	v_pk_fma_f32 v[36:37], v[68:69], v[2:3], v[36:37]
	v_pk_fma_f32 v[10:11], v[80:81], v[10:11], v[38:39]
	v_pk_fma_f32 v[14:15], v[84:85], v[14:15], v[40:41]
	v_pk_fma_f32 v[6:7], v[80:81], v[6:7], v[48:49]
	v_pk_fma_f32 v[2:3], v[84:85], v[2:3], v[50:51]
	v_pk_fma_f32 v[56:57], v[94:95], v[112:113], v[8:9] op_sel_hi:[1,0,1]
	v_pk_fma_f32 v[64:65], v[94:95], v[42:43], v[4:5] op_sel_hi:[1,0,1]
	v_pk_fma_f32 v[68:69], v[98:99], v[42:43], v[0:1] op_sel_hi:[1,0,1]
	v_pk_add_f32 v[0:1], v[30:31], v[32:33]
	v_pk_add_f32 v[4:5], v[34:35], v[36:37]
	v_pk_add_f32 v[8:9], v[10:11], v[14:15]
	v_pk_add_f32 v[2:3], v[6:7], v[2:3]
	v_add_f32_e32 v0, v0, v1
	v_add_f32_e32 v1, v4, v5
	v_add_f32_e32 v4, v8, v9
	v_add_f32_e32 v2, v2, v3
	v_add_u32_e32 v126, 0x1000, v21
	v_add_f32_dpp v29, v4, v4 quad_perm:[1,0,3,2] row_mask:0xf bank_mask:0xf bound_ctrl:1
	v_add_f32_dpp v72, v2, v2 quad_perm:[1,0,3,2] row_mask:0xf bank_mask:0xf bound_ctrl:1
	v_pk_mul_f32 v[12:13], v[74:75], v[12:13]
	ds_write2st64_b32 v27, v0, v1 offset0:192 offset1:196
	v_add_f32_dpp v29, v29, v29 quad_perm:[2,3,0,1] row_mask:0xf bank_mask:0xf bound_ctrl:1
	v_add_f32_dpp v73, v72, v72 quad_perm:[2,3,0,1] row_mask:0xf bank_mask:0xf bound_ctrl:1
	v_pk_fma_f32 v[58:59], v[96:97], v[112:113], v[44:45] op_sel_hi:[1,0,1]
	v_pk_fma_f32 v[60:61], v[98:99], v[112:113], v[12:13] op_sel_hi:[1,0,1]
	v_pk_fma_f32 v[62:63], v[100:101], v[112:113], v[46:47] op_sel_hi:[1,0,1]
	v_pk_fma_f32 v[66:67], v[96:97], v[42:43], v[52:53] op_sel_hi:[1,0,1]
	v_pk_fma_f32 v[54:55], v[100:101], v[42:43], v[54:55] op_sel_hi:[1,0,1]
	ds_read2_b32 v[70:71], v126 offset0:64 offset1:72
	ds_read_b128 v[0:3], v20 offset:4112
	ds_read_b128 v[4:7], v20 offset:4096
	ds_read_b128 v[8:11], v20 offset:3856
	ds_read_b128 v[12:15], v20 offset:3840
	ds_read_b128 v[30:33], v20 offset:3600
	ds_read_b128 v[34:37], v20 offset:3584
	ds_read_b128 v[38:41], v20 offset:3344
	ds_read_b128 v[42:45], v20 offset:3328
	ds_read_b128 v[46:49], v20 offset:3072
	ds_read_b128 v[50:53], v20 offset:3088
	v_add_f32_dpp v72, v29, v29 row_half_mirror row_mask:0xf bank_mask:0xf bound_ctrl:1
	v_add_f32_dpp v74, v73, v73 row_half_mirror row_mask:0xf bank_mask:0xf bound_ctrl:1
	v_pk_fma_f32 v[56:57], v[86:87], v[72:73], v[56:57] op_sel_hi:[1,0,1]
	v_pk_fma_f32 v[60:61], v[90:91], v[72:73], v[60:61] op_sel_hi:[1,0,1]
	v_pk_fma_f32 v[64:65], v[86:87], v[74:75], v[64:65] op_sel_hi:[1,0,1]
	v_pk_fma_f32 v[68:69], v[90:91], v[74:75], v[68:69] op_sel_hi:[1,0,1]
	v_pk_fma_f32 v[58:59], v[88:89], v[72:73], v[58:59] op_sel_hi:[1,0,1]
	v_pk_fma_f32 v[62:63], v[92:93], v[72:73], v[62:63] op_sel_hi:[1,0,1]
	v_pk_fma_f32 v[66:67], v[88:89], v[74:75], v[66:67] op_sel_hi:[1,0,1]
	v_pk_fma_f32 v[54:55], v[92:93], v[74:75], v[54:55] op_sel_hi:[1,0,1]
	v_pk_mul_f32 v[72:73], v[102:103], v[56:57]
	v_pk_mul_f32 v[74:75], v[106:107], v[60:61]
	v_pk_mul_f32 v[76:77], v[102:103], v[64:65]
	v_pk_mul_f32 v[78:79], v[106:107], v[68:69]
	v_pk_fma_f32 v[72:73], v[104:105], v[58:59], v[72:73]
	v_pk_fma_f32 v[74:75], v[108:109], v[62:63], v[74:75]
	v_pk_fma_f32 v[76:77], v[104:105], v[66:67], v[76:77]
	v_pk_fma_f32 v[78:79], v[108:109], v[54:55], v[78:79]
	v_pk_add_f32 v[72:73], v[72:73], v[74:75]
	v_pk_add_f32 v[74:75], v[76:77], v[78:79]
	s_waitcnt lgkmcnt(2)
	v_pk_mul_f32 v[76:77], v[42:43], v[56:57]
	v_pk_mul_f32 v[78:79], v[38:39], v[60:61]
	v_pk_mul_f32 v[42:43], v[42:43], v[64:65]
	v_pk_mul_f32 v[38:39], v[38:39], v[68:69]
	s_waitcnt lgkmcnt(1)
	v_pk_mul_f32 v[80:81], v[48:49], v[58:59]
	s_waitcnt lgkmcnt(0)
	v_pk_mul_f32 v[82:83], v[52:53], v[62:63]
	v_pk_fma_f32 v[58:59], v[44:45], v[58:59], v[76:77]
	v_pk_fma_f32 v[62:63], v[40:41], v[62:63], v[78:79]
	v_pk_fma_f32 v[42:43], v[44:45], v[66:67], v[42:43]
	v_pk_fma_f32 v[38:39], v[40:41], v[54:55], v[38:39]
	v_pk_mul_f32 v[56:57], v[46:47], v[56:57]
	v_pk_mul_f32 v[46:47], v[46:47], v[64:65]
	v_add_f32_e32 v29, v72, v73
	v_add_f32_e32 v64, v74, v75
	v_pk_add_f32 v[86:87], v[62:63], v[58:59]
	v_pk_add_f32 v[88:89], v[38:39], v[42:43]
	ds_write2st64_b32 v27, v29, v64 offset0:200 offset1:204
	v_add_f32_e32 v29, v86, v87
	v_add_f32_e32 v86, v88, v89
	v_pk_mul_f32 v[60:61], v[50:51], v[60:61]
	v_mov_b32_e32 v84, v71
	v_pk_mul_f32 v[48:49], v[48:49], v[66:67]
	v_pk_mul_f32 v[50:51], v[50:51], v[68:69]
	v_pk_mul_f32 v[52:53], v[52:53], v[54:55]
	v_add_f32_dpp v29, v29, v29 quad_perm:[1,0,3,2] row_mask:0xf bank_mask:0xf bound_ctrl:1
	v_add_f32_dpp v86, v86, v86 quad_perm:[1,0,3,2] row_mask:0xf bank_mask:0xf bound_ctrl:1
	v_add_u32_e32 v127, 0x1400, v21
	v_pk_fma_f32 v[72:73], v[70:71], v[12:13], v[56:57] op_sel_hi:[0,1,1]
	v_pk_fma_f32 v[74:75], v[70:71], v[14:15], v[80:81] op_sel_hi:[0,1,1]
	v_pk_fma_f32 v[76:77], v[70:71], v[8:9], v[60:61] op_sel_hi:[0,1,1]
	v_pk_fma_f32 v[70:71], v[70:71], v[10:11], v[82:83] op_sel_hi:[0,1,1]
	v_pk_fma_f32 v[78:79], v[84:85], v[12:13], v[46:47] op_sel_hi:[0,1,1]
	v_pk_fma_f32 v[80:81], v[84:85], v[14:15], v[48:49] op_sel_hi:[0,1,1]
	v_pk_fma_f32 v[82:83], v[84:85], v[8:9], v[50:51] op_sel_hi:[0,1,1]
	v_pk_fma_f32 v[84:85], v[84:85], v[10:11], v[52:53] op_sel_hi:[0,1,1]
	ds_read_b128 v[8:11], v20 offset:4608
	ds_read_b128 v[12:15], v20 offset:4624
; #define SCAN_STEP(w0, w1, a0, a1, b0, b1, k0, k1, r0, r1, vi, vj, t) do { \
;                 SCAN_ROW(S0, S1, S2, S3, w0, w1, a0, a1, b0, b1, k0, k1, r0, r1, vi, (t) * 512); \
;                 SCAN_ROW(T0, T1, T2, T3, w0, w1, a0, a1, b0, b1, k0, k1, r0, r1, vj, (t) * 512 + 256); } while (0)
;     ...
;             SCAN_LOAD(w0, w1, a0, a1, b0, b1, k0, k1, r0, r1, vi, vj, 0);
; #pragma unroll
;             for (int t = 0; t < 16; t += 2) {
;                 SCAN_LOAD(W0, W1, A0, A1, B0, B1, K0, K1, R0, R1, VI, VJ, t + 1);
;                 SCAN_STEP(w0, w1, a0, a1, b0, b1, k0, k1, r0, r1, vi, vj, t);
;                 if (t + 2 < 16) SCAN_LOAD(w0, w1, a0, a1, b0, b1, k0, k1, r0, r1, vi, vj, t + 2);
;                 SCAN_STEP(W0, W1, A0, A1, B0, B1, K0, K1, R0, R1, VI, VJ, t + 1);
	ds_read_b128 v[38:41], v20 offset:4864
	ds_read_b128 v[42:45], v20 offset:4880
	ds_read_b128 v[46:49], v20 offset:5120
	ds_read_b128 v[50:53], v20 offset:5136
	ds_read_b128 v[54:57], v20 offset:5376
	ds_read_b128 v[58:61], v20 offset:5392
	ds_read_b128 v[62:65], v20 offset:5632
	ds_read_b128 v[66:69], v20 offset:5648
	ds_read2_b32 v[90:91], v127 offset0:192 offset1:200
	v_add_f32_dpp v29, v29, v29 quad_perm:[2,3,0,1] row_mask:0xf bank_mask:0xf bound_ctrl:1
	v_add_f32_dpp v87, v86, v86 quad_perm:[2,3,0,1] row_mask:0xf bank_mask:0xf bound_ctrl:1
	v_add_u32_e32 v128, 0x1c00, v21
	v_add_f32_dpp v86, v29, v29 row_half_mirror row_mask:0xf bank_mask:0xf bound_ctrl:1
	v_add_f32_dpp v88, v87, v87 row_half_mirror row_mask:0xf bank_mask:0xf bound_ctrl:1
	v_pk_fma_f32 v[72:73], v[34:35], v[86:87], v[72:73] op_sel_hi:[1,0,1]
	v_pk_fma_f32 v[76:77], v[30:31], v[86:87], v[76:77] op_sel_hi:[1,0,1]
	v_pk_fma_f32 v[34:35], v[34:35], v[88:89], v[78:79] op_sel_hi:[1,0,1]
	v_pk_fma_f32 v[30:31], v[30:31], v[88:89], v[82:83] op_sel_hi:[1,0,1]
	v_pk_fma_f32 v[74:75], v[36:37], v[86:87], v[74:75] op_sel_hi:[1,0,1]
	v_pk_fma_f32 v[70:71], v[32:33], v[86:87], v[70:71] op_sel_hi:[1,0,1]
	v_pk_fma_f32 v[36:37], v[36:37], v[88:89], v[80:81] op_sel_hi:[1,0,1]
	v_pk_fma_f32 v[32:33], v[32:33], v[88:89], v[84:85] op_sel_hi:[1,0,1]
	v_pk_mul_f32 v[78:79], v[4:5], v[72:73]
	v_pk_mul_f32 v[80:81], v[0:1], v[76:77]
	v_pk_mul_f32 v[4:5], v[4:5], v[34:35]
	v_pk_mul_f32 v[0:1], v[0:1], v[30:31]
	s_waitcnt lgkmcnt(8)
	v_pk_mul_f32 v[82:83], v[38:39], v[72:73]
	s_waitcnt lgkmcnt(7)
	v_pk_mul_f32 v[84:85], v[42:43], v[76:77]
	v_pk_mul_f32 v[38:39], v[38:39], v[34:35]
	v_pk_mul_f32 v[42:43], v[42:43], v[30:31]
	v_pk_mul_f32 v[72:73], v[8:9], v[72:73]
	v_pk_mul_f32 v[86:87], v[10:11], v[74:75]
	v_pk_mul_f32 v[76:77], v[12:13], v[76:77]
	v_pk_mul_f32 v[88:89], v[14:15], v[70:71]
	v_pk_mul_f32 v[8:9], v[8:9], v[34:35]
	v_pk_mul_f32 v[10:11], v[10:11], v[36:37]
	v_pk_mul_f32 v[12:13], v[12:13], v[30:31]
	v_pk_mul_f32 v[14:15], v[14:15], v[32:33]
	v_pk_fma_f32 v[30:31], v[6:7], v[74:75], v[78:79]
	v_pk_fma_f32 v[34:35], v[2:3], v[70:71], v[80:81]
	v_pk_fma_f32 v[4:5], v[6:7], v[36:37], v[4:5]
	v_pk_fma_f32 v[0:1], v[2:3], v[32:33], v[0:1]
	v_pk_fma_f32 v[2:3], v[40:41], v[74:75], v[82:83]
	v_pk_fma_f32 v[6:7], v[44:45], v[70:71], v[84:85]
	v_pk_fma_f32 v[36:37], v[40:41], v[36:37], v[38:39]
	v_pk_fma_f32 v[32:33], v[44:45], v[32:33], v[42:43]
	s_waitcnt lgkmcnt(0)
	v_mov_b32_e32 v92, v91
	v_pk_add_f32 v[0:1], v[4:5], v[0:1]
	v_pk_add_f32 v[2:3], v[2:3], v[6:7]
	v_pk_add_f32 v[4:5], v[36:37], v[32:33]
	v_pk_fma_f32 v[78:79], v[54:55], v[92:93], v[8:9] op_sel_hi:[1,0,1]
	v_pk_add_f32 v[8:9], v[30:31], v[34:35]
	v_add_f32_e32 v0, v0, v1
	v_add_f32_e32 v1, v2, v3
	v_add_f32_e32 v2, v4, v5
	v_pk_fma_f32 v[74:75], v[58:59], v[90:91], v[76:77] op_sel_hi:[1,0,1]
	v_pk_fma_f32 v[76:77], v[60:61], v[90:91], v[88:89] op_sel_hi:[1,0,1]
	v_add_f32_e32 v6, v8, v9
	v_add_f32_dpp v29, v1, v1 quad_perm:[1,0,3,2] row_mask:0xf bank_mask:0xf bound_ctrl:1
	v_add_f32_dpp v88, v2, v2 quad_perm:[1,0,3,2] row_mask:0xf bank_mask:0xf bound_ctrl:1
	ds_write2st64_b32 v27, v6, v0 offset0:208 offset1:212
	v_add_f32_dpp v29, v29, v29 quad_perm:[2,3,0,1] row_mask:0xf bank_mask:0xf bound_ctrl:1
	v_add_f32_dpp v89, v88, v88 quad_perm:[2,3,0,1] row_mask:0xf bank_mask:0xf bound_ctrl:1
	v_pk_fma_f32 v[70:71], v[54:55], v[90:91], v[72:73] op_sel_hi:[1,0,1]
	v_pk_fma_f32 v[72:73], v[56:57], v[90:91], v[86:87] op_sel_hi:[1,0,1]
	v_pk_fma_f32 v[80:81], v[56:57], v[92:93], v[10:11] op_sel_hi:[1,0,1]
	v_pk_fma_f32 v[82:83], v[58:59], v[92:93], v[12:13] op_sel_hi:[1,0,1]
	v_pk_fma_f32 v[84:85], v[60:61], v[92:93], v[14:15] op_sel_hi:[1,0,1]
	ds_read2_b32 v[86:87], v128 offset0:64 offset1:72
	ds_read_b128 v[0:3], v20 offset:7184
	ds_read_b128 v[4:7], v20 offset:7168
	ds_read_b128 v[8:11], v20 offset:6928
	ds_read_b128 v[12:15], v20 offset:6912
	ds_read_b128 v[30:33], v20 offset:6672
	ds_read_b128 v[34:37], v20 offset:6656
	ds_read_b128 v[38:41], v20 offset:6416
	ds_read_b128 v[42:45], v20 offset:6400
	ds_read_b128 v[54:57], v20 offset:6144
	ds_read_b128 v[58:61], v20 offset:6160
	v_add_f32_dpp v88, v29, v29 row_half_mirror row_mask:0xf bank_mask:0xf bound_ctrl:1
	v_add_f32_dpp v90, v89, v89 row_half_mirror row_mask:0xf bank_mask:0xf bound_ctrl:1
	v_pk_fma_f32 v[70:71], v[46:47], v[88:89], v[70:71] op_sel_hi:[1,0,1]
	v_pk_fma_f32 v[74:75], v[50:51], v[88:89], v[74:75] op_sel_hi:[1,0,1]
	v_pk_fma_f32 v[46:47], v[46:47], v[90:91], v[78:79] op_sel_hi:[1,0,1]
	v_pk_fma_f32 v[50:51], v[50:51], v[90:91], v[82:83] op_sel_hi:[1,0,1]
	v_pk_fma_f32 v[72:73], v[48:49], v[88:89], v[72:73] op_sel_hi:[1,0,1]
	v_pk_fma_f32 v[76:77], v[52:53], v[88:89], v[76:77] op_sel_hi:[1,0,1]
	v_pk_fma_f32 v[48:49], v[48:49], v[90:91], v[80:81] op_sel_hi:[1,0,1]
	v_pk_fma_f32 v[52:53], v[52:53], v[90:91], v[84:85] op_sel_hi:[1,0,1]
	v_pk_mul_f32 v[78:79], v[62:63], v[70:71]
	v_pk_mul_f32 v[80:81], v[66:67], v[74:75]
	v_pk_mul_f32 v[62:63], v[62:63], v[46:47]
	v_pk_mul_f32 v[66:67], v[66:67], v[50:51]
	v_pk_fma_f32 v[78:79], v[64:65], v[72:73], v[78:79]
	v_pk_fma_f32 v[62:63], v[64:65], v[48:49], v[62:63]
	v_pk_fma_f32 v[64:65], v[68:69], v[52:53], v[66:67]
	v_pk_fma_f32 v[80:81], v[68:69], v[76:77], v[80:81]
	v_pk_add_f32 v[62:63], v[62:63], v[64:65]
	s_waitcnt lgkmcnt(2)
	v_pk_mul_f32 v[64:65], v[42:43], v[70:71]
	v_pk_mul_f32 v[68:69], v[38:39], v[74:75]
	v_pk_mul_f32 v[42:43], v[42:43], v[46:47]
	v_pk_mul_f32 v[38:39], v[38:39], v[50:51]
	v_pk_add_f32 v[66:67], v[78:79], v[80:81]
	s_waitcnt lgkmcnt(1)
; #define SCAN_STEP(w0, w1, a0, a1, b0, b1, k0, k1, r0, r1, vi, vj, t) do { \
;                 SCAN_ROW(S0, S1, S2, S3, w0, w1, a0, a1, b0, b1, k0, k1, r0, r1, vi, (t) * 512); \
;                 SCAN_ROW(T0, T1, T2, T3, w0, w1, a0, a1, b0, b1, k0, k1, r0, r1, vj, (t) * 512 + 256); } while (0)
;     ...
;             SCAN_LOAD(w0, w1, a0, a1, b0, b1, k0, k1, r0, r1, vi, vj, 0);
; #pragma unroll
;             for (int t = 0; t < 16; t += 2) {
;                 SCAN_LOAD(W0, W1, A0, A1, B0, B1, K0, K1, R0, R1, VI, VJ, t + 1);
;                 SCAN_STEP(w0, w1, a0, a1, b0, b1, k0, k1, r0, r1, vi, vj, t);
;                 if (t + 2 < 16) SCAN_LOAD(w0, w1, a0, a1, b0, b1, k0, k1, r0, r1, vi, vj, t + 2);
;                 SCAN_STEP(W0, W1, A0, A1, B0, B1, K0, K1, R0, R1, VI, VJ, t + 1);
	v_pk_mul_f32 v[70:71], v[54:55], v[70:71]
	v_pk_mul_f32 v[78:79], v[56:57], v[72:73]
	s_waitcnt lgkmcnt(0)
	v_pk_mul_f32 v[74:75], v[58:59], v[74:75]
	v_pk_mul_f32 v[80:81], v[60:61], v[76:77]
	v_pk_mul_f32 v[46:47], v[54:55], v[46:47]
	v_pk_mul_f32 v[54:55], v[56:57], v[48:49]
	v_pk_mul_f32 v[50:51], v[58:59], v[50:51]
	v_pk_mul_f32 v[56:57], v[60:61], v[52:53]
	v_pk_fma_f32 v[58:59], v[44:45], v[72:73], v[64:65]
	v_pk_fma_f32 v[60:61], v[40:41], v[76:77], v[68:69]
	v_pk_fma_f32 v[42:43], v[44:45], v[48:49], v[42:43]
	v_pk_fma_f32 v[38:39], v[40:41], v[52:53], v[38:39]
	v_mov_b32_e32 v82, v87
	v_add_f32_e32 v29, v66, v67
	v_add_f32_e32 v62, v62, v63
	v_pk_fma_f32 v[70:71], v[86:87], v[12:13], v[70:71] op_sel_hi:[0,1,1]
	v_pk_fma_f32 v[72:73], v[86:87], v[14:15], v[78:79] op_sel_hi:[0,1,1]
	v_pk_fma_f32 v[74:75], v[86:87], v[8:9], v[74:75] op_sel_hi:[0,1,1]
	v_pk_fma_f32 v[76:77], v[86:87], v[10:11], v[80:81] op_sel_hi:[0,1,1]
	v_pk_add_f32 v[86:87], v[60:61], v[58:59]
	v_pk_add_f32 v[88:89], v[38:39], v[42:43]
	ds_write2st64_b32 v27, v29, v62 offset0:216 offset1:220
	v_add_f32_e32 v29, v86, v87
	v_add_f32_e32 v86, v88, v89
	v_add_u32_e32 v129, 0x2000, v21
	v_add_f32_dpp v29, v29, v29 quad_perm:[1,0,3,2] row_mask:0xf bank_mask:0xf bound_ctrl:1
	v_add_f32_dpp v86, v86, v86 quad_perm:[1,0,3,2] row_mask:0xf bank_mask:0xf bound_ctrl:1
	v_pk_fma_f32 v[78:79], v[82:83], v[12:13], v[46:47] op_sel_hi:[0,1,1]
	v_pk_fma_f32 v[80:81], v[82:83], v[14:15], v[54:55] op_sel_hi:[0,1,1]
	v_pk_fma_f32 v[84:85], v[82:83], v[8:9], v[50:51] op_sel_hi:[0,1,1]
	v_pk_fma_f32 v[82:83], v[82:83], v[10:11], v[56:57] op_sel_hi:[0,1,1]
	ds_read_b128 v[8:11], v20 offset:7680
	ds_read_b128 v[12:15], v20 offset:7696
	ds_read_b128 v[38:41], v20 offset:7936
	ds_read_b128 v[42:45], v20 offset:7952
	ds_read_b128 v[46:49], v20 offset:8192
	ds_read_b128 v[50:53], v20 offset:8208
	ds_read_b128 v[54:57], v20 offset:8448
	ds_read_b128 v[58:61], v20 offset:8464
	ds_read_b128 v[62:65], v20 offset:8704
	ds_read_b128 v[66:69], v20 offset:8720
	ds_read2_b32 v[90:91], v129 offset0:192 offset1:200
	v_add_f32_dpp v29, v29, v29 quad_perm:[2,3,0,1] row_mask:0xf bank_mask:0xf bound_ctrl:1
	v_add_f32_dpp v87, v86, v86 quad_perm:[2,3,0,1] row_mask:0xf bank_mask:0xf bound_ctrl:1
	v_add_u32_e32 v130, 0x2800, v21
	v_add_f32_dpp v86, v29, v29 row_half_mirror row_mask:0xf bank_mask:0xf bound_ctrl:1
	v_add_f32_dpp v88, v87, v87 row_half_mirror row_mask:0xf bank_mask:0xf bound_ctrl:1
	v_pk_fma_f32 v[70:71], v[34:35], v[86:87], v[70:71] op_sel_hi:[1,0,1]
	v_pk_fma_f32 v[74:75], v[30:31], v[86:87], v[74:75] op_sel_hi:[1,0,1]
	v_pk_fma_f32 v[34:35], v[34:35], v[88:89], v[78:79] op_sel_hi:[1,0,1]
	v_pk_fma_f32 v[30:31], v[30:31], v[88:89], v[84:85] op_sel_hi:[1,0,1]
	v_pk_fma_f32 v[72:73], v[36:37], v[86:87], v[72:73] op_sel_hi:[1,0,1]
	v_pk_fma_f32 v[76:77], v[32:33], v[86:87], v[76:77] op_sel_hi:[1,0,1]
	v_pk_fma_f32 v[36:37], v[36:37], v[88:89], v[80:81] op_sel_hi:[1,0,1]
	v_pk_fma_f32 v[32:33], v[32:33], v[88:89], v[82:83] op_sel_hi:[1,0,1]
	v_pk_mul_f32 v[78:79], v[4:5], v[70:71]
	v_pk_mul_f32 v[80:81], v[0:1], v[74:75]
	v_pk_mul_f32 v[4:5], v[4:5], v[34:35]
	v_pk_mul_f32 v[0:1], v[0:1], v[30:31]
	s_waitcnt lgkmcnt(8)
	v_pk_mul_f32 v[82:83], v[38:39], v[70:71]
	s_waitcnt lgkmcnt(7)
	v_pk_mul_f32 v[84:85], v[42:43], v[74:75]
	v_pk_mul_f32 v[38:39], v[38:39], v[34:35]
	v_pk_mul_f32 v[42:43], v[42:43], v[30:31]
	v_pk_mul_f32 v[70:71], v[8:9], v[70:71]
	v_pk_mul_f32 v[86:87], v[10:11], v[72:73]
	v_pk_mul_f32 v[74:75], v[12:13], v[74:75]
	v_pk_mul_f32 v[88:89], v[14:15], v[76:77]
	v_pk_mul_f32 v[8:9], v[8:9], v[34:35]
	v_pk_mul_f32 v[10:11], v[10:11], v[36:37]
	v_pk_mul_f32 v[12:13], v[12:13], v[30:31]
	v_pk_mul_f32 v[14:15], v[14:15], v[32:33]
	v_pk_fma_f32 v[30:31], v[6:7], v[72:73], v[78:79]
	v_pk_fma_f32 v[34:35], v[2:3], v[76:77], v[80:81]
	v_pk_fma_f32 v[4:5], v[6:7], v[36:37], v[4:5]
	v_pk_fma_f32 v[0:1], v[2:3], v[32:33], v[0:1]
	v_pk_fma_f32 v[2:3], v[40:41], v[72:73], v[82:83]
	v_pk_fma_f32 v[6:7], v[44:45], v[76:77], v[84:85]
	v_pk_fma_f32 v[36:37], v[40:41], v[36:37], v[38:39]
	v_pk_fma_f32 v[32:33], v[44:45], v[32:33], v[42:43]
	s_waitcnt lgkmcnt(0)
	v_mov_b32_e32 v92, v91
	v_pk_add_f32 v[0:1], v[4:5], v[0:1]
	v_pk_add_f32 v[2:3], v[2:3], v[6:7]
	v_pk_add_f32 v[4:5], v[36:37], v[32:33]
	v_pk_fma_f32 v[78:79], v[54:55], v[92:93], v[8:9] op_sel_hi:[1,0,1]
	v_pk_add_f32 v[8:9], v[30:31], v[34:35]
	v_add_f32_e32 v0, v0, v1
	v_add_f32_e32 v1, v2, v3
	v_add_f32_e32 v2, v4, v5
	v_pk_fma_f32 v[76:77], v[60:61], v[90:91], v[88:89] op_sel_hi:[1,0,1]
	v_add_f32_e32 v6, v8, v9
	v_add_f32_dpp v29, v1, v1 quad_perm:[1,0,3,2] row_mask:0xf bank_mask:0xf bound_ctrl:1
	v_add_f32_dpp v88, v2, v2 quad_perm:[1,0,3,2] row_mask:0xf bank_mask:0xf bound_ctrl:1
	ds_write2st64_b32 v27, v6, v0 offset0:224 offset1:228
	v_add_f32_dpp v29, v29, v29 quad_perm:[2,3,0,1] row_mask:0xf bank_mask:0xf bound_ctrl:1
	v_add_f32_dpp v89, v88, v88 quad_perm:[2,3,0,1] row_mask:0xf bank_mask:0xf bound_ctrl:1
	v_pk_fma_f32 v[70:71], v[54:55], v[90:91], v[70:71] op_sel_hi:[1,0,1]
	v_pk_fma_f32 v[72:73], v[56:57], v[90:91], v[86:87] op_sel_hi:[1,0,1]
	v_pk_fma_f32 v[74:75], v[58:59], v[90:91], v[74:75] op_sel_hi:[1,0,1]
	v_pk_fma_f32 v[80:81], v[56:57], v[92:93], v[10:11] op_sel_hi:[1,0,1]
	v_pk_fma_f32 v[82:83], v[58:59], v[92:93], v[12:13] op_sel_hi:[1,0,1]
	v_pk_fma_f32 v[84:85], v[60:61], v[92:93], v[14:15] op_sel_hi:[1,0,1]
	ds_read2_b32 v[86:87], v130 offset0:64 offset1:72
	ds_read_b128 v[0:3], v20 offset:10256
	ds_read_b128 v[4:7], v20 offset:10240
	ds_read_b128 v[8:11], v20 offset:10000
	ds_read_b128 v[12:15], v20 offset:9984
; #define SCAN_STEP(w0, w1, a0, a1, b0, b1, k0, k1, r0, r1, vi, vj, t) do { \
;                 SCAN_ROW(S0, S1, S2, S3, w0, w1, a0, a1, b0, b1, k0, k1, r0, r1, vi, (t) * 512); \
;                 SCAN_ROW(T0, T1, T2, T3, w0, w1, a0, a1, b0, b1, k0, k1, r0, r1, vj, (t) * 512 + 256); } while (0)
;     ...
;             SCAN_LOAD(w0, w1, a0, a1, b0, b1, k0, k1, r0, r1, vi, vj, 0);
; #pragma unroll
;             for (int t = 0; t < 16; t += 2) {
;                 SCAN_LOAD(W0, W1, A0, A1, B0, B1, K0, K1, R0, R1, VI, VJ, t + 1);
;                 SCAN_STEP(w0, w1, a0, a1, b0, b1, k0, k1, r0, r1, vi, vj, t);
;                 if (t + 2 < 16) SCAN_LOAD(w0, w1, a0, a1, b0, b1, k0, k1, r0, r1, vi, vj, t + 2);
;                 SCAN_STEP(W0, W1, A0, A1, B0, B1, K0, K1, R0, R1, VI, VJ, t + 1);
	ds_read_b128 v[30:33], v20 offset:9744
	ds_read_b128 v[34:37], v20 offset:9728
	ds_read_b128 v[38:41], v20 offset:9488
	ds_read_b128 v[42:45], v20 offset:9472
	ds_read_b128 v[54:57], v20 offset:9216
	ds_read_b128 v[58:61], v20 offset:9232
	v_add_f32_dpp v88, v29, v29 row_half_mirror row_mask:0xf bank_mask:0xf bound_ctrl:1
	v_add_f32_dpp v90, v89, v89 row_half_mirror row_mask:0xf bank_mask:0xf bound_ctrl:1
	v_pk_fma_f32 v[70:71], v[46:47], v[88:89], v[70:71] op_sel_hi:[1,0,1]
	v_pk_fma_f32 v[74:75], v[50:51], v[88:89], v[74:75] op_sel_hi:[1,0,1]
	v_pk_fma_f32 v[46:47], v[46:47], v[90:91], v[78:79] op_sel_hi:[1,0,1]
	v_pk_fma_f32 v[50:51], v[50:51], v[90:91], v[82:83] op_sel_hi:[1,0,1]
	v_pk_fma_f32 v[72:73], v[48:49], v[88:89], v[72:73] op_sel_hi:[1,0,1]
	v_pk_fma_f32 v[76:77], v[52:53], v[88:89], v[76:77] op_sel_hi:[1,0,1]
	v_pk_fma_f32 v[48:49], v[48:49], v[90:91], v[80:81] op_sel_hi:[1,0,1]
	v_pk_fma_f32 v[52:53], v[52:53], v[90:91], v[84:85] op_sel_hi:[1,0,1]
	v_pk_mul_f32 v[78:79], v[62:63], v[70:71]
	v_pk_mul_f32 v[80:81], v[66:67], v[74:75]
	v_pk_mul_f32 v[62:63], v[62:63], v[46:47]
	v_pk_mul_f32 v[66:67], v[66:67], v[50:51]
	v_pk_fma_f32 v[78:79], v[64:65], v[72:73], v[78:79]
	v_pk_fma_f32 v[62:63], v[64:65], v[48:49], v[62:63]
	v_pk_fma_f32 v[64:65], v[68:69], v[52:53], v[66:67]
	v_pk_fma_f32 v[80:81], v[68:69], v[76:77], v[80:81]
	v_pk_add_f32 v[62:63], v[62:63], v[64:65]
	s_waitcnt lgkmcnt(2)
	v_pk_mul_f32 v[64:65], v[42:43], v[70:71]
	v_pk_mul_f32 v[68:69], v[38:39], v[74:75]
	v_pk_mul_f32 v[42:43], v[42:43], v[46:47]
	v_pk_mul_f32 v[38:39], v[38:39], v[50:51]
	v_pk_add_f32 v[66:67], v[78:79], v[80:81]
	s_waitcnt lgkmcnt(1)
	v_pk_mul_f32 v[70:71], v[54:55], v[70:71]
	v_pk_mul_f32 v[78:79], v[56:57], v[72:73]
	s_waitcnt lgkmcnt(0)
	v_pk_mul_f32 v[74:75], v[58:59], v[74:75]
	v_pk_mul_f32 v[80:81], v[60:61], v[76:77]
	v_pk_mul_f32 v[46:47], v[54:55], v[46:47]
	v_pk_mul_f32 v[54:55], v[56:57], v[48:49]
	v_pk_mul_f32 v[50:51], v[58:59], v[50:51]
	v_pk_mul_f32 v[56:57], v[60:61], v[52:53]
	v_pk_fma_f32 v[58:59], v[44:45], v[72:73], v[64:65]
	v_pk_fma_f32 v[60:61], v[40:41], v[76:77], v[68:69]
	v_pk_fma_f32 v[42:43], v[44:45], v[48:49], v[42:43]
	v_pk_fma_f32 v[38:39], v[40:41], v[52:53], v[38:39]
	v_mov_b32_e32 v82, v87
	v_add_f32_e32 v29, v66, v67
	v_add_f32_e32 v62, v62, v63
	v_pk_fma_f32 v[70:71], v[86:87], v[12:13], v[70:71] op_sel_hi:[0,1,1]
	v_pk_fma_f32 v[72:73], v[86:87], v[14:15], v[78:79] op_sel_hi:[0,1,1]
	v_pk_fma_f32 v[74:75], v[86:87], v[8:9], v[74:75] op_sel_hi:[0,1,1]
	v_pk_fma_f32 v[76:77], v[86:87], v[10:11], v[80:81] op_sel_hi:[0,1,1]
	v_pk_add_f32 v[86:87], v[60:61], v[58:59]
	v_pk_add_f32 v[88:89], v[38:39], v[42:43]
	ds_write2st64_b32 v27, v29, v62 offset0:232 offset1:236
	v_add_f32_e32 v29, v86, v87
	v_add_f32_e32 v86, v88, v89
	v_add_u32_e32 v131, 0x2c00, v21
	v_add_f32_dpp v29, v29, v29 quad_perm:[1,0,3,2] row_mask:0xf bank_mask:0xf bound_ctrl:1
	v_add_f32_dpp v86, v86, v86 quad_perm:[1,0,3,2] row_mask:0xf bank_mask:0xf bound_ctrl:1
	v_pk_fma_f32 v[78:79], v[82:83], v[12:13], v[46:47] op_sel_hi:[0,1,1]
	v_pk_fma_f32 v[80:81], v[82:83], v[14:15], v[54:55] op_sel_hi:[0,1,1]
	v_pk_fma_f32 v[84:85], v[82:83], v[8:9], v[50:51] op_sel_hi:[0,1,1]
	v_pk_fma_f32 v[82:83], v[82:83], v[10:11], v[56:57] op_sel_hi:[0,1,1]
	ds_read_b128 v[8:11], v20 offset:10752
	ds_read_b128 v[12:15], v20 offset:10768
	ds_read_b128 v[38:41], v20 offset:11008
	ds_read_b128 v[42:45], v20 offset:11024
	ds_read_b128 v[46:49], v20 offset:11264
	ds_read_b128 v[50:53], v20 offset:11280
	ds_read_b128 v[54:57], v20 offset:11520
	ds_read_b128 v[58:61], v20 offset:11536
	ds_read_b128 v[62:65], v20 offset:11776
	ds_read_b128 v[66:69], v20 offset:11792
	ds_read2_b32 v[90:91], v131 offset0:192 offset1:200
	v_add_f32_dpp v29, v29, v29 quad_perm:[2,3,0,1] row_mask:0xf bank_mask:0xf bound_ctrl:1
	v_add_f32_dpp v87, v86, v86 quad_perm:[2,3,0,1] row_mask:0xf bank_mask:0xf bound_ctrl:1
	v_add_u32_e32 v132, 0x3400, v21
	v_add_f32_dpp v86, v29, v29 row_half_mirror row_mask:0xf bank_mask:0xf bound_ctrl:1
	v_add_f32_dpp v88, v87, v87 row_half_mirror row_mask:0xf bank_mask:0xf bound_ctrl:1
	v_pk_fma_f32 v[70:71], v[34:35], v[86:87], v[70:71] op_sel_hi:[1,0,1]
	v_pk_fma_f32 v[74:75], v[30:31], v[86:87], v[74:75] op_sel_hi:[1,0,1]
	v_pk_fma_f32 v[34:35], v[34:35], v[88:89], v[78:79] op_sel_hi:[1,0,1]
	v_pk_fma_f32 v[30:31], v[30:31], v[88:89], v[84:85] op_sel_hi:[1,0,1]
	v_pk_fma_f32 v[72:73], v[36:37], v[86:87], v[72:73] op_sel_hi:[1,0,1]
	v_pk_fma_f32 v[76:77], v[32:33], v[86:87], v[76:77] op_sel_hi:[1,0,1]
	v_pk_fma_f32 v[36:37], v[36:37], v[88:89], v[80:81] op_sel_hi:[1,0,1]
	v_pk_fma_f32 v[32:33], v[32:33], v[88:89], v[82:83] op_sel_hi:[1,0,1]
	v_pk_mul_f32 v[78:79], v[4:5], v[70:71]
	v_pk_mul_f32 v[80:81], v[0:1], v[74:75]
	v_pk_mul_f32 v[4:5], v[4:5], v[34:35]
	v_pk_mul_f32 v[0:1], v[0:1], v[30:31]
	s_waitcnt lgkmcnt(8)
	v_pk_mul_f32 v[82:83], v[38:39], v[70:71]
	s_waitcnt lgkmcnt(7)
	v_pk_mul_f32 v[84:85], v[42:43], v[74:75]
	v_pk_mul_f32 v[38:39], v[38:39], v[34:35]
	v_pk_mul_f32 v[42:43], v[42:43], v[30:31]
	v_pk_mul_f32 v[70:71], v[8:9], v[70:71]
	v_pk_mul_f32 v[86:87], v[10:11], v[72:73]
	v_pk_mul_f32 v[74:75], v[12:13], v[74:75]
	v_pk_mul_f32 v[88:89], v[14:15], v[76:77]
	v_pk_mul_f32 v[8:9], v[8:9], v[34:35]
	v_pk_mul_f32 v[10:11], v[10:11], v[36:37]
	v_pk_mul_f32 v[12:13], v[12:13], v[30:31]
	v_pk_mul_f32 v[14:15], v[14:15], v[32:33]
	v_pk_fma_f32 v[30:31], v[6:7], v[72:73], v[78:79]
	v_pk_fma_f32 v[34:35], v[2:3], v[76:77], v[80:81]
	v_pk_fma_f32 v[4:5], v[6:7], v[36:37], v[4:5]
	v_pk_fma_f32 v[0:1], v[2:3], v[32:33], v[0:1]
	v_pk_fma_f32 v[2:3], v[40:41], v[72:73], v[82:83]
	v_pk_fma_f32 v[6:7], v[44:45], v[76:77], v[84:85]
	v_pk_fma_f32 v[36:37], v[40:41], v[36:37], v[38:39]
	v_pk_fma_f32 v[32:33], v[44:45], v[32:33], v[42:43]
	s_waitcnt lgkmcnt(0)
; #define SCAN_STEP(w0, w1, a0, a1, b0, b1, k0, k1, r0, r1, vi, vj, t) do { \
;                 SCAN_ROW(S0, S1, S2, S3, w0, w1, a0, a1, b0, b1, k0, k1, r0, r1, vi, (t) * 512); \
;                 SCAN_ROW(T0, T1, T2, T3, w0, w1, a0, a1, b0, b1, k0, k1, r0, r1, vj, (t) * 512 + 256); } while (0)
;     ...
;             SCAN_LOAD(w0, w1, a0, a1, b0, b1, k0, k1, r0, r1, vi, vj, 0);
; #pragma unroll
;             for (int t = 0; t < 16; t += 2) {
;                 SCAN_LOAD(W0, W1, A0, A1, B0, B1, K0, K1, R0, R1, VI, VJ, t + 1);
;                 SCAN_STEP(w0, w1, a0, a1, b0, b1, k0, k1, r0, r1, vi, vj, t);
;                 if (t + 2 < 16) SCAN_LOAD(w0, w1, a0, a1, b0, b1, k0, k1, r0, r1, vi, vj, t + 2);
;                 SCAN_STEP(W0, W1, A0, A1, B0, B1, K0, K1, R0, R1, VI, VJ, t + 1);
	v_mov_b32_e32 v92, v91
	v_pk_add_f32 v[0:1], v[4:5], v[0:1]
	v_pk_add_f32 v[2:3], v[2:3], v[6:7]
	v_pk_add_f32 v[4:5], v[36:37], v[32:33]
	v_pk_fma_f32 v[78:79], v[54:55], v[92:93], v[8:9] op_sel_hi:[1,0,1]
	v_pk_add_f32 v[8:9], v[30:31], v[34:35]
	v_add_f32_e32 v0, v0, v1
	v_add_f32_e32 v1, v2, v3
	v_add_f32_e32 v2, v4, v5
	v_pk_fma_f32 v[76:77], v[60:61], v[90:91], v[88:89] op_sel_hi:[1,0,1]
	v_add_f32_e32 v6, v8, v9
	v_add_f32_dpp v29, v1, v1 quad_perm:[1,0,3,2] row_mask:0xf bank_mask:0xf bound_ctrl:1
	v_add_f32_dpp v88, v2, v2 quad_perm:[1,0,3,2] row_mask:0xf bank_mask:0xf bound_ctrl:1
	ds_write2st64_b32 v27, v6, v0 offset0:240 offset1:244
	v_add_f32_dpp v29, v29, v29 quad_perm:[2,3,0,1] row_mask:0xf bank_mask:0xf bound_ctrl:1
	v_add_f32_dpp v89, v88, v88 quad_perm:[2,3,0,1] row_mask:0xf bank_mask:0xf bound_ctrl:1
	v_pk_fma_f32 v[70:71], v[54:55], v[90:91], v[70:71] op_sel_hi:[1,0,1]
	v_pk_fma_f32 v[72:73], v[56:57], v[90:91], v[86:87] op_sel_hi:[1,0,1]
	v_pk_fma_f32 v[74:75], v[58:59], v[90:91], v[74:75] op_sel_hi:[1,0,1]
	v_pk_fma_f32 v[80:81], v[56:57], v[92:93], v[10:11] op_sel_hi:[1,0,1]
	v_pk_fma_f32 v[82:83], v[58:59], v[92:93], v[12:13] op_sel_hi:[1,0,1]
	v_pk_fma_f32 v[84:85], v[60:61], v[92:93], v[14:15] op_sel_hi:[1,0,1]
	ds_read2_b32 v[86:87], v132 offset0:64 offset1:72
	ds_read_b128 v[0:3], v20 offset:13328
	ds_read_b128 v[4:7], v20 offset:13312
	ds_read_b128 v[8:11], v20 offset:13072
	ds_read_b128 v[12:15], v20 offset:13056
	ds_read_b128 v[30:33], v20 offset:12816
	ds_read_b128 v[34:37], v20 offset:12800
	ds_read_b128 v[38:41], v20 offset:12560
	ds_read_b128 v[42:45], v20 offset:12544
	ds_read_b128 v[54:57], v20 offset:12288
	ds_read_b128 v[58:61], v20 offset:12304
	v_add_f32_dpp v88, v29, v29 row_half_mirror row_mask:0xf bank_mask:0xf bound_ctrl:1
	v_add_f32_dpp v90, v89, v89 row_half_mirror row_mask:0xf bank_mask:0xf bound_ctrl:1
	v_pk_fma_f32 v[70:71], v[46:47], v[88:89], v[70:71] op_sel_hi:[1,0,1]
	v_pk_fma_f32 v[74:75], v[50:51], v[88:89], v[74:75] op_sel_hi:[1,0,1]
	v_pk_fma_f32 v[46:47], v[46:47], v[90:91], v[78:79] op_sel_hi:[1,0,1]
	v_pk_fma_f32 v[50:51], v[50:51], v[90:91], v[82:83] op_sel_hi:[1,0,1]
	v_pk_fma_f32 v[72:73], v[48:49], v[88:89], v[72:73] op_sel_hi:[1,0,1]
	v_pk_fma_f32 v[76:77], v[52:53], v[88:89], v[76:77] op_sel_hi:[1,0,1]
	v_pk_fma_f32 v[48:49], v[48:49], v[90:91], v[80:81] op_sel_hi:[1,0,1]
	v_pk_fma_f32 v[52:53], v[52:53], v[90:91], v[84:85] op_sel_hi:[1,0,1]
	v_pk_mul_f32 v[78:79], v[62:63], v[70:71]
	v_pk_mul_f32 v[80:81], v[66:67], v[74:75]
	v_pk_mul_f32 v[62:63], v[62:63], v[46:47]
	v_pk_mul_f32 v[66:67], v[66:67], v[50:51]
	v_pk_fma_f32 v[78:79], v[64:65], v[72:73], v[78:79]
	v_pk_fma_f32 v[62:63], v[64:65], v[48:49], v[62:63]
	v_pk_fma_f32 v[64:65], v[68:69], v[52:53], v[66:67]
	v_pk_fma_f32 v[80:81], v[68:69], v[76:77], v[80:81]
	v_pk_add_f32 v[62:63], v[62:63], v[64:65]
	s_waitcnt lgkmcnt(2)
	v_pk_mul_f32 v[64:65], v[42:43], v[70:71]
	v_pk_mul_f32 v[68:69], v[38:39], v[74:75]
	v_pk_mul_f32 v[42:43], v[42:43], v[46:47]
	v_pk_mul_f32 v[38:39], v[38:39], v[50:51]
	v_pk_add_f32 v[66:67], v[78:79], v[80:81]
	s_waitcnt lgkmcnt(1)
	v_pk_mul_f32 v[70:71], v[54:55], v[70:71]
	v_pk_mul_f32 v[78:79], v[56:57], v[72:73]
	s_waitcnt lgkmcnt(0)
	v_pk_mul_f32 v[74:75], v[58:59], v[74:75]
	v_pk_mul_f32 v[80:81], v[60:61], v[76:77]
	v_pk_mul_f32 v[46:47], v[54:55], v[46:47]
	v_pk_mul_f32 v[54:55], v[56:57], v[48:49]
	v_pk_mul_f32 v[50:51], v[58:59], v[50:51]
	v_pk_mul_f32 v[56:57], v[60:61], v[52:53]
	v_pk_fma_f32 v[58:59], v[44:45], v[72:73], v[64:65]
	v_pk_fma_f32 v[60:61], v[40:41], v[76:77], v[68:69]
	v_pk_fma_f32 v[42:43], v[44:45], v[48:49], v[42:43]
	v_pk_fma_f32 v[38:39], v[40:41], v[52:53], v[38:39]
	v_mov_b32_e32 v82, v87
	v_add_f32_e32 v29, v66, v67
	v_add_f32_e32 v62, v62, v63
	v_pk_fma_f32 v[70:71], v[86:87], v[12:13], v[70:71] op_sel_hi:[0,1,1]
	v_pk_fma_f32 v[72:73], v[86:87], v[14:15], v[78:79] op_sel_hi:[0,1,1]
	v_pk_fma_f32 v[74:75], v[86:87], v[8:9], v[74:75] op_sel_hi:[0,1,1]
	v_pk_fma_f32 v[76:77], v[86:87], v[10:11], v[80:81] op_sel_hi:[0,1,1]
	v_pk_add_f32 v[86:87], v[60:61], v[58:59]
	v_pk_add_f32 v[88:89], v[38:39], v[42:43]
	v_add_u32_e32 v19, 0xc000, v27
	v_add_u32_e32 v28, 0x3800, v21
	ds_write2st64_b32 v27, v29, v62 offset0:248 offset1:252
	v_add_f32_e32 v27, v86, v87
	v_add_f32_e32 v86, v88, v89
	v_pk_fma_f32 v[78:79], v[82:83], v[12:13], v[46:47] op_sel_hi:[0,1,1]
	v_pk_fma_f32 v[80:81], v[82:83], v[14:15], v[54:55] op_sel_hi:[0,1,1]
	v_pk_fma_f32 v[84:85], v[82:83], v[8:9], v[50:51] op_sel_hi:[0,1,1]
	v_pk_fma_f32 v[82:83], v[82:83], v[10:11], v[56:57] op_sel_hi:[0,1,1]
	ds_read_b128 v[8:11], v20 offset:13824
	ds_read_b128 v[12:15], v20 offset:13840
	ds_read_b128 v[38:41], v20 offset:14080
	ds_read_b128 v[42:45], v20 offset:14096
	ds_read_b128 v[46:49], v20 offset:14336
	ds_read_b128 v[50:53], v20 offset:14352
	ds_read_b128 v[54:57], v20 offset:14592
	ds_read_b128 v[58:61], v20 offset:14608
	ds_read_b128 v[62:65], v20 offset:14848
	ds_read_b128 v[66:69], v20 offset:14864
	ds_read2_b32 v[28:29], v28 offset0:192 offset1:200
	v_add_f32_dpp v27, v27, v27 quad_perm:[1,0,3,2] row_mask:0xf bank_mask:0xf bound_ctrl:1
	v_add_f32_dpp v86, v86, v86 quad_perm:[1,0,3,2] row_mask:0xf bank_mask:0xf bound_ctrl:1
	v_add_u32_e32 v26, 0x4000, v21
	v_add_f32_dpp v27, v27, v27 quad_perm:[2,3,0,1] row_mask:0xf bank_mask:0xf bound_ctrl:1
	v_add_f32_dpp v87, v86, v86 quad_perm:[2,3,0,1] row_mask:0xf bank_mask:0xf bound_ctrl:1
	s_waitcnt lgkmcnt(0)
; #define SCAN_STEP(w0, w1, a0, a1, b0, b1, k0, k1, r0, r1, vi, vj, t) do { \
;                 SCAN_ROW(S0, S1, S2, S3, w0, w1, a0, a1, b0, b1, k0, k1, r0, r1, vi, (t) * 512); \
;                 SCAN_ROW(T0, T1, T2, T3, w0, w1, a0, a1, b0, b1, k0, k1, r0, r1, vj, (t) * 512 + 256); } while (0)
;     ...
;             SCAN_LOAD(w0, w1, a0, a1, b0, b1, k0, k1, r0, r1, vi, vj, 0);
; #pragma unroll
;             for (int t = 0; t < 16; t += 2) {
;                 SCAN_LOAD(W0, W1, A0, A1, B0, B1, K0, K1, R0, R1, VI, VJ, t + 1);
;                 SCAN_STEP(w0, w1, a0, a1, b0, b1, k0, k1, r0, r1, vi, vj, t);
;                 if (t + 2 < 16) SCAN_LOAD(w0, w1, a0, a1, b0, b1, k0, k1, r0, r1, vi, vj, t + 2);
;                 SCAN_STEP(W0, W1, A0, A1, B0, B1, K0, K1, R0, R1, VI, VJ, t + 1);
	v_mov_b32_e32 v90, v29
	v_add_f32_dpp v86, v27, v27 row_half_mirror row_mask:0xf bank_mask:0xf bound_ctrl:1
	v_add_f32_dpp v88, v87, v87 row_half_mirror row_mask:0xf bank_mask:0xf bound_ctrl:1
	v_pk_fma_f32 v[70:71], v[34:35], v[86:87], v[70:71] op_sel_hi:[1,0,1]
	v_pk_fma_f32 v[72:73], v[36:37], v[86:87], v[72:73] op_sel_hi:[1,0,1]
	v_pk_fma_f32 v[74:75], v[30:31], v[86:87], v[74:75] op_sel_hi:[1,0,1]
	v_pk_fma_f32 v[76:77], v[32:33], v[86:87], v[76:77] op_sel_hi:[1,0,1]
	v_pk_fma_f32 v[34:35], v[34:35], v[88:89], v[78:79] op_sel_hi:[1,0,1]
	v_pk_fma_f32 v[30:31], v[30:31], v[88:89], v[84:85] op_sel_hi:[1,0,1]
	v_pk_fma_f32 v[36:37], v[36:37], v[88:89], v[80:81] op_sel_hi:[1,0,1]
	v_pk_fma_f32 v[32:33], v[32:33], v[88:89], v[82:83] op_sel_hi:[1,0,1]
	v_pk_mul_f32 v[78:79], v[4:5], v[70:71]
	v_pk_mul_f32 v[80:81], v[0:1], v[74:75]
	v_pk_mul_f32 v[4:5], v[4:5], v[34:35]
	v_pk_mul_f32 v[0:1], v[0:1], v[30:31]
	v_pk_mul_f32 v[82:83], v[38:39], v[70:71]
	v_pk_mul_f32 v[84:85], v[42:43], v[74:75]
	v_pk_mul_f32 v[70:71], v[8:9], v[70:71]
	v_pk_mul_f32 v[86:87], v[10:11], v[72:73]
	v_pk_mul_f32 v[74:75], v[12:13], v[74:75]
	v_pk_mul_f32 v[88:89], v[14:15], v[76:77]
	v_pk_mul_f32 v[38:39], v[38:39], v[34:35]
	v_pk_mul_f32 v[42:43], v[42:43], v[30:31]
	v_pk_mul_f32 v[8:9], v[8:9], v[34:35]
	v_pk_mul_f32 v[12:13], v[12:13], v[30:31]
	v_pk_mul_f32 v[14:15], v[14:15], v[32:33]
	v_pk_fma_f32 v[30:31], v[6:7], v[72:73], v[78:79]
	v_pk_fma_f32 v[34:35], v[2:3], v[76:77], v[80:81]
	v_pk_fma_f32 v[4:5], v[6:7], v[36:37], v[4:5]
	v_pk_fma_f32 v[0:1], v[2:3], v[32:33], v[0:1]
	v_pk_fma_f32 v[2:3], v[40:41], v[72:73], v[82:83]
	v_pk_fma_f32 v[6:7], v[44:45], v[76:77], v[84:85]
	v_pk_fma_f32 v[70:71], v[54:55], v[28:29], v[70:71] op_sel_hi:[1,0,1]
	v_pk_fma_f32 v[72:73], v[56:57], v[28:29], v[86:87] op_sel_hi:[1,0,1]
	v_pk_fma_f32 v[74:75], v[58:59], v[28:29], v[74:75] op_sel_hi:[1,0,1]
	v_pk_fma_f32 v[76:77], v[60:61], v[28:29], v[88:89] op_sel_hi:[1,0,1]
	v_pk_fma_f32 v[28:29], v[40:41], v[36:37], v[38:39]
	v_pk_fma_f32 v[32:33], v[44:45], v[32:33], v[42:43]
	v_pk_add_f32 v[0:1], v[4:5], v[0:1]
	v_pk_add_f32 v[2:3], v[2:3], v[6:7]
	v_pk_add_f32 v[4:5], v[28:29], v[32:33]
	v_pk_fma_f32 v[78:79], v[54:55], v[90:91], v[8:9] op_sel_hi:[1,0,1]
	v_pk_add_f32 v[8:9], v[30:31], v[34:35]
	v_add_f32_e32 v0, v0, v1
	v_add_f32_e32 v1, v2, v3
	v_add_f32_e32 v2, v4, v5
	v_add_f32_e32 v6, v8, v9
	v_add_f32_dpp v84, v1, v1 quad_perm:[1,0,3,2] row_mask:0xf bank_mask:0xf bound_ctrl:1
	v_add_f32_dpp v85, v2, v2 quad_perm:[1,0,3,2] row_mask:0xf bank_mask:0xf bound_ctrl:1
	v_pk_mul_f32 v[10:11], v[10:11], v[36:37]
	ds_write2st64_b32 v19, v6, v0 offset0:64 offset1:68
	v_add_f32_dpp v84, v84, v84 quad_perm:[2,3,0,1] row_mask:0xf bank_mask:0xf bound_ctrl:1
	v_add_f32_dpp v85, v85, v85 quad_perm:[2,3,0,1] row_mask:0xf bank_mask:0xf bound_ctrl:1
	v_pk_fma_f32 v[80:81], v[56:57], v[90:91], v[10:11] op_sel_hi:[1,0,1]
	v_pk_fma_f32 v[58:59], v[58:59], v[90:91], v[12:13] op_sel_hi:[1,0,1]
	v_pk_fma_f32 v[60:61], v[60:61], v[90:91], v[14:15] op_sel_hi:[1,0,1]
	ds_read2_b32 v[82:83], v26 offset0:64 offset1:72
	ds_read_b128 v[0:3], v20 offset:16400
	ds_read_b128 v[4:7], v20 offset:16384
	ds_read_b128 v[8:11], v20 offset:16144
	ds_read_b128 v[12:15], v20 offset:16128
	ds_read_b128 v[26:29], v20 offset:15888
	ds_read_b128 v[30:33], v20 offset:15872
	ds_read_b128 v[34:37], v20 offset:15632
	ds_read_b128 v[38:41], v20 offset:15616
	ds_read_b128 v[42:45], v20 offset:15360
	ds_read_b128 v[54:57], v20 offset:15376
	v_add_f32_dpp v84, v84, v84 row_half_mirror row_mask:0xf bank_mask:0xf bound_ctrl:1
	v_add_f32_dpp v86, v85, v85 row_half_mirror row_mask:0xf bank_mask:0xf bound_ctrl:1
	v_pk_fma_f32 v[70:71], v[46:47], v[84:85], v[70:71] op_sel_hi:[1,0,1]
	v_pk_fma_f32 v[74:75], v[50:51], v[84:85], v[74:75] op_sel_hi:[1,0,1]
	v_pk_fma_f32 v[46:47], v[46:47], v[86:87], v[78:79] op_sel_hi:[1,0,1]
	v_pk_fma_f32 v[50:51], v[50:51], v[86:87], v[58:59] op_sel_hi:[1,0,1]
	v_pk_fma_f32 v[72:73], v[48:49], v[84:85], v[72:73] op_sel_hi:[1,0,1]
	v_pk_fma_f32 v[76:77], v[52:53], v[84:85], v[76:77] op_sel_hi:[1,0,1]
	v_pk_fma_f32 v[48:49], v[48:49], v[86:87], v[80:81] op_sel_hi:[1,0,1]
	v_pk_fma_f32 v[52:53], v[52:53], v[86:87], v[60:61] op_sel_hi:[1,0,1]
	v_pk_mul_f32 v[58:59], v[62:63], v[70:71]
	v_pk_mul_f32 v[60:61], v[66:67], v[74:75]
	v_pk_mul_f32 v[62:63], v[62:63], v[46:47]
	v_pk_mul_f32 v[66:67], v[66:67], v[50:51]
	v_pk_fma_f32 v[58:59], v[64:65], v[72:73], v[58:59]
	v_pk_fma_f32 v[60:61], v[68:69], v[76:77], v[60:61]
	v_pk_fma_f32 v[62:63], v[64:65], v[48:49], v[62:63]
	v_pk_fma_f32 v[64:65], v[68:69], v[52:53], v[66:67]
	v_pk_add_f32 v[58:59], v[58:59], v[60:61]
	v_pk_add_f32 v[60:61], v[62:63], v[64:65]
	s_waitcnt lgkmcnt(2)
	v_pk_mul_f32 v[62:63], v[38:39], v[70:71]
	v_pk_mul_f32 v[64:65], v[34:35], v[74:75]
	v_pk_mul_f32 v[38:39], v[38:39], v[46:47]
	v_pk_mul_f32 v[34:35], v[34:35], v[50:51]
	s_waitcnt lgkmcnt(1)
	v_pk_mul_f32 v[66:67], v[42:43], v[70:71]
	v_pk_mul_f32 v[68:69], v[44:45], v[72:73]
	s_waitcnt lgkmcnt(0)
; #define SCAN_STEP(w0, w1, a0, a1, b0, b1, k0, k1, r0, r1, vi, vj, t) do { \
;                 SCAN_ROW(S0, S1, S2, S3, w0, w1, a0, a1, b0, b1, k0, k1, r0, r1, vi, (t) * 512); \
;                 SCAN_ROW(T0, T1, T2, T3, w0, w1, a0, a1, b0, b1, k0, k1, r0, r1, vj, (t) * 512 + 256); } while (0)
;     ...
;             SCAN_LOAD(w0, w1, a0, a1, b0, b1, k0, k1, r0, r1, vi, vj, 0);
; #pragma unroll
;             for (int t = 0; t < 16; t += 2) {
;                 SCAN_LOAD(W0, W1, A0, A1, B0, B1, K0, K1, R0, R1, VI, VJ, t + 1);
;                 SCAN_STEP(w0, w1, a0, a1, b0, b1, k0, k1, r0, r1, vi, vj, t);
;                 if (t + 2 < 16) SCAN_LOAD(w0, w1, a0, a1, b0, b1, k0, k1, r0, r1, vi, vj, t + 2);
;                 SCAN_STEP(W0, W1, A0, A1, B0, B1, K0, K1, R0, R1, VI, VJ, t + 1);
	v_pk_mul_f32 v[70:71], v[54:55], v[74:75]
	v_pk_mul_f32 v[74:75], v[56:57], v[76:77]
	v_pk_mul_f32 v[42:43], v[42:43], v[46:47]
	v_pk_mul_f32 v[46:47], v[54:55], v[50:51]
	v_pk_mul_f32 v[50:51], v[56:57], v[52:53]
	v_add_f32_e32 v58, v58, v59
	v_add_f32_e32 v59, v60, v61
	v_pk_fma_f32 v[54:55], v[40:41], v[72:73], v[62:63]
	v_pk_fma_f32 v[56:57], v[36:37], v[76:77], v[64:65]
	v_pk_fma_f32 v[38:39], v[40:41], v[48:49], v[38:39]
	v_pk_fma_f32 v[34:35], v[36:37], v[52:53], v[34:35]
	v_add_u32_e32 v25, 0x4400, v21
	v_mov_b32_e32 v78, v83
	v_pk_mul_f32 v[44:45], v[44:45], v[48:49]
	v_pk_fma_f32 v[66:67], v[82:83], v[12:13], v[66:67] op_sel_hi:[0,1,1]
	v_pk_fma_f32 v[68:69], v[82:83], v[14:15], v[68:69] op_sel_hi:[0,1,1]
	v_pk_fma_f32 v[70:71], v[82:83], v[8:9], v[70:71] op_sel_hi:[0,1,1]
	v_pk_fma_f32 v[72:73], v[82:83], v[10:11], v[74:75] op_sel_hi:[0,1,1]
	ds_write2st64_b32 v19, v58, v59 offset0:72 offset1:76
	v_pk_add_f32 v[82:83], v[56:57], v[54:55]
	v_pk_add_f32 v[84:85], v[34:35], v[38:39]
	v_pk_fma_f32 v[74:75], v[78:79], v[12:13], v[42:43] op_sel_hi:[0,1,1]
	v_pk_fma_f32 v[76:77], v[78:79], v[14:15], v[44:45] op_sel_hi:[0,1,1]
	v_pk_fma_f32 v[80:81], v[78:79], v[8:9], v[46:47] op_sel_hi:[0,1,1]
	v_pk_fma_f32 v[78:79], v[78:79], v[10:11], v[50:51] op_sel_hi:[0,1,1]
	ds_read_b128 v[8:11], v20 offset:16896
	ds_read_b128 v[12:15], v20 offset:16912
	ds_read_b128 v[34:37], v20 offset:17152
	ds_read_b128 v[38:41], v20 offset:17168
	ds_read_b128 v[42:45], v20 offset:17408
	ds_read_b128 v[46:49], v20 offset:17424
	ds_read_b128 v[50:53], v20 offset:17664
	ds_read_b128 v[54:57], v20 offset:17680
	ds_read_b128 v[58:61], v20 offset:17920
	ds_read_b128 v[62:65], v20 offset:17936
	ds_read2_b32 v[86:87], v25 offset0:192 offset1:200
	v_add_f32_e32 v25, v82, v83
	v_add_f32_e32 v82, v84, v85
	v_add_u32_e32 v24, 0x4c00, v21
	v_add_f32_dpp v25, v25, v25 quad_perm:[1,0,3,2] row_mask:0xf bank_mask:0xf bound_ctrl:1
	v_add_f32_dpp v82, v82, v82 quad_perm:[1,0,3,2] row_mask:0xf bank_mask:0xf bound_ctrl:1
	s_waitcnt lgkmcnt(0)
	v_mov_b32_e32 v88, v87
	v_add_f32_dpp v25, v25, v25 quad_perm:[2,3,0,1] row_mask:0xf bank_mask:0xf bound_ctrl:1
	v_add_f32_dpp v83, v82, v82 quad_perm:[2,3,0,1] row_mask:0xf bank_mask:0xf bound_ctrl:1
	v_add_u32_e32 v23, 0x5000, v21
	v_add_f32_dpp v82, v25, v25 row_half_mirror row_mask:0xf bank_mask:0xf bound_ctrl:1
	v_add_f32_dpp v84, v83, v83 row_half_mirror row_mask:0xf bank_mask:0xf bound_ctrl:1
	v_pk_fma_f32 v[66:67], v[30:31], v[82:83], v[66:67] op_sel_hi:[1,0,1]
	v_pk_fma_f32 v[70:71], v[26:27], v[82:83], v[70:71] op_sel_hi:[1,0,1]
	v_pk_fma_f32 v[30:31], v[30:31], v[84:85], v[74:75] op_sel_hi:[1,0,1]
	v_pk_fma_f32 v[26:27], v[26:27], v[84:85], v[80:81] op_sel_hi:[1,0,1]
	v_pk_fma_f32 v[68:69], v[32:33], v[82:83], v[68:69] op_sel_hi:[1,0,1]
	v_pk_fma_f32 v[72:73], v[28:29], v[82:83], v[72:73] op_sel_hi:[1,0,1]
	v_pk_fma_f32 v[32:33], v[32:33], v[84:85], v[76:77] op_sel_hi:[1,0,1]
	v_pk_fma_f32 v[28:29], v[28:29], v[84:85], v[78:79] op_sel_hi:[1,0,1]
	v_pk_mul_f32 v[74:75], v[4:5], v[66:67]
	v_pk_mul_f32 v[76:77], v[0:1], v[70:71]
	v_pk_mul_f32 v[4:5], v[4:5], v[30:31]
	v_pk_mul_f32 v[0:1], v[0:1], v[26:27]
	v_pk_mul_f32 v[78:79], v[34:35], v[66:67]
	v_pk_mul_f32 v[80:81], v[38:39], v[70:71]
	v_pk_mul_f32 v[34:35], v[34:35], v[30:31]
	v_pk_mul_f32 v[38:39], v[38:39], v[26:27]
	v_pk_mul_f32 v[66:67], v[8:9], v[66:67]
	v_pk_mul_f32 v[82:83], v[10:11], v[68:69]
	v_pk_mul_f32 v[70:71], v[12:13], v[70:71]
	v_pk_mul_f32 v[84:85], v[14:15], v[72:73]
	v_pk_mul_f32 v[8:9], v[8:9], v[30:31]
	v_pk_mul_f32 v[10:11], v[10:11], v[32:33]
	v_pk_mul_f32 v[12:13], v[12:13], v[26:27]
	v_pk_mul_f32 v[14:15], v[14:15], v[28:29]
	v_pk_fma_f32 v[26:27], v[6:7], v[68:69], v[74:75]
	v_pk_fma_f32 v[30:31], v[2:3], v[72:73], v[76:77]
	v_pk_fma_f32 v[4:5], v[6:7], v[32:33], v[4:5]
	v_pk_fma_f32 v[0:1], v[2:3], v[28:29], v[0:1]
	v_pk_fma_f32 v[2:3], v[36:37], v[68:69], v[78:79]
	v_pk_fma_f32 v[6:7], v[40:41], v[72:73], v[80:81]
	v_pk_fma_f32 v[32:33], v[36:37], v[32:33], v[34:35]
	v_pk_fma_f32 v[28:29], v[40:41], v[28:29], v[38:39]
	v_pk_add_f32 v[0:1], v[4:5], v[0:1]
	v_pk_add_f32 v[2:3], v[2:3], v[6:7]
	v_pk_add_f32 v[4:5], v[32:33], v[28:29]
	v_pk_fma_f32 v[40:41], v[50:51], v[88:89], v[8:9] op_sel_hi:[1,0,1]
	v_pk_add_f32 v[8:9], v[26:27], v[30:31]
	v_add_f32_e32 v0, v0, v1
	v_add_f32_e32 v1, v2, v3
	v_add_f32_e32 v2, v4, v5
	v_pk_fma_f32 v[68:69], v[52:53], v[86:87], v[82:83] op_sel_hi:[1,0,1]
	v_add_f32_e32 v6, v8, v9
	v_add_f32_dpp v82, v1, v1 quad_perm:[1,0,3,2] row_mask:0xf bank_mask:0xf bound_ctrl:1
	v_add_f32_dpp v83, v2, v2 quad_perm:[1,0,3,2] row_mask:0xf bank_mask:0xf bound_ctrl:1
	ds_write2st64_b32 v19, v6, v0 offset0:80 offset1:84
	v_add_f32_dpp v82, v82, v82 quad_perm:[2,3,0,1] row_mask:0xf bank_mask:0xf bound_ctrl:1
	v_add_f32_dpp v83, v83, v83 quad_perm:[2,3,0,1] row_mask:0xf bank_mask:0xf bound_ctrl:1
	v_pk_fma_f32 v[66:67], v[50:51], v[86:87], v[66:67] op_sel_hi:[1,0,1]
	v_pk_fma_f32 v[70:71], v[54:55], v[86:87], v[70:71] op_sel_hi:[1,0,1]
	v_pk_fma_f32 v[72:73], v[56:57], v[86:87], v[84:85] op_sel_hi:[1,0,1]
	v_pk_fma_f32 v[74:75], v[52:53], v[88:89], v[10:11] op_sel_hi:[1,0,1]
	v_pk_fma_f32 v[76:77], v[54:55], v[88:89], v[12:13] op_sel_hi:[1,0,1]
	v_pk_fma_f32 v[78:79], v[56:57], v[88:89], v[14:15] op_sel_hi:[1,0,1]
	ds_read2_b32 v[80:81], v24 offset0:64 offset1:72
	ds_read_b128 v[0:3], v20 offset:19472
	ds_read_b128 v[4:7], v20 offset:19456
	ds_read_b128 v[8:11], v20 offset:19216
	ds_read_b128 v[12:15], v20 offset:19200
	ds_read_b128 v[24:27], v20 offset:18960
	ds_read_b128 v[28:31], v20 offset:18944
	ds_read_b128 v[32:35], v20 offset:18704
	ds_read_b128 v[36:39], v20 offset:18688
	ds_read_b128 v[50:53], v20 offset:18432
	ds_read_b128 v[54:57], v20 offset:18448
	v_add_f32_dpp v82, v82, v82 row_half_mirror row_mask:0xf bank_mask:0xf bound_ctrl:1
	v_add_f32_dpp v84, v83, v83 row_half_mirror row_mask:0xf bank_mask:0xf bound_ctrl:1
	v_pk_fma_f32 v[66:67], v[42:43], v[82:83], v[66:67] op_sel_hi:[1,0,1]
	v_pk_fma_f32 v[68:69], v[44:45], v[82:83], v[68:69] op_sel_hi:[1,0,1]
	v_pk_fma_f32 v[70:71], v[46:47], v[82:83], v[70:71] op_sel_hi:[1,0,1]
	v_pk_fma_f32 v[40:41], v[42:43], v[84:85], v[40:41] op_sel_hi:[1,0,1]
	v_pk_fma_f32 v[42:43], v[44:45], v[84:85], v[74:75] op_sel_hi:[1,0,1]
	v_pk_fma_f32 v[44:45], v[46:47], v[84:85], v[76:77] op_sel_hi:[1,0,1]
	v_pk_fma_f32 v[72:73], v[48:49], v[82:83], v[72:73] op_sel_hi:[1,0,1]
	v_pk_fma_f32 v[46:47], v[48:49], v[84:85], v[78:79] op_sel_hi:[1,0,1]
	v_pk_mul_f32 v[48:49], v[58:59], v[66:67]
	v_pk_mul_f32 v[74:75], v[62:63], v[70:71]
	v_pk_mul_f32 v[58:59], v[58:59], v[40:41]
	v_pk_mul_f32 v[62:63], v[62:63], v[44:45]
	v_pk_fma_f32 v[48:49], v[60:61], v[68:69], v[48:49]
	v_pk_fma_f32 v[74:75], v[64:65], v[72:73], v[74:75]
	v_pk_fma_f32 v[58:59], v[60:61], v[42:43], v[58:59]
	v_pk_fma_f32 v[60:61], v[64:65], v[46:47], v[62:63]
	v_pk_add_f32 v[48:49], v[48:49], v[74:75]
	v_pk_add_f32 v[58:59], v[58:59], v[60:61]
	s_waitcnt lgkmcnt(2)
; #define SCAN_STEP(w0, w1, a0, a1, b0, b1, k0, k1, r0, r1, vi, vj, t) do { \
;                 SCAN_ROW(S0, S1, S2, S3, w0, w1, a0, a1, b0, b1, k0, k1, r0, r1, vi, (t) * 512); \
;                 SCAN_ROW(T0, T1, T2, T3, w0, w1, a0, a1, b0, b1, k0, k1, r0, r1, vj, (t) * 512 + 256); } while (0)
;     ...
;             SCAN_LOAD(w0, w1, a0, a1, b0, b1, k0, k1, r0, r1, vi, vj, 0);
; #pragma unroll
;             for (int t = 0; t < 16; t += 2) {
;                 SCAN_LOAD(W0, W1, A0, A1, B0, B1, K0, K1, R0, R1, VI, VJ, t + 1);
;                 SCAN_STEP(w0, w1, a0, a1, b0, b1, k0, k1, r0, r1, vi, vj, t);
;                 if (t + 2 < 16) SCAN_LOAD(w0, w1, a0, a1, b0, b1, k0, k1, r0, r1, vi, vj, t + 2);
;                 SCAN_STEP(W0, W1, A0, A1, B0, B1, K0, K1, R0, R1, VI, VJ, t + 1);
	v_pk_mul_f32 v[60:61], v[36:37], v[66:67]
	v_pk_mul_f32 v[62:63], v[32:33], v[70:71]
	v_pk_mul_f32 v[36:37], v[36:37], v[40:41]
	v_pk_mul_f32 v[32:33], v[32:33], v[44:45]
	s_waitcnt lgkmcnt(1)
	v_pk_mul_f32 v[64:65], v[50:51], v[66:67]
	v_pk_mul_f32 v[66:67], v[52:53], v[68:69]
	s_waitcnt lgkmcnt(0)
	v_pk_mul_f32 v[70:71], v[54:55], v[70:71]
	v_pk_mul_f32 v[74:75], v[56:57], v[72:73]
	v_pk_mul_f32 v[40:41], v[50:51], v[40:41]
	v_pk_mul_f32 v[50:51], v[52:53], v[42:43]
	v_pk_mul_f32 v[44:45], v[54:55], v[44:45]
	v_pk_mul_f32 v[52:53], v[56:57], v[46:47]
	v_add_f32_e32 v56, v48, v49
	v_add_f32_e32 v57, v58, v59
	v_pk_fma_f32 v[48:49], v[38:39], v[68:69], v[60:61]
	v_pk_fma_f32 v[54:55], v[34:35], v[72:73], v[62:63]
	v_pk_fma_f32 v[36:37], v[38:39], v[42:43], v[36:37]
	v_pk_fma_f32 v[32:33], v[34:35], v[46:47], v[32:33]
	v_mov_b32_e32 v76, v81
	v_pk_fma_f32 v[64:65], v[80:81], v[12:13], v[64:65] op_sel_hi:[0,1,1]
	v_pk_fma_f32 v[66:67], v[80:81], v[14:15], v[66:67] op_sel_hi:[0,1,1]
	v_pk_fma_f32 v[68:69], v[80:81], v[8:9], v[70:71] op_sel_hi:[0,1,1]
	v_pk_fma_f32 v[70:71], v[80:81], v[10:11], v[74:75] op_sel_hi:[0,1,1]
	ds_write2st64_b32 v19, v56, v57 offset0:88 offset1:92
	v_pk_add_f32 v[80:81], v[54:55], v[48:49]
	v_pk_add_f32 v[82:83], v[32:33], v[36:37]
	v_pk_fma_f32 v[72:73], v[76:77], v[12:13], v[40:41] op_sel_hi:[0,1,1]
	v_pk_fma_f32 v[74:75], v[76:77], v[14:15], v[50:51] op_sel_hi:[0,1,1]
	v_pk_fma_f32 v[78:79], v[76:77], v[8:9], v[44:45] op_sel_hi:[0,1,1]
	v_pk_fma_f32 v[76:77], v[76:77], v[10:11], v[52:53] op_sel_hi:[0,1,1]
	ds_read_b128 v[8:11], v20 offset:19968
	ds_read_b128 v[12:15], v20 offset:19984
	ds_read_b128 v[32:35], v20 offset:20224
	ds_read_b128 v[36:39], v20 offset:20240
	ds_read_b128 v[40:43], v20 offset:20480
	ds_read_b128 v[44:47], v20 offset:20496
	ds_read_b128 v[48:51], v20 offset:20736
	ds_read_b128 v[52:55], v20 offset:20752
	ds_read_b128 v[56:59], v20 offset:20992
	ds_read_b128 v[60:63], v20 offset:21008
	ds_read2_b32 v[84:85], v23 offset0:192 offset1:200
	v_add_f32_e32 v23, v80, v81
	v_add_f32_e32 v80, v82, v83
	v_add_u32_e32 v22, 0x5800, v21
	v_add_f32_dpp v23, v23, v23 quad_perm:[1,0,3,2] row_mask:0xf bank_mask:0xf bound_ctrl:1
	v_add_f32_dpp v80, v80, v80 quad_perm:[1,0,3,2] row_mask:0xf bank_mask:0xf bound_ctrl:1
	s_waitcnt lgkmcnt(0)
	v_mov_b32_e32 v86, v85
	v_add_f32_dpp v23, v23, v23 quad_perm:[2,3,0,1] row_mask:0xf bank_mask:0xf bound_ctrl:1
	v_add_f32_dpp v81, v80, v80 quad_perm:[2,3,0,1] row_mask:0xf bank_mask:0xf bound_ctrl:1
	v_add_u32_e32 v21, 0x5c00, v21
	v_add_f32_dpp v80, v23, v23 row_half_mirror row_mask:0xf bank_mask:0xf bound_ctrl:1
	v_add_f32_dpp v82, v81, v81 row_half_mirror row_mask:0xf bank_mask:0xf bound_ctrl:1
	v_pk_fma_f32 v[64:65], v[28:29], v[80:81], v[64:65] op_sel_hi:[1,0,1]
	v_pk_fma_f32 v[68:69], v[24:25], v[80:81], v[68:69] op_sel_hi:[1,0,1]
	v_pk_fma_f32 v[28:29], v[28:29], v[82:83], v[72:73] op_sel_hi:[1,0,1]
	v_pk_fma_f32 v[24:25], v[24:25], v[82:83], v[78:79] op_sel_hi:[1,0,1]
	v_pk_fma_f32 v[66:67], v[30:31], v[80:81], v[66:67] op_sel_hi:[1,0,1]
	v_pk_fma_f32 v[70:71], v[26:27], v[80:81], v[70:71] op_sel_hi:[1,0,1]
	v_pk_fma_f32 v[30:31], v[30:31], v[82:83], v[74:75] op_sel_hi:[1,0,1]
	v_pk_fma_f32 v[26:27], v[26:27], v[82:83], v[76:77] op_sel_hi:[1,0,1]
	v_pk_mul_f32 v[72:73], v[4:5], v[64:65]
	v_pk_mul_f32 v[74:75], v[0:1], v[68:69]
	v_pk_mul_f32 v[4:5], v[4:5], v[28:29]
	v_pk_mul_f32 v[0:1], v[0:1], v[24:25]
	v_pk_mul_f32 v[76:77], v[32:33], v[64:65]
	v_pk_mul_f32 v[78:79], v[36:37], v[68:69]
	v_pk_mul_f32 v[32:33], v[32:33], v[28:29]
	v_pk_mul_f32 v[36:37], v[36:37], v[24:25]
	v_pk_mul_f32 v[64:65], v[8:9], v[64:65]
	v_pk_mul_f32 v[80:81], v[10:11], v[66:67]
	v_pk_mul_f32 v[68:69], v[12:13], v[68:69]
	v_pk_mul_f32 v[82:83], v[14:15], v[70:71]
	v_pk_mul_f32 v[8:9], v[8:9], v[28:29]
	v_pk_mul_f32 v[10:11], v[10:11], v[30:31]
	v_pk_mul_f32 v[12:13], v[12:13], v[24:25]
	v_pk_mul_f32 v[14:15], v[14:15], v[26:27]
	v_pk_fma_f32 v[24:25], v[6:7], v[66:67], v[72:73]
	v_pk_fma_f32 v[28:29], v[2:3], v[70:71], v[74:75]
	v_pk_fma_f32 v[4:5], v[6:7], v[30:31], v[4:5]
	v_pk_fma_f32 v[0:1], v[2:3], v[26:27], v[0:1]
	v_pk_fma_f32 v[2:3], v[34:35], v[66:67], v[76:77]
	v_pk_fma_f32 v[6:7], v[38:39], v[70:71], v[78:79]
	v_pk_fma_f32 v[30:31], v[34:35], v[30:31], v[32:33]
	v_pk_fma_f32 v[26:27], v[38:39], v[26:27], v[36:37]
	v_pk_add_f32 v[0:1], v[4:5], v[0:1]
	v_pk_add_f32 v[2:3], v[2:3], v[6:7]
	v_pk_add_f32 v[4:5], v[30:31], v[26:27]
	v_pk_fma_f32 v[38:39], v[48:49], v[86:87], v[8:9] op_sel_hi:[1,0,1]
	v_pk_add_f32 v[8:9], v[24:25], v[28:29]
	v_add_f32_e32 v0, v0, v1
	v_add_f32_e32 v1, v2, v3
	v_add_f32_e32 v2, v4, v5
	v_pk_fma_f32 v[66:67], v[50:51], v[84:85], v[80:81] op_sel_hi:[1,0,1]
	v_add_f32_e32 v6, v8, v9
	v_add_f32_dpp v80, v1, v1 quad_perm:[1,0,3,2] row_mask:0xf bank_mask:0xf bound_ctrl:1
	v_add_f32_dpp v81, v2, v2 quad_perm:[1,0,3,2] row_mask:0xf bank_mask:0xf bound_ctrl:1
	ds_write2st64_b32 v19, v6, v0 offset0:96 offset1:100
	v_add_f32_dpp v80, v80, v80 quad_perm:[2,3,0,1] row_mask:0xf bank_mask:0xf bound_ctrl:1
	v_add_f32_dpp v81, v81, v81 quad_perm:[2,3,0,1] row_mask:0xf bank_mask:0xf bound_ctrl:1
	v_pk_fma_f32 v[64:65], v[48:49], v[84:85], v[64:65] op_sel_hi:[1,0,1]
	v_pk_fma_f32 v[68:69], v[52:53], v[84:85], v[68:69] op_sel_hi:[1,0,1]
	v_pk_fma_f32 v[70:71], v[54:55], v[84:85], v[82:83] op_sel_hi:[1,0,1]
	v_pk_fma_f32 v[72:73], v[50:51], v[86:87], v[10:11] op_sel_hi:[1,0,1]
	v_pk_fma_f32 v[74:75], v[52:53], v[86:87], v[12:13] op_sel_hi:[1,0,1]
	v_pk_fma_f32 v[76:77], v[54:55], v[86:87], v[14:15] op_sel_hi:[1,0,1]
	ds_read2_b32 v[78:79], v22 offset0:64 offset1:72
; #define SCAN_STEP(w0, w1, a0, a1, b0, b1, k0, k1, r0, r1, vi, vj, t) do { \
;                 SCAN_ROW(S0, S1, S2, S3, w0, w1, a0, a1, b0, b1, k0, k1, r0, r1, vi, (t) * 512); \
;                 SCAN_ROW(T0, T1, T2, T3, w0, w1, a0, a1, b0, b1, k0, k1, r0, r1, vj, (t) * 512 + 256); } while (0)
;     ...
;             SCAN_LOAD(w0, w1, a0, a1, b0, b1, k0, k1, r0, r1, vi, vj, 0);
; #pragma unroll
;             for (int t = 0; t < 16; t += 2) {
;                 SCAN_LOAD(W0, W1, A0, A1, B0, B1, K0, K1, R0, R1, VI, VJ, t + 1);
;                 SCAN_STEP(w0, w1, a0, a1, b0, b1, k0, k1, r0, r1, vi, vj, t);
;                 if (t + 2 < 16) SCAN_LOAD(w0, w1, a0, a1, b0, b1, k0, k1, r0, r1, vi, vj, t + 2);
;                 SCAN_STEP(W0, W1, A0, A1, B0, B1, K0, K1, R0, R1, VI, VJ, t + 1);
	ds_read_b128 v[0:3], v20 offset:22544
	ds_read_b128 v[4:7], v20 offset:22528
	ds_read_b128 v[8:11], v20 offset:22288
	ds_read_b128 v[12:15], v20 offset:22272
	ds_read_b128 v[22:25], v20 offset:22032
	ds_read_b128 v[26:29], v20 offset:22016
	ds_read_b128 v[30:33], v20 offset:21776
	ds_read_b128 v[34:37], v20 offset:21760
	ds_read_b128 v[48:51], v20 offset:21504
	ds_read_b128 v[52:55], v20 offset:21520
	v_add_f32_dpp v80, v80, v80 row_half_mirror row_mask:0xf bank_mask:0xf bound_ctrl:1
	v_add_f32_dpp v82, v81, v81 row_half_mirror row_mask:0xf bank_mask:0xf bound_ctrl:1
	v_pk_fma_f32 v[64:65], v[40:41], v[80:81], v[64:65] op_sel_hi:[1,0,1]
	v_pk_fma_f32 v[66:67], v[42:43], v[80:81], v[66:67] op_sel_hi:[1,0,1]
	v_pk_fma_f32 v[68:69], v[44:45], v[80:81], v[68:69] op_sel_hi:[1,0,1]
	v_pk_fma_f32 v[38:39], v[40:41], v[82:83], v[38:39] op_sel_hi:[1,0,1]
	v_pk_fma_f32 v[40:41], v[42:43], v[82:83], v[72:73] op_sel_hi:[1,0,1]
	v_pk_fma_f32 v[42:43], v[44:45], v[82:83], v[74:75] op_sel_hi:[1,0,1]
	v_pk_fma_f32 v[70:71], v[46:47], v[80:81], v[70:71] op_sel_hi:[1,0,1]
	v_pk_fma_f32 v[44:45], v[46:47], v[82:83], v[76:77] op_sel_hi:[1,0,1]
	v_pk_mul_f32 v[46:47], v[56:57], v[64:65]
	v_pk_mul_f32 v[72:73], v[60:61], v[68:69]
	v_pk_mul_f32 v[56:57], v[56:57], v[38:39]
	v_pk_mul_f32 v[60:61], v[60:61], v[42:43]
	v_pk_fma_f32 v[46:47], v[58:59], v[66:67], v[46:47]
	v_pk_fma_f32 v[72:73], v[62:63], v[70:71], v[72:73]
	v_pk_fma_f32 v[56:57], v[58:59], v[40:41], v[56:57]
	v_pk_fma_f32 v[58:59], v[62:63], v[44:45], v[60:61]
	v_pk_add_f32 v[46:47], v[46:47], v[72:73]
	v_pk_add_f32 v[56:57], v[56:57], v[58:59]
	s_waitcnt lgkmcnt(2)
	v_pk_mul_f32 v[58:59], v[34:35], v[64:65]
	v_pk_mul_f32 v[60:61], v[30:31], v[68:69]
	v_pk_mul_f32 v[34:35], v[34:35], v[38:39]
	v_pk_mul_f32 v[30:31], v[30:31], v[42:43]
	s_waitcnt lgkmcnt(1)
	v_pk_mul_f32 v[62:63], v[48:49], v[64:65]
	v_pk_mul_f32 v[64:65], v[50:51], v[66:67]
	s_waitcnt lgkmcnt(0)
	v_pk_mul_f32 v[68:69], v[52:53], v[68:69]
	v_pk_mul_f32 v[72:73], v[54:55], v[70:71]
	v_pk_mul_f32 v[38:39], v[48:49], v[38:39]
	v_pk_mul_f32 v[48:49], v[50:51], v[40:41]
	v_pk_mul_f32 v[42:43], v[52:53], v[42:43]
	v_pk_mul_f32 v[50:51], v[54:55], v[44:45]
	v_add_f32_e32 v54, v46, v47
	v_pk_fma_f32 v[46:47], v[36:37], v[66:67], v[58:59]
	v_pk_fma_f32 v[52:53], v[32:33], v[70:71], v[60:61]
	v_pk_fma_f32 v[34:35], v[36:37], v[40:41], v[34:35]
	v_pk_fma_f32 v[30:31], v[32:33], v[44:45], v[30:31]
	v_mov_b32_e32 v74, v79
	v_add_f32_e32 v55, v56, v57
	v_pk_fma_f32 v[62:63], v[78:79], v[12:13], v[62:63] op_sel_hi:[0,1,1]
	v_pk_fma_f32 v[64:65], v[78:79], v[14:15], v[64:65] op_sel_hi:[0,1,1]
	v_pk_fma_f32 v[66:67], v[78:79], v[8:9], v[68:69] op_sel_hi:[0,1,1]
	v_pk_fma_f32 v[68:69], v[78:79], v[10:11], v[72:73] op_sel_hi:[0,1,1]
	v_pk_add_f32 v[78:79], v[52:53], v[46:47]
	v_pk_add_f32 v[80:81], v[30:31], v[34:35]
	ds_write2st64_b32 v19, v54, v55 offset0:104 offset1:108
	v_add_f32_e32 v78, v78, v79
	v_add_f32_e32 v79, v80, v81
	v_pk_fma_f32 v[70:71], v[74:75], v[12:13], v[38:39] op_sel_hi:[0,1,1]
	v_pk_fma_f32 v[72:73], v[74:75], v[14:15], v[48:49] op_sel_hi:[0,1,1]
	v_pk_fma_f32 v[76:77], v[74:75], v[8:9], v[42:43] op_sel_hi:[0,1,1]
	v_pk_fma_f32 v[74:75], v[74:75], v[10:11], v[50:51] op_sel_hi:[0,1,1]
	ds_read_b128 v[8:11], v20 offset:23040
	ds_read_b128 v[12:15], v20 offset:23056
	ds_read_b128 v[30:33], v20 offset:23296
	ds_read_b128 v[34:37], v20 offset:23312
	ds_read_b128 v[38:41], v20 offset:23552
	ds_read_b128 v[42:45], v20 offset:23568
	ds_read_b128 v[46:49], v20 offset:23808
	ds_read_b128 v[50:53], v20 offset:23824
	ds_read_b128 v[54:57], v20 offset:24064
	ds_read_b128 v[58:61], v20 offset:24080
	ds_read2_b32 v[20:21], v21 offset0:192 offset1:200
	v_add_f32_dpp v78, v78, v78 quad_perm:[1,0,3,2] row_mask:0xf bank_mask:0xf bound_ctrl:1
	v_add_f32_dpp v79, v79, v79 quad_perm:[1,0,3,2] row_mask:0xf bank_mask:0xf bound_ctrl:1
	s_add_i32 s1, s1, 1
	v_add_f32_dpp v78, v78, v78 quad_perm:[2,3,0,1] row_mask:0xf bank_mask:0xf bound_ctrl:1
	v_add_f32_dpp v79, v79, v79 quad_perm:[2,3,0,1] row_mask:0xf bank_mask:0xf bound_ctrl:1
	s_waitcnt lgkmcnt(0)
; #define SCAN_STEP(w0, w1, a0, a1, b0, b1, k0, k1, r0, r1, vi, vj, t) do { \
;                 SCAN_ROW(S0, S1, S2, S3, w0, w1, a0, a1, b0, b1, k0, k1, r0, r1, vi, (t) * 512); \
;                 SCAN_ROW(T0, T1, T2, T3, w0, w1, a0, a1, b0, b1, k0, k1, r0, r1, vj, (t) * 512 + 256); } while (0)
;     ...
;             SCAN_LOAD(w0, w1, a0, a1, b0, b1, k0, k1, r0, r1, vi, vj, 0);
; #pragma unroll
;             for (int t = 0; t < 16; t += 2) {
;                 SCAN_LOAD(W0, W1, A0, A1, B0, B1, K0, K1, R0, R1, VI, VJ, t + 1);
;                 SCAN_STEP(w0, w1, a0, a1, b0, b1, k0, k1, r0, r1, vi, vj, t);
;                 if (t + 2 < 16) SCAN_LOAD(w0, w1, a0, a1, b0, b1, k0, k1, r0, r1, vi, vj, t + 2);
;                 SCAN_STEP(W0, W1, A0, A1, B0, B1, K0, K1, R0, R1, VI, VJ, t + 1);
;             }
;     ...
;             __syncthreads();
;         }
;         float* so = P.out + (samp ? O_RS + ((size_t)(l * 16 + b) * 16 + h) * 4096 : O_RP + ((size_t)(l * 4 + b) * 16 + h) * 4096) + js;
;         f32x4 o0, o1; o0.xy = S0; o0.zw = S1; o1.xy = S2; o1.zw = S3;
;         *(f32x4*)(so + i0 * 64) = o0; *(f32x4*)(so + i0 * 64 + 4) = o1;
;         o0.xy = T0; o0.zw = T1; o1.xy = T2; o1.zw = T3;
;         *(f32x4*)(so + i1 * 64) = o0; *(f32x4*)(so + i1 * 64 + 4) = o1;
	v_mov_b32_e32 v82, v21
	v_add_f32_dpp v78, v78, v78 row_half_mirror row_mask:0xf bank_mask:0xf bound_ctrl:1
	v_add_f32_dpp v80, v79, v79 row_half_mirror row_mask:0xf bank_mask:0xf bound_ctrl:1
	v_pk_fma_f32 v[62:63], v[26:27], v[78:79], v[62:63] op_sel_hi:[1,0,1]
	v_pk_fma_f32 v[66:67], v[22:23], v[78:79], v[66:67] op_sel_hi:[1,0,1]
	v_pk_fma_f32 v[26:27], v[26:27], v[80:81], v[70:71] op_sel_hi:[1,0,1]
	v_pk_fma_f32 v[22:23], v[22:23], v[80:81], v[76:77] op_sel_hi:[1,0,1]
	v_pk_fma_f32 v[64:65], v[28:29], v[78:79], v[64:65] op_sel_hi:[1,0,1]
	v_pk_fma_f32 v[68:69], v[24:25], v[78:79], v[68:69] op_sel_hi:[1,0,1]
	v_pk_fma_f32 v[28:29], v[28:29], v[80:81], v[72:73] op_sel_hi:[1,0,1]
	v_pk_fma_f32 v[24:25], v[24:25], v[80:81], v[74:75] op_sel_hi:[1,0,1]
	v_pk_mul_f32 v[70:71], v[4:5], v[62:63]
	v_pk_mul_f32 v[72:73], v[0:1], v[66:67]
	v_pk_mul_f32 v[4:5], v[4:5], v[26:27]
	v_pk_mul_f32 v[0:1], v[0:1], v[22:23]
	v_pk_mul_f32 v[74:75], v[30:31], v[62:63]
	v_pk_mul_f32 v[76:77], v[34:35], v[66:67]
	v_pk_mul_f32 v[30:31], v[30:31], v[26:27]
	v_pk_mul_f32 v[34:35], v[34:35], v[22:23]
	v_pk_mul_f32 v[62:63], v[8:9], v[62:63]
	v_pk_mul_f32 v[78:79], v[10:11], v[64:65]
	v_pk_mul_f32 v[66:67], v[12:13], v[66:67]
	v_pk_mul_f32 v[80:81], v[14:15], v[68:69]
	v_pk_mul_f32 v[8:9], v[8:9], v[26:27]
	v_pk_mul_f32 v[10:11], v[10:11], v[28:29]
	v_pk_mul_f32 v[12:13], v[12:13], v[22:23]
	v_pk_mul_f32 v[14:15], v[14:15], v[24:25]
	v_pk_fma_f32 v[22:23], v[6:7], v[64:65], v[70:71]
	v_pk_fma_f32 v[26:27], v[2:3], v[68:69], v[72:73]
	v_pk_fma_f32 v[4:5], v[6:7], v[28:29], v[4:5]
	v_pk_fma_f32 v[0:1], v[2:3], v[24:25], v[0:1]
	v_pk_fma_f32 v[2:3], v[32:33], v[64:65], v[74:75]
	v_pk_fma_f32 v[6:7], v[36:37], v[68:69], v[76:77]
	v_pk_fma_f32 v[28:29], v[32:33], v[28:29], v[30:31]
	v_pk_fma_f32 v[24:25], v[36:37], v[24:25], v[34:35]
	v_pk_fma_f32 v[30:31], v[46:47], v[82:83], v[8:9] op_sel_hi:[1,0,1]
	v_pk_add_f32 v[8:9], v[22:23], v[26:27]
	v_pk_add_f32 v[0:1], v[4:5], v[0:1]
	v_pk_add_f32 v[2:3], v[2:3], v[6:7]
	v_pk_add_f32 v[4:5], v[28:29], v[24:25]
	v_add_f32_e32 v6, v8, v9
	v_add_f32_e32 v0, v0, v1
	v_add_f32_e32 v1, v2, v3
	v_add_f32_e32 v2, v4, v5
	ds_write2st64_b32 v19, v6, v0 offset0:112 offset1:116
	v_add_f32_dpp v0, v1, v1 quad_perm:[1,0,3,2] row_mask:0xf bank_mask:0xf bound_ctrl:1
	v_add_f32_dpp v1, v2, v2 quad_perm:[1,0,3,2] row_mask:0xf bank_mask:0xf bound_ctrl:1
	v_pk_fma_f32 v[62:63], v[46:47], v[20:21], v[62:63] op_sel_hi:[1,0,1]
	v_add_f32_dpp v0, v0, v0 quad_perm:[2,3,0,1] row_mask:0xf bank_mask:0xf bound_ctrl:1
	v_add_f32_dpp v1, v1, v1 quad_perm:[2,3,0,1] row_mask:0xf bank_mask:0xf bound_ctrl:1
	v_pk_fma_f32 v[64:65], v[48:49], v[20:21], v[78:79] op_sel_hi:[1,0,1]
	v_pk_fma_f32 v[66:67], v[50:51], v[20:21], v[66:67] op_sel_hi:[1,0,1]
	v_pk_fma_f32 v[20:21], v[52:53], v[20:21], v[80:81] op_sel_hi:[1,0,1]
	v_pk_fma_f32 v[34:35], v[50:51], v[82:83], v[12:13] op_sel_hi:[1,0,1]
	v_add_f32_dpp v0, v0, v0 row_half_mirror row_mask:0xf bank_mask:0xf bound_ctrl:1
	v_add_f32_dpp v2, v1, v1 row_half_mirror row_mask:0xf bank_mask:0xf bound_ctrl:1
	v_pk_fma_f32 v[32:33], v[48:49], v[82:83], v[10:11] op_sel_hi:[1,0,1]
	v_pk_fma_f32 v[36:37], v[52:53], v[82:83], v[14:15] op_sel_hi:[1,0,1]
	v_pk_fma_f32 v[8:9], v[38:39], v[0:1], v[62:63] op_sel_hi:[1,0,1]
	v_pk_fma_f32 v[10:11], v[40:41], v[0:1], v[64:65] op_sel_hi:[1,0,1]
	v_pk_fma_f32 v[12:13], v[42:43], v[0:1], v[66:67] op_sel_hi:[1,0,1]
	v_pk_fma_f32 v[14:15], v[44:45], v[0:1], v[20:21] op_sel_hi:[1,0,1]
	v_pk_fma_f32 v[4:5], v[38:39], v[2:3], v[30:31] op_sel_hi:[1,0,1]
	v_pk_fma_f32 v[0:1], v[42:43], v[2:3], v[34:35] op_sel_hi:[1,0,1]
	v_pk_fma_f32 v[6:7], v[40:41], v[2:3], v[32:33] op_sel_hi:[1,0,1]
	v_pk_fma_f32 v[2:3], v[44:45], v[2:3], v[36:37] op_sel_hi:[1,0,1]
	v_pk_mul_f32 v[20:21], v[54:55], v[8:9]
	v_pk_mul_f32 v[22:23], v[58:59], v[12:13]
	v_pk_mul_f32 v[24:25], v[54:55], v[4:5]
	v_pk_mul_f32 v[26:27], v[58:59], v[0:1]
	v_pk_fma_f32 v[20:21], v[56:57], v[10:11], v[20:21]
	v_pk_fma_f32 v[22:23], v[60:61], v[14:15], v[22:23]
	v_pk_fma_f32 v[24:25], v[56:57], v[6:7], v[24:25]
	v_pk_fma_f32 v[26:27], v[60:61], v[2:3], v[26:27]
	v_pk_add_f32 v[20:21], v[20:21], v[22:23]
	v_pk_add_f32 v[22:23], v[24:25], v[26:27]
	s_cmpk_eq_i32 s1, 0xc8
	v_add_f32_e32 v20, v20, v21
	v_add_f32_e32 v21, v22, v23
	ds_write2st64_b32 v19, v20, v21 offset0:120 offset1:124
	s_waitcnt lgkmcnt(0)
	s_barrier
	s_cbranch_scc0 .LBB0_1395
	s_setprio 0
	s_lshl_b64 s[6:7], s[6:7], 18
	s_add_u32 s1, s72, s6
	s_addc_u32 s6, s73, s7
	s_lshl_b32 s0, s0, 14
	s_add_u32 s0, s1, s0
	s_addc_u32 s1, s6, 0
	v_lshlrev_b32_e32 v18, 2, v17
	v_mov_b32_e32 v19, 0
	v_lshlrev_b32_e32 v16, 6, v16
	v_lshl_add_u64 v[18:19], s[0:1], 0, v[18:19]
	v_ashrrev_i32_e32 v17, 31, v16
	v_lshl_add_u64 v[16:17], v[16:17], 2, v[18:19]
	s_mov_b64 s[0:1], 0x8500000
	v_lshl_add_u64 v[18:19], v[16:17], 0, s[0:1]
	s_mov_b32 s0, 0x8500000
	v_add_co_u32_e32 v16, vcc, s0, v16
	s_nop 1
	v_addc_co_u32_e32 v17, vcc, 0, v17, vcc
	global_store_dwordx4 v[16:17], v[8:11], off
	global_store_dwordx4 v[18:19], v[12:15], off offset:16
	global_store_dwordx4 v[18:19], v[4:7], off offset:2048
	global_store_dwordx4 v[18:19], v[0:3], off offset:2064

;     ...
;         } else if (resume) {
;             const float* s0 = P.out + O_RP + ((size_t)(l * 4 + b) * 16 + h) * 4096 + js;
;             const f32x4 a0 = *(const f32x4*)(s0 + i0 * 64), a1 = *(const f32x4*)(s0 + i0 * 64 + 4), c0v = *(const f32x4*)(s0 + i1 * 64), c1v = *(const f32x4*)(s0 + i1 * 64 + 4);
;             S0 = a0.xy; S1 = a0.zw; S2 = a1.xy; S3 = a1.zw; T0 = c0v.xy; T1 = c0v.zw; T2 = c1v.xy; T3 = c1v.zw;
;         } else { S0 = (f32x2){0.f, 0.f}; S1 = S0; S2 = S0; S3 = S0; T0 = S0; T1 = S0; T2 = S0; T3 = S0; }
;         __syncthreads();
;         for (int c = c0; c < nch; ++c) {
;             const float* bb = bufs + (c & 1) * (16 * 384) + js;
;             const float* bv = bufs + (c & 1) * (16 * 384) + 320 + i0;
;             float* yb = ybuf + (c & 1) * 8192 + w * 64 + lane;
;             f32x4 w0, w1, a0, a1, b0, b1, k0, k1, r0, r1; float vi, vj;
;             f32x4 W0, W1, A0, A1, B0, B1, K0, K1, R0, R1; float VI, VJ;
.LBB0_1810:
	s_andn2_saveexec_b64 s[2:3], s[6:7]
	s_cbranch_execz .LBB0_1814
	s_lshl_b64 s[4:5], s[4:5], 18
	s_add_u32 s1, s72, s4
	v_lshrrev_b32_e32 v1, 3, v0
	v_lshlrev_b32_e32 v0, 3, v0
	s_addc_u32 s7, s73, s5
	s_lshl_b32 s0, s0, 14
	v_lshl_or_b32 v17, v38, 4, v1
	v_and_b32_e32 v16, 56, v0
	s_add_u32 s6, s1, s0
	s_addc_u32 s7, s7, 0
	v_mov_b32_e32 v1, 0
	v_lshlrev_b32_e32 v0, 2, v16
	v_lshlrev_b32_e32 v18, 6, v17
	v_lshl_add_u64 v[0:1], s[6:7], 0, v[0:1]
	v_ashrrev_i32_e32 v19, 31, v18
	v_lshl_add_u64 v[0:1], v[18:19], 2, v[0:1]
	s_mov_b32 s1, 0x8500000
	s_mov_b64 s[6:7], 0x8500000
	v_add_co_u32_e32 v6, vcc, s1, v0
	v_lshl_add_u64 v[4:5], v[0:1], 0, s[6:7]
	s_nop 0
	v_addc_co_u32_e32 v7, vcc, 0, v1, vcc
	global_load_dwordx4 v[8:11], v[4:5], off offset:16
	global_load_dwordx4 v[0:3], v[4:5], off offset:2048
	global_load_dwordx4 v[12:15], v[6:7], off
	s_nop 0
	global_load_dwordx4 v[4:7], v[4:5], off offset:2064
	v_and_b32_e32 v20, 0x3fffffc0, v20
	v_lshlrev_b32_e32 v20, 2, v20
	v_add3_u32 v20, 0, v20, v21
	s_movk_i32 s1, 0xc8
	s_barrier
	s_setprio 3
.LBB0_1812:
	s_and_b32 s6, s1, 1
	s_mul_i32 s7, s6, 0x6000
	v_lshl_add_u32 v29, s6, 15, v20
	s_add_i32 s6, s7, 0
	v_lshl_add_u32 v23, v17, 2, s6
	v_lshl_add_u32 v22, v16, 2, s6
	v_add_u32_e32 v31, 0x400, v23
	v_add_u32_e32 v114, 0x800, v23
	ds_read_b128 v[32:35], v22
	ds_read_b128 v[36:39], v22 offset:16
	ds_read_b128 v[40:43], v22 offset:256
	ds_read_b128 v[44:47], v22 offset:272
	ds_read_b128 v[48:51], v22 offset:512
	ds_read_b128 v[52:55], v22 offset:528
	ds_read_b128 v[56:59], v22 offset:768
	ds_read_b128 v[60:63], v22 offset:784
	ds_read_b128 v[64:67], v22 offset:1024
	ds_read_b128 v[68:71], v22 offset:1040
	ds_read_b128 v[72:75], v22 offset:1536
	ds_read_b128 v[76:79], v22 offset:1552
	ds_read_b128 v[80:83], v22 offset:1792
	s_waitcnt vmcnt(8)
	ds_read_b128 v[84:87], v22 offset:1808
	s_waitcnt vmcnt(7)
	ds_read_b128 v[88:91], v22 offset:2048
	s_waitcnt vmcnt(6)
	ds_read_b128 v[92:95], v22 offset:2064
	ds_read_b128 v[96:99], v22 offset:2304
	ds_read_b128 v[100:103], v22 offset:2320
	ds_read_b128 v[104:107], v22 offset:2560
	ds_read_b128 v[108:111], v22 offset:2576
	ds_read2_b32 v[112:113], v31 offset0:64 offset1:72
	ds_read2_b32 v[114:115], v114 offset0:192 offset1:200
	s_waitcnt vmcnt(1) lgkmcnt(14)
	v_pk_mul_f32 v[116:117], v[12:13], v[40:41]
	v_pk_mul_f32 v[118:119], v[8:9], v[44:45]
	v_pk_mul_f32 v[40:41], v[0:1], v[40:41]
	s_waitcnt vmcnt(0)
	v_pk_mul_f32 v[44:45], v[4:5], v[44:45]
	v_pk_fma_f32 v[116:117], v[14:15], v[42:43], v[116:117]
	v_pk_fma_f32 v[118:119], v[10:11], v[46:47], v[118:119]
	s_waitcnt lgkmcnt(1)
	v_pk_mul_f32 v[120:121], v[56:57], v[112:113] op_sel_hi:[1,0]
	v_pk_mul_f32 v[122:123], v[58:59], v[112:113] op_sel_hi:[1,0]
	v_pk_mul_f32 v[124:125], v[60:61], v[112:113] op_sel_hi:[1,0]
	v_pk_mul_f32 v[126:127], v[62:63], v[112:113] op_sel_hi:[1,0]
	v_mov_b32_e32 v112, v113
	v_pk_fma_f32 v[40:41], v[2:3], v[42:43], v[40:41]
	v_pk_fma_f32 v[42:43], v[6:7], v[46:47], v[44:45]
	v_pk_add_f32 v[46:47], v[116:117], v[118:119]
	v_pk_mul_f32 v[56:57], v[56:57], v[112:113] op_sel_hi:[1,0]
	v_pk_add_f32 v[40:41], v[40:41], v[42:43]
	v_pk_fma_f32 v[12:13], v[12:13], v[32:33], v[120:121]
	v_add_f32_e32 v31, v46, v47
	v_pk_fma_f32 v[0:1], v[0:1], v[32:33], v[56:57]
	v_add_f32_e32 v32, v40, v41
	v_add_f32_dpp v31, v31, v31 quad_perm:[1,0,3,2] row_mask:0xf bank_mask:0xf bound_ctrl:1
	v_pk_mul_f32 v[58:59], v[58:59], v[112:113] op_sel_hi:[1,0]
	v_add_f32_dpp v32, v32, v32 quad_perm:[1,0,3,2] row_mask:0xf bank_mask:0xf bound_ctrl:1
	v_pk_mul_f32 v[60:61], v[60:61], v[112:113] op_sel_hi:[1,0]
	v_add_f32_dpp v31, v31, v31 quad_perm:[2,3,0,1] row_mask:0xf bank_mask:0xf bound_ctrl:1
	v_add_f32_dpp v33, v32, v32 quad_perm:[2,3,0,1] row_mask:0xf bank_mask:0xf bound_ctrl:1
	v_pk_fma_f32 v[14:15], v[14:15], v[34:35], v[122:123]
	v_pk_fma_f32 v[8:9], v[8:9], v[36:37], v[124:125]
	v_pk_mul_f32 v[62:63], v[62:63], v[112:113] op_sel_hi:[1,0]
	v_pk_fma_f32 v[2:3], v[2:3], v[34:35], v[58:59]
	v_pk_fma_f32 v[4:5], v[4:5], v[36:37], v[60:61]
	v_add_f32_dpp v32, v31, v31 row_half_mirror row_mask:0xf bank_mask:0xf bound_ctrl:1
	v_add_f32_dpp v34, v33, v33 row_half_mirror row_mask:0xf bank_mask:0xf bound_ctrl:1
	v_pk_fma_f32 v[10:11], v[10:11], v[38:39], v[126:127]
	v_pk_fma_f32 v[6:7], v[6:7], v[38:39], v[62:63]
	v_pk_fma_f32 v[12:13], v[48:49], v[32:33], v[12:13] op_sel_hi:[1,0,1]
	v_pk_fma_f32 v[8:9], v[52:53], v[32:33], v[8:9] op_sel_hi:[1,0,1]
	v_pk_fma_f32 v[0:1], v[48:49], v[34:35], v[0:1] op_sel_hi:[1,0,1]
	v_pk_fma_f32 v[4:5], v[52:53], v[34:35], v[4:5] op_sel_hi:[1,0,1]
	v_pk_fma_f32 v[14:15], v[50:51], v[32:33], v[14:15] op_sel_hi:[1,0,1]
	v_pk_fma_f32 v[10:11], v[54:55], v[32:33], v[10:11] op_sel_hi:[1,0,1]
	v_pk_fma_f32 v[2:3], v[50:51], v[34:35], v[2:3] op_sel_hi:[1,0,1]
	v_pk_fma_f32 v[6:7], v[54:55], v[34:35], v[6:7] op_sel_hi:[1,0,1]
	v_pk_mul_f32 v[32:33], v[64:65], v[12:13]
	v_pk_mul_f32 v[34:35], v[68:69], v[8:9]
	v_pk_mul_f32 v[36:37], v[64:65], v[0:1]
	v_pk_mul_f32 v[38:39], v[68:69], v[4:5]
	v_pk_mul_f32 v[40:41], v[80:81], v[12:13]
	v_pk_mul_f32 v[42:43], v[84:85], v[8:9]
	v_pk_mul_f32 v[50:51], v[80:81], v[0:1]
	v_pk_mul_f32 v[52:53], v[84:85], v[4:5]
	s_waitcnt lgkmcnt(0)
; #define SCAN_STEP(w0, w1, a0, a1, b0, b1, k0, k1, r0, r1, vi, vj, t) do { \
;                 SCAN_ROW(S0, S1, S2, S3, w0, w1, a0, a1, b0, b1, k0, k1, r0, r1, vi, (t) * 512); \
;                 SCAN_ROW(T0, T1, T2, T3, w0, w1, a0, a1, b0, b1, k0, k1, r0, r1, vj, (t) * 512 + 256); } while (0)
;     ...
;             SCAN_LOAD(w0, w1, a0, a1, b0, b1, k0, k1, r0, r1, vi, vj, 0);
; #pragma unroll
;             for (int t = 0; t < 16; t += 2) {
;                 SCAN_LOAD(W0, W1, A0, A1, B0, B1, K0, K1, R0, R1, VI, VJ, t + 1);
;                 SCAN_STEP(w0, w1, a0, a1, b0, b1, k0, k1, r0, r1, vi, vj, t);
;                 if (t + 2 < 16) SCAN_LOAD(w0, w1, a0, a1, b0, b1, k0, k1, r0, r1, vi, vj, t + 2);
;                 SCAN_STEP(W0, W1, A0, A1, B0, B1, K0, K1, R0, R1, VI, VJ, t + 1);
	v_mov_b32_e32 v44, v115
	v_pk_mul_f32 v[46:47], v[74:75], v[14:15]
	v_pk_mul_f32 v[8:9], v[76:77], v[8:9]
	v_pk_mul_f32 v[48:49], v[78:79], v[10:11]
	v_pk_mul_f32 v[0:1], v[72:73], v[0:1]
	v_pk_mul_f32 v[54:55], v[74:75], v[2:3]
	v_pk_mul_f32 v[4:5], v[76:77], v[4:5]
	v_pk_mul_f32 v[56:57], v[78:79], v[6:7]
	v_pk_fma_f32 v[32:33], v[66:67], v[14:15], v[32:33]
	v_pk_fma_f32 v[34:35], v[70:71], v[10:11], v[34:35]
	v_pk_fma_f32 v[36:37], v[66:67], v[2:3], v[36:37]
	v_pk_fma_f32 v[38:39], v[70:71], v[6:7], v[38:39]
	v_pk_fma_f32 v[14:15], v[82:83], v[14:15], v[40:41]
	v_pk_fma_f32 v[10:11], v[86:87], v[10:11], v[42:43]
	v_pk_fma_f32 v[2:3], v[82:83], v[2:3], v[50:51]
	v_pk_fma_f32 v[6:7], v[86:87], v[6:7], v[52:53]
	v_pk_fma_f32 v[62:63], v[100:101], v[114:115], v[8:9] op_sel_hi:[1,0,1]
	v_pk_fma_f32 v[66:67], v[96:97], v[44:45], v[0:1] op_sel_hi:[1,0,1]
	v_pk_fma_f32 v[70:71], v[100:101], v[44:45], v[4:5] op_sel_hi:[1,0,1]
	v_pk_add_f32 v[0:1], v[32:33], v[34:35]
	v_pk_add_f32 v[4:5], v[36:37], v[38:39]
	v_pk_add_f32 v[8:9], v[14:15], v[10:11]
	v_pk_add_f32 v[2:3], v[2:3], v[6:7]
	v_add_f32_e32 v0, v0, v1
	v_add_f32_e32 v1, v4, v5
	v_add_f32_e32 v4, v8, v9
	v_add_f32_e32 v2, v2, v3
	v_add_u32_e32 v128, 0x1000, v23
	v_add_f32_dpp v31, v4, v4 quad_perm:[1,0,3,2] row_mask:0xf bank_mask:0xf bound_ctrl:1
	v_add_f32_dpp v74, v2, v2 quad_perm:[1,0,3,2] row_mask:0xf bank_mask:0xf bound_ctrl:1
	v_pk_mul_f32 v[12:13], v[72:73], v[12:13]
	ds_write2st64_b32 v29, v0, v1 offset0:192 offset1:196
	v_add_f32_dpp v31, v31, v31 quad_perm:[2,3,0,1] row_mask:0xf bank_mask:0xf bound_ctrl:1
	v_add_f32_dpp v75, v74, v74 quad_perm:[2,3,0,1] row_mask:0xf bank_mask:0xf bound_ctrl:1
	v_pk_fma_f32 v[58:59], v[96:97], v[114:115], v[12:13] op_sel_hi:[1,0,1]
	v_pk_fma_f32 v[60:61], v[98:99], v[114:115], v[46:47] op_sel_hi:[1,0,1]
	v_pk_fma_f32 v[64:65], v[102:103], v[114:115], v[48:49] op_sel_hi:[1,0,1]
	v_pk_fma_f32 v[68:69], v[98:99], v[44:45], v[54:55] op_sel_hi:[1,0,1]
	v_pk_fma_f32 v[56:57], v[102:103], v[44:45], v[56:57] op_sel_hi:[1,0,1]
	ds_read2_b32 v[72:73], v128 offset0:64 offset1:72
	ds_read_b128 v[0:3], v22 offset:4112
	ds_read_b128 v[4:7], v22 offset:4096
	ds_read_b128 v[8:11], v22 offset:3856
	ds_read_b128 v[12:15], v22 offset:3840
	ds_read_b128 v[32:35], v22 offset:3600
	ds_read_b128 v[36:39], v22 offset:3584
	ds_read_b128 v[40:43], v22 offset:3344
	ds_read_b128 v[44:47], v22 offset:3328
	ds_read_b128 v[48:51], v22 offset:3072
	ds_read_b128 v[52:55], v22 offset:3088
	v_add_f32_dpp v74, v31, v31 row_half_mirror row_mask:0xf bank_mask:0xf bound_ctrl:1
	v_add_f32_dpp v76, v75, v75 row_half_mirror row_mask:0xf bank_mask:0xf bound_ctrl:1
	v_pk_fma_f32 v[58:59], v[88:89], v[74:75], v[58:59] op_sel_hi:[1,0,1]
	v_pk_fma_f32 v[62:63], v[92:93], v[74:75], v[62:63] op_sel_hi:[1,0,1]
	v_pk_fma_f32 v[66:67], v[88:89], v[76:77], v[66:67] op_sel_hi:[1,0,1]
	v_pk_fma_f32 v[70:71], v[92:93], v[76:77], v[70:71] op_sel_hi:[1,0,1]
	v_pk_fma_f32 v[60:61], v[90:91], v[74:75], v[60:61] op_sel_hi:[1,0,1]
	v_pk_fma_f32 v[64:65], v[94:95], v[74:75], v[64:65] op_sel_hi:[1,0,1]
	v_pk_fma_f32 v[68:69], v[90:91], v[76:77], v[68:69] op_sel_hi:[1,0,1]
	v_pk_fma_f32 v[56:57], v[94:95], v[76:77], v[56:57] op_sel_hi:[1,0,1]
	v_pk_mul_f32 v[74:75], v[104:105], v[58:59]
	v_pk_mul_f32 v[76:77], v[108:109], v[62:63]
	v_pk_mul_f32 v[78:79], v[104:105], v[66:67]
	v_pk_mul_f32 v[80:81], v[108:109], v[70:71]
	v_pk_fma_f32 v[74:75], v[106:107], v[60:61], v[74:75]
	v_pk_fma_f32 v[76:77], v[110:111], v[64:65], v[76:77]
	v_pk_fma_f32 v[78:79], v[106:107], v[68:69], v[78:79]
	v_pk_fma_f32 v[80:81], v[110:111], v[56:57], v[80:81]
	v_pk_add_f32 v[74:75], v[74:75], v[76:77]
	v_pk_add_f32 v[76:77], v[78:79], v[80:81]
	s_waitcnt lgkmcnt(2)
	v_pk_mul_f32 v[78:79], v[44:45], v[58:59]
	v_pk_mul_f32 v[80:81], v[40:41], v[62:63]
	v_pk_mul_f32 v[44:45], v[44:45], v[66:67]
	v_pk_mul_f32 v[40:41], v[40:41], v[70:71]
	s_waitcnt lgkmcnt(1)
	v_pk_mul_f32 v[82:83], v[50:51], v[60:61]
	s_waitcnt lgkmcnt(0)
	v_pk_mul_f32 v[84:85], v[54:55], v[64:65]
	v_pk_fma_f32 v[60:61], v[46:47], v[60:61], v[78:79]
	v_pk_fma_f32 v[64:65], v[42:43], v[64:65], v[80:81]
	v_pk_fma_f32 v[44:45], v[46:47], v[68:69], v[44:45]
	v_pk_fma_f32 v[40:41], v[42:43], v[56:57], v[40:41]
	v_pk_mul_f32 v[58:59], v[48:49], v[58:59]
	v_pk_mul_f32 v[48:49], v[48:49], v[66:67]
	v_add_f32_e32 v31, v74, v75
	v_add_f32_e32 v66, v76, v77
	v_pk_add_f32 v[88:89], v[64:65], v[60:61]
	v_pk_add_f32 v[90:91], v[40:41], v[44:45]
	ds_write2st64_b32 v29, v31, v66 offset0:200 offset1:204
	v_add_f32_e32 v31, v88, v89
	v_add_f32_e32 v88, v90, v91
	v_pk_mul_f32 v[62:63], v[52:53], v[62:63]
	v_mov_b32_e32 v86, v73
	v_pk_mul_f32 v[50:51], v[50:51], v[68:69]
	v_pk_mul_f32 v[52:53], v[52:53], v[70:71]
	v_pk_mul_f32 v[54:55], v[54:55], v[56:57]
	v_add_f32_dpp v31, v31, v31 quad_perm:[1,0,3,2] row_mask:0xf bank_mask:0xf bound_ctrl:1
	v_add_f32_dpp v88, v88, v88 quad_perm:[1,0,3,2] row_mask:0xf bank_mask:0xf bound_ctrl:1
	v_add_u32_e32 v129, 0x1400, v23
	v_pk_fma_f32 v[74:75], v[72:73], v[12:13], v[58:59] op_sel_hi:[0,1,1]
	v_pk_fma_f32 v[76:77], v[72:73], v[14:15], v[82:83] op_sel_hi:[0,1,1]
	v_pk_fma_f32 v[78:79], v[72:73], v[8:9], v[62:63] op_sel_hi:[0,1,1]
	v_pk_fma_f32 v[72:73], v[72:73], v[10:11], v[84:85] op_sel_hi:[0,1,1]
	v_pk_fma_f32 v[80:81], v[86:87], v[12:13], v[48:49] op_sel_hi:[0,1,1]
	v_pk_fma_f32 v[82:83], v[86:87], v[14:15], v[50:51] op_sel_hi:[0,1,1]
	v_pk_fma_f32 v[84:85], v[86:87], v[8:9], v[52:53] op_sel_hi:[0,1,1]
	v_pk_fma_f32 v[86:87], v[86:87], v[10:11], v[54:55] op_sel_hi:[0,1,1]
	ds_read_b128 v[8:11], v22 offset:4608
	ds_read_b128 v[12:15], v22 offset:4624
; #define SCAN_STEP(w0, w1, a0, a1, b0, b1, k0, k1, r0, r1, vi, vj, t) do { \
;                 SCAN_ROW(S0, S1, S2, S3, w0, w1, a0, a1, b0, b1, k0, k1, r0, r1, vi, (t) * 512); \
;                 SCAN_ROW(T0, T1, T2, T3, w0, w1, a0, a1, b0, b1, k0, k1, r0, r1, vj, (t) * 512 + 256); } while (0)
;     ...
;             SCAN_LOAD(w0, w1, a0, a1, b0, b1, k0, k1, r0, r1, vi, vj, 0);
; #pragma unroll
;             for (int t = 0; t < 16; t += 2) {
;                 SCAN_LOAD(W0, W1, A0, A1, B0, B1, K0, K1, R0, R1, VI, VJ, t + 1);
;                 SCAN_STEP(w0, w1, a0, a1, b0, b1, k0, k1, r0, r1, vi, vj, t);
;                 if (t + 2 < 16) SCAN_LOAD(w0, w1, a0, a1, b0, b1, k0, k1, r0, r1, vi, vj, t + 2);
;                 SCAN_STEP(W0, W1, A0, A1, B0, B1, K0, K1, R0, R1, VI, VJ, t + 1);
	ds_read_b128 v[40:43], v22 offset:4864
	ds_read_b128 v[44:47], v22 offset:4880
	ds_read_b128 v[48:51], v22 offset:5120
	ds_read_b128 v[52:55], v22 offset:5136
	ds_read_b128 v[56:59], v22 offset:5376
	ds_read_b128 v[60:63], v22 offset:5392
	ds_read_b128 v[64:67], v22 offset:5632
	ds_read_b128 v[68:71], v22 offset:5648
	ds_read2_b32 v[92:93], v129 offset0:192 offset1:200
	v_add_f32_dpp v31, v31, v31 quad_perm:[2,3,0,1] row_mask:0xf bank_mask:0xf bound_ctrl:1
	v_add_f32_dpp v89, v88, v88 quad_perm:[2,3,0,1] row_mask:0xf bank_mask:0xf bound_ctrl:1
	v_add_u32_e32 v130, 0x1c00, v23
	v_add_f32_dpp v88, v31, v31 row_half_mirror row_mask:0xf bank_mask:0xf bound_ctrl:1
	v_add_f32_dpp v90, v89, v89 row_half_mirror row_mask:0xf bank_mask:0xf bound_ctrl:1
	v_pk_fma_f32 v[74:75], v[36:37], v[88:89], v[74:75] op_sel_hi:[1,0,1]
	v_pk_fma_f32 v[78:79], v[32:33], v[88:89], v[78:79] op_sel_hi:[1,0,1]
	v_pk_fma_f32 v[36:37], v[36:37], v[90:91], v[80:81] op_sel_hi:[1,0,1]
	v_pk_fma_f32 v[32:33], v[32:33], v[90:91], v[84:85] op_sel_hi:[1,0,1]
	v_pk_fma_f32 v[76:77], v[38:39], v[88:89], v[76:77] op_sel_hi:[1,0,1]
	v_pk_fma_f32 v[72:73], v[34:35], v[88:89], v[72:73] op_sel_hi:[1,0,1]
	v_pk_fma_f32 v[38:39], v[38:39], v[90:91], v[82:83] op_sel_hi:[1,0,1]
	v_pk_fma_f32 v[34:35], v[34:35], v[90:91], v[86:87] op_sel_hi:[1,0,1]
	v_pk_mul_f32 v[80:81], v[4:5], v[74:75]
	v_pk_mul_f32 v[82:83], v[0:1], v[78:79]
	v_pk_mul_f32 v[4:5], v[4:5], v[36:37]
	v_pk_mul_f32 v[0:1], v[0:1], v[32:33]
	s_waitcnt lgkmcnt(8)
	v_pk_mul_f32 v[84:85], v[40:41], v[74:75]
	s_waitcnt lgkmcnt(7)
	v_pk_mul_f32 v[86:87], v[44:45], v[78:79]
	v_pk_mul_f32 v[40:41], v[40:41], v[36:37]
	v_pk_mul_f32 v[44:45], v[44:45], v[32:33]
	v_pk_mul_f32 v[74:75], v[8:9], v[74:75]
	v_pk_mul_f32 v[88:89], v[10:11], v[76:77]
	v_pk_mul_f32 v[78:79], v[12:13], v[78:79]
	v_pk_mul_f32 v[90:91], v[14:15], v[72:73]
	v_pk_mul_f32 v[8:9], v[8:9], v[36:37]
	v_pk_mul_f32 v[10:11], v[10:11], v[38:39]
	v_pk_mul_f32 v[12:13], v[12:13], v[32:33]
	v_pk_mul_f32 v[14:15], v[14:15], v[34:35]
	v_pk_fma_f32 v[32:33], v[6:7], v[76:77], v[80:81]
	v_pk_fma_f32 v[36:37], v[2:3], v[72:73], v[82:83]
	v_pk_fma_f32 v[4:5], v[6:7], v[38:39], v[4:5]
	v_pk_fma_f32 v[0:1], v[2:3], v[34:35], v[0:1]
	v_pk_fma_f32 v[2:3], v[42:43], v[76:77], v[84:85]
	v_pk_fma_f32 v[6:7], v[46:47], v[72:73], v[86:87]
	v_pk_fma_f32 v[38:39], v[42:43], v[38:39], v[40:41]
	v_pk_fma_f32 v[34:35], v[46:47], v[34:35], v[44:45]
	s_waitcnt lgkmcnt(0)
	v_mov_b32_e32 v94, v93
	v_pk_add_f32 v[0:1], v[4:5], v[0:1]
	v_pk_add_f32 v[2:3], v[2:3], v[6:7]
	v_pk_add_f32 v[4:5], v[38:39], v[34:35]
	v_pk_fma_f32 v[80:81], v[56:57], v[94:95], v[8:9] op_sel_hi:[1,0,1]
	v_pk_add_f32 v[8:9], v[32:33], v[36:37]
	v_add_f32_e32 v0, v0, v1
	v_add_f32_e32 v1, v2, v3
	v_add_f32_e32 v2, v4, v5
	v_pk_fma_f32 v[76:77], v[60:61], v[92:93], v[78:79] op_sel_hi:[1,0,1]
	v_pk_fma_f32 v[78:79], v[62:63], v[92:93], v[90:91] op_sel_hi:[1,0,1]
	v_add_f32_e32 v6, v8, v9
	v_add_f32_dpp v31, v1, v1 quad_perm:[1,0,3,2] row_mask:0xf bank_mask:0xf bound_ctrl:1
	v_add_f32_dpp v90, v2, v2 quad_perm:[1,0,3,2] row_mask:0xf bank_mask:0xf bound_ctrl:1
	ds_write2st64_b32 v29, v6, v0 offset0:208 offset1:212
	v_add_f32_dpp v31, v31, v31 quad_perm:[2,3,0,1] row_mask:0xf bank_mask:0xf bound_ctrl:1
	v_add_f32_dpp v91, v90, v90 quad_perm:[2,3,0,1] row_mask:0xf bank_mask:0xf bound_ctrl:1
	v_pk_fma_f32 v[72:73], v[56:57], v[92:93], v[74:75] op_sel_hi:[1,0,1]
	v_pk_fma_f32 v[74:75], v[58:59], v[92:93], v[88:89] op_sel_hi:[1,0,1]
	v_pk_fma_f32 v[82:83], v[58:59], v[94:95], v[10:11] op_sel_hi:[1,0,1]
	v_pk_fma_f32 v[84:85], v[60:61], v[94:95], v[12:13] op_sel_hi:[1,0,1]
	v_pk_fma_f32 v[86:87], v[62:63], v[94:95], v[14:15] op_sel_hi:[1,0,1]
	ds_read2_b32 v[88:89], v130 offset0:64 offset1:72
	ds_read_b128 v[0:3], v22 offset:7184
	ds_read_b128 v[4:7], v22 offset:7168
	ds_read_b128 v[8:11], v22 offset:6928
	ds_read_b128 v[12:15], v22 offset:6912
	ds_read_b128 v[32:35], v22 offset:6672
	ds_read_b128 v[36:39], v22 offset:6656
	ds_read_b128 v[40:43], v22 offset:6416
	ds_read_b128 v[44:47], v22 offset:6400
	ds_read_b128 v[56:59], v22 offset:6144
	ds_read_b128 v[60:63], v22 offset:6160
	v_add_f32_dpp v90, v31, v31 row_half_mirror row_mask:0xf bank_mask:0xf bound_ctrl:1
	v_add_f32_dpp v92, v91, v91 row_half_mirror row_mask:0xf bank_mask:0xf bound_ctrl:1
	v_pk_fma_f32 v[72:73], v[48:49], v[90:91], v[72:73] op_sel_hi:[1,0,1]
	v_pk_fma_f32 v[76:77], v[52:53], v[90:91], v[76:77] op_sel_hi:[1,0,1]
	v_pk_fma_f32 v[48:49], v[48:49], v[92:93], v[80:81] op_sel_hi:[1,0,1]
	v_pk_fma_f32 v[52:53], v[52:53], v[92:93], v[84:85] op_sel_hi:[1,0,1]
	v_pk_fma_f32 v[74:75], v[50:51], v[90:91], v[74:75] op_sel_hi:[1,0,1]
	v_pk_fma_f32 v[78:79], v[54:55], v[90:91], v[78:79] op_sel_hi:[1,0,1]
	v_pk_fma_f32 v[50:51], v[50:51], v[92:93], v[82:83] op_sel_hi:[1,0,1]
	v_pk_fma_f32 v[54:55], v[54:55], v[92:93], v[86:87] op_sel_hi:[1,0,1]
	v_pk_mul_f32 v[80:81], v[64:65], v[72:73]
	v_pk_mul_f32 v[82:83], v[68:69], v[76:77]
	v_pk_mul_f32 v[64:65], v[64:65], v[48:49]
	v_pk_mul_f32 v[68:69], v[68:69], v[52:53]
	v_pk_fma_f32 v[80:81], v[66:67], v[74:75], v[80:81]
	v_pk_fma_f32 v[64:65], v[66:67], v[50:51], v[64:65]
	v_pk_fma_f32 v[66:67], v[70:71], v[54:55], v[68:69]
	v_pk_fma_f32 v[82:83], v[70:71], v[78:79], v[82:83]
	v_pk_add_f32 v[64:65], v[64:65], v[66:67]
	s_waitcnt lgkmcnt(2)
	v_pk_mul_f32 v[66:67], v[44:45], v[72:73]
	v_pk_mul_f32 v[70:71], v[40:41], v[76:77]
	v_pk_mul_f32 v[44:45], v[44:45], v[48:49]
	v_pk_mul_f32 v[40:41], v[40:41], v[52:53]
	v_pk_add_f32 v[68:69], v[80:81], v[82:83]
	s_waitcnt lgkmcnt(1)
; #define SCAN_STEP(w0, w1, a0, a1, b0, b1, k0, k1, r0, r1, vi, vj, t) do { \
;                 SCAN_ROW(S0, S1, S2, S3, w0, w1, a0, a1, b0, b1, k0, k1, r0, r1, vi, (t) * 512); \
;                 SCAN_ROW(T0, T1, T2, T3, w0, w1, a0, a1, b0, b1, k0, k1, r0, r1, vj, (t) * 512 + 256); } while (0)
;     ...
;             SCAN_LOAD(w0, w1, a0, a1, b0, b1, k0, k1, r0, r1, vi, vj, 0);
; #pragma unroll
;             for (int t = 0; t < 16; t += 2) {
;                 SCAN_LOAD(W0, W1, A0, A1, B0, B1, K0, K1, R0, R1, VI, VJ, t + 1);
;                 SCAN_STEP(w0, w1, a0, a1, b0, b1, k0, k1, r0, r1, vi, vj, t);
;                 if (t + 2 < 16) SCAN_LOAD(w0, w1, a0, a1, b0, b1, k0, k1, r0, r1, vi, vj, t + 2);
;                 SCAN_STEP(W0, W1, A0, A1, B0, B1, K0, K1, R0, R1, VI, VJ, t + 1);
	v_pk_mul_f32 v[72:73], v[56:57], v[72:73]
	v_pk_mul_f32 v[80:81], v[58:59], v[74:75]
	s_waitcnt lgkmcnt(0)
	v_pk_mul_f32 v[76:77], v[60:61], v[76:77]
	v_pk_mul_f32 v[82:83], v[62:63], v[78:79]
	v_pk_mul_f32 v[48:49], v[56:57], v[48:49]
	v_pk_mul_f32 v[56:57], v[58:59], v[50:51]
	v_pk_mul_f32 v[52:53], v[60:61], v[52:53]
	v_pk_mul_f32 v[58:59], v[62:63], v[54:55]
	v_pk_fma_f32 v[60:61], v[46:47], v[74:75], v[66:67]
	v_pk_fma_f32 v[62:63], v[42:43], v[78:79], v[70:71]
	v_pk_fma_f32 v[44:45], v[46:47], v[50:51], v[44:45]
	v_pk_fma_f32 v[40:41], v[42:43], v[54:55], v[40:41]
	v_mov_b32_e32 v84, v89
	v_add_f32_e32 v31, v68, v69
	v_add_f32_e32 v64, v64, v65
	v_pk_fma_f32 v[72:73], v[88:89], v[12:13], v[72:73] op_sel_hi:[0,1,1]
	v_pk_fma_f32 v[74:75], v[88:89], v[14:15], v[80:81] op_sel_hi:[0,1,1]
	v_pk_fma_f32 v[76:77], v[88:89], v[8:9], v[76:77] op_sel_hi:[0,1,1]
	v_pk_fma_f32 v[78:79], v[88:89], v[10:11], v[82:83] op_sel_hi:[0,1,1]
	v_pk_add_f32 v[88:89], v[62:63], v[60:61]
	v_pk_add_f32 v[90:91], v[40:41], v[44:45]
	ds_write2st64_b32 v29, v31, v64 offset0:216 offset1:220
	v_add_f32_e32 v31, v88, v89
	v_add_f32_e32 v88, v90, v91
	v_add_u32_e32 v131, 0x2000, v23
	v_add_f32_dpp v31, v31, v31 quad_perm:[1,0,3,2] row_mask:0xf bank_mask:0xf bound_ctrl:1
	v_add_f32_dpp v88, v88, v88 quad_perm:[1,0,3,2] row_mask:0xf bank_mask:0xf bound_ctrl:1
	v_pk_fma_f32 v[80:81], v[84:85], v[12:13], v[48:49] op_sel_hi:[0,1,1]
	v_pk_fma_f32 v[82:83], v[84:85], v[14:15], v[56:57] op_sel_hi:[0,1,1]
	v_pk_fma_f32 v[86:87], v[84:85], v[8:9], v[52:53] op_sel_hi:[0,1,1]
	v_pk_fma_f32 v[84:85], v[84:85], v[10:11], v[58:59] op_sel_hi:[0,1,1]
	ds_read_b128 v[8:11], v22 offset:7680
	ds_read_b128 v[12:15], v22 offset:7696
	ds_read_b128 v[40:43], v22 offset:7936
	ds_read_b128 v[44:47], v22 offset:7952
	ds_read_b128 v[48:51], v22 offset:8192
	ds_read_b128 v[52:55], v22 offset:8208
	ds_read_b128 v[56:59], v22 offset:8448
	ds_read_b128 v[60:63], v22 offset:8464
	ds_read_b128 v[64:67], v22 offset:8704
	ds_read_b128 v[68:71], v22 offset:8720
	ds_read2_b32 v[92:93], v131 offset0:192 offset1:200
	v_add_f32_dpp v31, v31, v31 quad_perm:[2,3,0,1] row_mask:0xf bank_mask:0xf bound_ctrl:1
	v_add_f32_dpp v89, v88, v88 quad_perm:[2,3,0,1] row_mask:0xf bank_mask:0xf bound_ctrl:1
	v_add_u32_e32 v132, 0x2800, v23
	v_add_f32_dpp v88, v31, v31 row_half_mirror row_mask:0xf bank_mask:0xf bound_ctrl:1
	v_add_f32_dpp v90, v89, v89 row_half_mirror row_mask:0xf bank_mask:0xf bound_ctrl:1
	v_pk_fma_f32 v[72:73], v[36:37], v[88:89], v[72:73] op_sel_hi:[1,0,1]
	v_pk_fma_f32 v[76:77], v[32:33], v[88:89], v[76:77] op_sel_hi:[1,0,1]
	v_pk_fma_f32 v[36:37], v[36:37], v[90:91], v[80:81] op_sel_hi:[1,0,1]
	v_pk_fma_f32 v[32:33], v[32:33], v[90:91], v[86:87] op_sel_hi:[1,0,1]
	v_pk_fma_f32 v[74:75], v[38:39], v[88:89], v[74:75] op_sel_hi:[1,0,1]
	v_pk_fma_f32 v[78:79], v[34:35], v[88:89], v[78:79] op_sel_hi:[1,0,1]
	v_pk_fma_f32 v[38:39], v[38:39], v[90:91], v[82:83] op_sel_hi:[1,0,1]
	v_pk_fma_f32 v[34:35], v[34:35], v[90:91], v[84:85] op_sel_hi:[1,0,1]
	v_pk_mul_f32 v[80:81], v[4:5], v[72:73]
	v_pk_mul_f32 v[82:83], v[0:1], v[76:77]
	v_pk_mul_f32 v[4:5], v[4:5], v[36:37]
	v_pk_mul_f32 v[0:1], v[0:1], v[32:33]
	s_waitcnt lgkmcnt(8)
	v_pk_mul_f32 v[84:85], v[40:41], v[72:73]
	s_waitcnt lgkmcnt(7)
	v_pk_mul_f32 v[86:87], v[44:45], v[76:77]
	v_pk_mul_f32 v[40:41], v[40:41], v[36:37]
	v_pk_mul_f32 v[44:45], v[44:45], v[32:33]
	v_pk_mul_f32 v[72:73], v[8:9], v[72:73]
	v_pk_mul_f32 v[88:89], v[10:11], v[74:75]
	v_pk_mul_f32 v[76:77], v[12:13], v[76:77]
	v_pk_mul_f32 v[90:91], v[14:15], v[78:79]
	v_pk_mul_f32 v[8:9], v[8:9], v[36:37]
	v_pk_mul_f32 v[10:11], v[10:11], v[38:39]
	v_pk_mul_f32 v[12:13], v[12:13], v[32:33]
	v_pk_mul_f32 v[14:15], v[14:15], v[34:35]
	v_pk_fma_f32 v[32:33], v[6:7], v[74:75], v[80:81]
	v_pk_fma_f32 v[36:37], v[2:3], v[78:79], v[82:83]
	v_pk_fma_f32 v[4:5], v[6:7], v[38:39], v[4:5]
	v_pk_fma_f32 v[0:1], v[2:3], v[34:35], v[0:1]
	v_pk_fma_f32 v[2:3], v[42:43], v[74:75], v[84:85]
	v_pk_fma_f32 v[6:7], v[46:47], v[78:79], v[86:87]
	v_pk_fma_f32 v[38:39], v[42:43], v[38:39], v[40:41]
	v_pk_fma_f32 v[34:35], v[46:47], v[34:35], v[44:45]
	s_waitcnt lgkmcnt(0)
	v_mov_b32_e32 v94, v93
	v_pk_add_f32 v[0:1], v[4:5], v[0:1]
	v_pk_add_f32 v[2:3], v[2:3], v[6:7]
	v_pk_add_f32 v[4:5], v[38:39], v[34:35]
	v_pk_fma_f32 v[80:81], v[56:57], v[94:95], v[8:9] op_sel_hi:[1,0,1]
	v_pk_add_f32 v[8:9], v[32:33], v[36:37]
	v_add_f32_e32 v0, v0, v1
	v_add_f32_e32 v1, v2, v3
	v_add_f32_e32 v2, v4, v5
	v_pk_fma_f32 v[78:79], v[62:63], v[92:93], v[90:91] op_sel_hi:[1,0,1]
	v_add_f32_e32 v6, v8, v9
	v_add_f32_dpp v31, v1, v1 quad_perm:[1,0,3,2] row_mask:0xf bank_mask:0xf bound_ctrl:1
	v_add_f32_dpp v90, v2, v2 quad_perm:[1,0,3,2] row_mask:0xf bank_mask:0xf bound_ctrl:1
	ds_write2st64_b32 v29, v6, v0 offset0:224 offset1:228
	v_add_f32_dpp v31, v31, v31 quad_perm:[2,3,0,1] row_mask:0xf bank_mask:0xf bound_ctrl:1
	v_add_f32_dpp v91, v90, v90 quad_perm:[2,3,0,1] row_mask:0xf bank_mask:0xf bound_ctrl:1
	v_pk_fma_f32 v[72:73], v[56:57], v[92:93], v[72:73] op_sel_hi:[1,0,1]
	v_pk_fma_f32 v[74:75], v[58:59], v[92:93], v[88:89] op_sel_hi:[1,0,1]
	v_pk_fma_f32 v[76:77], v[60:61], v[92:93], v[76:77] op_sel_hi:[1,0,1]
	v_pk_fma_f32 v[82:83], v[58:59], v[94:95], v[10:11] op_sel_hi:[1,0,1]
	v_pk_fma_f32 v[84:85], v[60:61], v[94:95], v[12:13] op_sel_hi:[1,0,1]
	v_pk_fma_f32 v[86:87], v[62:63], v[94:95], v[14:15] op_sel_hi:[1,0,1]
	ds_read2_b32 v[88:89], v132 offset0:64 offset1:72
	ds_read_b128 v[0:3], v22 offset:10256
	ds_read_b128 v[4:7], v22 offset:10240
	ds_read_b128 v[8:11], v22 offset:10000
	ds_read_b128 v[12:15], v22 offset:9984
; #define SCAN_STEP(w0, w1, a0, a1, b0, b1, k0, k1, r0, r1, vi, vj, t) do { \
;                 SCAN_ROW(S0, S1, S2, S3, w0, w1, a0, a1, b0, b1, k0, k1, r0, r1, vi, (t) * 512); \
;                 SCAN_ROW(T0, T1, T2, T3, w0, w1, a0, a1, b0, b1, k0, k1, r0, r1, vj, (t) * 512 + 256); } while (0)
;     ...
;             SCAN_LOAD(w0, w1, a0, a1, b0, b1, k0, k1, r0, r1, vi, vj, 0);
; #pragma unroll
;             for (int t = 0; t < 16; t += 2) {
;                 SCAN_LOAD(W0, W1, A0, A1, B0, B1, K0, K1, R0, R1, VI, VJ, t + 1);
;                 SCAN_STEP(w0, w1, a0, a1, b0, b1, k0, k1, r0, r1, vi, vj, t);
;                 if (t + 2 < 16) SCAN_LOAD(w0, w1, a0, a1, b0, b1, k0, k1, r0, r1, vi, vj, t + 2);
;                 SCAN_STEP(W0, W1, A0, A1, B0, B1, K0, K1, R0, R1, VI, VJ, t + 1);
	ds_read_b128 v[32:35], v22 offset:9744
	ds_read_b128 v[36:39], v22 offset:9728
	ds_read_b128 v[40:43], v22 offset:9488
	ds_read_b128 v[44:47], v22 offset:9472
	ds_read_b128 v[56:59], v22 offset:9216
	ds_read_b128 v[60:63], v22 offset:9232
	v_add_f32_dpp v90, v31, v31 row_half_mirror row_mask:0xf bank_mask:0xf bound_ctrl:1
	v_add_f32_dpp v92, v91, v91 row_half_mirror row_mask:0xf bank_mask:0xf bound_ctrl:1
	v_pk_fma_f32 v[72:73], v[48:49], v[90:91], v[72:73] op_sel_hi:[1,0,1]
	v_pk_fma_f32 v[76:77], v[52:53], v[90:91], v[76:77] op_sel_hi:[1,0,1]
	v_pk_fma_f32 v[48:49], v[48:49], v[92:93], v[80:81] op_sel_hi:[1,0,1]
	v_pk_fma_f32 v[52:53], v[52:53], v[92:93], v[84:85] op_sel_hi:[1,0,1]
	v_pk_fma_f32 v[74:75], v[50:51], v[90:91], v[74:75] op_sel_hi:[1,0,1]
	v_pk_fma_f32 v[78:79], v[54:55], v[90:91], v[78:79] op_sel_hi:[1,0,1]
	v_pk_fma_f32 v[50:51], v[50:51], v[92:93], v[82:83] op_sel_hi:[1,0,1]
	v_pk_fma_f32 v[54:55], v[54:55], v[92:93], v[86:87] op_sel_hi:[1,0,1]
	v_pk_mul_f32 v[80:81], v[64:65], v[72:73]
	v_pk_mul_f32 v[82:83], v[68:69], v[76:77]
	v_pk_mul_f32 v[64:65], v[64:65], v[48:49]
	v_pk_mul_f32 v[68:69], v[68:69], v[52:53]
	v_pk_fma_f32 v[80:81], v[66:67], v[74:75], v[80:81]
	v_pk_fma_f32 v[64:65], v[66:67], v[50:51], v[64:65]
	v_pk_fma_f32 v[66:67], v[70:71], v[54:55], v[68:69]
	v_pk_fma_f32 v[82:83], v[70:71], v[78:79], v[82:83]
	v_pk_add_f32 v[64:65], v[64:65], v[66:67]
	s_waitcnt lgkmcnt(2)
	v_pk_mul_f32 v[66:67], v[44:45], v[72:73]
	v_pk_mul_f32 v[70:71], v[40:41], v[76:77]
	v_pk_mul_f32 v[44:45], v[44:45], v[48:49]
	v_pk_mul_f32 v[40:41], v[40:41], v[52:53]
	v_pk_add_f32 v[68:69], v[80:81], v[82:83]
	s_waitcnt lgkmcnt(1)
	v_pk_mul_f32 v[72:73], v[56:57], v[72:73]
	v_pk_mul_f32 v[80:81], v[58:59], v[74:75]
	s_waitcnt lgkmcnt(0)
	v_pk_mul_f32 v[76:77], v[60:61], v[76:77]
	v_pk_mul_f32 v[82:83], v[62:63], v[78:79]
	v_pk_mul_f32 v[48:49], v[56:57], v[48:49]
	v_pk_mul_f32 v[56:57], v[58:59], v[50:51]
	v_pk_mul_f32 v[52:53], v[60:61], v[52:53]
	v_pk_mul_f32 v[58:59], v[62:63], v[54:55]
	v_pk_fma_f32 v[60:61], v[46:47], v[74:75], v[66:67]
	v_pk_fma_f32 v[62:63], v[42:43], v[78:79], v[70:71]
	v_pk_fma_f32 v[44:45], v[46:47], v[50:51], v[44:45]
	v_pk_fma_f32 v[40:41], v[42:43], v[54:55], v[40:41]
	v_mov_b32_e32 v84, v89
	v_add_f32_e32 v31, v68, v69
	v_add_f32_e32 v64, v64, v65
	v_pk_fma_f32 v[72:73], v[88:89], v[12:13], v[72:73] op_sel_hi:[0,1,1]
	v_pk_fma_f32 v[74:75], v[88:89], v[14:15], v[80:81] op_sel_hi:[0,1,1]
	v_pk_fma_f32 v[76:77], v[88:89], v[8:9], v[76:77] op_sel_hi:[0,1,1]
	v_pk_fma_f32 v[78:79], v[88:89], v[10:11], v[82:83] op_sel_hi:[0,1,1]
	v_pk_add_f32 v[88:89], v[62:63], v[60:61]
	v_pk_add_f32 v[90:91], v[40:41], v[44:45]
	ds_write2st64_b32 v29, v31, v64 offset0:232 offset1:236
	v_add_f32_e32 v31, v88, v89
	v_add_f32_e32 v88, v90, v91
	v_add_u32_e32 v133, 0x2c00, v23
	v_add_f32_dpp v31, v31, v31 quad_perm:[1,0,3,2] row_mask:0xf bank_mask:0xf bound_ctrl:1
	v_add_f32_dpp v88, v88, v88 quad_perm:[1,0,3,2] row_mask:0xf bank_mask:0xf bound_ctrl:1
	v_pk_fma_f32 v[80:81], v[84:85], v[12:13], v[48:49] op_sel_hi:[0,1,1]
	v_pk_fma_f32 v[82:83], v[84:85], v[14:15], v[56:57] op_sel_hi:[0,1,1]
	v_pk_fma_f32 v[86:87], v[84:85], v[8:9], v[52:53] op_sel_hi:[0,1,1]
	v_pk_fma_f32 v[84:85], v[84:85], v[10:11], v[58:59] op_sel_hi:[0,1,1]
	ds_read_b128 v[8:11], v22 offset:10752
	ds_read_b128 v[12:15], v22 offset:10768
	ds_read_b128 v[40:43], v22 offset:11008
	ds_read_b128 v[44:47], v22 offset:11024
	ds_read_b128 v[48:51], v22 offset:11264
	ds_read_b128 v[52:55], v22 offset:11280
	ds_read_b128 v[56:59], v22 offset:11520
	ds_read_b128 v[60:63], v22 offset:11536
	ds_read_b128 v[64:67], v22 offset:11776
	ds_read_b128 v[68:71], v22 offset:11792
	ds_read2_b32 v[92:93], v133 offset0:192 offset1:200
	v_add_f32_dpp v31, v31, v31 quad_perm:[2,3,0,1] row_mask:0xf bank_mask:0xf bound_ctrl:1
	v_add_f32_dpp v89, v88, v88 quad_perm:[2,3,0,1] row_mask:0xf bank_mask:0xf bound_ctrl:1
	v_add_u32_e32 v134, 0x3400, v23
	v_add_f32_dpp v88, v31, v31 row_half_mirror row_mask:0xf bank_mask:0xf bound_ctrl:1
	v_add_f32_dpp v90, v89, v89 row_half_mirror row_mask:0xf bank_mask:0xf bound_ctrl:1
	v_pk_fma_f32 v[72:73], v[36:37], v[88:89], v[72:73] op_sel_hi:[1,0,1]
	v_pk_fma_f32 v[76:77], v[32:33], v[88:89], v[76:77] op_sel_hi:[1,0,1]
	v_pk_fma_f32 v[36:37], v[36:37], v[90:91], v[80:81] op_sel_hi:[1,0,1]
	v_pk_fma_f32 v[32:33], v[32:33], v[90:91], v[86:87] op_sel_hi:[1,0,1]
	v_pk_fma_f32 v[74:75], v[38:39], v[88:89], v[74:75] op_sel_hi:[1,0,1]
	v_pk_fma_f32 v[78:79], v[34:35], v[88:89], v[78:79] op_sel_hi:[1,0,1]
	v_pk_fma_f32 v[38:39], v[38:39], v[90:91], v[82:83] op_sel_hi:[1,0,1]
	v_pk_fma_f32 v[34:35], v[34:35], v[90:91], v[84:85] op_sel_hi:[1,0,1]
	v_pk_mul_f32 v[80:81], v[4:5], v[72:73]
	v_pk_mul_f32 v[82:83], v[0:1], v[76:77]
	v_pk_mul_f32 v[4:5], v[4:5], v[36:37]
	v_pk_mul_f32 v[0:1], v[0:1], v[32:33]
	s_waitcnt lgkmcnt(8)
	v_pk_mul_f32 v[84:85], v[40:41], v[72:73]
	s_waitcnt lgkmcnt(7)
	v_pk_mul_f32 v[86:87], v[44:45], v[76:77]
	v_pk_mul_f32 v[40:41], v[40:41], v[36:37]
	v_pk_mul_f32 v[44:45], v[44:45], v[32:33]
	v_pk_mul_f32 v[72:73], v[8:9], v[72:73]
	v_pk_mul_f32 v[88:89], v[10:11], v[74:75]
	v_pk_mul_f32 v[76:77], v[12:13], v[76:77]
	v_pk_mul_f32 v[90:91], v[14:15], v[78:79]
	v_pk_mul_f32 v[8:9], v[8:9], v[36:37]
	v_pk_mul_f32 v[10:11], v[10:11], v[38:39]
	v_pk_mul_f32 v[12:13], v[12:13], v[32:33]
	v_pk_mul_f32 v[14:15], v[14:15], v[34:35]
	v_pk_fma_f32 v[32:33], v[6:7], v[74:75], v[80:81]
	v_pk_fma_f32 v[36:37], v[2:3], v[78:79], v[82:83]
	v_pk_fma_f32 v[4:5], v[6:7], v[38:39], v[4:5]
	v_pk_fma_f32 v[0:1], v[2:3], v[34:35], v[0:1]
	v_pk_fma_f32 v[2:3], v[42:43], v[74:75], v[84:85]
	v_pk_fma_f32 v[6:7], v[46:47], v[78:79], v[86:87]
	v_pk_fma_f32 v[38:39], v[42:43], v[38:39], v[40:41]
	v_pk_fma_f32 v[34:35], v[46:47], v[34:35], v[44:45]
	s_waitcnt lgkmcnt(0)
; #define SCAN_STEP(w0, w1, a0, a1, b0, b1, k0, k1, r0, r1, vi, vj, t) do { \
;                 SCAN_ROW(S0, S1, S2, S3, w0, w1, a0, a1, b0, b1, k0, k1, r0, r1, vi, (t) * 512); \
;                 SCAN_ROW(T0, T1, T2, T3, w0, w1, a0, a1, b0, b1, k0, k1, r0, r1, vj, (t) * 512 + 256); } while (0)
;     ...
;             SCAN_LOAD(w0, w1, a0, a1, b0, b1, k0, k1, r0, r1, vi, vj, 0);
; #pragma unroll
;             for (int t = 0; t < 16; t += 2) {
;                 SCAN_LOAD(W0, W1, A0, A1, B0, B1, K0, K1, R0, R1, VI, VJ, t + 1);
;                 SCAN_STEP(w0, w1, a0, a1, b0, b1, k0, k1, r0, r1, vi, vj, t);
;                 if (t + 2 < 16) SCAN_LOAD(w0, w1, a0, a1, b0, b1, k0, k1, r0, r1, vi, vj, t + 2);
;                 SCAN_STEP(W0, W1, A0, A1, B0, B1, K0, K1, R0, R1, VI, VJ, t + 1);
	v_mov_b32_e32 v94, v93
	v_pk_add_f32 v[0:1], v[4:5], v[0:1]
	v_pk_add_f32 v[2:3], v[2:3], v[6:7]
	v_pk_add_f32 v[4:5], v[38:39], v[34:35]
	v_pk_fma_f32 v[80:81], v[56:57], v[94:95], v[8:9] op_sel_hi:[1,0,1]
	v_pk_add_f32 v[8:9], v[32:33], v[36:37]
	v_add_f32_e32 v0, v0, v1
	v_add_f32_e32 v1, v2, v3
	v_add_f32_e32 v2, v4, v5
	v_pk_fma_f32 v[78:79], v[62:63], v[92:93], v[90:91] op_sel_hi:[1,0,1]
	v_add_f32_e32 v6, v8, v9
	v_add_f32_dpp v31, v1, v1 quad_perm:[1,0,3,2] row_mask:0xf bank_mask:0xf bound_ctrl:1
	v_add_f32_dpp v90, v2, v2 quad_perm:[1,0,3,2] row_mask:0xf bank_mask:0xf bound_ctrl:1
	ds_write2st64_b32 v29, v6, v0 offset0:240 offset1:244
	v_add_f32_dpp v31, v31, v31 quad_perm:[2,3,0,1] row_mask:0xf bank_mask:0xf bound_ctrl:1
	v_add_f32_dpp v91, v90, v90 quad_perm:[2,3,0,1] row_mask:0xf bank_mask:0xf bound_ctrl:1
	v_pk_fma_f32 v[72:73], v[56:57], v[92:93], v[72:73] op_sel_hi:[1,0,1]
	v_pk_fma_f32 v[74:75], v[58:59], v[92:93], v[88:89] op_sel_hi:[1,0,1]
	v_pk_fma_f32 v[76:77], v[60:61], v[92:93], v[76:77] op_sel_hi:[1,0,1]
	v_pk_fma_f32 v[82:83], v[58:59], v[94:95], v[10:11] op_sel_hi:[1,0,1]
	v_pk_fma_f32 v[84:85], v[60:61], v[94:95], v[12:13] op_sel_hi:[1,0,1]
	v_pk_fma_f32 v[86:87], v[62:63], v[94:95], v[14:15] op_sel_hi:[1,0,1]
	ds_read2_b32 v[88:89], v134 offset0:64 offset1:72
	ds_read_b128 v[0:3], v22 offset:13328
	ds_read_b128 v[4:7], v22 offset:13312
	ds_read_b128 v[8:11], v22 offset:13072
	ds_read_b128 v[12:15], v22 offset:13056
	ds_read_b128 v[32:35], v22 offset:12816
	ds_read_b128 v[36:39], v22 offset:12800
	ds_read_b128 v[40:43], v22 offset:12560
	ds_read_b128 v[44:47], v22 offset:12544
	ds_read_b128 v[56:59], v22 offset:12288
	ds_read_b128 v[60:63], v22 offset:12304
	v_add_f32_dpp v90, v31, v31 row_half_mirror row_mask:0xf bank_mask:0xf bound_ctrl:1
	v_add_f32_dpp v92, v91, v91 row_half_mirror row_mask:0xf bank_mask:0xf bound_ctrl:1
	v_pk_fma_f32 v[72:73], v[48:49], v[90:91], v[72:73] op_sel_hi:[1,0,1]
	v_pk_fma_f32 v[76:77], v[52:53], v[90:91], v[76:77] op_sel_hi:[1,0,1]
	v_pk_fma_f32 v[48:49], v[48:49], v[92:93], v[80:81] op_sel_hi:[1,0,1]
	v_pk_fma_f32 v[52:53], v[52:53], v[92:93], v[84:85] op_sel_hi:[1,0,1]
	v_pk_fma_f32 v[74:75], v[50:51], v[90:91], v[74:75] op_sel_hi:[1,0,1]
	v_pk_fma_f32 v[78:79], v[54:55], v[90:91], v[78:79] op_sel_hi:[1,0,1]
	v_pk_fma_f32 v[50:51], v[50:51], v[92:93], v[82:83] op_sel_hi:[1,0,1]
	v_pk_fma_f32 v[54:55], v[54:55], v[92:93], v[86:87] op_sel_hi:[1,0,1]
	v_pk_mul_f32 v[80:81], v[64:65], v[72:73]
	v_pk_mul_f32 v[82:83], v[68:69], v[76:77]
	v_pk_mul_f32 v[64:65], v[64:65], v[48:49]
	v_pk_mul_f32 v[68:69], v[68:69], v[52:53]
	v_pk_fma_f32 v[80:81], v[66:67], v[74:75], v[80:81]
	v_pk_fma_f32 v[64:65], v[66:67], v[50:51], v[64:65]
	v_pk_fma_f32 v[66:67], v[70:71], v[54:55], v[68:69]
	v_pk_fma_f32 v[82:83], v[70:71], v[78:79], v[82:83]
	v_pk_add_f32 v[64:65], v[64:65], v[66:67]
	s_waitcnt lgkmcnt(2)
	v_pk_mul_f32 v[66:67], v[44:45], v[72:73]
	v_pk_mul_f32 v[70:71], v[40:41], v[76:77]
	v_pk_mul_f32 v[44:45], v[44:45], v[48:49]
	v_pk_mul_f32 v[40:41], v[40:41], v[52:53]
	v_pk_add_f32 v[68:69], v[80:81], v[82:83]
	s_waitcnt lgkmcnt(1)
	v_pk_mul_f32 v[72:73], v[56:57], v[72:73]
	v_pk_mul_f32 v[80:81], v[58:59], v[74:75]
	s_waitcnt lgkmcnt(0)
	v_pk_mul_f32 v[76:77], v[60:61], v[76:77]
	v_pk_mul_f32 v[82:83], v[62:63], v[78:79]
	v_pk_mul_f32 v[48:49], v[56:57], v[48:49]
	v_pk_mul_f32 v[56:57], v[58:59], v[50:51]
	v_pk_mul_f32 v[52:53], v[60:61], v[52:53]
	v_pk_mul_f32 v[58:59], v[62:63], v[54:55]
	v_pk_fma_f32 v[60:61], v[46:47], v[74:75], v[66:67]
	v_pk_fma_f32 v[62:63], v[42:43], v[78:79], v[70:71]
	v_pk_fma_f32 v[44:45], v[46:47], v[50:51], v[44:45]
	v_pk_fma_f32 v[40:41], v[42:43], v[54:55], v[40:41]
	v_mov_b32_e32 v84, v89
	v_add_f32_e32 v31, v68, v69
	v_add_f32_e32 v64, v64, v65
	v_pk_fma_f32 v[72:73], v[88:89], v[12:13], v[72:73] op_sel_hi:[0,1,1]
	v_pk_fma_f32 v[74:75], v[88:89], v[14:15], v[80:81] op_sel_hi:[0,1,1]
	v_pk_fma_f32 v[76:77], v[88:89], v[8:9], v[76:77] op_sel_hi:[0,1,1]
	v_pk_fma_f32 v[78:79], v[88:89], v[10:11], v[82:83] op_sel_hi:[0,1,1]
	v_pk_add_f32 v[88:89], v[62:63], v[60:61]
	v_pk_add_f32 v[90:91], v[40:41], v[44:45]
	v_add_u32_e32 v21, 0xc000, v29
	v_add_u32_e32 v30, 0x3800, v23
	ds_write2st64_b32 v29, v31, v64 offset0:248 offset1:252
	v_add_f32_e32 v29, v88, v89
	v_add_f32_e32 v88, v90, v91
	v_pk_fma_f32 v[80:81], v[84:85], v[12:13], v[48:49] op_sel_hi:[0,1,1]
	v_pk_fma_f32 v[82:83], v[84:85], v[14:15], v[56:57] op_sel_hi:[0,1,1]
	v_pk_fma_f32 v[86:87], v[84:85], v[8:9], v[52:53] op_sel_hi:[0,1,1]
	v_pk_fma_f32 v[84:85], v[84:85], v[10:11], v[58:59] op_sel_hi:[0,1,1]
	ds_read_b128 v[8:11], v22 offset:13824
	ds_read_b128 v[12:15], v22 offset:13840
	ds_read_b128 v[40:43], v22 offset:14080
	ds_read_b128 v[44:47], v22 offset:14096
	ds_read_b128 v[48:51], v22 offset:14336
	ds_read_b128 v[52:55], v22 offset:14352
	ds_read_b128 v[56:59], v22 offset:14592
	ds_read_b128 v[60:63], v22 offset:14608
	ds_read_b128 v[64:67], v22 offset:14848
	ds_read_b128 v[68:71], v22 offset:14864
	ds_read2_b32 v[30:31], v30 offset0:192 offset1:200
	v_add_f32_dpp v29, v29, v29 quad_perm:[1,0,3,2] row_mask:0xf bank_mask:0xf bound_ctrl:1
	v_add_f32_dpp v88, v88, v88 quad_perm:[1,0,3,2] row_mask:0xf bank_mask:0xf bound_ctrl:1
	v_add_u32_e32 v28, 0x4000, v23
	v_add_f32_dpp v29, v29, v29 quad_perm:[2,3,0,1] row_mask:0xf bank_mask:0xf bound_ctrl:1
	v_add_f32_dpp v89, v88, v88 quad_perm:[2,3,0,1] row_mask:0xf bank_mask:0xf bound_ctrl:1
	s_waitcnt lgkmcnt(0)
; #define SCAN_STEP(w0, w1, a0, a1, b0, b1, k0, k1, r0, r1, vi, vj, t) do { \
;                 SCAN_ROW(S0, S1, S2, S3, w0, w1, a0, a1, b0, b1, k0, k1, r0, r1, vi, (t) * 512); \
;                 SCAN_ROW(T0, T1, T2, T3, w0, w1, a0, a1, b0, b1, k0, k1, r0, r1, vj, (t) * 512 + 256); } while (0)
;     ...
;             SCAN_LOAD(w0, w1, a0, a1, b0, b1, k0, k1, r0, r1, vi, vj, 0);
; #pragma unroll
;             for (int t = 0; t < 16; t += 2) {
;                 SCAN_LOAD(W0, W1, A0, A1, B0, B1, K0, K1, R0, R1, VI, VJ, t + 1);
;                 SCAN_STEP(w0, w1, a0, a1, b0, b1, k0, k1, r0, r1, vi, vj, t);
;                 if (t + 2 < 16) SCAN_LOAD(w0, w1, a0, a1, b0, b1, k0, k1, r0, r1, vi, vj, t + 2);
;                 SCAN_STEP(W0, W1, A0, A1, B0, B1, K0, K1, R0, R1, VI, VJ, t + 1);
	v_mov_b32_e32 v92, v31
	v_add_f32_dpp v88, v29, v29 row_half_mirror row_mask:0xf bank_mask:0xf bound_ctrl:1
	v_add_f32_dpp v90, v89, v89 row_half_mirror row_mask:0xf bank_mask:0xf bound_ctrl:1
	v_pk_fma_f32 v[72:73], v[36:37], v[88:89], v[72:73] op_sel_hi:[1,0,1]
	v_pk_fma_f32 v[74:75], v[38:39], v[88:89], v[74:75] op_sel_hi:[1,0,1]
	v_pk_fma_f32 v[76:77], v[32:33], v[88:89], v[76:77] op_sel_hi:[1,0,1]
	v_pk_fma_f32 v[78:79], v[34:35], v[88:89], v[78:79] op_sel_hi:[1,0,1]
	v_pk_fma_f32 v[36:37], v[36:37], v[90:91], v[80:81] op_sel_hi:[1,0,1]
	v_pk_fma_f32 v[32:33], v[32:33], v[90:91], v[86:87] op_sel_hi:[1,0,1]
	v_pk_fma_f32 v[38:39], v[38:39], v[90:91], v[82:83] op_sel_hi:[1,0,1]
	v_pk_fma_f32 v[34:35], v[34:35], v[90:91], v[84:85] op_sel_hi:[1,0,1]
	v_pk_mul_f32 v[80:81], v[4:5], v[72:73]
	v_pk_mul_f32 v[82:83], v[0:1], v[76:77]
	v_pk_mul_f32 v[4:5], v[4:5], v[36:37]
	v_pk_mul_f32 v[0:1], v[0:1], v[32:33]
	v_pk_mul_f32 v[84:85], v[40:41], v[72:73]
	v_pk_mul_f32 v[86:87], v[44:45], v[76:77]
	v_pk_mul_f32 v[72:73], v[8:9], v[72:73]
	v_pk_mul_f32 v[88:89], v[10:11], v[74:75]
	v_pk_mul_f32 v[76:77], v[12:13], v[76:77]
	v_pk_mul_f32 v[90:91], v[14:15], v[78:79]
	v_pk_mul_f32 v[40:41], v[40:41], v[36:37]
	v_pk_mul_f32 v[44:45], v[44:45], v[32:33]
	v_pk_mul_f32 v[8:9], v[8:9], v[36:37]
	v_pk_mul_f32 v[12:13], v[12:13], v[32:33]
	v_pk_mul_f32 v[14:15], v[14:15], v[34:35]
	v_pk_fma_f32 v[32:33], v[6:7], v[74:75], v[80:81]
	v_pk_fma_f32 v[36:37], v[2:3], v[78:79], v[82:83]
	v_pk_fma_f32 v[4:5], v[6:7], v[38:39], v[4:5]
	v_pk_fma_f32 v[0:1], v[2:3], v[34:35], v[0:1]
	v_pk_fma_f32 v[2:3], v[42:43], v[74:75], v[84:85]
	v_pk_fma_f32 v[6:7], v[46:47], v[78:79], v[86:87]
	v_pk_fma_f32 v[72:73], v[56:57], v[30:31], v[72:73] op_sel_hi:[1,0,1]
	v_pk_fma_f32 v[74:75], v[58:59], v[30:31], v[88:89] op_sel_hi:[1,0,1]
	v_pk_fma_f32 v[76:77], v[60:61], v[30:31], v[76:77] op_sel_hi:[1,0,1]
	v_pk_fma_f32 v[78:79], v[62:63], v[30:31], v[90:91] op_sel_hi:[1,0,1]
	v_pk_fma_f32 v[30:31], v[42:43], v[38:39], v[40:41]
	v_pk_fma_f32 v[34:35], v[46:47], v[34:35], v[44:45]
	v_pk_add_f32 v[0:1], v[4:5], v[0:1]
	v_pk_add_f32 v[2:3], v[2:3], v[6:7]
	v_pk_add_f32 v[4:5], v[30:31], v[34:35]
	v_pk_fma_f32 v[80:81], v[56:57], v[92:93], v[8:9] op_sel_hi:[1,0,1]
	v_pk_add_f32 v[8:9], v[32:33], v[36:37]
	v_add_f32_e32 v0, v0, v1
	v_add_f32_e32 v1, v2, v3
	v_add_f32_e32 v2, v4, v5
	v_add_f32_e32 v6, v8, v9
	v_add_f32_dpp v86, v1, v1 quad_perm:[1,0,3,2] row_mask:0xf bank_mask:0xf bound_ctrl:1
	v_add_f32_dpp v87, v2, v2 quad_perm:[1,0,3,2] row_mask:0xf bank_mask:0xf bound_ctrl:1
	v_pk_mul_f32 v[10:11], v[10:11], v[38:39]
	ds_write2st64_b32 v21, v6, v0 offset0:64 offset1:68
	v_add_f32_dpp v86, v86, v86 quad_perm:[2,3,0,1] row_mask:0xf bank_mask:0xf bound_ctrl:1
	v_add_f32_dpp v87, v87, v87 quad_perm:[2,3,0,1] row_mask:0xf bank_mask:0xf bound_ctrl:1
	v_pk_fma_f32 v[82:83], v[58:59], v[92:93], v[10:11] op_sel_hi:[1,0,1]
	v_pk_fma_f32 v[60:61], v[60:61], v[92:93], v[12:13] op_sel_hi:[1,0,1]
	v_pk_fma_f32 v[62:63], v[62:63], v[92:93], v[14:15] op_sel_hi:[1,0,1]
	ds_read2_b32 v[84:85], v28 offset0:64 offset1:72
	ds_read_b128 v[0:3], v22 offset:16400
	ds_read_b128 v[4:7], v22 offset:16384
	ds_read_b128 v[8:11], v22 offset:16144
	ds_read_b128 v[12:15], v22 offset:16128
	ds_read_b128 v[28:31], v22 offset:15888
	ds_read_b128 v[32:35], v22 offset:15872
	ds_read_b128 v[36:39], v22 offset:15632
	ds_read_b128 v[40:43], v22 offset:15616
	ds_read_b128 v[44:47], v22 offset:15360
	ds_read_b128 v[56:59], v22 offset:15376
	v_add_f32_dpp v86, v86, v86 row_half_mirror row_mask:0xf bank_mask:0xf bound_ctrl:1
	v_add_f32_dpp v88, v87, v87 row_half_mirror row_mask:0xf bank_mask:0xf bound_ctrl:1
	v_pk_fma_f32 v[72:73], v[48:49], v[86:87], v[72:73] op_sel_hi:[1,0,1]
	v_pk_fma_f32 v[76:77], v[52:53], v[86:87], v[76:77] op_sel_hi:[1,0,1]
	v_pk_fma_f32 v[48:49], v[48:49], v[88:89], v[80:81] op_sel_hi:[1,0,1]
	v_pk_fma_f32 v[52:53], v[52:53], v[88:89], v[60:61] op_sel_hi:[1,0,1]
	v_pk_fma_f32 v[74:75], v[50:51], v[86:87], v[74:75] op_sel_hi:[1,0,1]
	v_pk_fma_f32 v[78:79], v[54:55], v[86:87], v[78:79] op_sel_hi:[1,0,1]
	v_pk_fma_f32 v[50:51], v[50:51], v[88:89], v[82:83] op_sel_hi:[1,0,1]
	v_pk_fma_f32 v[54:55], v[54:55], v[88:89], v[62:63] op_sel_hi:[1,0,1]
	v_pk_mul_f32 v[60:61], v[64:65], v[72:73]
	v_pk_mul_f32 v[62:63], v[68:69], v[76:77]
	v_pk_mul_f32 v[64:65], v[64:65], v[48:49]
	v_pk_mul_f32 v[68:69], v[68:69], v[52:53]
	v_pk_fma_f32 v[60:61], v[66:67], v[74:75], v[60:61]
	v_pk_fma_f32 v[62:63], v[70:71], v[78:79], v[62:63]
	v_pk_fma_f32 v[64:65], v[66:67], v[50:51], v[64:65]
	v_pk_fma_f32 v[66:67], v[70:71], v[54:55], v[68:69]
	v_pk_add_f32 v[60:61], v[60:61], v[62:63]
	v_pk_add_f32 v[62:63], v[64:65], v[66:67]
	s_waitcnt lgkmcnt(2)
	v_pk_mul_f32 v[64:65], v[40:41], v[72:73]
	v_pk_mul_f32 v[66:67], v[36:37], v[76:77]
	v_pk_mul_f32 v[40:41], v[40:41], v[48:49]
	v_pk_mul_f32 v[36:37], v[36:37], v[52:53]
	s_waitcnt lgkmcnt(1)
	v_pk_mul_f32 v[68:69], v[44:45], v[72:73]
	v_pk_mul_f32 v[70:71], v[46:47], v[74:75]
	s_waitcnt lgkmcnt(0)
; #define SCAN_STEP(w0, w1, a0, a1, b0, b1, k0, k1, r0, r1, vi, vj, t) do { \
;                 SCAN_ROW(S0, S1, S2, S3, w0, w1, a0, a1, b0, b1, k0, k1, r0, r1, vi, (t) * 512); \
;                 SCAN_ROW(T0, T1, T2, T3, w0, w1, a0, a1, b0, b1, k0, k1, r0, r1, vj, (t) * 512 + 256); } while (0)
;     ...
;             SCAN_LOAD(w0, w1, a0, a1, b0, b1, k0, k1, r0, r1, vi, vj, 0);
; #pragma unroll
;             for (int t = 0; t < 16; t += 2) {
;                 SCAN_LOAD(W0, W1, A0, A1, B0, B1, K0, K1, R0, R1, VI, VJ, t + 1);
;                 SCAN_STEP(w0, w1, a0, a1, b0, b1, k0, k1, r0, r1, vi, vj, t);
;                 if (t + 2 < 16) SCAN_LOAD(w0, w1, a0, a1, b0, b1, k0, k1, r0, r1, vi, vj, t + 2);
;                 SCAN_STEP(W0, W1, A0, A1, B0, B1, K0, K1, R0, R1, VI, VJ, t + 1);
	v_pk_mul_f32 v[72:73], v[56:57], v[76:77]
	v_pk_mul_f32 v[76:77], v[58:59], v[78:79]
	v_pk_mul_f32 v[44:45], v[44:45], v[48:49]
	v_pk_mul_f32 v[48:49], v[56:57], v[52:53]
	v_pk_mul_f32 v[52:53], v[58:59], v[54:55]
	v_add_f32_e32 v60, v60, v61
	v_add_f32_e32 v61, v62, v63
	v_pk_fma_f32 v[56:57], v[42:43], v[74:75], v[64:65]
	v_pk_fma_f32 v[58:59], v[38:39], v[78:79], v[66:67]
	v_pk_fma_f32 v[40:41], v[42:43], v[50:51], v[40:41]
	v_pk_fma_f32 v[36:37], v[38:39], v[54:55], v[36:37]
	v_add_u32_e32 v27, 0x4400, v23
	v_mov_b32_e32 v80, v85
	v_pk_mul_f32 v[46:47], v[46:47], v[50:51]
	v_pk_fma_f32 v[68:69], v[84:85], v[12:13], v[68:69] op_sel_hi:[0,1,1]
	v_pk_fma_f32 v[70:71], v[84:85], v[14:15], v[70:71] op_sel_hi:[0,1,1]
	v_pk_fma_f32 v[72:73], v[84:85], v[8:9], v[72:73] op_sel_hi:[0,1,1]
	v_pk_fma_f32 v[74:75], v[84:85], v[10:11], v[76:77] op_sel_hi:[0,1,1]
	ds_write2st64_b32 v21, v60, v61 offset0:72 offset1:76
	v_pk_add_f32 v[84:85], v[58:59], v[56:57]
	v_pk_add_f32 v[86:87], v[36:37], v[40:41]
	v_pk_fma_f32 v[76:77], v[80:81], v[12:13], v[44:45] op_sel_hi:[0,1,1]
	v_pk_fma_f32 v[78:79], v[80:81], v[14:15], v[46:47] op_sel_hi:[0,1,1]
	v_pk_fma_f32 v[82:83], v[80:81], v[8:9], v[48:49] op_sel_hi:[0,1,1]
	v_pk_fma_f32 v[80:81], v[80:81], v[10:11], v[52:53] op_sel_hi:[0,1,1]
	ds_read_b128 v[8:11], v22 offset:16896
	ds_read_b128 v[12:15], v22 offset:16912
	ds_read_b128 v[36:39], v22 offset:17152
	ds_read_b128 v[40:43], v22 offset:17168
	ds_read_b128 v[44:47], v22 offset:17408
	ds_read_b128 v[48:51], v22 offset:17424
	ds_read_b128 v[52:55], v22 offset:17664
	ds_read_b128 v[56:59], v22 offset:17680
	ds_read_b128 v[60:63], v22 offset:17920
	ds_read_b128 v[64:67], v22 offset:17936
	ds_read2_b32 v[88:89], v27 offset0:192 offset1:200
	v_add_f32_e32 v27, v84, v85
	v_add_f32_e32 v84, v86, v87
	v_add_u32_e32 v26, 0x4c00, v23
	v_add_f32_dpp v27, v27, v27 quad_perm:[1,0,3,2] row_mask:0xf bank_mask:0xf bound_ctrl:1
	v_add_f32_dpp v84, v84, v84 quad_perm:[1,0,3,2] row_mask:0xf bank_mask:0xf bound_ctrl:1
	s_waitcnt lgkmcnt(0)
	v_mov_b32_e32 v90, v89
	v_add_f32_dpp v27, v27, v27 quad_perm:[2,3,0,1] row_mask:0xf bank_mask:0xf bound_ctrl:1
	v_add_f32_dpp v85, v84, v84 quad_perm:[2,3,0,1] row_mask:0xf bank_mask:0xf bound_ctrl:1
	v_add_u32_e32 v25, 0x5000, v23
	v_add_f32_dpp v84, v27, v27 row_half_mirror row_mask:0xf bank_mask:0xf bound_ctrl:1
	v_add_f32_dpp v86, v85, v85 row_half_mirror row_mask:0xf bank_mask:0xf bound_ctrl:1
	v_pk_fma_f32 v[68:69], v[32:33], v[84:85], v[68:69] op_sel_hi:[1,0,1]
	v_pk_fma_f32 v[72:73], v[28:29], v[84:85], v[72:73] op_sel_hi:[1,0,1]
	v_pk_fma_f32 v[32:33], v[32:33], v[86:87], v[76:77] op_sel_hi:[1,0,1]
	v_pk_fma_f32 v[28:29], v[28:29], v[86:87], v[82:83] op_sel_hi:[1,0,1]
	v_pk_fma_f32 v[70:71], v[34:35], v[84:85], v[70:71] op_sel_hi:[1,0,1]
	v_pk_fma_f32 v[74:75], v[30:31], v[84:85], v[74:75] op_sel_hi:[1,0,1]
	v_pk_fma_f32 v[34:35], v[34:35], v[86:87], v[78:79] op_sel_hi:[1,0,1]
	v_pk_fma_f32 v[30:31], v[30:31], v[86:87], v[80:81] op_sel_hi:[1,0,1]
	v_pk_mul_f32 v[76:77], v[4:5], v[68:69]
	v_pk_mul_f32 v[78:79], v[0:1], v[72:73]
	v_pk_mul_f32 v[4:5], v[4:5], v[32:33]
	v_pk_mul_f32 v[0:1], v[0:1], v[28:29]
	v_pk_mul_f32 v[80:81], v[36:37], v[68:69]
	v_pk_mul_f32 v[82:83], v[40:41], v[72:73]
	v_pk_mul_f32 v[36:37], v[36:37], v[32:33]
	v_pk_mul_f32 v[40:41], v[40:41], v[28:29]
	v_pk_mul_f32 v[68:69], v[8:9], v[68:69]
	v_pk_mul_f32 v[84:85], v[10:11], v[70:71]
	v_pk_mul_f32 v[72:73], v[12:13], v[72:73]
	v_pk_mul_f32 v[86:87], v[14:15], v[74:75]
	v_pk_mul_f32 v[8:9], v[8:9], v[32:33]
	v_pk_mul_f32 v[10:11], v[10:11], v[34:35]
	v_pk_mul_f32 v[12:13], v[12:13], v[28:29]
	v_pk_mul_f32 v[14:15], v[14:15], v[30:31]
	v_pk_fma_f32 v[28:29], v[6:7], v[70:71], v[76:77]
	v_pk_fma_f32 v[32:33], v[2:3], v[74:75], v[78:79]
	v_pk_fma_f32 v[4:5], v[6:7], v[34:35], v[4:5]
	v_pk_fma_f32 v[0:1], v[2:3], v[30:31], v[0:1]
	v_pk_fma_f32 v[2:3], v[38:39], v[70:71], v[80:81]
	v_pk_fma_f32 v[6:7], v[42:43], v[74:75], v[82:83]
	v_pk_fma_f32 v[34:35], v[38:39], v[34:35], v[36:37]
	v_pk_fma_f32 v[30:31], v[42:43], v[30:31], v[40:41]
	v_pk_add_f32 v[0:1], v[4:5], v[0:1]
	v_pk_add_f32 v[2:3], v[2:3], v[6:7]
	v_pk_add_f32 v[4:5], v[34:35], v[30:31]
	v_pk_fma_f32 v[42:43], v[52:53], v[90:91], v[8:9] op_sel_hi:[1,0,1]
	v_pk_add_f32 v[8:9], v[28:29], v[32:33]
	v_add_f32_e32 v0, v0, v1
	v_add_f32_e32 v1, v2, v3
	v_add_f32_e32 v2, v4, v5
	v_pk_fma_f32 v[70:71], v[54:55], v[88:89], v[84:85] op_sel_hi:[1,0,1]
	v_add_f32_e32 v6, v8, v9
	v_add_f32_dpp v84, v1, v1 quad_perm:[1,0,3,2] row_mask:0xf bank_mask:0xf bound_ctrl:1
	v_add_f32_dpp v85, v2, v2 quad_perm:[1,0,3,2] row_mask:0xf bank_mask:0xf bound_ctrl:1
	ds_write2st64_b32 v21, v6, v0 offset0:80 offset1:84
	v_add_f32_dpp v84, v84, v84 quad_perm:[2,3,0,1] row_mask:0xf bank_mask:0xf bound_ctrl:1
	v_add_f32_dpp v85, v85, v85 quad_perm:[2,3,0,1] row_mask:0xf bank_mask:0xf bound_ctrl:1
	v_pk_fma_f32 v[68:69], v[52:53], v[88:89], v[68:69] op_sel_hi:[1,0,1]
	v_pk_fma_f32 v[72:73], v[56:57], v[88:89], v[72:73] op_sel_hi:[1,0,1]
	v_pk_fma_f32 v[74:75], v[58:59], v[88:89], v[86:87] op_sel_hi:[1,0,1]
	v_pk_fma_f32 v[76:77], v[54:55], v[90:91], v[10:11] op_sel_hi:[1,0,1]
	v_pk_fma_f32 v[78:79], v[56:57], v[90:91], v[12:13] op_sel_hi:[1,0,1]
	v_pk_fma_f32 v[80:81], v[58:59], v[90:91], v[14:15] op_sel_hi:[1,0,1]
	ds_read2_b32 v[82:83], v26 offset0:64 offset1:72
	ds_read_b128 v[0:3], v22 offset:19472
	ds_read_b128 v[4:7], v22 offset:19456
	ds_read_b128 v[8:11], v22 offset:19216
	ds_read_b128 v[12:15], v22 offset:19200
	ds_read_b128 v[26:29], v22 offset:18960
	ds_read_b128 v[30:33], v22 offset:18944
	ds_read_b128 v[34:37], v22 offset:18704
	ds_read_b128 v[38:41], v22 offset:18688
	ds_read_b128 v[52:55], v22 offset:18432
	ds_read_b128 v[56:59], v22 offset:18448
	v_add_f32_dpp v84, v84, v84 row_half_mirror row_mask:0xf bank_mask:0xf bound_ctrl:1
	v_add_f32_dpp v86, v85, v85 row_half_mirror row_mask:0xf bank_mask:0xf bound_ctrl:1
	v_pk_fma_f32 v[68:69], v[44:45], v[84:85], v[68:69] op_sel_hi:[1,0,1]
	v_pk_fma_f32 v[70:71], v[46:47], v[84:85], v[70:71] op_sel_hi:[1,0,1]
	v_pk_fma_f32 v[72:73], v[48:49], v[84:85], v[72:73] op_sel_hi:[1,0,1]
	v_pk_fma_f32 v[42:43], v[44:45], v[86:87], v[42:43] op_sel_hi:[1,0,1]
	v_pk_fma_f32 v[44:45], v[46:47], v[86:87], v[76:77] op_sel_hi:[1,0,1]
	v_pk_fma_f32 v[46:47], v[48:49], v[86:87], v[78:79] op_sel_hi:[1,0,1]
	v_pk_fma_f32 v[74:75], v[50:51], v[84:85], v[74:75] op_sel_hi:[1,0,1]
	v_pk_fma_f32 v[48:49], v[50:51], v[86:87], v[80:81] op_sel_hi:[1,0,1]
	v_pk_mul_f32 v[50:51], v[60:61], v[68:69]
	v_pk_mul_f32 v[76:77], v[64:65], v[72:73]
	v_pk_mul_f32 v[60:61], v[60:61], v[42:43]
	v_pk_mul_f32 v[64:65], v[64:65], v[46:47]
	v_pk_fma_f32 v[50:51], v[62:63], v[70:71], v[50:51]
	v_pk_fma_f32 v[76:77], v[66:67], v[74:75], v[76:77]
	v_pk_fma_f32 v[60:61], v[62:63], v[44:45], v[60:61]
	v_pk_fma_f32 v[62:63], v[66:67], v[48:49], v[64:65]
	v_pk_add_f32 v[50:51], v[50:51], v[76:77]
	v_pk_add_f32 v[60:61], v[60:61], v[62:63]
	s_waitcnt lgkmcnt(2)
; #define SCAN_STEP(w0, w1, a0, a1, b0, b1, k0, k1, r0, r1, vi, vj, t) do { \
;                 SCAN_ROW(S0, S1, S2, S3, w0, w1, a0, a1, b0, b1, k0, k1, r0, r1, vi, (t) * 512); \
;                 SCAN_ROW(T0, T1, T2, T3, w0, w1, a0, a1, b0, b1, k0, k1, r0, r1, vj, (t) * 512 + 256); } while (0)
;     ...
;             SCAN_LOAD(w0, w1, a0, a1, b0, b1, k0, k1, r0, r1, vi, vj, 0);
; #pragma unroll
;             for (int t = 0; t < 16; t += 2) {
;                 SCAN_LOAD(W0, W1, A0, A1, B0, B1, K0, K1, R0, R1, VI, VJ, t + 1);
;                 SCAN_STEP(w0, w1, a0, a1, b0, b1, k0, k1, r0, r1, vi, vj, t);
;                 if (t + 2 < 16) SCAN_LOAD(w0, w1, a0, a1, b0, b1, k0, k1, r0, r1, vi, vj, t + 2);
;                 SCAN_STEP(W0, W1, A0, A1, B0, B1, K0, K1, R0, R1, VI, VJ, t + 1);
	v_pk_mul_f32 v[62:63], v[38:39], v[68:69]
	v_pk_mul_f32 v[64:65], v[34:35], v[72:73]
	v_pk_mul_f32 v[38:39], v[38:39], v[42:43]
	v_pk_mul_f32 v[34:35], v[34:35], v[46:47]
	s_waitcnt lgkmcnt(1)
	v_pk_mul_f32 v[66:67], v[52:53], v[68:69]
	v_pk_mul_f32 v[68:69], v[54:55], v[70:71]
	s_waitcnt lgkmcnt(0)
	v_pk_mul_f32 v[72:73], v[56:57], v[72:73]
	v_pk_mul_f32 v[76:77], v[58:59], v[74:75]
	v_pk_mul_f32 v[42:43], v[52:53], v[42:43]
	v_pk_mul_f32 v[52:53], v[54:55], v[44:45]
	v_pk_mul_f32 v[46:47], v[56:57], v[46:47]
	v_pk_mul_f32 v[54:55], v[58:59], v[48:49]
	v_add_f32_e32 v58, v50, v51
	v_add_f32_e32 v59, v60, v61
	v_pk_fma_f32 v[50:51], v[40:41], v[70:71], v[62:63]
	v_pk_fma_f32 v[56:57], v[36:37], v[74:75], v[64:65]
	v_pk_fma_f32 v[38:39], v[40:41], v[44:45], v[38:39]
	v_pk_fma_f32 v[34:35], v[36:37], v[48:49], v[34:35]
	v_mov_b32_e32 v78, v83
	v_pk_fma_f32 v[66:67], v[82:83], v[12:13], v[66:67] op_sel_hi:[0,1,1]
	v_pk_fma_f32 v[68:69], v[82:83], v[14:15], v[68:69] op_sel_hi:[0,1,1]
	v_pk_fma_f32 v[70:71], v[82:83], v[8:9], v[72:73] op_sel_hi:[0,1,1]
	v_pk_fma_f32 v[72:73], v[82:83], v[10:11], v[76:77] op_sel_hi:[0,1,1]
	ds_write2st64_b32 v21, v58, v59 offset0:88 offset1:92
	v_pk_add_f32 v[82:83], v[56:57], v[50:51]
	v_pk_add_f32 v[84:85], v[34:35], v[38:39]
	v_pk_fma_f32 v[74:75], v[78:79], v[12:13], v[42:43] op_sel_hi:[0,1,1]
	v_pk_fma_f32 v[76:77], v[78:79], v[14:15], v[52:53] op_sel_hi:[0,1,1]
	v_pk_fma_f32 v[80:81], v[78:79], v[8:9], v[46:47] op_sel_hi:[0,1,1]
	v_pk_fma_f32 v[78:79], v[78:79], v[10:11], v[54:55] op_sel_hi:[0,1,1]
	ds_read_b128 v[8:11], v22 offset:19968
	ds_read_b128 v[12:15], v22 offset:19984
	ds_read_b128 v[34:37], v22 offset:20224
	ds_read_b128 v[38:41], v22 offset:20240
	ds_read_b128 v[42:45], v22 offset:20480
	ds_read_b128 v[46:49], v22 offset:20496
	ds_read_b128 v[50:53], v22 offset:20736
	ds_read_b128 v[54:57], v22 offset:20752
	ds_read_b128 v[58:61], v22 offset:20992
	ds_read_b128 v[62:65], v22 offset:21008
	ds_read2_b32 v[86:87], v25 offset0:192 offset1:200
	v_add_f32_e32 v25, v82, v83
	v_add_f32_e32 v82, v84, v85
	v_add_u32_e32 v24, 0x5800, v23
	v_add_f32_dpp v25, v25, v25 quad_perm:[1,0,3,2] row_mask:0xf bank_mask:0xf bound_ctrl:1
	v_add_f32_dpp v82, v82, v82 quad_perm:[1,0,3,2] row_mask:0xf bank_mask:0xf bound_ctrl:1
	s_waitcnt lgkmcnt(0)
	v_mov_b32_e32 v88, v87
	v_add_f32_dpp v25, v25, v25 quad_perm:[2,3,0,1] row_mask:0xf bank_mask:0xf bound_ctrl:1
	v_add_f32_dpp v83, v82, v82 quad_perm:[2,3,0,1] row_mask:0xf bank_mask:0xf bound_ctrl:1
	v_add_u32_e32 v23, 0x5c00, v23
	v_add_f32_dpp v82, v25, v25 row_half_mirror row_mask:0xf bank_mask:0xf bound_ctrl:1
	v_add_f32_dpp v84, v83, v83 row_half_mirror row_mask:0xf bank_mask:0xf bound_ctrl:1
	v_pk_fma_f32 v[66:67], v[30:31], v[82:83], v[66:67] op_sel_hi:[1,0,1]
	v_pk_fma_f32 v[70:71], v[26:27], v[82:83], v[70:71] op_sel_hi:[1,0,1]
	v_pk_fma_f32 v[30:31], v[30:31], v[84:85], v[74:75] op_sel_hi:[1,0,1]
	v_pk_fma_f32 v[26:27], v[26:27], v[84:85], v[80:81] op_sel_hi:[1,0,1]
	v_pk_fma_f32 v[68:69], v[32:33], v[82:83], v[68:69] op_sel_hi:[1,0,1]
	v_pk_fma_f32 v[72:73], v[28:29], v[82:83], v[72:73] op_sel_hi:[1,0,1]
	v_pk_fma_f32 v[32:33], v[32:33], v[84:85], v[76:77] op_sel_hi:[1,0,1]
	v_pk_fma_f32 v[28:29], v[28:29], v[84:85], v[78:79] op_sel_hi:[1,0,1]
	v_pk_mul_f32 v[74:75], v[4:5], v[66:67]
	v_pk_mul_f32 v[76:77], v[0:1], v[70:71]
	v_pk_mul_f32 v[4:5], v[4:5], v[30:31]
	v_pk_mul_f32 v[0:1], v[0:1], v[26:27]
	v_pk_mul_f32 v[78:79], v[34:35], v[66:67]
	v_pk_mul_f32 v[80:81], v[38:39], v[70:71]
	v_pk_mul_f32 v[34:35], v[34:35], v[30:31]
	v_pk_mul_f32 v[38:39], v[38:39], v[26:27]
	v_pk_mul_f32 v[66:67], v[8:9], v[66:67]
	v_pk_mul_f32 v[82:83], v[10:11], v[68:69]
	v_pk_mul_f32 v[70:71], v[12:13], v[70:71]
	v_pk_mul_f32 v[84:85], v[14:15], v[72:73]
	v_pk_mul_f32 v[8:9], v[8:9], v[30:31]
	v_pk_mul_f32 v[10:11], v[10:11], v[32:33]
	v_pk_mul_f32 v[12:13], v[12:13], v[26:27]
	v_pk_mul_f32 v[14:15], v[14:15], v[28:29]
	v_pk_fma_f32 v[26:27], v[6:7], v[68:69], v[74:75]
	v_pk_fma_f32 v[30:31], v[2:3], v[72:73], v[76:77]
	v_pk_fma_f32 v[4:5], v[6:7], v[32:33], v[4:5]
	v_pk_fma_f32 v[0:1], v[2:3], v[28:29], v[0:1]
	v_pk_fma_f32 v[2:3], v[36:37], v[68:69], v[78:79]
	v_pk_fma_f32 v[6:7], v[40:41], v[72:73], v[80:81]
	v_pk_fma_f32 v[32:33], v[36:37], v[32:33], v[34:35]
	v_pk_fma_f32 v[28:29], v[40:41], v[28:29], v[38:39]
	v_pk_add_f32 v[0:1], v[4:5], v[0:1]
	v_pk_add_f32 v[2:3], v[2:3], v[6:7]
	v_pk_add_f32 v[4:5], v[32:33], v[28:29]
	v_pk_fma_f32 v[40:41], v[50:51], v[88:89], v[8:9] op_sel_hi:[1,0,1]
	v_pk_add_f32 v[8:9], v[26:27], v[30:31]
	v_add_f32_e32 v0, v0, v1
	v_add_f32_e32 v1, v2, v3
	v_add_f32_e32 v2, v4, v5
	v_pk_fma_f32 v[68:69], v[52:53], v[86:87], v[82:83] op_sel_hi:[1,0,1]
	v_add_f32_e32 v6, v8, v9
	v_add_f32_dpp v82, v1, v1 quad_perm:[1,0,3,2] row_mask:0xf bank_mask:0xf bound_ctrl:1
	v_add_f32_dpp v83, v2, v2 quad_perm:[1,0,3,2] row_mask:0xf bank_mask:0xf bound_ctrl:1
	ds_write2st64_b32 v21, v6, v0 offset0:96 offset1:100
	v_add_f32_dpp v82, v82, v82 quad_perm:[2,3,0,1] row_mask:0xf bank_mask:0xf bound_ctrl:1
	v_add_f32_dpp v83, v83, v83 quad_perm:[2,3,0,1] row_mask:0xf bank_mask:0xf bound_ctrl:1
	v_pk_fma_f32 v[66:67], v[50:51], v[86:87], v[66:67] op_sel_hi:[1,0,1]
	v_pk_fma_f32 v[70:71], v[54:55], v[86:87], v[70:71] op_sel_hi:[1,0,1]
	v_pk_fma_f32 v[72:73], v[56:57], v[86:87], v[84:85] op_sel_hi:[1,0,1]
	v_pk_fma_f32 v[74:75], v[52:53], v[88:89], v[10:11] op_sel_hi:[1,0,1]
	v_pk_fma_f32 v[76:77], v[54:55], v[88:89], v[12:13] op_sel_hi:[1,0,1]
	v_pk_fma_f32 v[78:79], v[56:57], v[88:89], v[14:15] op_sel_hi:[1,0,1]
	ds_read2_b32 v[80:81], v24 offset0:64 offset1:72
; #define SCAN_STEP(w0, w1, a0, a1, b0, b1, k0, k1, r0, r1, vi, vj, t) do { \
;                 SCAN_ROW(S0, S1, S2, S3, w0, w1, a0, a1, b0, b1, k0, k1, r0, r1, vi, (t) * 512); \
;                 SCAN_ROW(T0, T1, T2, T3, w0, w1, a0, a1, b0, b1, k0, k1, r0, r1, vj, (t) * 512 + 256); } while (0)
;     ...
;             SCAN_LOAD(w0, w1, a0, a1, b0, b1, k0, k1, r0, r1, vi, vj, 0);
; #pragma unroll
;             for (int t = 0; t < 16; t += 2) {
;                 SCAN_LOAD(W0, W1, A0, A1, B0, B1, K0, K1, R0, R1, VI, VJ, t + 1);
;                 SCAN_STEP(w0, w1, a0, a1, b0, b1, k0, k1, r0, r1, vi, vj, t);
;                 if (t + 2 < 16) SCAN_LOAD(w0, w1, a0, a1, b0, b1, k0, k1, r0, r1, vi, vj, t + 2);
;                 SCAN_STEP(W0, W1, A0, A1, B0, B1, K0, K1, R0, R1, VI, VJ, t + 1);
	ds_read_b128 v[0:3], v22 offset:22544
	ds_read_b128 v[4:7], v22 offset:22528
	ds_read_b128 v[8:11], v22 offset:22288
	ds_read_b128 v[12:15], v22 offset:22272
	ds_read_b128 v[24:27], v22 offset:22032
	ds_read_b128 v[28:31], v22 offset:22016
	ds_read_b128 v[32:35], v22 offset:21776
	ds_read_b128 v[36:39], v22 offset:21760
	ds_read_b128 v[50:53], v22 offset:21504
	ds_read_b128 v[54:57], v22 offset:21520
	v_add_f32_dpp v82, v82, v82 row_half_mirror row_mask:0xf bank_mask:0xf bound_ctrl:1
	v_add_f32_dpp v84, v83, v83 row_half_mirror row_mask:0xf bank_mask:0xf bound_ctrl:1
	v_pk_fma_f32 v[66:67], v[42:43], v[82:83], v[66:67] op_sel_hi:[1,0,1]
	v_pk_fma_f32 v[68:69], v[44:45], v[82:83], v[68:69] op_sel_hi:[1,0,1]
	v_pk_fma_f32 v[70:71], v[46:47], v[82:83], v[70:71] op_sel_hi:[1,0,1]
	v_pk_fma_f32 v[40:41], v[42:43], v[84:85], v[40:41] op_sel_hi:[1,0,1]
	v_pk_fma_f32 v[42:43], v[44:45], v[84:85], v[74:75] op_sel_hi:[1,0,1]
	v_pk_fma_f32 v[44:45], v[46:47], v[84:85], v[76:77] op_sel_hi:[1,0,1]
	v_pk_fma_f32 v[72:73], v[48:49], v[82:83], v[72:73] op_sel_hi:[1,0,1]
	v_pk_fma_f32 v[46:47], v[48:49], v[84:85], v[78:79] op_sel_hi:[1,0,1]
	v_pk_mul_f32 v[48:49], v[58:59], v[66:67]
	v_pk_mul_f32 v[74:75], v[62:63], v[70:71]
	v_pk_mul_f32 v[58:59], v[58:59], v[40:41]
	v_pk_mul_f32 v[62:63], v[62:63], v[44:45]
	v_pk_fma_f32 v[48:49], v[60:61], v[68:69], v[48:49]
	v_pk_fma_f32 v[74:75], v[64:65], v[72:73], v[74:75]
	v_pk_fma_f32 v[58:59], v[60:61], v[42:43], v[58:59]
	v_pk_fma_f32 v[60:61], v[64:65], v[46:47], v[62:63]
	v_pk_add_f32 v[48:49], v[48:49], v[74:75]
	v_pk_add_f32 v[58:59], v[58:59], v[60:61]
	s_waitcnt lgkmcnt(2)
	v_pk_mul_f32 v[60:61], v[36:37], v[66:67]
	v_pk_mul_f32 v[62:63], v[32:33], v[70:71]
	v_pk_mul_f32 v[36:37], v[36:37], v[40:41]
	v_pk_mul_f32 v[32:33], v[32:33], v[44:45]
	s_waitcnt lgkmcnt(1)
	v_pk_mul_f32 v[64:65], v[50:51], v[66:67]
	v_pk_mul_f32 v[66:67], v[52:53], v[68:69]
	s_waitcnt lgkmcnt(0)
	v_pk_mul_f32 v[70:71], v[54:55], v[70:71]
	v_pk_mul_f32 v[74:75], v[56:57], v[72:73]
	v_pk_mul_f32 v[40:41], v[50:51], v[40:41]
	v_pk_mul_f32 v[50:51], v[52:53], v[42:43]
	v_pk_mul_f32 v[44:45], v[54:55], v[44:45]
	v_pk_mul_f32 v[52:53], v[56:57], v[46:47]
	v_add_f32_e32 v56, v48, v49
	v_pk_fma_f32 v[48:49], v[38:39], v[68:69], v[60:61]
	v_pk_fma_f32 v[54:55], v[34:35], v[72:73], v[62:63]
	v_pk_fma_f32 v[36:37], v[38:39], v[42:43], v[36:37]
	v_pk_fma_f32 v[32:33], v[34:35], v[46:47], v[32:33]
	v_mov_b32_e32 v76, v81
	v_add_f32_e32 v57, v58, v59
	v_pk_fma_f32 v[64:65], v[80:81], v[12:13], v[64:65] op_sel_hi:[0,1,1]
	v_pk_fma_f32 v[66:67], v[80:81], v[14:15], v[66:67] op_sel_hi:[0,1,1]
	v_pk_fma_f32 v[68:69], v[80:81], v[8:9], v[70:71] op_sel_hi:[0,1,1]
	v_pk_fma_f32 v[70:71], v[80:81], v[10:11], v[74:75] op_sel_hi:[0,1,1]
	v_pk_add_f32 v[80:81], v[54:55], v[48:49]
	v_pk_add_f32 v[82:83], v[32:33], v[36:37]
	ds_write2st64_b32 v21, v56, v57 offset0:104 offset1:108
	v_add_f32_e32 v80, v80, v81
	v_add_f32_e32 v81, v82, v83
	v_pk_fma_f32 v[72:73], v[76:77], v[12:13], v[40:41] op_sel_hi:[0,1,1]
	v_pk_fma_f32 v[74:75], v[76:77], v[14:15], v[50:51] op_sel_hi:[0,1,1]
	v_pk_fma_f32 v[78:79], v[76:77], v[8:9], v[44:45] op_sel_hi:[0,1,1]
	v_pk_fma_f32 v[76:77], v[76:77], v[10:11], v[52:53] op_sel_hi:[0,1,1]
	ds_read_b128 v[8:11], v22 offset:23040
	ds_read_b128 v[12:15], v22 offset:23056
	ds_read_b128 v[32:35], v22 offset:23296
	ds_read_b128 v[36:39], v22 offset:23312
	ds_read_b128 v[40:43], v22 offset:23552
	ds_read_b128 v[44:47], v22 offset:23568
	ds_read_b128 v[48:51], v22 offset:23808
	ds_read_b128 v[52:55], v22 offset:23824
	ds_read_b128 v[56:59], v22 offset:24064
	ds_read_b128 v[60:63], v22 offset:24080
	ds_read2_b32 v[22:23], v23 offset0:192 offset1:200
	v_add_f32_dpp v80, v80, v80 quad_perm:[1,0,3,2] row_mask:0xf bank_mask:0xf bound_ctrl:1
	v_add_f32_dpp v81, v81, v81 quad_perm:[1,0,3,2] row_mask:0xf bank_mask:0xf bound_ctrl:1
	s_add_i32 s1, s1, 1
	v_add_f32_dpp v80, v80, v80 quad_perm:[2,3,0,1] row_mask:0xf bank_mask:0xf bound_ctrl:1
	v_add_f32_dpp v81, v81, v81 quad_perm:[2,3,0,1] row_mask:0xf bank_mask:0xf bound_ctrl:1
	s_waitcnt lgkmcnt(0)
;     ...
;             __syncthreads();
;         }
;         float* so = P.out + (samp ? O_RS + ((size_t)(l * 16 + b) * 16 + h) * 4096 : O_RP + ((size_t)(l * 4 + b) * 16 + h) * 4096) + js;
;         f32x4 o0, o1; o0.xy = S0; o0.zw = S1; o1.xy = S2; o1.zw = S3;
;         *(f32x4*)(so + i0 * 64) = o0; *(f32x4*)(so + i0 * 64 + 4) = o1;
;         o0.xy = T0; o0.zw = T1; o1.xy = T2; o1.zw = T3;
;         *(f32x4*)(so + i1 * 64) = o0; *(f32x4*)(so + i1 * 64 + 4) = o1;
	v_mov_b32_e32 v84, v23
	v_add_f32_dpp v80, v80, v80 row_half_mirror row_mask:0xf bank_mask:0xf bound_ctrl:1
	v_add_f32_dpp v82, v81, v81 row_half_mirror row_mask:0xf bank_mask:0xf bound_ctrl:1
	v_pk_fma_f32 v[64:65], v[28:29], v[80:81], v[64:65] op_sel_hi:[1,0,1]
	v_pk_fma_f32 v[68:69], v[24:25], v[80:81], v[68:69] op_sel_hi:[1,0,1]
	v_pk_fma_f32 v[28:29], v[28:29], v[82:83], v[72:73] op_sel_hi:[1,0,1]
	v_pk_fma_f32 v[24:25], v[24:25], v[82:83], v[78:79] op_sel_hi:[1,0,1]
	v_pk_fma_f32 v[66:67], v[30:31], v[80:81], v[66:67] op_sel_hi:[1,0,1]
	v_pk_fma_f32 v[70:71], v[26:27], v[80:81], v[70:71] op_sel_hi:[1,0,1]
	v_pk_fma_f32 v[30:31], v[30:31], v[82:83], v[74:75] op_sel_hi:[1,0,1]
	v_pk_fma_f32 v[26:27], v[26:27], v[82:83], v[76:77] op_sel_hi:[1,0,1]
	v_pk_mul_f32 v[72:73], v[4:5], v[64:65]
	v_pk_mul_f32 v[74:75], v[0:1], v[68:69]
	v_pk_mul_f32 v[4:5], v[4:5], v[28:29]
	v_pk_mul_f32 v[0:1], v[0:1], v[24:25]
	v_pk_mul_f32 v[76:77], v[32:33], v[64:65]
	v_pk_mul_f32 v[78:79], v[36:37], v[68:69]
	v_pk_mul_f32 v[32:33], v[32:33], v[28:29]
	v_pk_mul_f32 v[36:37], v[36:37], v[24:25]
	v_pk_mul_f32 v[64:65], v[8:9], v[64:65]
	v_pk_mul_f32 v[80:81], v[10:11], v[66:67]
	v_pk_mul_f32 v[68:69], v[12:13], v[68:69]
	v_pk_mul_f32 v[82:83], v[14:15], v[70:71]
	v_pk_mul_f32 v[8:9], v[8:9], v[28:29]
	v_pk_mul_f32 v[10:11], v[10:11], v[30:31]
	v_pk_mul_f32 v[12:13], v[12:13], v[24:25]
	v_pk_mul_f32 v[14:15], v[14:15], v[26:27]
	v_pk_fma_f32 v[24:25], v[6:7], v[66:67], v[72:73]
	v_pk_fma_f32 v[28:29], v[2:3], v[70:71], v[74:75]
	v_pk_fma_f32 v[4:5], v[6:7], v[30:31], v[4:5]
	v_pk_fma_f32 v[0:1], v[2:3], v[26:27], v[0:1]
	v_pk_fma_f32 v[2:3], v[34:35], v[66:67], v[76:77]
	v_pk_fma_f32 v[6:7], v[38:39], v[70:71], v[78:79]
	v_pk_fma_f32 v[30:31], v[34:35], v[30:31], v[32:33]
	v_pk_fma_f32 v[26:27], v[38:39], v[26:27], v[36:37]
	v_pk_fma_f32 v[32:33], v[48:49], v[84:85], v[8:9] op_sel_hi:[1,0,1]
	v_pk_add_f32 v[8:9], v[24:25], v[28:29]
	v_pk_add_f32 v[0:1], v[4:5], v[0:1]
	v_pk_add_f32 v[2:3], v[2:3], v[6:7]
	v_pk_add_f32 v[4:5], v[30:31], v[26:27]
	v_add_f32_e32 v6, v8, v9
	v_add_f32_e32 v0, v0, v1
	v_add_f32_e32 v1, v2, v3
	v_add_f32_e32 v2, v4, v5
	ds_write2st64_b32 v21, v6, v0 offset0:112 offset1:116
	v_add_f32_dpp v0, v1, v1 quad_perm:[1,0,3,2] row_mask:0xf bank_mask:0xf bound_ctrl:1
	v_add_f32_dpp v1, v2, v2 quad_perm:[1,0,3,2] row_mask:0xf bank_mask:0xf bound_ctrl:1
	v_pk_fma_f32 v[64:65], v[48:49], v[22:23], v[64:65] op_sel_hi:[1,0,1]
	v_add_f32_dpp v0, v0, v0 quad_perm:[2,3,0,1] row_mask:0xf bank_mask:0xf bound_ctrl:1
	v_add_f32_dpp v1, v1, v1 quad_perm:[2,3,0,1] row_mask:0xf bank_mask:0xf bound_ctrl:1
	v_pk_fma_f32 v[66:67], v[50:51], v[22:23], v[80:81] op_sel_hi:[1,0,1]
	v_pk_fma_f32 v[68:69], v[52:53], v[22:23], v[68:69] op_sel_hi:[1,0,1]
	v_pk_fma_f32 v[22:23], v[54:55], v[22:23], v[82:83] op_sel_hi:[1,0,1]
	v_pk_fma_f32 v[36:37], v[52:53], v[84:85], v[12:13] op_sel_hi:[1,0,1]
	v_add_f32_dpp v0, v0, v0 row_half_mirror row_mask:0xf bank_mask:0xf bound_ctrl:1
	v_add_f32_dpp v6, v1, v1 row_half_mirror row_mask:0xf bank_mask:0xf bound_ctrl:1
	v_pk_fma_f32 v[34:35], v[50:51], v[84:85], v[10:11] op_sel_hi:[1,0,1]
	v_pk_fma_f32 v[38:39], v[54:55], v[84:85], v[14:15] op_sel_hi:[1,0,1]
	v_pk_fma_f32 v[12:13], v[40:41], v[0:1], v[64:65] op_sel_hi:[1,0,1]
	v_pk_fma_f32 v[14:15], v[42:43], v[0:1], v[66:67] op_sel_hi:[1,0,1]
	v_pk_fma_f32 v[8:9], v[44:45], v[0:1], v[68:69] op_sel_hi:[1,0,1]
	v_pk_fma_f32 v[10:11], v[46:47], v[0:1], v[22:23] op_sel_hi:[1,0,1]
	v_pk_fma_f32 v[0:1], v[40:41], v[6:7], v[32:33] op_sel_hi:[1,0,1]
	v_pk_fma_f32 v[4:5], v[44:45], v[6:7], v[36:37] op_sel_hi:[1,0,1]
	v_pk_fma_f32 v[2:3], v[42:43], v[6:7], v[34:35] op_sel_hi:[1,0,1]
	v_pk_fma_f32 v[6:7], v[46:47], v[6:7], v[38:39] op_sel_hi:[1,0,1]
	v_pk_mul_f32 v[22:23], v[56:57], v[12:13]
	v_pk_mul_f32 v[24:25], v[60:61], v[8:9]
	v_pk_mul_f32 v[26:27], v[56:57], v[0:1]
	v_pk_mul_f32 v[28:29], v[60:61], v[4:5]
	v_pk_fma_f32 v[22:23], v[58:59], v[14:15], v[22:23]
	v_pk_fma_f32 v[24:25], v[62:63], v[10:11], v[24:25]
	v_pk_fma_f32 v[26:27], v[58:59], v[2:3], v[26:27]
	v_pk_fma_f32 v[28:29], v[62:63], v[6:7], v[28:29]
	v_pk_add_f32 v[22:23], v[22:23], v[24:25]
	v_pk_add_f32 v[24:25], v[26:27], v[28:29]
	s_cmpk_eq_i32 s1, 0x100
	v_add_f32_e32 v22, v22, v23
	v_add_f32_e32 v23, v24, v25
	ds_write2st64_b32 v21, v22, v23 offset0:120 offset1:124
	s_waitcnt lgkmcnt(0)
	s_barrier
	s_cbranch_scc0 .LBB0_1812
	s_setprio 0
	s_add_u32 s1, s72, s4
	s_addc_u32 s4, s73, s5
	s_add_u32 s0, s1, s0
	s_addc_u32 s1, s4, 0
	v_lshlrev_b32_e32 v16, 2, v16
	v_mov_b32_e32 v17, 0
	v_lshl_add_u64 v[16:17], s[0:1], 0, v[16:17]
	v_lshl_add_u64 v[16:17], v[18:19], 2, v[16:17]
	s_mov_b64 s[0:1], 0x8500000
	v_lshl_add_u64 v[18:19], v[16:17], 0, s[0:1]
	v_add_co_u32_e32 v16, vcc, 0x8500000, v16
	s_nop 1
	v_addc_co_u32_e32 v17, vcc, 0, v17, vcc
	global_store_dwordx4 v[16:17], v[12:15], off
	global_store_dwordx4 v[18:19], v[8:11], off offset:16
	global_store_dwordx4 v[18:19], v[0:3], off offset:2048
	global_store_dwordx4 v[18:19], v[4:7], off offset:2064

; #define SCAN_STEP(w0, w1, a0, a1, b0, b1, k0, k1, r0, r1, vi, vj, t) do { \
;                 SCAN_ROW(S0, S1, S2, S3, w0, w1, a0, a1, b0, b1, k0, k1, r0, r1, vi, (t) * 512); \
;                 SCAN_ROW(T0, T1, T2, T3, w0, w1, a0, a1, b0, b1, k0, k1, r0, r1, vj, (t) * 512 + 256); } while (0)
;     ...
;         } else { S0 = (f32x2){0.f, 0.f}; S1 = S0; S2 = S0; S3 = S0; T0 = S0; T1 = S0; T2 = S0; T3 = S0; }
;         __syncthreads();
;         for (int c = c0; c < nch; ++c) {
;             const float* bb = bufs + (c & 1) * (16 * 384) + js;
;             const float* bv = bufs + (c & 1) * (16 * 384) + 320 + i0;
;             float* yb = ybuf + (c & 1) * 8192 + w * 64 + lane;
;             f32x4 w0, w1, a0, a1, b0, b1, k0, k1, r0, r1; float vi, vj;
;             f32x4 W0, W1, A0, A1, B0, B1, K0, K1, R0, R1; float VI, VJ;
;     ...
;             SCAN_LOAD(w0, w1, a0, a1, b0, b1, k0, k1, r0, r1, vi, vj, 0);
; #pragma unroll
;             for (int t = 0; t < 16; t += 2) {
;                 SCAN_LOAD(W0, W1, A0, A1, B0, B1, K0, K1, R0, R1, VI, VJ, t + 1);
;                 SCAN_STEP(w0, w1, a0, a1, b0, b1, k0, k1, r0, r1, vi, vj, t);
.LBB0_3704:
	s_andn2_saveexec_b64 s[0:1], s[10:11]
	s_cbranch_execz .LBB0_3708
	v_lshrrev_b32_e32 v0, 3, v22
	v_lshl_or_b32 v16, v10, 4, v0
	v_lshlrev_b32_e32 v0, 3, v22
	v_and_b32_e32 v17, 56, v0
	v_and_b32_e32 v0, 0x3fffffc0, v18
	v_lshlrev_b32_e32 v0, 2, v0
	v_lshlrev_b32_e32 v1, 2, v22
	v_mov_b32_e32 v8, 0
	s_mov_b32 s3, 0
	v_add3_u32 v18, 0, v0, v1
	v_mov_b32_e32 v9, v8
	v_mov_b32_e32 v10, v8
	v_mov_b32_e32 v11, v8
	v_mov_b32_e32 v12, v8
	v_mov_b32_e32 v13, v8
	v_mov_b32_e32 v14, v8
	v_mov_b32_e32 v15, v8
	v_mov_b32_e32 v4, v8
	v_mov_b32_e32 v5, v8
	v_mov_b32_e32 v6, v8
	v_mov_b32_e32 v7, v8
	v_mov_b32_e32 v0, v8
	v_mov_b32_e32 v1, v8
	v_mov_b32_e32 v2, v8
	v_mov_b32_e32 v3, v8
	s_barrier
	s_setprio 3
.LBB0_3706:
	s_and_b32 s10, s3, 1
	s_mul_i32 s4, s10, 0x6000
	s_add_i32 s4, s4, 0
	v_lshl_add_u32 v21, v16, 2, s4
	v_lshl_add_u32 v20, v17, 2, s4
	v_add_u32_e32 v29, 0x400, v21
	v_add_u32_e32 v112, 0x800, v21
	ds_read_b128 v[30:33], v20
	ds_read_b128 v[34:37], v20 offset:16
	ds_read_b128 v[38:41], v20 offset:256
	ds_read_b128 v[42:45], v20 offset:272
	ds_read_b128 v[46:49], v20 offset:512
	ds_read_b128 v[50:53], v20 offset:528
	ds_read_b128 v[54:57], v20 offset:768
	ds_read_b128 v[58:61], v20 offset:784
	ds_read_b128 v[62:65], v20 offset:1024
	ds_read_b128 v[66:69], v20 offset:1040
	ds_read_b128 v[70:73], v20 offset:1536
	ds_read_b128 v[74:77], v20 offset:1552
	ds_read_b128 v[78:81], v20 offset:1792
	ds_read_b128 v[82:85], v20 offset:1808
	s_waitcnt vmcnt(3)
	ds_read_b128 v[86:89], v20 offset:2048
	ds_read_b128 v[90:93], v20 offset:2064
	s_waitcnt vmcnt(2)
	ds_read_b128 v[94:97], v20 offset:2304
	ds_read_b128 v[98:101], v20 offset:2320
	ds_read_b128 v[102:105], v20 offset:2560
	ds_read_b128 v[106:109], v20 offset:2576
	ds_read2_b32 v[110:111], v29 offset0:64 offset1:72
	ds_read2_b32 v[112:113], v112 offset0:192 offset1:200
	s_waitcnt lgkmcnt(14)
	v_pk_mul_f32 v[114:115], v[8:9], v[38:39]
	v_pk_mul_f32 v[116:117], v[12:13], v[42:43]
	v_pk_mul_f32 v[38:39], v[4:5], v[38:39]
	v_pk_mul_f32 v[42:43], v[0:1], v[42:43]
	v_pk_fma_f32 v[114:115], v[10:11], v[40:41], v[114:115]
	v_pk_fma_f32 v[116:117], v[14:15], v[44:45], v[116:117]
	s_waitcnt lgkmcnt(1)
	v_pk_mul_f32 v[118:119], v[54:55], v[110:111] op_sel_hi:[1,0]
	v_pk_mul_f32 v[120:121], v[56:57], v[110:111] op_sel_hi:[1,0]
	v_pk_mul_f32 v[122:123], v[58:59], v[110:111] op_sel_hi:[1,0]
	v_pk_mul_f32 v[124:125], v[60:61], v[110:111] op_sel_hi:[1,0]
	v_mov_b32_e32 v110, v111
	v_pk_fma_f32 v[38:39], v[6:7], v[40:41], v[38:39]
	v_pk_fma_f32 v[40:41], v[2:3], v[44:45], v[42:43]
	v_pk_add_f32 v[44:45], v[114:115], v[116:117]
	v_pk_mul_f32 v[54:55], v[54:55], v[110:111] op_sel_hi:[1,0]
	v_pk_add_f32 v[38:39], v[38:39], v[40:41]
	v_pk_fma_f32 v[8:9], v[8:9], v[30:31], v[118:119]
	v_add_f32_e32 v29, v44, v45
	v_pk_fma_f32 v[4:5], v[4:5], v[30:31], v[54:55]
	v_add_f32_e32 v30, v38, v39
	v_add_f32_dpp v29, v29, v29 quad_perm:[1,0,3,2] row_mask:0xf bank_mask:0xf bound_ctrl:1
	v_pk_mul_f32 v[56:57], v[56:57], v[110:111] op_sel_hi:[1,0]
	v_add_f32_dpp v30, v30, v30 quad_perm:[1,0,3,2] row_mask:0xf bank_mask:0xf bound_ctrl:1
	v_pk_mul_f32 v[58:59], v[58:59], v[110:111] op_sel_hi:[1,0]
	v_add_f32_dpp v29, v29, v29 quad_perm:[2,3,0,1] row_mask:0xf bank_mask:0xf bound_ctrl:1
	v_add_f32_dpp v31, v30, v30 quad_perm:[2,3,0,1] row_mask:0xf bank_mask:0xf bound_ctrl:1
	v_pk_fma_f32 v[10:11], v[10:11], v[32:33], v[120:121]
	v_pk_fma_f32 v[12:13], v[12:13], v[34:35], v[122:123]
	v_pk_mul_f32 v[60:61], v[60:61], v[110:111] op_sel_hi:[1,0]
	v_pk_fma_f32 v[6:7], v[6:7], v[32:33], v[56:57]
	v_pk_fma_f32 v[0:1], v[0:1], v[34:35], v[58:59]
	v_add_f32_dpp v30, v29, v29 row_half_mirror row_mask:0xf bank_mask:0xf bound_ctrl:1
	v_add_f32_dpp v32, v31, v31 row_half_mirror row_mask:0xf bank_mask:0xf bound_ctrl:1
	v_pk_fma_f32 v[14:15], v[14:15], v[36:37], v[124:125]
	v_pk_fma_f32 v[2:3], v[2:3], v[36:37], v[60:61]
	v_pk_fma_f32 v[8:9], v[46:47], v[30:31], v[8:9] op_sel_hi:[1,0,1]
	v_pk_fma_f32 v[12:13], v[50:51], v[30:31], v[12:13] op_sel_hi:[1,0,1]
	v_pk_fma_f32 v[4:5], v[46:47], v[32:33], v[4:5] op_sel_hi:[1,0,1]
	v_pk_fma_f32 v[0:1], v[50:51], v[32:33], v[0:1] op_sel_hi:[1,0,1]
	v_pk_fma_f32 v[10:11], v[48:49], v[30:31], v[10:11] op_sel_hi:[1,0,1]
	v_pk_fma_f32 v[14:15], v[52:53], v[30:31], v[14:15] op_sel_hi:[1,0,1]
	v_pk_fma_f32 v[6:7], v[48:49], v[32:33], v[6:7] op_sel_hi:[1,0,1]
	v_pk_fma_f32 v[2:3], v[52:53], v[32:33], v[2:3] op_sel_hi:[1,0,1]
	v_pk_mul_f32 v[30:31], v[62:63], v[8:9]
	v_pk_mul_f32 v[32:33], v[66:67], v[12:13]
	v_pk_mul_f32 v[34:35], v[62:63], v[4:5]
	v_pk_mul_f32 v[36:37], v[66:67], v[0:1]
	v_pk_mul_f32 v[38:39], v[78:79], v[8:9]
	v_pk_mul_f32 v[40:41], v[82:83], v[12:13]
	v_pk_mul_f32 v[48:49], v[78:79], v[4:5]
	v_pk_mul_f32 v[50:51], v[82:83], v[0:1]
	s_waitcnt lgkmcnt(0)
; #define SCAN_STEP(w0, w1, a0, a1, b0, b1, k0, k1, r0, r1, vi, vj, t) do { \
;                 SCAN_ROW(S0, S1, S2, S3, w0, w1, a0, a1, b0, b1, k0, k1, r0, r1, vi, (t) * 512); \
;                 SCAN_ROW(T0, T1, T2, T3, w0, w1, a0, a1, b0, b1, k0, k1, r0, r1, vj, (t) * 512 + 256); } while (0)
;     ...
;             SCAN_LOAD(w0, w1, a0, a1, b0, b1, k0, k1, r0, r1, vi, vj, 0);
; #pragma unroll
;             for (int t = 0; t < 16; t += 2) {
;                 SCAN_LOAD(W0, W1, A0, A1, B0, B1, K0, K1, R0, R1, VI, VJ, t + 1);
;                 SCAN_STEP(w0, w1, a0, a1, b0, b1, k0, k1, r0, r1, vi, vj, t);
;                 if (t + 2 < 16) SCAN_LOAD(w0, w1, a0, a1, b0, b1, k0, k1, r0, r1, vi, vj, t + 2);
;                 SCAN_STEP(W0, W1, A0, A1, B0, B1, K0, K1, R0, R1, VI, VJ, t + 1);
	v_mov_b32_e32 v42, v113
	v_pk_mul_f32 v[8:9], v[70:71], v[8:9]
	v_pk_mul_f32 v[44:45], v[72:73], v[10:11]
	v_pk_mul_f32 v[46:47], v[76:77], v[14:15]
	v_pk_mul_f32 v[4:5], v[70:71], v[4:5]
	v_pk_mul_f32 v[52:53], v[72:73], v[6:7]
	v_pk_mul_f32 v[0:1], v[74:75], v[0:1]
	v_pk_mul_f32 v[54:55], v[76:77], v[2:3]
	v_pk_fma_f32 v[30:31], v[64:65], v[10:11], v[30:31]
	v_pk_fma_f32 v[32:33], v[68:69], v[14:15], v[32:33]
	v_pk_fma_f32 v[34:35], v[64:65], v[6:7], v[34:35]
	v_pk_fma_f32 v[36:37], v[68:69], v[2:3], v[36:37]
	v_pk_fma_f32 v[10:11], v[80:81], v[10:11], v[38:39]
	v_pk_fma_f32 v[14:15], v[84:85], v[14:15], v[40:41]
	v_pk_fma_f32 v[6:7], v[80:81], v[6:7], v[48:49]
	v_pk_fma_f32 v[2:3], v[84:85], v[2:3], v[50:51]
	v_pk_fma_f32 v[56:57], v[94:95], v[112:113], v[8:9] op_sel_hi:[1,0,1]
	v_pk_fma_f32 v[64:65], v[94:95], v[42:43], v[4:5] op_sel_hi:[1,0,1]
	v_pk_fma_f32 v[68:69], v[98:99], v[42:43], v[0:1] op_sel_hi:[1,0,1]
	v_pk_add_f32 v[0:1], v[30:31], v[32:33]
	v_pk_add_f32 v[4:5], v[34:35], v[36:37]
	v_pk_add_f32 v[8:9], v[10:11], v[14:15]
	v_pk_add_f32 v[2:3], v[6:7], v[2:3]
	v_add_f32_e32 v0, v0, v1
	v_add_f32_e32 v1, v4, v5
	v_add_f32_e32 v4, v8, v9
	v_add_f32_e32 v2, v2, v3
	v_lshl_add_u32 v27, s10, 15, v18
	v_add_f32_dpp v29, v4, v4 quad_perm:[1,0,3,2] row_mask:0xf bank_mask:0xf bound_ctrl:1
	v_add_f32_dpp v72, v2, v2 quad_perm:[1,0,3,2] row_mask:0xf bank_mask:0xf bound_ctrl:1
	v_add_u32_e32 v126, 0x1000, v21
	v_pk_mul_f32 v[12:13], v[74:75], v[12:13]
	ds_write2st64_b32 v27, v0, v1 offset0:192 offset1:196
	v_add_f32_dpp v29, v29, v29 quad_perm:[2,3,0,1] row_mask:0xf bank_mask:0xf bound_ctrl:1
	v_add_f32_dpp v73, v72, v72 quad_perm:[2,3,0,1] row_mask:0xf bank_mask:0xf bound_ctrl:1
	v_pk_fma_f32 v[58:59], v[96:97], v[112:113], v[44:45] op_sel_hi:[1,0,1]
	v_pk_fma_f32 v[60:61], v[98:99], v[112:113], v[12:13] op_sel_hi:[1,0,1]
	v_pk_fma_f32 v[62:63], v[100:101], v[112:113], v[46:47] op_sel_hi:[1,0,1]
	v_pk_fma_f32 v[66:67], v[96:97], v[42:43], v[52:53] op_sel_hi:[1,0,1]
	v_pk_fma_f32 v[54:55], v[100:101], v[42:43], v[54:55] op_sel_hi:[1,0,1]
	ds_read2_b32 v[70:71], v126 offset0:64 offset1:72
	ds_read_b128 v[0:3], v20 offset:4112
	ds_read_b128 v[4:7], v20 offset:4096
	ds_read_b128 v[8:11], v20 offset:3856
	ds_read_b128 v[12:15], v20 offset:3840
	ds_read_b128 v[30:33], v20 offset:3600
	ds_read_b128 v[34:37], v20 offset:3584
	ds_read_b128 v[38:41], v20 offset:3344
	ds_read_b128 v[42:45], v20 offset:3328
	ds_read_b128 v[46:49], v20 offset:3072
	ds_read_b128 v[50:53], v20 offset:3088
	v_add_f32_dpp v72, v29, v29 row_half_mirror row_mask:0xf bank_mask:0xf bound_ctrl:1
	v_add_f32_dpp v74, v73, v73 row_half_mirror row_mask:0xf bank_mask:0xf bound_ctrl:1
	v_pk_fma_f32 v[56:57], v[86:87], v[72:73], v[56:57] op_sel_hi:[1,0,1]
	v_pk_fma_f32 v[60:61], v[90:91], v[72:73], v[60:61] op_sel_hi:[1,0,1]
	v_pk_fma_f32 v[64:65], v[86:87], v[74:75], v[64:65] op_sel_hi:[1,0,1]
	v_pk_fma_f32 v[68:69], v[90:91], v[74:75], v[68:69] op_sel_hi:[1,0,1]
	v_pk_fma_f32 v[58:59], v[88:89], v[72:73], v[58:59] op_sel_hi:[1,0,1]
	v_pk_fma_f32 v[62:63], v[92:93], v[72:73], v[62:63] op_sel_hi:[1,0,1]
	v_pk_fma_f32 v[66:67], v[88:89], v[74:75], v[66:67] op_sel_hi:[1,0,1]
	v_pk_fma_f32 v[54:55], v[92:93], v[74:75], v[54:55] op_sel_hi:[1,0,1]
	v_pk_mul_f32 v[72:73], v[102:103], v[56:57]
	v_pk_mul_f32 v[74:75], v[106:107], v[60:61]
	v_pk_mul_f32 v[76:77], v[102:103], v[64:65]
	v_pk_mul_f32 v[78:79], v[106:107], v[68:69]
	v_pk_fma_f32 v[72:73], v[104:105], v[58:59], v[72:73]
	v_pk_fma_f32 v[74:75], v[108:109], v[62:63], v[74:75]
	v_pk_fma_f32 v[76:77], v[104:105], v[66:67], v[76:77]
	v_pk_fma_f32 v[78:79], v[108:109], v[54:55], v[78:79]
	v_pk_add_f32 v[72:73], v[72:73], v[74:75]
	v_pk_add_f32 v[74:75], v[76:77], v[78:79]
	s_waitcnt lgkmcnt(2)
	v_pk_mul_f32 v[76:77], v[42:43], v[56:57]
	v_pk_mul_f32 v[78:79], v[38:39], v[60:61]
	v_pk_mul_f32 v[42:43], v[42:43], v[64:65]
	v_pk_mul_f32 v[38:39], v[38:39], v[68:69]
	s_waitcnt lgkmcnt(1)
	v_pk_mul_f32 v[80:81], v[48:49], v[58:59]
	s_waitcnt lgkmcnt(0)
	v_pk_mul_f32 v[82:83], v[52:53], v[62:63]
	v_pk_fma_f32 v[58:59], v[44:45], v[58:59], v[76:77]
	v_pk_fma_f32 v[62:63], v[40:41], v[62:63], v[78:79]
	v_pk_fma_f32 v[42:43], v[44:45], v[66:67], v[42:43]
	v_pk_fma_f32 v[38:39], v[40:41], v[54:55], v[38:39]
	v_pk_mul_f32 v[56:57], v[46:47], v[56:57]
	v_pk_mul_f32 v[46:47], v[46:47], v[64:65]
	v_add_f32_e32 v29, v72, v73
	v_add_f32_e32 v64, v74, v75
	v_pk_add_f32 v[86:87], v[62:63], v[58:59]
	v_pk_add_f32 v[88:89], v[38:39], v[42:43]
	ds_write2st64_b32 v27, v29, v64 offset0:200 offset1:204
	v_add_f32_e32 v29, v86, v87
	v_add_f32_e32 v86, v88, v89
	v_pk_mul_f32 v[60:61], v[50:51], v[60:61]
	v_mov_b32_e32 v84, v71
	v_pk_mul_f32 v[48:49], v[48:49], v[66:67]
	v_pk_mul_f32 v[50:51], v[50:51], v[68:69]
	v_pk_mul_f32 v[52:53], v[52:53], v[54:55]
	v_add_f32_dpp v29, v29, v29 quad_perm:[1,0,3,2] row_mask:0xf bank_mask:0xf bound_ctrl:1
	v_add_f32_dpp v86, v86, v86 quad_perm:[1,0,3,2] row_mask:0xf bank_mask:0xf bound_ctrl:1
	v_add_u32_e32 v127, 0x1400, v21
	v_pk_fma_f32 v[72:73], v[70:71], v[12:13], v[56:57] op_sel_hi:[0,1,1]
	v_pk_fma_f32 v[74:75], v[70:71], v[14:15], v[80:81] op_sel_hi:[0,1,1]
	v_pk_fma_f32 v[76:77], v[70:71], v[8:9], v[60:61] op_sel_hi:[0,1,1]
	v_pk_fma_f32 v[70:71], v[70:71], v[10:11], v[82:83] op_sel_hi:[0,1,1]
	v_pk_fma_f32 v[78:79], v[84:85], v[12:13], v[46:47] op_sel_hi:[0,1,1]
	v_pk_fma_f32 v[80:81], v[84:85], v[14:15], v[48:49] op_sel_hi:[0,1,1]
	v_pk_fma_f32 v[82:83], v[84:85], v[8:9], v[50:51] op_sel_hi:[0,1,1]
	v_pk_fma_f32 v[84:85], v[84:85], v[10:11], v[52:53] op_sel_hi:[0,1,1]
	ds_read_b128 v[8:11], v20 offset:4608
; #define SCAN_STEP(w0, w1, a0, a1, b0, b1, k0, k1, r0, r1, vi, vj, t) do { \
;                 SCAN_ROW(S0, S1, S2, S3, w0, w1, a0, a1, b0, b1, k0, k1, r0, r1, vi, (t) * 512); \
;                 SCAN_ROW(T0, T1, T2, T3, w0, w1, a0, a1, b0, b1, k0, k1, r0, r1, vj, (t) * 512 + 256); } while (0)
;     ...
;             SCAN_LOAD(w0, w1, a0, a1, b0, b1, k0, k1, r0, r1, vi, vj, 0);
; #pragma unroll
;             for (int t = 0; t < 16; t += 2) {
;                 SCAN_LOAD(W0, W1, A0, A1, B0, B1, K0, K1, R0, R1, VI, VJ, t + 1);
;                 SCAN_STEP(w0, w1, a0, a1, b0, b1, k0, k1, r0, r1, vi, vj, t);
;                 if (t + 2 < 16) SCAN_LOAD(w0, w1, a0, a1, b0, b1, k0, k1, r0, r1, vi, vj, t + 2);
;                 SCAN_STEP(W0, W1, A0, A1, B0, B1, K0, K1, R0, R1, VI, VJ, t + 1);
	ds_read_b128 v[12:15], v20 offset:4624
	ds_read_b128 v[38:41], v20 offset:4864
	ds_read_b128 v[42:45], v20 offset:4880
	ds_read_b128 v[46:49], v20 offset:5120
	ds_read_b128 v[50:53], v20 offset:5136
	ds_read_b128 v[54:57], v20 offset:5376
	ds_read_b128 v[58:61], v20 offset:5392
	ds_read_b128 v[62:65], v20 offset:5632
	ds_read_b128 v[66:69], v20 offset:5648
	ds_read2_b32 v[90:91], v127 offset0:192 offset1:200
	v_add_f32_dpp v29, v29, v29 quad_perm:[2,3,0,1] row_mask:0xf bank_mask:0xf bound_ctrl:1
	v_add_f32_dpp v87, v86, v86 quad_perm:[2,3,0,1] row_mask:0xf bank_mask:0xf bound_ctrl:1
	v_add_u32_e32 v128, 0x1c00, v21
	v_add_f32_dpp v86, v29, v29 row_half_mirror row_mask:0xf bank_mask:0xf bound_ctrl:1
	v_add_f32_dpp v88, v87, v87 row_half_mirror row_mask:0xf bank_mask:0xf bound_ctrl:1
	v_pk_fma_f32 v[72:73], v[34:35], v[86:87], v[72:73] op_sel_hi:[1,0,1]
	v_pk_fma_f32 v[76:77], v[30:31], v[86:87], v[76:77] op_sel_hi:[1,0,1]
	v_pk_fma_f32 v[34:35], v[34:35], v[88:89], v[78:79] op_sel_hi:[1,0,1]
	v_pk_fma_f32 v[30:31], v[30:31], v[88:89], v[82:83] op_sel_hi:[1,0,1]
	v_pk_fma_f32 v[74:75], v[36:37], v[86:87], v[74:75] op_sel_hi:[1,0,1]
	v_pk_fma_f32 v[70:71], v[32:33], v[86:87], v[70:71] op_sel_hi:[1,0,1]
	v_pk_fma_f32 v[36:37], v[36:37], v[88:89], v[80:81] op_sel_hi:[1,0,1]
	v_pk_fma_f32 v[32:33], v[32:33], v[88:89], v[84:85] op_sel_hi:[1,0,1]
	v_pk_mul_f32 v[78:79], v[4:5], v[72:73]
	v_pk_mul_f32 v[80:81], v[0:1], v[76:77]
	v_pk_mul_f32 v[4:5], v[4:5], v[34:35]
	v_pk_mul_f32 v[0:1], v[0:1], v[30:31]
	s_waitcnt lgkmcnt(8)
	v_pk_mul_f32 v[82:83], v[38:39], v[72:73]
	s_waitcnt lgkmcnt(7)
	v_pk_mul_f32 v[84:85], v[42:43], v[76:77]
	v_pk_mul_f32 v[38:39], v[38:39], v[34:35]
	v_pk_mul_f32 v[42:43], v[42:43], v[30:31]
	v_pk_mul_f32 v[72:73], v[8:9], v[72:73]
	v_pk_mul_f32 v[86:87], v[10:11], v[74:75]
	v_pk_mul_f32 v[76:77], v[12:13], v[76:77]
	v_pk_mul_f32 v[88:89], v[14:15], v[70:71]
	v_pk_mul_f32 v[8:9], v[8:9], v[34:35]
	v_pk_mul_f32 v[10:11], v[10:11], v[36:37]
	v_pk_mul_f32 v[12:13], v[12:13], v[30:31]
	v_pk_mul_f32 v[14:15], v[14:15], v[32:33]
	v_pk_fma_f32 v[30:31], v[6:7], v[74:75], v[78:79]
	v_pk_fma_f32 v[34:35], v[2:3], v[70:71], v[80:81]
	v_pk_fma_f32 v[4:5], v[6:7], v[36:37], v[4:5]
	v_pk_fma_f32 v[0:1], v[2:3], v[32:33], v[0:1]
	v_pk_fma_f32 v[2:3], v[40:41], v[74:75], v[82:83]
	v_pk_fma_f32 v[6:7], v[44:45], v[70:71], v[84:85]
	v_pk_fma_f32 v[36:37], v[40:41], v[36:37], v[38:39]
	v_pk_fma_f32 v[32:33], v[44:45], v[32:33], v[42:43]
	s_waitcnt lgkmcnt(0)
	v_mov_b32_e32 v92, v91
	v_pk_add_f32 v[0:1], v[4:5], v[0:1]
	v_pk_add_f32 v[2:3], v[2:3], v[6:7]
	v_pk_add_f32 v[4:5], v[36:37], v[32:33]
	v_pk_fma_f32 v[78:79], v[54:55], v[92:93], v[8:9] op_sel_hi:[1,0,1]
	v_pk_add_f32 v[8:9], v[30:31], v[34:35]
	v_add_f32_e32 v0, v0, v1
	v_add_f32_e32 v1, v2, v3
	v_add_f32_e32 v2, v4, v5
	v_pk_fma_f32 v[74:75], v[58:59], v[90:91], v[76:77] op_sel_hi:[1,0,1]
	v_pk_fma_f32 v[76:77], v[60:61], v[90:91], v[88:89] op_sel_hi:[1,0,1]
	v_add_f32_e32 v6, v8, v9
	v_add_f32_dpp v29, v1, v1 quad_perm:[1,0,3,2] row_mask:0xf bank_mask:0xf bound_ctrl:1
	v_add_f32_dpp v88, v2, v2 quad_perm:[1,0,3,2] row_mask:0xf bank_mask:0xf bound_ctrl:1
	ds_write2st64_b32 v27, v6, v0 offset0:208 offset1:212
	v_add_f32_dpp v29, v29, v29 quad_perm:[2,3,0,1] row_mask:0xf bank_mask:0xf bound_ctrl:1
	v_add_f32_dpp v89, v88, v88 quad_perm:[2,3,0,1] row_mask:0xf bank_mask:0xf bound_ctrl:1
	v_pk_fma_f32 v[70:71], v[54:55], v[90:91], v[72:73] op_sel_hi:[1,0,1]
	v_pk_fma_f32 v[72:73], v[56:57], v[90:91], v[86:87] op_sel_hi:[1,0,1]
	v_pk_fma_f32 v[80:81], v[56:57], v[92:93], v[10:11] op_sel_hi:[1,0,1]
	v_pk_fma_f32 v[82:83], v[58:59], v[92:93], v[12:13] op_sel_hi:[1,0,1]
	v_pk_fma_f32 v[84:85], v[60:61], v[92:93], v[14:15] op_sel_hi:[1,0,1]
	ds_read2_b32 v[86:87], v128 offset0:64 offset1:72
	ds_read_b128 v[0:3], v20 offset:7184
	ds_read_b128 v[4:7], v20 offset:7168
	ds_read_b128 v[8:11], v20 offset:6928
	ds_read_b128 v[12:15], v20 offset:6912
	ds_read_b128 v[30:33], v20 offset:6672
	ds_read_b128 v[34:37], v20 offset:6656
	ds_read_b128 v[38:41], v20 offset:6416
	ds_read_b128 v[42:45], v20 offset:6400
	ds_read_b128 v[54:57], v20 offset:6144
	ds_read_b128 v[58:61], v20 offset:6160
	v_add_f32_dpp v88, v29, v29 row_half_mirror row_mask:0xf bank_mask:0xf bound_ctrl:1
	v_add_f32_dpp v90, v89, v89 row_half_mirror row_mask:0xf bank_mask:0xf bound_ctrl:1
	v_pk_fma_f32 v[70:71], v[46:47], v[88:89], v[70:71] op_sel_hi:[1,0,1]
	v_pk_fma_f32 v[74:75], v[50:51], v[88:89], v[74:75] op_sel_hi:[1,0,1]
	v_pk_fma_f32 v[46:47], v[46:47], v[90:91], v[78:79] op_sel_hi:[1,0,1]
	v_pk_fma_f32 v[50:51], v[50:51], v[90:91], v[82:83] op_sel_hi:[1,0,1]
	v_pk_fma_f32 v[72:73], v[48:49], v[88:89], v[72:73] op_sel_hi:[1,0,1]
	v_pk_fma_f32 v[76:77], v[52:53], v[88:89], v[76:77] op_sel_hi:[1,0,1]
	v_pk_fma_f32 v[48:49], v[48:49], v[90:91], v[80:81] op_sel_hi:[1,0,1]
	v_pk_fma_f32 v[52:53], v[52:53], v[90:91], v[84:85] op_sel_hi:[1,0,1]
	v_pk_mul_f32 v[78:79], v[62:63], v[70:71]
	v_pk_mul_f32 v[80:81], v[66:67], v[74:75]
	v_pk_mul_f32 v[62:63], v[62:63], v[46:47]
	v_pk_mul_f32 v[66:67], v[66:67], v[50:51]
	v_pk_fma_f32 v[78:79], v[64:65], v[72:73], v[78:79]
	v_pk_fma_f32 v[62:63], v[64:65], v[48:49], v[62:63]
	v_pk_fma_f32 v[64:65], v[68:69], v[52:53], v[66:67]
	v_pk_fma_f32 v[80:81], v[68:69], v[76:77], v[80:81]
	v_pk_add_f32 v[62:63], v[62:63], v[64:65]
	s_waitcnt lgkmcnt(2)
	v_pk_mul_f32 v[64:65], v[42:43], v[70:71]
	v_pk_mul_f32 v[68:69], v[38:39], v[74:75]
	v_pk_mul_f32 v[42:43], v[42:43], v[46:47]
	v_pk_mul_f32 v[38:39], v[38:39], v[50:51]
	v_pk_add_f32 v[66:67], v[78:79], v[80:81]
	s_waitcnt lgkmcnt(1)
; #define SCAN_STEP(w0, w1, a0, a1, b0, b1, k0, k1, r0, r1, vi, vj, t) do { \
;                 SCAN_ROW(S0, S1, S2, S3, w0, w1, a0, a1, b0, b1, k0, k1, r0, r1, vi, (t) * 512); \
;                 SCAN_ROW(T0, T1, T2, T3, w0, w1, a0, a1, b0, b1, k0, k1, r0, r1, vj, (t) * 512 + 256); } while (0)
;     ...
;             SCAN_LOAD(w0, w1, a0, a1, b0, b1, k0, k1, r0, r1, vi, vj, 0);
; #pragma unroll
;             for (int t = 0; t < 16; t += 2) {
;                 SCAN_LOAD(W0, W1, A0, A1, B0, B1, K0, K1, R0, R1, VI, VJ, t + 1);
;                 SCAN_STEP(w0, w1, a0, a1, b0, b1, k0, k1, r0, r1, vi, vj, t);
;                 if (t + 2 < 16) SCAN_LOAD(w0, w1, a0, a1, b0, b1, k0, k1, r0, r1, vi, vj, t + 2);
;                 SCAN_STEP(W0, W1, A0, A1, B0, B1, K0, K1, R0, R1, VI, VJ, t + 1);
	v_pk_mul_f32 v[70:71], v[54:55], v[70:71]
	v_pk_mul_f32 v[78:79], v[56:57], v[72:73]
	s_waitcnt lgkmcnt(0)
	v_pk_mul_f32 v[74:75], v[58:59], v[74:75]
	v_pk_mul_f32 v[80:81], v[60:61], v[76:77]
	v_pk_mul_f32 v[46:47], v[54:55], v[46:47]
	v_pk_mul_f32 v[54:55], v[56:57], v[48:49]
	v_pk_mul_f32 v[50:51], v[58:59], v[50:51]
	v_pk_mul_f32 v[56:57], v[60:61], v[52:53]
	v_pk_fma_f32 v[58:59], v[44:45], v[72:73], v[64:65]
	v_pk_fma_f32 v[60:61], v[40:41], v[76:77], v[68:69]
	v_pk_fma_f32 v[42:43], v[44:45], v[48:49], v[42:43]
	v_pk_fma_f32 v[38:39], v[40:41], v[52:53], v[38:39]
	v_mov_b32_e32 v82, v87
	v_add_f32_e32 v29, v66, v67
	v_add_f32_e32 v62, v62, v63
	v_pk_fma_f32 v[70:71], v[86:87], v[12:13], v[70:71] op_sel_hi:[0,1,1]
	v_pk_fma_f32 v[72:73], v[86:87], v[14:15], v[78:79] op_sel_hi:[0,1,1]
	v_pk_fma_f32 v[74:75], v[86:87], v[8:9], v[74:75] op_sel_hi:[0,1,1]
	v_pk_fma_f32 v[76:77], v[86:87], v[10:11], v[80:81] op_sel_hi:[0,1,1]
	v_pk_add_f32 v[86:87], v[60:61], v[58:59]
	v_pk_add_f32 v[88:89], v[38:39], v[42:43]
	ds_write2st64_b32 v27, v29, v62 offset0:216 offset1:220
	v_add_f32_e32 v29, v86, v87
	v_add_f32_e32 v86, v88, v89
	v_add_u32_e32 v129, 0x2000, v21
	v_add_f32_dpp v29, v29, v29 quad_perm:[1,0,3,2] row_mask:0xf bank_mask:0xf bound_ctrl:1
	v_add_f32_dpp v86, v86, v86 quad_perm:[1,0,3,2] row_mask:0xf bank_mask:0xf bound_ctrl:1
	v_pk_fma_f32 v[78:79], v[82:83], v[12:13], v[46:47] op_sel_hi:[0,1,1]
	v_pk_fma_f32 v[80:81], v[82:83], v[14:15], v[54:55] op_sel_hi:[0,1,1]
	v_pk_fma_f32 v[84:85], v[82:83], v[8:9], v[50:51] op_sel_hi:[0,1,1]
	v_pk_fma_f32 v[82:83], v[82:83], v[10:11], v[56:57] op_sel_hi:[0,1,1]
	ds_read_b128 v[8:11], v20 offset:7680
	ds_read_b128 v[12:15], v20 offset:7696
	ds_read_b128 v[38:41], v20 offset:7936
	ds_read_b128 v[42:45], v20 offset:7952
	ds_read_b128 v[46:49], v20 offset:8192
	ds_read_b128 v[50:53], v20 offset:8208
	ds_read_b128 v[54:57], v20 offset:8448
	ds_read_b128 v[58:61], v20 offset:8464
	ds_read_b128 v[62:65], v20 offset:8704
	ds_read_b128 v[66:69], v20 offset:8720
	ds_read2_b32 v[90:91], v129 offset0:192 offset1:200
	v_add_f32_dpp v29, v29, v29 quad_perm:[2,3,0,1] row_mask:0xf bank_mask:0xf bound_ctrl:1
	v_add_f32_dpp v87, v86, v86 quad_perm:[2,3,0,1] row_mask:0xf bank_mask:0xf bound_ctrl:1
	v_add_u32_e32 v130, 0x2800, v21
	v_add_f32_dpp v86, v29, v29 row_half_mirror row_mask:0xf bank_mask:0xf bound_ctrl:1
	v_add_f32_dpp v88, v87, v87 row_half_mirror row_mask:0xf bank_mask:0xf bound_ctrl:1
	v_pk_fma_f32 v[70:71], v[34:35], v[86:87], v[70:71] op_sel_hi:[1,0,1]
	v_pk_fma_f32 v[74:75], v[30:31], v[86:87], v[74:75] op_sel_hi:[1,0,1]
	v_pk_fma_f32 v[34:35], v[34:35], v[88:89], v[78:79] op_sel_hi:[1,0,1]
	v_pk_fma_f32 v[30:31], v[30:31], v[88:89], v[84:85] op_sel_hi:[1,0,1]
	v_pk_fma_f32 v[72:73], v[36:37], v[86:87], v[72:73] op_sel_hi:[1,0,1]
	v_pk_fma_f32 v[76:77], v[32:33], v[86:87], v[76:77] op_sel_hi:[1,0,1]
	v_pk_fma_f32 v[36:37], v[36:37], v[88:89], v[80:81] op_sel_hi:[1,0,1]
	v_pk_fma_f32 v[32:33], v[32:33], v[88:89], v[82:83] op_sel_hi:[1,0,1]
	v_pk_mul_f32 v[78:79], v[4:5], v[70:71]
	v_pk_mul_f32 v[80:81], v[0:1], v[74:75]
	v_pk_mul_f32 v[4:5], v[4:5], v[34:35]
	v_pk_mul_f32 v[0:1], v[0:1], v[30:31]
	s_waitcnt lgkmcnt(8)
	v_pk_mul_f32 v[82:83], v[38:39], v[70:71]
	s_waitcnt lgkmcnt(7)
	v_pk_mul_f32 v[84:85], v[42:43], v[74:75]
	v_pk_mul_f32 v[38:39], v[38:39], v[34:35]
	v_pk_mul_f32 v[42:43], v[42:43], v[30:31]
	v_pk_mul_f32 v[70:71], v[8:9], v[70:71]
	v_pk_mul_f32 v[86:87], v[10:11], v[72:73]
	v_pk_mul_f32 v[74:75], v[12:13], v[74:75]
	v_pk_mul_f32 v[88:89], v[14:15], v[76:77]
	v_pk_mul_f32 v[8:9], v[8:9], v[34:35]
	v_pk_mul_f32 v[10:11], v[10:11], v[36:37]
	v_pk_mul_f32 v[12:13], v[12:13], v[30:31]
	v_pk_mul_f32 v[14:15], v[14:15], v[32:33]
	v_pk_fma_f32 v[30:31], v[6:7], v[72:73], v[78:79]
	v_pk_fma_f32 v[34:35], v[2:3], v[76:77], v[80:81]
	v_pk_fma_f32 v[4:5], v[6:7], v[36:37], v[4:5]
	v_pk_fma_f32 v[0:1], v[2:3], v[32:33], v[0:1]
	v_pk_fma_f32 v[2:3], v[40:41], v[72:73], v[82:83]
	v_pk_fma_f32 v[6:7], v[44:45], v[76:77], v[84:85]
	v_pk_fma_f32 v[36:37], v[40:41], v[36:37], v[38:39]
	v_pk_fma_f32 v[32:33], v[44:45], v[32:33], v[42:43]
	s_waitcnt lgkmcnt(0)
	v_mov_b32_e32 v92, v91
	v_pk_add_f32 v[0:1], v[4:5], v[0:1]
	v_pk_add_f32 v[2:3], v[2:3], v[6:7]
	v_pk_add_f32 v[4:5], v[36:37], v[32:33]
	v_pk_fma_f32 v[78:79], v[54:55], v[92:93], v[8:9] op_sel_hi:[1,0,1]
	v_pk_add_f32 v[8:9], v[30:31], v[34:35]
	v_add_f32_e32 v0, v0, v1
	v_add_f32_e32 v1, v2, v3
	v_add_f32_e32 v2, v4, v5
	v_pk_fma_f32 v[76:77], v[60:61], v[90:91], v[88:89] op_sel_hi:[1,0,1]
	v_add_f32_e32 v6, v8, v9
	v_add_f32_dpp v29, v1, v1 quad_perm:[1,0,3,2] row_mask:0xf bank_mask:0xf bound_ctrl:1
	v_add_f32_dpp v88, v2, v2 quad_perm:[1,0,3,2] row_mask:0xf bank_mask:0xf bound_ctrl:1
	ds_write2st64_b32 v27, v6, v0 offset0:224 offset1:228
	v_add_f32_dpp v29, v29, v29 quad_perm:[2,3,0,1] row_mask:0xf bank_mask:0xf bound_ctrl:1
	v_add_f32_dpp v89, v88, v88 quad_perm:[2,3,0,1] row_mask:0xf bank_mask:0xf bound_ctrl:1
	v_pk_fma_f32 v[70:71], v[54:55], v[90:91], v[70:71] op_sel_hi:[1,0,1]
	v_pk_fma_f32 v[72:73], v[56:57], v[90:91], v[86:87] op_sel_hi:[1,0,1]
	v_pk_fma_f32 v[74:75], v[58:59], v[90:91], v[74:75] op_sel_hi:[1,0,1]
	v_pk_fma_f32 v[80:81], v[56:57], v[92:93], v[10:11] op_sel_hi:[1,0,1]
	v_pk_fma_f32 v[82:83], v[58:59], v[92:93], v[12:13] op_sel_hi:[1,0,1]
	v_pk_fma_f32 v[84:85], v[60:61], v[92:93], v[14:15] op_sel_hi:[1,0,1]
	ds_read2_b32 v[86:87], v130 offset0:64 offset1:72
	ds_read_b128 v[0:3], v20 offset:10256
	ds_read_b128 v[4:7], v20 offset:10240
	ds_read_b128 v[8:11], v20 offset:10000
	ds_read_b128 v[12:15], v20 offset:9984
; #define SCAN_STEP(w0, w1, a0, a1, b0, b1, k0, k1, r0, r1, vi, vj, t) do { \
;                 SCAN_ROW(S0, S1, S2, S3, w0, w1, a0, a1, b0, b1, k0, k1, r0, r1, vi, (t) * 512); \
;                 SCAN_ROW(T0, T1, T2, T3, w0, w1, a0, a1, b0, b1, k0, k1, r0, r1, vj, (t) * 512 + 256); } while (0)
;     ...
;             SCAN_LOAD(w0, w1, a0, a1, b0, b1, k0, k1, r0, r1, vi, vj, 0);
; #pragma unroll
;             for (int t = 0; t < 16; t += 2) {
;                 SCAN_LOAD(W0, W1, A0, A1, B0, B1, K0, K1, R0, R1, VI, VJ, t + 1);
;                 SCAN_STEP(w0, w1, a0, a1, b0, b1, k0, k1, r0, r1, vi, vj, t);
;                 if (t + 2 < 16) SCAN_LOAD(w0, w1, a0, a1, b0, b1, k0, k1, r0, r1, vi, vj, t + 2);
;                 SCAN_STEP(W0, W1, A0, A1, B0, B1, K0, K1, R0, R1, VI, VJ, t + 1);
	ds_read_b128 v[30:33], v20 offset:9744
	ds_read_b128 v[34:37], v20 offset:9728
	ds_read_b128 v[38:41], v20 offset:9488
	ds_read_b128 v[42:45], v20 offset:9472
	ds_read_b128 v[54:57], v20 offset:9216
	ds_read_b128 v[58:61], v20 offset:9232
	v_add_f32_dpp v88, v29, v29 row_half_mirror row_mask:0xf bank_mask:0xf bound_ctrl:1
	v_add_f32_dpp v90, v89, v89 row_half_mirror row_mask:0xf bank_mask:0xf bound_ctrl:1
	v_pk_fma_f32 v[70:71], v[46:47], v[88:89], v[70:71] op_sel_hi:[1,0,1]
	v_pk_fma_f32 v[74:75], v[50:51], v[88:89], v[74:75] op_sel_hi:[1,0,1]
	v_pk_fma_f32 v[46:47], v[46:47], v[90:91], v[78:79] op_sel_hi:[1,0,1]
	v_pk_fma_f32 v[50:51], v[50:51], v[90:91], v[82:83] op_sel_hi:[1,0,1]
	v_pk_fma_f32 v[72:73], v[48:49], v[88:89], v[72:73] op_sel_hi:[1,0,1]
	v_pk_fma_f32 v[76:77], v[52:53], v[88:89], v[76:77] op_sel_hi:[1,0,1]
	v_pk_fma_f32 v[48:49], v[48:49], v[90:91], v[80:81] op_sel_hi:[1,0,1]
	v_pk_fma_f32 v[52:53], v[52:53], v[90:91], v[84:85] op_sel_hi:[1,0,1]
	v_pk_mul_f32 v[78:79], v[62:63], v[70:71]
	v_pk_mul_f32 v[80:81], v[66:67], v[74:75]
	v_pk_mul_f32 v[62:63], v[62:63], v[46:47]
	v_pk_mul_f32 v[66:67], v[66:67], v[50:51]
	v_pk_fma_f32 v[78:79], v[64:65], v[72:73], v[78:79]
	v_pk_fma_f32 v[62:63], v[64:65], v[48:49], v[62:63]
	v_pk_fma_f32 v[64:65], v[68:69], v[52:53], v[66:67]
	v_pk_fma_f32 v[80:81], v[68:69], v[76:77], v[80:81]
	v_pk_add_f32 v[62:63], v[62:63], v[64:65]
	s_waitcnt lgkmcnt(2)
	v_pk_mul_f32 v[64:65], v[42:43], v[70:71]
	v_pk_mul_f32 v[68:69], v[38:39], v[74:75]
	v_pk_mul_f32 v[42:43], v[42:43], v[46:47]
	v_pk_mul_f32 v[38:39], v[38:39], v[50:51]
	v_pk_add_f32 v[66:67], v[78:79], v[80:81]
	s_waitcnt lgkmcnt(1)
	v_pk_mul_f32 v[70:71], v[54:55], v[70:71]
	v_pk_mul_f32 v[78:79], v[56:57], v[72:73]
	s_waitcnt lgkmcnt(0)
	v_pk_mul_f32 v[74:75], v[58:59], v[74:75]
	v_pk_mul_f32 v[80:81], v[60:61], v[76:77]
	v_pk_mul_f32 v[46:47], v[54:55], v[46:47]
	v_pk_mul_f32 v[54:55], v[56:57], v[48:49]
	v_pk_mul_f32 v[50:51], v[58:59], v[50:51]
	v_pk_mul_f32 v[56:57], v[60:61], v[52:53]
	v_pk_fma_f32 v[58:59], v[44:45], v[72:73], v[64:65]
	v_pk_fma_f32 v[60:61], v[40:41], v[76:77], v[68:69]
	v_pk_fma_f32 v[42:43], v[44:45], v[48:49], v[42:43]
	v_pk_fma_f32 v[38:39], v[40:41], v[52:53], v[38:39]
	v_mov_b32_e32 v82, v87
	v_add_f32_e32 v29, v66, v67
	v_add_f32_e32 v62, v62, v63
	v_pk_fma_f32 v[70:71], v[86:87], v[12:13], v[70:71] op_sel_hi:[0,1,1]
	v_pk_fma_f32 v[72:73], v[86:87], v[14:15], v[78:79] op_sel_hi:[0,1,1]
	v_pk_fma_f32 v[74:75], v[86:87], v[8:9], v[74:75] op_sel_hi:[0,1,1]
	v_pk_fma_f32 v[76:77], v[86:87], v[10:11], v[80:81] op_sel_hi:[0,1,1]
	v_pk_add_f32 v[86:87], v[60:61], v[58:59]
	v_pk_add_f32 v[88:89], v[38:39], v[42:43]
	ds_write2st64_b32 v27, v29, v62 offset0:232 offset1:236
	v_add_f32_e32 v29, v86, v87
	v_add_f32_e32 v86, v88, v89
	v_add_u32_e32 v131, 0x2c00, v21
	v_add_f32_dpp v29, v29, v29 quad_perm:[1,0,3,2] row_mask:0xf bank_mask:0xf bound_ctrl:1
	v_add_f32_dpp v86, v86, v86 quad_perm:[1,0,3,2] row_mask:0xf bank_mask:0xf bound_ctrl:1
	v_pk_fma_f32 v[78:79], v[82:83], v[12:13], v[46:47] op_sel_hi:[0,1,1]
	v_pk_fma_f32 v[80:81], v[82:83], v[14:15], v[54:55] op_sel_hi:[0,1,1]
	v_pk_fma_f32 v[84:85], v[82:83], v[8:9], v[50:51] op_sel_hi:[0,1,1]
	v_pk_fma_f32 v[82:83], v[82:83], v[10:11], v[56:57] op_sel_hi:[0,1,1]
	ds_read_b128 v[8:11], v20 offset:10752
	ds_read_b128 v[12:15], v20 offset:10768
	ds_read_b128 v[38:41], v20 offset:11008
	ds_read_b128 v[42:45], v20 offset:11024
	ds_read_b128 v[46:49], v20 offset:11264
	ds_read_b128 v[50:53], v20 offset:11280
	ds_read_b128 v[54:57], v20 offset:11520
	ds_read_b128 v[58:61], v20 offset:11536
	ds_read_b128 v[62:65], v20 offset:11776
	ds_read_b128 v[66:69], v20 offset:11792
	ds_read2_b32 v[90:91], v131 offset0:192 offset1:200
	v_add_f32_dpp v29, v29, v29 quad_perm:[2,3,0,1] row_mask:0xf bank_mask:0xf bound_ctrl:1
	v_add_f32_dpp v87, v86, v86 quad_perm:[2,3,0,1] row_mask:0xf bank_mask:0xf bound_ctrl:1
	v_add_u32_e32 v132, 0x3400, v21
	v_add_f32_dpp v86, v29, v29 row_half_mirror row_mask:0xf bank_mask:0xf bound_ctrl:1
	v_add_f32_dpp v88, v87, v87 row_half_mirror row_mask:0xf bank_mask:0xf bound_ctrl:1
	v_pk_fma_f32 v[70:71], v[34:35], v[86:87], v[70:71] op_sel_hi:[1,0,1]
	v_pk_fma_f32 v[74:75], v[30:31], v[86:87], v[74:75] op_sel_hi:[1,0,1]
	v_pk_fma_f32 v[34:35], v[34:35], v[88:89], v[78:79] op_sel_hi:[1,0,1]
	v_pk_fma_f32 v[30:31], v[30:31], v[88:89], v[84:85] op_sel_hi:[1,0,1]
	v_pk_fma_f32 v[72:73], v[36:37], v[86:87], v[72:73] op_sel_hi:[1,0,1]
	v_pk_fma_f32 v[76:77], v[32:33], v[86:87], v[76:77] op_sel_hi:[1,0,1]
	v_pk_fma_f32 v[36:37], v[36:37], v[88:89], v[80:81] op_sel_hi:[1,0,1]
	v_pk_fma_f32 v[32:33], v[32:33], v[88:89], v[82:83] op_sel_hi:[1,0,1]
	v_pk_mul_f32 v[78:79], v[4:5], v[70:71]
	v_pk_mul_f32 v[80:81], v[0:1], v[74:75]
	v_pk_mul_f32 v[4:5], v[4:5], v[34:35]
	v_pk_mul_f32 v[0:1], v[0:1], v[30:31]
	s_waitcnt lgkmcnt(8)
	v_pk_mul_f32 v[82:83], v[38:39], v[70:71]
	s_waitcnt lgkmcnt(7)
	v_pk_mul_f32 v[84:85], v[42:43], v[74:75]
	v_pk_mul_f32 v[38:39], v[38:39], v[34:35]
	v_pk_mul_f32 v[42:43], v[42:43], v[30:31]
	v_pk_mul_f32 v[70:71], v[8:9], v[70:71]
	v_pk_mul_f32 v[86:87], v[10:11], v[72:73]
	v_pk_mul_f32 v[74:75], v[12:13], v[74:75]
	v_pk_mul_f32 v[88:89], v[14:15], v[76:77]
	v_pk_mul_f32 v[8:9], v[8:9], v[34:35]
	v_pk_mul_f32 v[10:11], v[10:11], v[36:37]
	v_pk_mul_f32 v[12:13], v[12:13], v[30:31]
	v_pk_mul_f32 v[14:15], v[14:15], v[32:33]
	v_pk_fma_f32 v[30:31], v[6:7], v[72:73], v[78:79]
	v_pk_fma_f32 v[34:35], v[2:3], v[76:77], v[80:81]
	v_pk_fma_f32 v[4:5], v[6:7], v[36:37], v[4:5]
	v_pk_fma_f32 v[0:1], v[2:3], v[32:33], v[0:1]
	v_pk_fma_f32 v[2:3], v[40:41], v[72:73], v[82:83]
	v_pk_fma_f32 v[6:7], v[44:45], v[76:77], v[84:85]
	v_pk_fma_f32 v[36:37], v[40:41], v[36:37], v[38:39]
	v_pk_fma_f32 v[32:33], v[44:45], v[32:33], v[42:43]
	s_waitcnt lgkmcnt(0)
; #define SCAN_STEP(w0, w1, a0, a1, b0, b1, k0, k1, r0, r1, vi, vj, t) do { \
;                 SCAN_ROW(S0, S1, S2, S3, w0, w1, a0, a1, b0, b1, k0, k1, r0, r1, vi, (t) * 512); \
;                 SCAN_ROW(T0, T1, T2, T3, w0, w1, a0, a1, b0, b1, k0, k1, r0, r1, vj, (t) * 512 + 256); } while (0)
;     ...
;             SCAN_LOAD(w0, w1, a0, a1, b0, b1, k0, k1, r0, r1, vi, vj, 0);
; #pragma unroll
;             for (int t = 0; t < 16; t += 2) {
;                 SCAN_LOAD(W0, W1, A0, A1, B0, B1, K0, K1, R0, R1, VI, VJ, t + 1);
;                 SCAN_STEP(w0, w1, a0, a1, b0, b1, k0, k1, r0, r1, vi, vj, t);
;                 if (t + 2 < 16) SCAN_LOAD(w0, w1, a0, a1, b0, b1, k0, k1, r0, r1, vi, vj, t + 2);
;                 SCAN_STEP(W0, W1, A0, A1, B0, B1, K0, K1, R0, R1, VI, VJ, t + 1);
	v_mov_b32_e32 v92, v91
	v_pk_add_f32 v[0:1], v[4:5], v[0:1]
	v_pk_add_f32 v[2:3], v[2:3], v[6:7]
	v_pk_add_f32 v[4:5], v[36:37], v[32:33]
	v_pk_fma_f32 v[78:79], v[54:55], v[92:93], v[8:9] op_sel_hi:[1,0,1]
	v_pk_add_f32 v[8:9], v[30:31], v[34:35]
	v_add_f32_e32 v0, v0, v1
	v_add_f32_e32 v1, v2, v3
	v_add_f32_e32 v2, v4, v5
	v_pk_fma_f32 v[76:77], v[60:61], v[90:91], v[88:89] op_sel_hi:[1,0,1]
	v_add_f32_e32 v6, v8, v9
	v_add_f32_dpp v29, v1, v1 quad_perm:[1,0,3,2] row_mask:0xf bank_mask:0xf bound_ctrl:1
	v_add_f32_dpp v88, v2, v2 quad_perm:[1,0,3,2] row_mask:0xf bank_mask:0xf bound_ctrl:1
	ds_write2st64_b32 v27, v6, v0 offset0:240 offset1:244
	v_add_f32_dpp v29, v29, v29 quad_perm:[2,3,0,1] row_mask:0xf bank_mask:0xf bound_ctrl:1
	v_add_f32_dpp v89, v88, v88 quad_perm:[2,3,0,1] row_mask:0xf bank_mask:0xf bound_ctrl:1
	v_pk_fma_f32 v[70:71], v[54:55], v[90:91], v[70:71] op_sel_hi:[1,0,1]
	v_pk_fma_f32 v[72:73], v[56:57], v[90:91], v[86:87] op_sel_hi:[1,0,1]
	v_pk_fma_f32 v[74:75], v[58:59], v[90:91], v[74:75] op_sel_hi:[1,0,1]
	v_pk_fma_f32 v[80:81], v[56:57], v[92:93], v[10:11] op_sel_hi:[1,0,1]
	v_pk_fma_f32 v[82:83], v[58:59], v[92:93], v[12:13] op_sel_hi:[1,0,1]
	v_pk_fma_f32 v[84:85], v[60:61], v[92:93], v[14:15] op_sel_hi:[1,0,1]
	ds_read2_b32 v[86:87], v132 offset0:64 offset1:72
	ds_read_b128 v[0:3], v20 offset:13328
	ds_read_b128 v[4:7], v20 offset:13312
	ds_read_b128 v[8:11], v20 offset:13072
	ds_read_b128 v[12:15], v20 offset:13056
	ds_read_b128 v[30:33], v20 offset:12816
	ds_read_b128 v[34:37], v20 offset:12800
	ds_read_b128 v[38:41], v20 offset:12560
	ds_read_b128 v[42:45], v20 offset:12544
	ds_read_b128 v[54:57], v20 offset:12288
	ds_read_b128 v[58:61], v20 offset:12304
	v_add_f32_dpp v88, v29, v29 row_half_mirror row_mask:0xf bank_mask:0xf bound_ctrl:1
	v_add_f32_dpp v90, v89, v89 row_half_mirror row_mask:0xf bank_mask:0xf bound_ctrl:1
	v_pk_fma_f32 v[70:71], v[46:47], v[88:89], v[70:71] op_sel_hi:[1,0,1]
	v_pk_fma_f32 v[74:75], v[50:51], v[88:89], v[74:75] op_sel_hi:[1,0,1]
	v_pk_fma_f32 v[46:47], v[46:47], v[90:91], v[78:79] op_sel_hi:[1,0,1]
	v_pk_fma_f32 v[50:51], v[50:51], v[90:91], v[82:83] op_sel_hi:[1,0,1]
	v_pk_fma_f32 v[72:73], v[48:49], v[88:89], v[72:73] op_sel_hi:[1,0,1]
	v_pk_fma_f32 v[76:77], v[52:53], v[88:89], v[76:77] op_sel_hi:[1,0,1]
	v_pk_fma_f32 v[48:49], v[48:49], v[90:91], v[80:81] op_sel_hi:[1,0,1]
	v_pk_fma_f32 v[52:53], v[52:53], v[90:91], v[84:85] op_sel_hi:[1,0,1]
	v_pk_mul_f32 v[78:79], v[62:63], v[70:71]
	v_pk_mul_f32 v[80:81], v[66:67], v[74:75]
	v_pk_mul_f32 v[62:63], v[62:63], v[46:47]
	v_pk_mul_f32 v[66:67], v[66:67], v[50:51]
	v_pk_fma_f32 v[78:79], v[64:65], v[72:73], v[78:79]
	v_pk_fma_f32 v[62:63], v[64:65], v[48:49], v[62:63]
	v_pk_fma_f32 v[64:65], v[68:69], v[52:53], v[66:67]
	v_pk_fma_f32 v[80:81], v[68:69], v[76:77], v[80:81]
	v_pk_add_f32 v[62:63], v[62:63], v[64:65]
	s_waitcnt lgkmcnt(2)
	v_pk_mul_f32 v[64:65], v[42:43], v[70:71]
	v_pk_mul_f32 v[68:69], v[38:39], v[74:75]
	v_pk_mul_f32 v[42:43], v[42:43], v[46:47]
	v_pk_mul_f32 v[38:39], v[38:39], v[50:51]
	v_pk_add_f32 v[66:67], v[78:79], v[80:81]
	s_waitcnt lgkmcnt(1)
	v_pk_mul_f32 v[70:71], v[54:55], v[70:71]
	v_pk_mul_f32 v[78:79], v[56:57], v[72:73]
	s_waitcnt lgkmcnt(0)
	v_pk_mul_f32 v[74:75], v[58:59], v[74:75]
	v_pk_mul_f32 v[80:81], v[60:61], v[76:77]
	v_pk_mul_f32 v[46:47], v[54:55], v[46:47]
	v_pk_mul_f32 v[54:55], v[56:57], v[48:49]
	v_pk_mul_f32 v[50:51], v[58:59], v[50:51]
	v_pk_mul_f32 v[56:57], v[60:61], v[52:53]
	v_pk_fma_f32 v[58:59], v[44:45], v[72:73], v[64:65]
	v_pk_fma_f32 v[60:61], v[40:41], v[76:77], v[68:69]
	v_pk_fma_f32 v[42:43], v[44:45], v[48:49], v[42:43]
	v_pk_fma_f32 v[38:39], v[40:41], v[52:53], v[38:39]
	v_mov_b32_e32 v82, v87
	v_add_f32_e32 v29, v66, v67
	v_add_f32_e32 v62, v62, v63
	v_pk_fma_f32 v[70:71], v[86:87], v[12:13], v[70:71] op_sel_hi:[0,1,1]
	v_pk_fma_f32 v[72:73], v[86:87], v[14:15], v[78:79] op_sel_hi:[0,1,1]
	v_pk_fma_f32 v[74:75], v[86:87], v[8:9], v[74:75] op_sel_hi:[0,1,1]
	v_pk_fma_f32 v[76:77], v[86:87], v[10:11], v[80:81] op_sel_hi:[0,1,1]
	v_pk_add_f32 v[86:87], v[60:61], v[58:59]
	v_pk_add_f32 v[88:89], v[38:39], v[42:43]
	v_add_u32_e32 v19, 0xc000, v27
	v_add_u32_e32 v28, 0x3800, v21
	ds_write2st64_b32 v27, v29, v62 offset0:248 offset1:252
	v_add_f32_e32 v27, v86, v87
	v_add_f32_e32 v86, v88, v89
	v_pk_fma_f32 v[78:79], v[82:83], v[12:13], v[46:47] op_sel_hi:[0,1,1]
	v_pk_fma_f32 v[80:81], v[82:83], v[14:15], v[54:55] op_sel_hi:[0,1,1]
	v_pk_fma_f32 v[84:85], v[82:83], v[8:9], v[50:51] op_sel_hi:[0,1,1]
	v_pk_fma_f32 v[82:83], v[82:83], v[10:11], v[56:57] op_sel_hi:[0,1,1]
	ds_read_b128 v[8:11], v20 offset:13824
	ds_read_b128 v[12:15], v20 offset:13840
	ds_read_b128 v[38:41], v20 offset:14080
	ds_read_b128 v[42:45], v20 offset:14096
	ds_read_b128 v[46:49], v20 offset:14336
	ds_read_b128 v[50:53], v20 offset:14352
	ds_read_b128 v[54:57], v20 offset:14592
	ds_read_b128 v[58:61], v20 offset:14608
	ds_read_b128 v[62:65], v20 offset:14848
	ds_read_b128 v[66:69], v20 offset:14864
	ds_read2_b32 v[28:29], v28 offset0:192 offset1:200
	v_add_f32_dpp v27, v27, v27 quad_perm:[1,0,3,2] row_mask:0xf bank_mask:0xf bound_ctrl:1
	v_add_f32_dpp v86, v86, v86 quad_perm:[1,0,3,2] row_mask:0xf bank_mask:0xf bound_ctrl:1
	v_add_u32_e32 v26, 0x4000, v21
	v_add_f32_dpp v27, v27, v27 quad_perm:[2,3,0,1] row_mask:0xf bank_mask:0xf bound_ctrl:1
	v_add_f32_dpp v87, v86, v86 quad_perm:[2,3,0,1] row_mask:0xf bank_mask:0xf bound_ctrl:1
	s_waitcnt lgkmcnt(0)
; #define SCAN_STEP(w0, w1, a0, a1, b0, b1, k0, k1, r0, r1, vi, vj, t) do { \
;                 SCAN_ROW(S0, S1, S2, S3, w0, w1, a0, a1, b0, b1, k0, k1, r0, r1, vi, (t) * 512); \
;                 SCAN_ROW(T0, T1, T2, T3, w0, w1, a0, a1, b0, b1, k0, k1, r0, r1, vj, (t) * 512 + 256); } while (0)
;     ...
;             SCAN_LOAD(w0, w1, a0, a1, b0, b1, k0, k1, r0, r1, vi, vj, 0);
; #pragma unroll
;             for (int t = 0; t < 16; t += 2) {
;                 SCAN_LOAD(W0, W1, A0, A1, B0, B1, K0, K1, R0, R1, VI, VJ, t + 1);
;                 SCAN_STEP(w0, w1, a0, a1, b0, b1, k0, k1, r0, r1, vi, vj, t);
;                 if (t + 2 < 16) SCAN_LOAD(w0, w1, a0, a1, b0, b1, k0, k1, r0, r1, vi, vj, t + 2);
;                 SCAN_STEP(W0, W1, A0, A1, B0, B1, K0, K1, R0, R1, VI, VJ, t + 1);
	v_mov_b32_e32 v90, v29
	v_add_f32_dpp v86, v27, v27 row_half_mirror row_mask:0xf bank_mask:0xf bound_ctrl:1
	v_add_f32_dpp v88, v87, v87 row_half_mirror row_mask:0xf bank_mask:0xf bound_ctrl:1
	v_pk_fma_f32 v[70:71], v[34:35], v[86:87], v[70:71] op_sel_hi:[1,0,1]
	v_pk_fma_f32 v[72:73], v[36:37], v[86:87], v[72:73] op_sel_hi:[1,0,1]
	v_pk_fma_f32 v[74:75], v[30:31], v[86:87], v[74:75] op_sel_hi:[1,0,1]
	v_pk_fma_f32 v[76:77], v[32:33], v[86:87], v[76:77] op_sel_hi:[1,0,1]
	v_pk_fma_f32 v[34:35], v[34:35], v[88:89], v[78:79] op_sel_hi:[1,0,1]
	v_pk_fma_f32 v[30:31], v[30:31], v[88:89], v[84:85] op_sel_hi:[1,0,1]
	v_pk_fma_f32 v[36:37], v[36:37], v[88:89], v[80:81] op_sel_hi:[1,0,1]
	v_pk_fma_f32 v[32:33], v[32:33], v[88:89], v[82:83] op_sel_hi:[1,0,1]
	v_pk_mul_f32 v[78:79], v[4:5], v[70:71]
	v_pk_mul_f32 v[80:81], v[0:1], v[74:75]
	v_pk_mul_f32 v[4:5], v[4:5], v[34:35]
	v_pk_mul_f32 v[0:1], v[0:1], v[30:31]
	v_pk_mul_f32 v[82:83], v[38:39], v[70:71]
	v_pk_mul_f32 v[84:85], v[42:43], v[74:75]
	v_pk_mul_f32 v[70:71], v[8:9], v[70:71]
	v_pk_mul_f32 v[86:87], v[10:11], v[72:73]
	v_pk_mul_f32 v[74:75], v[12:13], v[74:75]
	v_pk_mul_f32 v[88:89], v[14:15], v[76:77]
	v_pk_mul_f32 v[38:39], v[38:39], v[34:35]
	v_pk_mul_f32 v[42:43], v[42:43], v[30:31]
	v_pk_mul_f32 v[8:9], v[8:9], v[34:35]
	v_pk_mul_f32 v[12:13], v[12:13], v[30:31]
	v_pk_mul_f32 v[14:15], v[14:15], v[32:33]
	v_pk_fma_f32 v[30:31], v[6:7], v[72:73], v[78:79]
	v_pk_fma_f32 v[34:35], v[2:3], v[76:77], v[80:81]
	v_pk_fma_f32 v[4:5], v[6:7], v[36:37], v[4:5]
	v_pk_fma_f32 v[0:1], v[2:3], v[32:33], v[0:1]
	v_pk_fma_f32 v[2:3], v[40:41], v[72:73], v[82:83]
	v_pk_fma_f32 v[6:7], v[44:45], v[76:77], v[84:85]
	v_pk_fma_f32 v[70:71], v[54:55], v[28:29], v[70:71] op_sel_hi:[1,0,1]
	v_pk_fma_f32 v[72:73], v[56:57], v[28:29], v[86:87] op_sel_hi:[1,0,1]
	v_pk_fma_f32 v[74:75], v[58:59], v[28:29], v[74:75] op_sel_hi:[1,0,1]
	v_pk_fma_f32 v[76:77], v[60:61], v[28:29], v[88:89] op_sel_hi:[1,0,1]
	v_pk_fma_f32 v[28:29], v[40:41], v[36:37], v[38:39]
	v_pk_fma_f32 v[32:33], v[44:45], v[32:33], v[42:43]
	v_pk_add_f32 v[0:1], v[4:5], v[0:1]
	v_pk_add_f32 v[2:3], v[2:3], v[6:7]
	v_pk_add_f32 v[4:5], v[28:29], v[32:33]
	v_pk_fma_f32 v[78:79], v[54:55], v[90:91], v[8:9] op_sel_hi:[1,0,1]
	v_pk_add_f32 v[8:9], v[30:31], v[34:35]
	v_add_f32_e32 v0, v0, v1
	v_add_f32_e32 v1, v2, v3
	v_add_f32_e32 v2, v4, v5
	v_add_f32_e32 v6, v8, v9
	v_add_f32_dpp v84, v1, v1 quad_perm:[1,0,3,2] row_mask:0xf bank_mask:0xf bound_ctrl:1
	v_add_f32_dpp v85, v2, v2 quad_perm:[1,0,3,2] row_mask:0xf bank_mask:0xf bound_ctrl:1
	v_pk_mul_f32 v[10:11], v[10:11], v[36:37]
	ds_write2st64_b32 v19, v6, v0 offset0:64 offset1:68
	v_add_f32_dpp v84, v84, v84 quad_perm:[2,3,0,1] row_mask:0xf bank_mask:0xf bound_ctrl:1
	v_add_f32_dpp v85, v85, v85 quad_perm:[2,3,0,1] row_mask:0xf bank_mask:0xf bound_ctrl:1
	v_pk_fma_f32 v[80:81], v[56:57], v[90:91], v[10:11] op_sel_hi:[1,0,1]
	v_pk_fma_f32 v[58:59], v[58:59], v[90:91], v[12:13] op_sel_hi:[1,0,1]
	v_pk_fma_f32 v[60:61], v[60:61], v[90:91], v[14:15] op_sel_hi:[1,0,1]
	ds_read2_b32 v[82:83], v26 offset0:64 offset1:72
	ds_read_b128 v[0:3], v20 offset:16400
	ds_read_b128 v[4:7], v20 offset:16384
	ds_read_b128 v[8:11], v20 offset:16144
	ds_read_b128 v[12:15], v20 offset:16128
	ds_read_b128 v[26:29], v20 offset:15888
	ds_read_b128 v[30:33], v20 offset:15872
	ds_read_b128 v[34:37], v20 offset:15632
	ds_read_b128 v[38:41], v20 offset:15616
	ds_read_b128 v[42:45], v20 offset:15360
	ds_read_b128 v[54:57], v20 offset:15376
	v_add_f32_dpp v84, v84, v84 row_half_mirror row_mask:0xf bank_mask:0xf bound_ctrl:1
	v_add_f32_dpp v86, v85, v85 row_half_mirror row_mask:0xf bank_mask:0xf bound_ctrl:1
	v_pk_fma_f32 v[70:71], v[46:47], v[84:85], v[70:71] op_sel_hi:[1,0,1]
	v_pk_fma_f32 v[74:75], v[50:51], v[84:85], v[74:75] op_sel_hi:[1,0,1]
	v_pk_fma_f32 v[46:47], v[46:47], v[86:87], v[78:79] op_sel_hi:[1,0,1]
	v_pk_fma_f32 v[50:51], v[50:51], v[86:87], v[58:59] op_sel_hi:[1,0,1]
	v_pk_fma_f32 v[72:73], v[48:49], v[84:85], v[72:73] op_sel_hi:[1,0,1]
	v_pk_fma_f32 v[76:77], v[52:53], v[84:85], v[76:77] op_sel_hi:[1,0,1]
	v_pk_fma_f32 v[48:49], v[48:49], v[86:87], v[80:81] op_sel_hi:[1,0,1]
	v_pk_fma_f32 v[52:53], v[52:53], v[86:87], v[60:61] op_sel_hi:[1,0,1]
	v_pk_mul_f32 v[58:59], v[62:63], v[70:71]
	v_pk_mul_f32 v[60:61], v[66:67], v[74:75]
	v_pk_mul_f32 v[62:63], v[62:63], v[46:47]
	v_pk_mul_f32 v[66:67], v[66:67], v[50:51]
	v_pk_fma_f32 v[58:59], v[64:65], v[72:73], v[58:59]
	v_pk_fma_f32 v[60:61], v[68:69], v[76:77], v[60:61]
	v_pk_fma_f32 v[62:63], v[64:65], v[48:49], v[62:63]
	v_pk_fma_f32 v[64:65], v[68:69], v[52:53], v[66:67]
	v_pk_add_f32 v[58:59], v[58:59], v[60:61]
	v_pk_add_f32 v[60:61], v[62:63], v[64:65]
	s_waitcnt lgkmcnt(2)
	v_pk_mul_f32 v[62:63], v[38:39], v[70:71]
	v_pk_mul_f32 v[64:65], v[34:35], v[74:75]
	v_pk_mul_f32 v[38:39], v[38:39], v[46:47]
	v_pk_mul_f32 v[34:35], v[34:35], v[50:51]
	s_waitcnt lgkmcnt(1)
	v_pk_mul_f32 v[66:67], v[42:43], v[70:71]
	v_pk_mul_f32 v[68:69], v[44:45], v[72:73]
	s_waitcnt lgkmcnt(0)
; #define SCAN_STEP(w0, w1, a0, a1, b0, b1, k0, k1, r0, r1, vi, vj, t) do { \
;                 SCAN_ROW(S0, S1, S2, S3, w0, w1, a0, a1, b0, b1, k0, k1, r0, r1, vi, (t) * 512); \
;                 SCAN_ROW(T0, T1, T2, T3, w0, w1, a0, a1, b0, b1, k0, k1, r0, r1, vj, (t) * 512 + 256); } while (0)
;     ...
;             SCAN_LOAD(w0, w1, a0, a1, b0, b1, k0, k1, r0, r1, vi, vj, 0);
; #pragma unroll
;             for (int t = 0; t < 16; t += 2) {
;                 SCAN_LOAD(W0, W1, A0, A1, B0, B1, K0, K1, R0, R1, VI, VJ, t + 1);
;                 SCAN_STEP(w0, w1, a0, a1, b0, b1, k0, k1, r0, r1, vi, vj, t);
;                 if (t + 2 < 16) SCAN_LOAD(w0, w1, a0, a1, b0, b1, k0, k1, r0, r1, vi, vj, t + 2);
;                 SCAN_STEP(W0, W1, A0, A1, B0, B1, K0, K1, R0, R1, VI, VJ, t + 1);
	v_pk_mul_f32 v[70:71], v[54:55], v[74:75]
	v_pk_mul_f32 v[74:75], v[56:57], v[76:77]
	v_pk_mul_f32 v[42:43], v[42:43], v[46:47]
	v_pk_mul_f32 v[46:47], v[54:55], v[50:51]
	v_pk_mul_f32 v[50:51], v[56:57], v[52:53]
	v_add_f32_e32 v58, v58, v59
	v_add_f32_e32 v59, v60, v61
	v_pk_fma_f32 v[54:55], v[40:41], v[72:73], v[62:63]
	v_pk_fma_f32 v[56:57], v[36:37], v[76:77], v[64:65]
	v_pk_fma_f32 v[38:39], v[40:41], v[48:49], v[38:39]
	v_pk_fma_f32 v[34:35], v[36:37], v[52:53], v[34:35]
	v_add_u32_e32 v25, 0x4400, v21
	v_mov_b32_e32 v78, v83
	v_pk_mul_f32 v[44:45], v[44:45], v[48:49]
	v_pk_fma_f32 v[66:67], v[82:83], v[12:13], v[66:67] op_sel_hi:[0,1,1]
	v_pk_fma_f32 v[68:69], v[82:83], v[14:15], v[68:69] op_sel_hi:[0,1,1]
	v_pk_fma_f32 v[70:71], v[82:83], v[8:9], v[70:71] op_sel_hi:[0,1,1]
	v_pk_fma_f32 v[72:73], v[82:83], v[10:11], v[74:75] op_sel_hi:[0,1,1]
	ds_write2st64_b32 v19, v58, v59 offset0:72 offset1:76
	v_pk_add_f32 v[82:83], v[56:57], v[54:55]
	v_pk_add_f32 v[84:85], v[34:35], v[38:39]
	v_pk_fma_f32 v[74:75], v[78:79], v[12:13], v[42:43] op_sel_hi:[0,1,1]
	v_pk_fma_f32 v[76:77], v[78:79], v[14:15], v[44:45] op_sel_hi:[0,1,1]
	v_pk_fma_f32 v[80:81], v[78:79], v[8:9], v[46:47] op_sel_hi:[0,1,1]
	v_pk_fma_f32 v[78:79], v[78:79], v[10:11], v[50:51] op_sel_hi:[0,1,1]
	ds_read_b128 v[8:11], v20 offset:16896
	ds_read_b128 v[12:15], v20 offset:16912
	ds_read_b128 v[34:37], v20 offset:17152
	ds_read_b128 v[38:41], v20 offset:17168
	ds_read_b128 v[42:45], v20 offset:17408
	ds_read_b128 v[46:49], v20 offset:17424
	ds_read_b128 v[50:53], v20 offset:17664
	ds_read_b128 v[54:57], v20 offset:17680
	ds_read_b128 v[58:61], v20 offset:17920
	ds_read_b128 v[62:65], v20 offset:17936
	ds_read2_b32 v[86:87], v25 offset0:192 offset1:200
	v_add_f32_e32 v25, v82, v83
	v_add_f32_e32 v82, v84, v85
	v_add_u32_e32 v24, 0x4c00, v21
	v_add_f32_dpp v25, v25, v25 quad_perm:[1,0,3,2] row_mask:0xf bank_mask:0xf bound_ctrl:1
	v_add_f32_dpp v82, v82, v82 quad_perm:[1,0,3,2] row_mask:0xf bank_mask:0xf bound_ctrl:1
	s_waitcnt lgkmcnt(0)
	v_mov_b32_e32 v88, v87
	v_add_f32_dpp v25, v25, v25 quad_perm:[2,3,0,1] row_mask:0xf bank_mask:0xf bound_ctrl:1
	v_add_f32_dpp v83, v82, v82 quad_perm:[2,3,0,1] row_mask:0xf bank_mask:0xf bound_ctrl:1
	v_add_u32_e32 v23, 0x5000, v21
	v_add_f32_dpp v82, v25, v25 row_half_mirror row_mask:0xf bank_mask:0xf bound_ctrl:1
	v_add_f32_dpp v84, v83, v83 row_half_mirror row_mask:0xf bank_mask:0xf bound_ctrl:1
	v_pk_fma_f32 v[66:67], v[30:31], v[82:83], v[66:67] op_sel_hi:[1,0,1]
	v_pk_fma_f32 v[70:71], v[26:27], v[82:83], v[70:71] op_sel_hi:[1,0,1]
	v_pk_fma_f32 v[30:31], v[30:31], v[84:85], v[74:75] op_sel_hi:[1,0,1]
	v_pk_fma_f32 v[26:27], v[26:27], v[84:85], v[80:81] op_sel_hi:[1,0,1]
	v_pk_fma_f32 v[68:69], v[32:33], v[82:83], v[68:69] op_sel_hi:[1,0,1]
	v_pk_fma_f32 v[72:73], v[28:29], v[82:83], v[72:73] op_sel_hi:[1,0,1]
	v_pk_fma_f32 v[32:33], v[32:33], v[84:85], v[76:77] op_sel_hi:[1,0,1]
	v_pk_fma_f32 v[28:29], v[28:29], v[84:85], v[78:79] op_sel_hi:[1,0,1]
	v_pk_mul_f32 v[74:75], v[4:5], v[66:67]
	v_pk_mul_f32 v[76:77], v[0:1], v[70:71]
	v_pk_mul_f32 v[4:5], v[4:5], v[30:31]
	v_pk_mul_f32 v[0:1], v[0:1], v[26:27]
	v_pk_mul_f32 v[78:79], v[34:35], v[66:67]
	v_pk_mul_f32 v[80:81], v[38:39], v[70:71]
	v_pk_mul_f32 v[34:35], v[34:35], v[30:31]
	v_pk_mul_f32 v[38:39], v[38:39], v[26:27]
	v_pk_mul_f32 v[66:67], v[8:9], v[66:67]
	v_pk_mul_f32 v[82:83], v[10:11], v[68:69]
	v_pk_mul_f32 v[70:71], v[12:13], v[70:71]
	v_pk_mul_f32 v[84:85], v[14:15], v[72:73]
	v_pk_mul_f32 v[8:9], v[8:9], v[30:31]
	v_pk_mul_f32 v[10:11], v[10:11], v[32:33]
	v_pk_mul_f32 v[12:13], v[12:13], v[26:27]
	v_pk_mul_f32 v[14:15], v[14:15], v[28:29]
	v_pk_fma_f32 v[26:27], v[6:7], v[68:69], v[74:75]
	v_pk_fma_f32 v[30:31], v[2:3], v[72:73], v[76:77]
	v_pk_fma_f32 v[4:5], v[6:7], v[32:33], v[4:5]
	v_pk_fma_f32 v[0:1], v[2:3], v[28:29], v[0:1]
	v_pk_fma_f32 v[2:3], v[36:37], v[68:69], v[78:79]
	v_pk_fma_f32 v[6:7], v[40:41], v[72:73], v[80:81]
	v_pk_fma_f32 v[32:33], v[36:37], v[32:33], v[34:35]
	v_pk_fma_f32 v[28:29], v[40:41], v[28:29], v[38:39]
	v_pk_add_f32 v[0:1], v[4:5], v[0:1]
	v_pk_add_f32 v[2:3], v[2:3], v[6:7]
	v_pk_add_f32 v[4:5], v[32:33], v[28:29]
	v_pk_fma_f32 v[40:41], v[50:51], v[88:89], v[8:9] op_sel_hi:[1,0,1]
	v_pk_add_f32 v[8:9], v[26:27], v[30:31]
	v_add_f32_e32 v0, v0, v1
	v_add_f32_e32 v1, v2, v3
	v_add_f32_e32 v2, v4, v5
	v_pk_fma_f32 v[68:69], v[52:53], v[86:87], v[82:83] op_sel_hi:[1,0,1]
	v_add_f32_e32 v6, v8, v9
	v_add_f32_dpp v82, v1, v1 quad_perm:[1,0,3,2] row_mask:0xf bank_mask:0xf bound_ctrl:1
	v_add_f32_dpp v83, v2, v2 quad_perm:[1,0,3,2] row_mask:0xf bank_mask:0xf bound_ctrl:1
	ds_write2st64_b32 v19, v6, v0 offset0:80 offset1:84
	v_add_f32_dpp v82, v82, v82 quad_perm:[2,3,0,1] row_mask:0xf bank_mask:0xf bound_ctrl:1
	v_add_f32_dpp v83, v83, v83 quad_perm:[2,3,0,1] row_mask:0xf bank_mask:0xf bound_ctrl:1
	v_pk_fma_f32 v[66:67], v[50:51], v[86:87], v[66:67] op_sel_hi:[1,0,1]
	v_pk_fma_f32 v[70:71], v[54:55], v[86:87], v[70:71] op_sel_hi:[1,0,1]
	v_pk_fma_f32 v[72:73], v[56:57], v[86:87], v[84:85] op_sel_hi:[1,0,1]
	v_pk_fma_f32 v[74:75], v[52:53], v[88:89], v[10:11] op_sel_hi:[1,0,1]
	v_pk_fma_f32 v[76:77], v[54:55], v[88:89], v[12:13] op_sel_hi:[1,0,1]
	v_pk_fma_f32 v[78:79], v[56:57], v[88:89], v[14:15] op_sel_hi:[1,0,1]
	ds_read2_b32 v[80:81], v24 offset0:64 offset1:72
	ds_read_b128 v[0:3], v20 offset:19472
	ds_read_b128 v[4:7], v20 offset:19456
	ds_read_b128 v[8:11], v20 offset:19216
	ds_read_b128 v[12:15], v20 offset:19200
	ds_read_b128 v[24:27], v20 offset:18960
	ds_read_b128 v[28:31], v20 offset:18944
	ds_read_b128 v[32:35], v20 offset:18704
	ds_read_b128 v[36:39], v20 offset:18688
	ds_read_b128 v[50:53], v20 offset:18432
	ds_read_b128 v[54:57], v20 offset:18448
	v_add_f32_dpp v82, v82, v82 row_half_mirror row_mask:0xf bank_mask:0xf bound_ctrl:1
	v_add_f32_dpp v84, v83, v83 row_half_mirror row_mask:0xf bank_mask:0xf bound_ctrl:1
	v_pk_fma_f32 v[66:67], v[42:43], v[82:83], v[66:67] op_sel_hi:[1,0,1]
	v_pk_fma_f32 v[68:69], v[44:45], v[82:83], v[68:69] op_sel_hi:[1,0,1]
	v_pk_fma_f32 v[70:71], v[46:47], v[82:83], v[70:71] op_sel_hi:[1,0,1]
	v_pk_fma_f32 v[40:41], v[42:43], v[84:85], v[40:41] op_sel_hi:[1,0,1]
	v_pk_fma_f32 v[42:43], v[44:45], v[84:85], v[74:75] op_sel_hi:[1,0,1]
	v_pk_fma_f32 v[44:45], v[46:47], v[84:85], v[76:77] op_sel_hi:[1,0,1]
	v_pk_fma_f32 v[72:73], v[48:49], v[82:83], v[72:73] op_sel_hi:[1,0,1]
	v_pk_fma_f32 v[46:47], v[48:49], v[84:85], v[78:79] op_sel_hi:[1,0,1]
	v_pk_mul_f32 v[48:49], v[58:59], v[66:67]
	v_pk_mul_f32 v[74:75], v[62:63], v[70:71]
	v_pk_mul_f32 v[58:59], v[58:59], v[40:41]
	v_pk_mul_f32 v[62:63], v[62:63], v[44:45]
	v_pk_fma_f32 v[48:49], v[60:61], v[68:69], v[48:49]
	v_pk_fma_f32 v[74:75], v[64:65], v[72:73], v[74:75]
	v_pk_fma_f32 v[58:59], v[60:61], v[42:43], v[58:59]
	v_pk_fma_f32 v[60:61], v[64:65], v[46:47], v[62:63]
	v_pk_add_f32 v[48:49], v[48:49], v[74:75]
	v_pk_add_f32 v[58:59], v[58:59], v[60:61]
	s_waitcnt lgkmcnt(2)
; #define SCAN_STEP(w0, w1, a0, a1, b0, b1, k0, k1, r0, r1, vi, vj, t) do { \
;                 SCAN_ROW(S0, S1, S2, S3, w0, w1, a0, a1, b0, b1, k0, k1, r0, r1, vi, (t) * 512); \
;                 SCAN_ROW(T0, T1, T2, T3, w0, w1, a0, a1, b0, b1, k0, k1, r0, r1, vj, (t) * 512 + 256); } while (0)
;     ...
;             SCAN_LOAD(w0, w1, a0, a1, b0, b1, k0, k1, r0, r1, vi, vj, 0);
; #pragma unroll
;             for (int t = 0; t < 16; t += 2) {
;                 SCAN_LOAD(W0, W1, A0, A1, B0, B1, K0, K1, R0, R1, VI, VJ, t + 1);
;                 SCAN_STEP(w0, w1, a0, a1, b0, b1, k0, k1, r0, r1, vi, vj, t);
;                 if (t + 2 < 16) SCAN_LOAD(w0, w1, a0, a1, b0, b1, k0, k1, r0, r1, vi, vj, t + 2);
;                 SCAN_STEP(W0, W1, A0, A1, B0, B1, K0, K1, R0, R1, VI, VJ, t + 1);
	v_pk_mul_f32 v[60:61], v[36:37], v[66:67]
	v_pk_mul_f32 v[62:63], v[32:33], v[70:71]
	v_pk_mul_f32 v[36:37], v[36:37], v[40:41]
	v_pk_mul_f32 v[32:33], v[32:33], v[44:45]
	s_waitcnt lgkmcnt(1)
	v_pk_mul_f32 v[64:65], v[50:51], v[66:67]
	v_pk_mul_f32 v[66:67], v[52:53], v[68:69]
	s_waitcnt lgkmcnt(0)
	v_pk_mul_f32 v[70:71], v[54:55], v[70:71]
	v_pk_mul_f32 v[74:75], v[56:57], v[72:73]
	v_pk_mul_f32 v[40:41], v[50:51], v[40:41]
	v_pk_mul_f32 v[50:51], v[52:53], v[42:43]
	v_pk_mul_f32 v[44:45], v[54:55], v[44:45]
	v_pk_mul_f32 v[52:53], v[56:57], v[46:47]
	v_add_f32_e32 v56, v48, v49
	v_add_f32_e32 v57, v58, v59
	v_pk_fma_f32 v[48:49], v[38:39], v[68:69], v[60:61]
	v_pk_fma_f32 v[54:55], v[34:35], v[72:73], v[62:63]
	v_pk_fma_f32 v[36:37], v[38:39], v[42:43], v[36:37]
	v_pk_fma_f32 v[32:33], v[34:35], v[46:47], v[32:33]
	v_mov_b32_e32 v76, v81
	v_pk_fma_f32 v[64:65], v[80:81], v[12:13], v[64:65] op_sel_hi:[0,1,1]
	v_pk_fma_f32 v[66:67], v[80:81], v[14:15], v[66:67] op_sel_hi:[0,1,1]
	v_pk_fma_f32 v[68:69], v[80:81], v[8:9], v[70:71] op_sel_hi:[0,1,1]
	v_pk_fma_f32 v[70:71], v[80:81], v[10:11], v[74:75] op_sel_hi:[0,1,1]
	ds_write2st64_b32 v19, v56, v57 offset0:88 offset1:92
	v_pk_add_f32 v[80:81], v[54:55], v[48:49]
	v_pk_add_f32 v[82:83], v[32:33], v[36:37]
	v_pk_fma_f32 v[72:73], v[76:77], v[12:13], v[40:41] op_sel_hi:[0,1,1]
	v_pk_fma_f32 v[74:75], v[76:77], v[14:15], v[50:51] op_sel_hi:[0,1,1]
	v_pk_fma_f32 v[78:79], v[76:77], v[8:9], v[44:45] op_sel_hi:[0,1,1]
	v_pk_fma_f32 v[76:77], v[76:77], v[10:11], v[52:53] op_sel_hi:[0,1,1]
	ds_read_b128 v[8:11], v20 offset:19968
	ds_read_b128 v[12:15], v20 offset:19984
	ds_read_b128 v[32:35], v20 offset:20224
	ds_read_b128 v[36:39], v20 offset:20240
	ds_read_b128 v[40:43], v20 offset:20480
	ds_read_b128 v[44:47], v20 offset:20496
	ds_read_b128 v[48:51], v20 offset:20736
	ds_read_b128 v[52:55], v20 offset:20752
	ds_read_b128 v[56:59], v20 offset:20992
	ds_read_b128 v[60:63], v20 offset:21008
	ds_read2_b32 v[84:85], v23 offset0:192 offset1:200
	v_add_f32_e32 v23, v80, v81
	v_add_f32_e32 v80, v82, v83
	v_add_u32_e32 v22, 0x5800, v21
	v_add_f32_dpp v23, v23, v23 quad_perm:[1,0,3,2] row_mask:0xf bank_mask:0xf bound_ctrl:1
	v_add_f32_dpp v80, v80, v80 quad_perm:[1,0,3,2] row_mask:0xf bank_mask:0xf bound_ctrl:1
	s_waitcnt lgkmcnt(0)
	v_mov_b32_e32 v86, v85
	v_add_f32_dpp v23, v23, v23 quad_perm:[2,3,0,1] row_mask:0xf bank_mask:0xf bound_ctrl:1
	v_add_f32_dpp v81, v80, v80 quad_perm:[2,3,0,1] row_mask:0xf bank_mask:0xf bound_ctrl:1
	v_add_u32_e32 v21, 0x5c00, v21
	v_add_f32_dpp v80, v23, v23 row_half_mirror row_mask:0xf bank_mask:0xf bound_ctrl:1
	v_add_f32_dpp v82, v81, v81 row_half_mirror row_mask:0xf bank_mask:0xf bound_ctrl:1
	v_pk_fma_f32 v[64:65], v[28:29], v[80:81], v[64:65] op_sel_hi:[1,0,1]
	v_pk_fma_f32 v[68:69], v[24:25], v[80:81], v[68:69] op_sel_hi:[1,0,1]
	v_pk_fma_f32 v[28:29], v[28:29], v[82:83], v[72:73] op_sel_hi:[1,0,1]
	v_pk_fma_f32 v[24:25], v[24:25], v[82:83], v[78:79] op_sel_hi:[1,0,1]
	v_pk_fma_f32 v[66:67], v[30:31], v[80:81], v[66:67] op_sel_hi:[1,0,1]
	v_pk_fma_f32 v[70:71], v[26:27], v[80:81], v[70:71] op_sel_hi:[1,0,1]
	v_pk_fma_f32 v[30:31], v[30:31], v[82:83], v[74:75] op_sel_hi:[1,0,1]
	v_pk_fma_f32 v[26:27], v[26:27], v[82:83], v[76:77] op_sel_hi:[1,0,1]
	v_pk_mul_f32 v[72:73], v[4:5], v[64:65]
	v_pk_mul_f32 v[74:75], v[0:1], v[68:69]
	v_pk_mul_f32 v[4:5], v[4:5], v[28:29]
	v_pk_mul_f32 v[0:1], v[0:1], v[24:25]
	v_pk_mul_f32 v[76:77], v[32:33], v[64:65]
	v_pk_mul_f32 v[78:79], v[36:37], v[68:69]
	v_pk_mul_f32 v[32:33], v[32:33], v[28:29]
	v_pk_mul_f32 v[36:37], v[36:37], v[24:25]
	v_pk_mul_f32 v[64:65], v[8:9], v[64:65]
	v_pk_mul_f32 v[80:81], v[10:11], v[66:67]
	v_pk_mul_f32 v[68:69], v[12:13], v[68:69]
	v_pk_mul_f32 v[82:83], v[14:15], v[70:71]
	v_pk_mul_f32 v[8:9], v[8:9], v[28:29]
	v_pk_mul_f32 v[10:11], v[10:11], v[30:31]
	v_pk_mul_f32 v[12:13], v[12:13], v[24:25]
	v_pk_mul_f32 v[14:15], v[14:15], v[26:27]
	v_pk_fma_f32 v[24:25], v[6:7], v[66:67], v[72:73]
	v_pk_fma_f32 v[28:29], v[2:3], v[70:71], v[74:75]
	v_pk_fma_f32 v[4:5], v[6:7], v[30:31], v[4:5]
	v_pk_fma_f32 v[0:1], v[2:3], v[26:27], v[0:1]
	v_pk_fma_f32 v[2:3], v[34:35], v[66:67], v[76:77]
	v_pk_fma_f32 v[6:7], v[38:39], v[70:71], v[78:79]
	v_pk_fma_f32 v[30:31], v[34:35], v[30:31], v[32:33]
	v_pk_fma_f32 v[26:27], v[38:39], v[26:27], v[36:37]
	v_pk_add_f32 v[0:1], v[4:5], v[0:1]
	v_pk_add_f32 v[2:3], v[2:3], v[6:7]
	v_pk_add_f32 v[4:5], v[30:31], v[26:27]
	v_pk_fma_f32 v[38:39], v[48:49], v[86:87], v[8:9] op_sel_hi:[1,0,1]
	v_pk_add_f32 v[8:9], v[24:25], v[28:29]
	v_add_f32_e32 v0, v0, v1
	v_add_f32_e32 v1, v2, v3
	v_add_f32_e32 v2, v4, v5
	v_pk_fma_f32 v[66:67], v[50:51], v[84:85], v[80:81] op_sel_hi:[1,0,1]
	v_add_f32_e32 v6, v8, v9
	v_add_f32_dpp v80, v1, v1 quad_perm:[1,0,3,2] row_mask:0xf bank_mask:0xf bound_ctrl:1
	v_add_f32_dpp v81, v2, v2 quad_perm:[1,0,3,2] row_mask:0xf bank_mask:0xf bound_ctrl:1
	ds_write2st64_b32 v19, v6, v0 offset0:96 offset1:100
	v_add_f32_dpp v80, v80, v80 quad_perm:[2,3,0,1] row_mask:0xf bank_mask:0xf bound_ctrl:1
	v_add_f32_dpp v81, v81, v81 quad_perm:[2,3,0,1] row_mask:0xf bank_mask:0xf bound_ctrl:1
	v_pk_fma_f32 v[64:65], v[48:49], v[84:85], v[64:65] op_sel_hi:[1,0,1]
	v_pk_fma_f32 v[68:69], v[52:53], v[84:85], v[68:69] op_sel_hi:[1,0,1]
	v_pk_fma_f32 v[70:71], v[54:55], v[84:85], v[82:83] op_sel_hi:[1,0,1]
	v_pk_fma_f32 v[72:73], v[50:51], v[86:87], v[10:11] op_sel_hi:[1,0,1]
	v_pk_fma_f32 v[74:75], v[52:53], v[86:87], v[12:13] op_sel_hi:[1,0,1]
	v_pk_fma_f32 v[76:77], v[54:55], v[86:87], v[14:15] op_sel_hi:[1,0,1]
	ds_read2_b32 v[78:79], v22 offset0:64 offset1:72
; #define SCAN_STEP(w0, w1, a0, a1, b0, b1, k0, k1, r0, r1, vi, vj, t) do { \
;                 SCAN_ROW(S0, S1, S2, S3, w0, w1, a0, a1, b0, b1, k0, k1, r0, r1, vi, (t) * 512); \
;                 SCAN_ROW(T0, T1, T2, T3, w0, w1, a0, a1, b0, b1, k0, k1, r0, r1, vj, (t) * 512 + 256); } while (0)
;     ...
;             SCAN_LOAD(w0, w1, a0, a1, b0, b1, k0, k1, r0, r1, vi, vj, 0);
; #pragma unroll
;             for (int t = 0; t < 16; t += 2) {
;                 SCAN_LOAD(W0, W1, A0, A1, B0, B1, K0, K1, R0, R1, VI, VJ, t + 1);
;                 SCAN_STEP(w0, w1, a0, a1, b0, b1, k0, k1, r0, r1, vi, vj, t);
;                 if (t + 2 < 16) SCAN_LOAD(w0, w1, a0, a1, b0, b1, k0, k1, r0, r1, vi, vj, t + 2);
;                 SCAN_STEP(W0, W1, A0, A1, B0, B1, K0, K1, R0, R1, VI, VJ, t + 1);
	ds_read_b128 v[0:3], v20 offset:22544
	ds_read_b128 v[4:7], v20 offset:22528
	ds_read_b128 v[8:11], v20 offset:22288
	ds_read_b128 v[12:15], v20 offset:22272
	ds_read_b128 v[22:25], v20 offset:22032
	ds_read_b128 v[26:29], v20 offset:22016
	ds_read_b128 v[30:33], v20 offset:21776
	ds_read_b128 v[34:37], v20 offset:21760
	ds_read_b128 v[48:51], v20 offset:21504
	ds_read_b128 v[52:55], v20 offset:21520
	v_add_f32_dpp v80, v80, v80 row_half_mirror row_mask:0xf bank_mask:0xf bound_ctrl:1
	v_add_f32_dpp v82, v81, v81 row_half_mirror row_mask:0xf bank_mask:0xf bound_ctrl:1
	v_pk_fma_f32 v[64:65], v[40:41], v[80:81], v[64:65] op_sel_hi:[1,0,1]
	v_pk_fma_f32 v[66:67], v[42:43], v[80:81], v[66:67] op_sel_hi:[1,0,1]
	v_pk_fma_f32 v[68:69], v[44:45], v[80:81], v[68:69] op_sel_hi:[1,0,1]
	v_pk_fma_f32 v[38:39], v[40:41], v[82:83], v[38:39] op_sel_hi:[1,0,1]
	v_pk_fma_f32 v[40:41], v[42:43], v[82:83], v[72:73] op_sel_hi:[1,0,1]
	v_pk_fma_f32 v[42:43], v[44:45], v[82:83], v[74:75] op_sel_hi:[1,0,1]
	v_pk_fma_f32 v[70:71], v[46:47], v[80:81], v[70:71] op_sel_hi:[1,0,1]
	v_pk_fma_f32 v[44:45], v[46:47], v[82:83], v[76:77] op_sel_hi:[1,0,1]
	v_pk_mul_f32 v[46:47], v[56:57], v[64:65]
	v_pk_mul_f32 v[72:73], v[60:61], v[68:69]
	v_pk_mul_f32 v[56:57], v[56:57], v[38:39]
	v_pk_mul_f32 v[60:61], v[60:61], v[42:43]
	v_pk_fma_f32 v[46:47], v[58:59], v[66:67], v[46:47]
	v_pk_fma_f32 v[72:73], v[62:63], v[70:71], v[72:73]
	v_pk_fma_f32 v[56:57], v[58:59], v[40:41], v[56:57]
	v_pk_fma_f32 v[58:59], v[62:63], v[44:45], v[60:61]
	v_pk_add_f32 v[46:47], v[46:47], v[72:73]
	v_pk_add_f32 v[56:57], v[56:57], v[58:59]
	s_waitcnt lgkmcnt(2)
	v_pk_mul_f32 v[58:59], v[34:35], v[64:65]
	v_pk_mul_f32 v[60:61], v[30:31], v[68:69]
	v_pk_mul_f32 v[34:35], v[34:35], v[38:39]
	v_pk_mul_f32 v[30:31], v[30:31], v[42:43]
	s_waitcnt lgkmcnt(1)
	v_pk_mul_f32 v[62:63], v[48:49], v[64:65]
	v_pk_mul_f32 v[64:65], v[50:51], v[66:67]
	s_waitcnt lgkmcnt(0)
	v_pk_mul_f32 v[68:69], v[52:53], v[68:69]
	v_pk_mul_f32 v[72:73], v[54:55], v[70:71]
	v_pk_mul_f32 v[38:39], v[48:49], v[38:39]
	v_pk_mul_f32 v[48:49], v[50:51], v[40:41]
	v_pk_mul_f32 v[42:43], v[52:53], v[42:43]
	v_pk_mul_f32 v[50:51], v[54:55], v[44:45]
	v_add_f32_e32 v54, v46, v47
	v_pk_fma_f32 v[46:47], v[36:37], v[66:67], v[58:59]
	v_pk_fma_f32 v[52:53], v[32:33], v[70:71], v[60:61]
	v_pk_fma_f32 v[34:35], v[36:37], v[40:41], v[34:35]
	v_pk_fma_f32 v[30:31], v[32:33], v[44:45], v[30:31]
	v_mov_b32_e32 v74, v79
	v_add_f32_e32 v55, v56, v57
	v_pk_fma_f32 v[62:63], v[78:79], v[12:13], v[62:63] op_sel_hi:[0,1,1]
	v_pk_fma_f32 v[64:65], v[78:79], v[14:15], v[64:65] op_sel_hi:[0,1,1]
	v_pk_fma_f32 v[66:67], v[78:79], v[8:9], v[68:69] op_sel_hi:[0,1,1]
	v_pk_fma_f32 v[68:69], v[78:79], v[10:11], v[72:73] op_sel_hi:[0,1,1]
	v_pk_add_f32 v[78:79], v[52:53], v[46:47]
	v_pk_add_f32 v[80:81], v[30:31], v[34:35]
	ds_write2st64_b32 v19, v54, v55 offset0:104 offset1:108
	v_add_f32_e32 v78, v78, v79
	v_add_f32_e32 v79, v80, v81
	v_pk_fma_f32 v[70:71], v[74:75], v[12:13], v[38:39] op_sel_hi:[0,1,1]
	v_pk_fma_f32 v[72:73], v[74:75], v[14:15], v[48:49] op_sel_hi:[0,1,1]
	v_pk_fma_f32 v[76:77], v[74:75], v[8:9], v[42:43] op_sel_hi:[0,1,1]
	v_pk_fma_f32 v[74:75], v[74:75], v[10:11], v[50:51] op_sel_hi:[0,1,1]
	ds_read_b128 v[8:11], v20 offset:23040
	ds_read_b128 v[12:15], v20 offset:23056
	ds_read_b128 v[30:33], v20 offset:23296
	ds_read_b128 v[34:37], v20 offset:23312
	ds_read_b128 v[38:41], v20 offset:23552
	ds_read_b128 v[42:45], v20 offset:23568
	ds_read_b128 v[46:49], v20 offset:23808
	ds_read_b128 v[50:53], v20 offset:23824
	ds_read_b128 v[54:57], v20 offset:24064
	ds_read_b128 v[58:61], v20 offset:24080
	ds_read2_b32 v[20:21], v21 offset0:192 offset1:200
	v_add_f32_dpp v78, v78, v78 quad_perm:[1,0,3,2] row_mask:0xf bank_mask:0xf bound_ctrl:1
	v_add_f32_dpp v79, v79, v79 quad_perm:[1,0,3,2] row_mask:0xf bank_mask:0xf bound_ctrl:1
	s_add_i32 s3, s3, 1
	v_add_f32_dpp v78, v78, v78 quad_perm:[2,3,0,1] row_mask:0xf bank_mask:0xf bound_ctrl:1
	v_add_f32_dpp v79, v79, v79 quad_perm:[2,3,0,1] row_mask:0xf bank_mask:0xf bound_ctrl:1
	s_waitcnt lgkmcnt(0)
; #define SCAN_STEP(w0, w1, a0, a1, b0, b1, k0, k1, r0, r1, vi, vj, t) do { \
;                 SCAN_ROW(S0, S1, S2, S3, w0, w1, a0, a1, b0, b1, k0, k1, r0, r1, vi, (t) * 512); \
;                 SCAN_ROW(T0, T1, T2, T3, w0, w1, a0, a1, b0, b1, k0, k1, r0, r1, vj, (t) * 512 + 256); } while (0)
;     ...
;             SCAN_LOAD(w0, w1, a0, a1, b0, b1, k0, k1, r0, r1, vi, vj, 0);
; #pragma unroll
;             for (int t = 0; t < 16; t += 2) {
;                 SCAN_LOAD(W0, W1, A0, A1, B0, B1, K0, K1, R0, R1, VI, VJ, t + 1);
;                 SCAN_STEP(w0, w1, a0, a1, b0, b1, k0, k1, r0, r1, vi, vj, t);
;                 if (t + 2 < 16) SCAN_LOAD(w0, w1, a0, a1, b0, b1, k0, k1, r0, r1, vi, vj, t + 2);
;                 SCAN_STEP(W0, W1, A0, A1, B0, B1, K0, K1, R0, R1, VI, VJ, t + 1);
;             }
;     ...
;             __syncthreads();
;         }
;         float* so = P.out + (samp ? O_RS + ((size_t)(l * 16 + b) * 16 + h) * 4096 : O_RP + ((size_t)(l * 4 + b) * 16 + h) * 4096) + js;
;         f32x4 o0, o1; o0.xy = S0; o0.zw = S1; o1.xy = S2; o1.zw = S3;
;         *(f32x4*)(so + i0 * 64) = o0; *(f32x4*)(so + i0 * 64 + 4) = o1;
;         o0.xy = T0; o0.zw = T1; o1.xy = T2; o1.zw = T3;
;         *(f32x4*)(so + i1 * 64) = o0; *(f32x4*)(so + i1 * 64 + 4) = o1;
	v_mov_b32_e32 v82, v21
	v_add_f32_dpp v78, v78, v78 row_half_mirror row_mask:0xf bank_mask:0xf bound_ctrl:1
	v_add_f32_dpp v80, v79, v79 row_half_mirror row_mask:0xf bank_mask:0xf bound_ctrl:1
	v_pk_fma_f32 v[62:63], v[26:27], v[78:79], v[62:63] op_sel_hi:[1,0,1]
	v_pk_fma_f32 v[66:67], v[22:23], v[78:79], v[66:67] op_sel_hi:[1,0,1]
	v_pk_fma_f32 v[26:27], v[26:27], v[80:81], v[70:71] op_sel_hi:[1,0,1]
	v_pk_fma_f32 v[22:23], v[22:23], v[80:81], v[76:77] op_sel_hi:[1,0,1]
	v_pk_fma_f32 v[64:65], v[28:29], v[78:79], v[64:65] op_sel_hi:[1,0,1]
	v_pk_fma_f32 v[68:69], v[24:25], v[78:79], v[68:69] op_sel_hi:[1,0,1]
	v_pk_fma_f32 v[28:29], v[28:29], v[80:81], v[72:73] op_sel_hi:[1,0,1]
	v_pk_fma_f32 v[24:25], v[24:25], v[80:81], v[74:75] op_sel_hi:[1,0,1]
	v_pk_mul_f32 v[70:71], v[4:5], v[62:63]
	v_pk_mul_f32 v[72:73], v[0:1], v[66:67]
	v_pk_mul_f32 v[4:5], v[4:5], v[26:27]
	v_pk_mul_f32 v[0:1], v[0:1], v[22:23]
	v_pk_mul_f32 v[74:75], v[30:31], v[62:63]
	v_pk_mul_f32 v[76:77], v[34:35], v[66:67]
	v_pk_mul_f32 v[30:31], v[30:31], v[26:27]
	v_pk_mul_f32 v[34:35], v[34:35], v[22:23]
	v_pk_mul_f32 v[62:63], v[8:9], v[62:63]
	v_pk_mul_f32 v[78:79], v[10:11], v[64:65]
	v_pk_mul_f32 v[66:67], v[12:13], v[66:67]
	v_pk_mul_f32 v[80:81], v[14:15], v[68:69]
	v_pk_mul_f32 v[8:9], v[8:9], v[26:27]
	v_pk_mul_f32 v[10:11], v[10:11], v[28:29]
	v_pk_mul_f32 v[12:13], v[12:13], v[22:23]
	v_pk_mul_f32 v[14:15], v[14:15], v[24:25]
	v_pk_fma_f32 v[22:23], v[6:7], v[64:65], v[70:71]
	v_pk_fma_f32 v[26:27], v[2:3], v[68:69], v[72:73]
	v_pk_fma_f32 v[4:5], v[6:7], v[28:29], v[4:5]
	v_pk_fma_f32 v[0:1], v[2:3], v[24:25], v[0:1]
	v_pk_fma_f32 v[2:3], v[32:33], v[64:65], v[74:75]
	v_pk_fma_f32 v[6:7], v[36:37], v[68:69], v[76:77]
	v_pk_fma_f32 v[28:29], v[32:33], v[28:29], v[30:31]
	v_pk_fma_f32 v[24:25], v[36:37], v[24:25], v[34:35]
	v_pk_fma_f32 v[30:31], v[46:47], v[82:83], v[8:9] op_sel_hi:[1,0,1]
	v_pk_add_f32 v[8:9], v[22:23], v[26:27]
	v_pk_add_f32 v[0:1], v[4:5], v[0:1]
	v_pk_add_f32 v[2:3], v[2:3], v[6:7]
	v_pk_add_f32 v[4:5], v[28:29], v[24:25]
	v_add_f32_e32 v6, v8, v9
	v_add_f32_e32 v0, v0, v1
	v_add_f32_e32 v1, v2, v3
	v_add_f32_e32 v2, v4, v5
	ds_write2st64_b32 v19, v6, v0 offset0:112 offset1:116
	v_add_f32_dpp v0, v1, v1 quad_perm:[1,0,3,2] row_mask:0xf bank_mask:0xf bound_ctrl:1
	v_add_f32_dpp v1, v2, v2 quad_perm:[1,0,3,2] row_mask:0xf bank_mask:0xf bound_ctrl:1
	v_pk_fma_f32 v[62:63], v[46:47], v[20:21], v[62:63] op_sel_hi:[1,0,1]
	v_add_f32_dpp v0, v0, v0 quad_perm:[2,3,0,1] row_mask:0xf bank_mask:0xf bound_ctrl:1
	v_add_f32_dpp v1, v1, v1 quad_perm:[2,3,0,1] row_mask:0xf bank_mask:0xf bound_ctrl:1
	v_pk_fma_f32 v[64:65], v[48:49], v[20:21], v[78:79] op_sel_hi:[1,0,1]
	v_pk_fma_f32 v[66:67], v[50:51], v[20:21], v[66:67] op_sel_hi:[1,0,1]
	v_pk_fma_f32 v[20:21], v[52:53], v[20:21], v[80:81] op_sel_hi:[1,0,1]
	v_pk_fma_f32 v[34:35], v[50:51], v[82:83], v[12:13] op_sel_hi:[1,0,1]
	v_add_f32_dpp v0, v0, v0 row_half_mirror row_mask:0xf bank_mask:0xf bound_ctrl:1
	v_add_f32_dpp v2, v1, v1 row_half_mirror row_mask:0xf bank_mask:0xf bound_ctrl:1
	v_pk_fma_f32 v[32:33], v[48:49], v[82:83], v[10:11] op_sel_hi:[1,0,1]
	v_pk_fma_f32 v[36:37], v[52:53], v[82:83], v[14:15] op_sel_hi:[1,0,1]
	v_pk_fma_f32 v[8:9], v[38:39], v[0:1], v[62:63] op_sel_hi:[1,0,1]
	v_pk_fma_f32 v[10:11], v[40:41], v[0:1], v[64:65] op_sel_hi:[1,0,1]
	v_pk_fma_f32 v[12:13], v[42:43], v[0:1], v[66:67] op_sel_hi:[1,0,1]
	v_pk_fma_f32 v[14:15], v[44:45], v[0:1], v[20:21] op_sel_hi:[1,0,1]
	v_pk_fma_f32 v[4:5], v[38:39], v[2:3], v[30:31] op_sel_hi:[1,0,1]
	v_pk_fma_f32 v[0:1], v[42:43], v[2:3], v[34:35] op_sel_hi:[1,0,1]
	v_pk_fma_f32 v[6:7], v[40:41], v[2:3], v[32:33] op_sel_hi:[1,0,1]
	v_pk_fma_f32 v[2:3], v[44:45], v[2:3], v[36:37] op_sel_hi:[1,0,1]
	v_pk_mul_f32 v[20:21], v[54:55], v[8:9]
	v_pk_mul_f32 v[22:23], v[58:59], v[12:13]
	v_pk_mul_f32 v[24:25], v[54:55], v[4:5]
	v_pk_mul_f32 v[26:27], v[58:59], v[0:1]
	v_pk_fma_f32 v[20:21], v[56:57], v[10:11], v[20:21]
	v_pk_fma_f32 v[22:23], v[60:61], v[14:15], v[22:23]
	v_pk_fma_f32 v[24:25], v[56:57], v[6:7], v[24:25]
	v_pk_fma_f32 v[26:27], v[60:61], v[2:3], v[26:27]
	v_pk_add_f32 v[20:21], v[20:21], v[22:23]
	v_pk_add_f32 v[22:23], v[24:25], v[26:27]
	s_cmpk_eq_i32 s3, 0xc8
	v_add_f32_e32 v20, v20, v21
	v_add_f32_e32 v21, v22, v23
	ds_write2st64_b32 v19, v20, v21 offset0:120 offset1:124
	s_waitcnt lgkmcnt(0)
	s_barrier
	s_cbranch_scc0 .LBB0_3706
	s_setprio 0
	s_lshl_b64 s[4:5], s[8:9], 18
	s_add_u32 s3, s72, s4
	s_addc_u32 s4, s73, s5
	s_lshl_b32 s2, s2, 14
	s_add_u32 s2, s3, s2
	s_addc_u32 s3, s4, 0
	v_lshlrev_b32_e32 v18, 2, v17
	v_mov_b32_e32 v19, 0
	v_lshlrev_b32_e32 v16, 6, v16
	v_lshl_add_u64 v[18:19], s[2:3], 0, v[18:19]
	v_ashrrev_i32_e32 v17, 31, v16
	v_lshl_add_u64 v[16:17], v[16:17], 2, v[18:19]
	s_mov_b64 s[2:3], 0x8600000
	v_lshl_add_u64 v[18:19], v[16:17], 0, s[2:3]
	s_mov_b32 s2, 0x8600000
	v_add_co_u32_e32 v16, vcc, s2, v16
	s_nop 1
	v_addc_co_u32_e32 v17, vcc, 0, v17, vcc
	global_store_dwordx4 v[16:17], v[8:11], off
	global_store_dwordx4 v[18:19], v[12:15], off offset:16
	global_store_dwordx4 v[18:19], v[4:7], off offset:2048
	global_store_dwordx4 v[18:19], v[0:3], off offset:2064

; #define SCAN_STEP(w0, w1, a0, a1, b0, b1, k0, k1, r0, r1, vi, vj, t) do { \
;                 SCAN_ROW(S0, S1, S2, S3, w0, w1, a0, a1, b0, b1, k0, k1, r0, r1, vi, (t) * 512); \
;                 SCAN_ROW(T0, T1, T2, T3, w0, w1, a0, a1, b0, b1, k0, k1, r0, r1, vj, (t) * 512 + 256); } while (0)
;     ...
;         } else if (resume) {
;             const float* s0 = P.out + O_RP + ((size_t)(l * 4 + b) * 16 + h) * 4096 + js;
;             const f32x4 a0 = *(const f32x4*)(s0 + i0 * 64), a1 = *(const f32x4*)(s0 + i0 * 64 + 4), c0v = *(const f32x4*)(s0 + i1 * 64), c1v = *(const f32x4*)(s0 + i1 * 64 + 4);
;             S0 = a0.xy; S1 = a0.zw; S2 = a1.xy; S3 = a1.zw; T0 = c0v.xy; T1 = c0v.zw; T2 = c1v.xy; T3 = c1v.zw;
;         } else { S0 = (f32x2){0.f, 0.f}; S1 = S0; S2 = S0; S3 = S0; T0 = S0; T1 = S0; T2 = S0; T3 = S0; }
;         __syncthreads();
;         for (int c = c0; c < nch; ++c) {
;             const float* bb = bufs + (c & 1) * (16 * 384) + js;
;             const float* bv = bufs + (c & 1) * (16 * 384) + 320 + i0;
;             float* yb = ybuf + (c & 1) * 8192 + w * 64 + lane;
;             f32x4 w0, w1, a0, a1, b0, b1, k0, k1, r0, r1; float vi, vj;
;             f32x4 W0, W1, A0, A1, B0, B1, K0, K1, R0, R1; float VI, VJ;
;     ...
;             SCAN_LOAD(w0, w1, a0, a1, b0, b1, k0, k1, r0, r1, vi, vj, 0);
; #pragma unroll
;             for (int t = 0; t < 16; t += 2) {
;                 SCAN_LOAD(W0, W1, A0, A1, B0, B1, K0, K1, R0, R1, VI, VJ, t + 1);
;                 SCAN_STEP(w0, w1, a0, a1, b0, b1, k0, k1, r0, r1, vi, vj, t);
.LBB0_4117:
	s_andn2_saveexec_b64 s[0:1], s[10:11]
	s_cbranch_execz .LBB0_4121
	s_lshl_b64 s[4:5], s[8:9], 18
	s_add_u32 s3, s4, 0x100000
	s_addc_u32 s6, s5, 0
	s_add_u32 s4, s72, s3
	v_lshrrev_b32_e32 v1, 3, v0
	v_lshlrev_b32_e32 v0, 3, v0
	s_addc_u32 s5, s73, s6
	s_lshl_b32 s2, s2, 14
	v_lshl_or_b32 v17, v38, 4, v1
	v_and_b32_e32 v16, 56, v0
	s_add_u32 s4, s4, s2
	s_addc_u32 s5, s5, 0
	v_mov_b32_e32 v1, 0
	v_lshlrev_b32_e32 v0, 2, v16
	v_lshlrev_b32_e32 v18, 6, v17
	v_lshl_add_u64 v[0:1], s[4:5], 0, v[0:1]
	v_ashrrev_i32_e32 v19, 31, v18
	v_lshl_add_u64 v[0:1], v[18:19], 2, v[0:1]
	s_mov_b64 s[4:5], 0x8500000
	v_lshl_add_u64 v[22:23], v[0:1], 0, s[4:5]
	s_mov_b32 s4, 0x8500000
	v_add_co_u32_e32 v24, vcc, s4, v0
	v_and_b32_e32 v20, 0x3fffffc0, v20
	s_nop 0
	v_addc_co_u32_e32 v25, vcc, 0, v1, vcc
	global_load_dwordx4 v[8:11], v[22:23], off offset:16
	global_load_dwordx4 v[0:3], v[22:23], off offset:2048
	global_load_dwordx4 v[12:15], v[24:25], off
	global_load_dwordx4 v[4:7], v[22:23], off offset:2064
	v_lshlrev_b32_e32 v20, 2, v20
	v_add3_u32 v20, 0, v20, v21
	s_movk_i32 s7, 0xc8
	s_barrier
	s_setprio 3
.LBB0_4119:
	s_and_b32 s8, s7, 1
	s_mul_i32 s4, s8, 0x6000
	s_add_i32 s4, s4, 0
	v_lshl_add_u32 v23, v17, 2, s4
	v_lshl_add_u32 v22, v16, 2, s4
	v_add_u32_e32 v31, 0x400, v23
	v_add_u32_e32 v114, 0x800, v23
	ds_read_b128 v[32:35], v22
	ds_read_b128 v[36:39], v22 offset:16
	ds_read_b128 v[40:43], v22 offset:256
	ds_read_b128 v[44:47], v22 offset:272
	ds_read_b128 v[48:51], v22 offset:512
	ds_read_b128 v[52:55], v22 offset:528
	ds_read_b128 v[56:59], v22 offset:768
	ds_read_b128 v[60:63], v22 offset:784
	ds_read_b128 v[64:67], v22 offset:1024
	ds_read_b128 v[68:71], v22 offset:1040
	ds_read_b128 v[72:75], v22 offset:1536
	ds_read_b128 v[76:79], v22 offset:1552
	ds_read_b128 v[80:83], v22 offset:1792
	s_waitcnt vmcnt(8)
	ds_read_b128 v[84:87], v22 offset:1808
	s_waitcnt vmcnt(7)
	ds_read_b128 v[88:91], v22 offset:2048
	s_waitcnt vmcnt(6)
	ds_read_b128 v[92:95], v22 offset:2064
	ds_read_b128 v[96:99], v22 offset:2304
	ds_read_b128 v[100:103], v22 offset:2320
	ds_read_b128 v[104:107], v22 offset:2560
	ds_read_b128 v[108:111], v22 offset:2576
	ds_read2_b32 v[112:113], v31 offset0:64 offset1:72
	ds_read2_b32 v[114:115], v114 offset0:192 offset1:200
	s_waitcnt vmcnt(1) lgkmcnt(14)
	v_pk_mul_f32 v[116:117], v[12:13], v[40:41]
	v_pk_mul_f32 v[118:119], v[8:9], v[44:45]
	v_pk_mul_f32 v[40:41], v[0:1], v[40:41]
	s_waitcnt vmcnt(0)
	v_pk_mul_f32 v[44:45], v[4:5], v[44:45]
	v_pk_fma_f32 v[116:117], v[14:15], v[42:43], v[116:117]
	v_pk_fma_f32 v[118:119], v[10:11], v[46:47], v[118:119]
	s_waitcnt lgkmcnt(1)
	v_pk_mul_f32 v[120:121], v[56:57], v[112:113] op_sel_hi:[1,0]
	v_pk_mul_f32 v[122:123], v[58:59], v[112:113] op_sel_hi:[1,0]
	v_pk_mul_f32 v[124:125], v[60:61], v[112:113] op_sel_hi:[1,0]
	v_pk_mul_f32 v[126:127], v[62:63], v[112:113] op_sel_hi:[1,0]
	v_mov_b32_e32 v112, v113
	v_pk_fma_f32 v[40:41], v[2:3], v[42:43], v[40:41]
	v_pk_fma_f32 v[42:43], v[6:7], v[46:47], v[44:45]
	v_pk_add_f32 v[46:47], v[116:117], v[118:119]
	v_pk_mul_f32 v[56:57], v[56:57], v[112:113] op_sel_hi:[1,0]
	v_pk_add_f32 v[40:41], v[40:41], v[42:43]
	v_pk_fma_f32 v[12:13], v[12:13], v[32:33], v[120:121]
	v_add_f32_e32 v31, v46, v47
	v_pk_fma_f32 v[0:1], v[0:1], v[32:33], v[56:57]
	v_add_f32_e32 v32, v40, v41
	v_add_f32_dpp v31, v31, v31 quad_perm:[1,0,3,2] row_mask:0xf bank_mask:0xf bound_ctrl:1
	v_pk_mul_f32 v[58:59], v[58:59], v[112:113] op_sel_hi:[1,0]
	v_add_f32_dpp v32, v32, v32 quad_perm:[1,0,3,2] row_mask:0xf bank_mask:0xf bound_ctrl:1
	v_pk_mul_f32 v[60:61], v[60:61], v[112:113] op_sel_hi:[1,0]
	v_add_f32_dpp v31, v31, v31 quad_perm:[2,3,0,1] row_mask:0xf bank_mask:0xf bound_ctrl:1
	v_add_f32_dpp v33, v32, v32 quad_perm:[2,3,0,1] row_mask:0xf bank_mask:0xf bound_ctrl:1
	v_pk_fma_f32 v[14:15], v[14:15], v[34:35], v[122:123]
	v_pk_fma_f32 v[8:9], v[8:9], v[36:37], v[124:125]
	v_pk_mul_f32 v[62:63], v[62:63], v[112:113] op_sel_hi:[1,0]
	v_pk_fma_f32 v[2:3], v[2:3], v[34:35], v[58:59]
	v_pk_fma_f32 v[4:5], v[4:5], v[36:37], v[60:61]
	v_add_f32_dpp v32, v31, v31 row_half_mirror row_mask:0xf bank_mask:0xf bound_ctrl:1
	v_add_f32_dpp v34, v33, v33 row_half_mirror row_mask:0xf bank_mask:0xf bound_ctrl:1
	v_pk_fma_f32 v[10:11], v[10:11], v[38:39], v[126:127]
	v_pk_fma_f32 v[6:7], v[6:7], v[38:39], v[62:63]
	v_pk_fma_f32 v[12:13], v[48:49], v[32:33], v[12:13] op_sel_hi:[1,0,1]
	v_pk_fma_f32 v[8:9], v[52:53], v[32:33], v[8:9] op_sel_hi:[1,0,1]
	v_pk_fma_f32 v[0:1], v[48:49], v[34:35], v[0:1] op_sel_hi:[1,0,1]
	v_pk_fma_f32 v[4:5], v[52:53], v[34:35], v[4:5] op_sel_hi:[1,0,1]
	v_pk_fma_f32 v[14:15], v[50:51], v[32:33], v[14:15] op_sel_hi:[1,0,1]
	v_pk_fma_f32 v[10:11], v[54:55], v[32:33], v[10:11] op_sel_hi:[1,0,1]
	v_pk_fma_f32 v[2:3], v[50:51], v[34:35], v[2:3] op_sel_hi:[1,0,1]
	v_pk_fma_f32 v[6:7], v[54:55], v[34:35], v[6:7] op_sel_hi:[1,0,1]
	v_pk_mul_f32 v[32:33], v[64:65], v[12:13]
	v_pk_mul_f32 v[34:35], v[68:69], v[8:9]
	v_pk_mul_f32 v[36:37], v[64:65], v[0:1]
	v_pk_mul_f32 v[38:39], v[68:69], v[4:5]
	v_pk_mul_f32 v[40:41], v[80:81], v[12:13]
	v_pk_mul_f32 v[42:43], v[84:85], v[8:9]
	v_pk_mul_f32 v[50:51], v[80:81], v[0:1]
	v_pk_mul_f32 v[52:53], v[84:85], v[4:5]
	s_waitcnt lgkmcnt(0)
; #define SCAN_STEP(w0, w1, a0, a1, b0, b1, k0, k1, r0, r1, vi, vj, t) do { \
;                 SCAN_ROW(S0, S1, S2, S3, w0, w1, a0, a1, b0, b1, k0, k1, r0, r1, vi, (t) * 512); \
;                 SCAN_ROW(T0, T1, T2, T3, w0, w1, a0, a1, b0, b1, k0, k1, r0, r1, vj, (t) * 512 + 256); } while (0)
;     ...
;             SCAN_LOAD(w0, w1, a0, a1, b0, b1, k0, k1, r0, r1, vi, vj, 0);
; #pragma unroll
;             for (int t = 0; t < 16; t += 2) {
;                 SCAN_LOAD(W0, W1, A0, A1, B0, B1, K0, K1, R0, R1, VI, VJ, t + 1);
;                 SCAN_STEP(w0, w1, a0, a1, b0, b1, k0, k1, r0, r1, vi, vj, t);
;                 if (t + 2 < 16) SCAN_LOAD(w0, w1, a0, a1, b0, b1, k0, k1, r0, r1, vi, vj, t + 2);
;                 SCAN_STEP(W0, W1, A0, A1, B0, B1, K0, K1, R0, R1, VI, VJ, t + 1);
	v_mov_b32_e32 v44, v115
	v_pk_mul_f32 v[46:47], v[74:75], v[14:15]
	v_pk_mul_f32 v[8:9], v[76:77], v[8:9]
	v_pk_mul_f32 v[48:49], v[78:79], v[10:11]
	v_pk_mul_f32 v[0:1], v[72:73], v[0:1]
	v_pk_mul_f32 v[54:55], v[74:75], v[2:3]
	v_pk_mul_f32 v[4:5], v[76:77], v[4:5]
	v_pk_mul_f32 v[56:57], v[78:79], v[6:7]
	v_pk_fma_f32 v[32:33], v[66:67], v[14:15], v[32:33]
	v_pk_fma_f32 v[34:35], v[70:71], v[10:11], v[34:35]
	v_pk_fma_f32 v[36:37], v[66:67], v[2:3], v[36:37]
	v_pk_fma_f32 v[38:39], v[70:71], v[6:7], v[38:39]
	v_pk_fma_f32 v[14:15], v[82:83], v[14:15], v[40:41]
	v_pk_fma_f32 v[10:11], v[86:87], v[10:11], v[42:43]
	v_pk_fma_f32 v[2:3], v[82:83], v[2:3], v[50:51]
	v_pk_fma_f32 v[6:7], v[86:87], v[6:7], v[52:53]
	v_pk_fma_f32 v[62:63], v[100:101], v[114:115], v[8:9] op_sel_hi:[1,0,1]
	v_pk_fma_f32 v[66:67], v[96:97], v[44:45], v[0:1] op_sel_hi:[1,0,1]
	v_pk_fma_f32 v[70:71], v[100:101], v[44:45], v[4:5] op_sel_hi:[1,0,1]
	v_pk_add_f32 v[0:1], v[32:33], v[34:35]
	v_pk_add_f32 v[4:5], v[36:37], v[38:39]
	v_pk_add_f32 v[8:9], v[14:15], v[10:11]
	v_pk_add_f32 v[2:3], v[2:3], v[6:7]
	v_add_f32_e32 v0, v0, v1
	v_add_f32_e32 v1, v4, v5
	v_add_f32_e32 v4, v8, v9
	v_add_f32_e32 v2, v2, v3
	v_lshl_add_u32 v29, s8, 15, v20
	v_add_f32_dpp v31, v4, v4 quad_perm:[1,0,3,2] row_mask:0xf bank_mask:0xf bound_ctrl:1
	v_add_f32_dpp v74, v2, v2 quad_perm:[1,0,3,2] row_mask:0xf bank_mask:0xf bound_ctrl:1
	v_add_u32_e32 v128, 0x1000, v23
	v_pk_mul_f32 v[12:13], v[72:73], v[12:13]
	ds_write2st64_b32 v29, v0, v1 offset0:192 offset1:196
	v_add_f32_dpp v31, v31, v31 quad_perm:[2,3,0,1] row_mask:0xf bank_mask:0xf bound_ctrl:1
	v_add_f32_dpp v75, v74, v74 quad_perm:[2,3,0,1] row_mask:0xf bank_mask:0xf bound_ctrl:1
	v_pk_fma_f32 v[58:59], v[96:97], v[114:115], v[12:13] op_sel_hi:[1,0,1]
	v_pk_fma_f32 v[60:61], v[98:99], v[114:115], v[46:47] op_sel_hi:[1,0,1]
	v_pk_fma_f32 v[64:65], v[102:103], v[114:115], v[48:49] op_sel_hi:[1,0,1]
	v_pk_fma_f32 v[68:69], v[98:99], v[44:45], v[54:55] op_sel_hi:[1,0,1]
	v_pk_fma_f32 v[56:57], v[102:103], v[44:45], v[56:57] op_sel_hi:[1,0,1]
	ds_read2_b32 v[72:73], v128 offset0:64 offset1:72
	ds_read_b128 v[0:3], v22 offset:4112
	ds_read_b128 v[4:7], v22 offset:4096
	ds_read_b128 v[8:11], v22 offset:3856
	ds_read_b128 v[12:15], v22 offset:3840
	ds_read_b128 v[32:35], v22 offset:3600
	ds_read_b128 v[36:39], v22 offset:3584
	ds_read_b128 v[40:43], v22 offset:3344
	ds_read_b128 v[44:47], v22 offset:3328
	ds_read_b128 v[48:51], v22 offset:3072
	ds_read_b128 v[52:55], v22 offset:3088
	v_add_f32_dpp v74, v31, v31 row_half_mirror row_mask:0xf bank_mask:0xf bound_ctrl:1
	v_add_f32_dpp v76, v75, v75 row_half_mirror row_mask:0xf bank_mask:0xf bound_ctrl:1
	v_pk_fma_f32 v[58:59], v[88:89], v[74:75], v[58:59] op_sel_hi:[1,0,1]
	v_pk_fma_f32 v[62:63], v[92:93], v[74:75], v[62:63] op_sel_hi:[1,0,1]
	v_pk_fma_f32 v[66:67], v[88:89], v[76:77], v[66:67] op_sel_hi:[1,0,1]
	v_pk_fma_f32 v[70:71], v[92:93], v[76:77], v[70:71] op_sel_hi:[1,0,1]
	v_pk_fma_f32 v[60:61], v[90:91], v[74:75], v[60:61] op_sel_hi:[1,0,1]
	v_pk_fma_f32 v[64:65], v[94:95], v[74:75], v[64:65] op_sel_hi:[1,0,1]
	v_pk_fma_f32 v[68:69], v[90:91], v[76:77], v[68:69] op_sel_hi:[1,0,1]
	v_pk_fma_f32 v[56:57], v[94:95], v[76:77], v[56:57] op_sel_hi:[1,0,1]
	v_pk_mul_f32 v[74:75], v[104:105], v[58:59]
	v_pk_mul_f32 v[76:77], v[108:109], v[62:63]
	v_pk_mul_f32 v[78:79], v[104:105], v[66:67]
	v_pk_mul_f32 v[80:81], v[108:109], v[70:71]
	v_pk_fma_f32 v[74:75], v[106:107], v[60:61], v[74:75]
	v_pk_fma_f32 v[76:77], v[110:111], v[64:65], v[76:77]
	v_pk_fma_f32 v[78:79], v[106:107], v[68:69], v[78:79]
	v_pk_fma_f32 v[80:81], v[110:111], v[56:57], v[80:81]
	v_pk_add_f32 v[74:75], v[74:75], v[76:77]
	v_pk_add_f32 v[76:77], v[78:79], v[80:81]
	s_waitcnt lgkmcnt(2)
	v_pk_mul_f32 v[78:79], v[44:45], v[58:59]
	v_pk_mul_f32 v[80:81], v[40:41], v[62:63]
	v_pk_mul_f32 v[44:45], v[44:45], v[66:67]
	v_pk_mul_f32 v[40:41], v[40:41], v[70:71]
	s_waitcnt lgkmcnt(1)
	v_pk_mul_f32 v[82:83], v[50:51], v[60:61]
	s_waitcnt lgkmcnt(0)
	v_pk_mul_f32 v[84:85], v[54:55], v[64:65]
	v_pk_fma_f32 v[60:61], v[46:47], v[60:61], v[78:79]
	v_pk_fma_f32 v[64:65], v[42:43], v[64:65], v[80:81]
	v_pk_fma_f32 v[44:45], v[46:47], v[68:69], v[44:45]
	v_pk_fma_f32 v[40:41], v[42:43], v[56:57], v[40:41]
	v_pk_mul_f32 v[58:59], v[48:49], v[58:59]
	v_pk_mul_f32 v[48:49], v[48:49], v[66:67]
	v_add_f32_e32 v31, v74, v75
	v_add_f32_e32 v66, v76, v77
	v_pk_add_f32 v[88:89], v[64:65], v[60:61]
	v_pk_add_f32 v[90:91], v[40:41], v[44:45]
	ds_write2st64_b32 v29, v31, v66 offset0:200 offset1:204
	v_add_f32_e32 v31, v88, v89
	v_add_f32_e32 v88, v90, v91
	v_pk_mul_f32 v[62:63], v[52:53], v[62:63]
	v_mov_b32_e32 v86, v73
	v_pk_mul_f32 v[50:51], v[50:51], v[68:69]
	v_pk_mul_f32 v[52:53], v[52:53], v[70:71]
	v_pk_mul_f32 v[54:55], v[54:55], v[56:57]
	v_add_f32_dpp v31, v31, v31 quad_perm:[1,0,3,2] row_mask:0xf bank_mask:0xf bound_ctrl:1
	v_add_f32_dpp v88, v88, v88 quad_perm:[1,0,3,2] row_mask:0xf bank_mask:0xf bound_ctrl:1
	v_add_u32_e32 v129, 0x1400, v23
	v_pk_fma_f32 v[74:75], v[72:73], v[12:13], v[58:59] op_sel_hi:[0,1,1]
	v_pk_fma_f32 v[76:77], v[72:73], v[14:15], v[82:83] op_sel_hi:[0,1,1]
	v_pk_fma_f32 v[78:79], v[72:73], v[8:9], v[62:63] op_sel_hi:[0,1,1]
	v_pk_fma_f32 v[72:73], v[72:73], v[10:11], v[84:85] op_sel_hi:[0,1,1]
	v_pk_fma_f32 v[80:81], v[86:87], v[12:13], v[48:49] op_sel_hi:[0,1,1]
	v_pk_fma_f32 v[82:83], v[86:87], v[14:15], v[50:51] op_sel_hi:[0,1,1]
	v_pk_fma_f32 v[84:85], v[86:87], v[8:9], v[52:53] op_sel_hi:[0,1,1]
	v_pk_fma_f32 v[86:87], v[86:87], v[10:11], v[54:55] op_sel_hi:[0,1,1]
	ds_read_b128 v[8:11], v22 offset:4608
; #define SCAN_STEP(w0, w1, a0, a1, b0, b1, k0, k1, r0, r1, vi, vj, t) do { \
;                 SCAN_ROW(S0, S1, S2, S3, w0, w1, a0, a1, b0, b1, k0, k1, r0, r1, vi, (t) * 512); \
;                 SCAN_ROW(T0, T1, T2, T3, w0, w1, a0, a1, b0, b1, k0, k1, r0, r1, vj, (t) * 512 + 256); } while (0)
;     ...
;             SCAN_LOAD(w0, w1, a0, a1, b0, b1, k0, k1, r0, r1, vi, vj, 0);
; #pragma unroll
;             for (int t = 0; t < 16; t += 2) {
;                 SCAN_LOAD(W0, W1, A0, A1, B0, B1, K0, K1, R0, R1, VI, VJ, t + 1);
;                 SCAN_STEP(w0, w1, a0, a1, b0, b1, k0, k1, r0, r1, vi, vj, t);
;                 if (t + 2 < 16) SCAN_LOAD(w0, w1, a0, a1, b0, b1, k0, k1, r0, r1, vi, vj, t + 2);
;                 SCAN_STEP(W0, W1, A0, A1, B0, B1, K0, K1, R0, R1, VI, VJ, t + 1);
	ds_read_b128 v[12:15], v22 offset:4624
	ds_read_b128 v[40:43], v22 offset:4864
	ds_read_b128 v[44:47], v22 offset:4880
	ds_read_b128 v[48:51], v22 offset:5120
	ds_read_b128 v[52:55], v22 offset:5136
	ds_read_b128 v[56:59], v22 offset:5376
	ds_read_b128 v[60:63], v22 offset:5392
	ds_read_b128 v[64:67], v22 offset:5632
	ds_read_b128 v[68:71], v22 offset:5648
	ds_read2_b32 v[92:93], v129 offset0:192 offset1:200
	v_add_f32_dpp v31, v31, v31 quad_perm:[2,3,0,1] row_mask:0xf bank_mask:0xf bound_ctrl:1
	v_add_f32_dpp v89, v88, v88 quad_perm:[2,3,0,1] row_mask:0xf bank_mask:0xf bound_ctrl:1
	v_add_u32_e32 v130, 0x1c00, v23
	v_add_f32_dpp v88, v31, v31 row_half_mirror row_mask:0xf bank_mask:0xf bound_ctrl:1
	v_add_f32_dpp v90, v89, v89 row_half_mirror row_mask:0xf bank_mask:0xf bound_ctrl:1
	v_pk_fma_f32 v[74:75], v[36:37], v[88:89], v[74:75] op_sel_hi:[1,0,1]
	v_pk_fma_f32 v[78:79], v[32:33], v[88:89], v[78:79] op_sel_hi:[1,0,1]
	v_pk_fma_f32 v[36:37], v[36:37], v[90:91], v[80:81] op_sel_hi:[1,0,1]
	v_pk_fma_f32 v[32:33], v[32:33], v[90:91], v[84:85] op_sel_hi:[1,0,1]
	v_pk_fma_f32 v[76:77], v[38:39], v[88:89], v[76:77] op_sel_hi:[1,0,1]
	v_pk_fma_f32 v[72:73], v[34:35], v[88:89], v[72:73] op_sel_hi:[1,0,1]
	v_pk_fma_f32 v[38:39], v[38:39], v[90:91], v[82:83] op_sel_hi:[1,0,1]
	v_pk_fma_f32 v[34:35], v[34:35], v[90:91], v[86:87] op_sel_hi:[1,0,1]
	v_pk_mul_f32 v[80:81], v[4:5], v[74:75]
	v_pk_mul_f32 v[82:83], v[0:1], v[78:79]
	v_pk_mul_f32 v[4:5], v[4:5], v[36:37]
	v_pk_mul_f32 v[0:1], v[0:1], v[32:33]
	s_waitcnt lgkmcnt(8)
	v_pk_mul_f32 v[84:85], v[40:41], v[74:75]
	s_waitcnt lgkmcnt(7)
	v_pk_mul_f32 v[86:87], v[44:45], v[78:79]
	v_pk_mul_f32 v[40:41], v[40:41], v[36:37]
	v_pk_mul_f32 v[44:45], v[44:45], v[32:33]
	v_pk_mul_f32 v[74:75], v[8:9], v[74:75]
	v_pk_mul_f32 v[88:89], v[10:11], v[76:77]
	v_pk_mul_f32 v[78:79], v[12:13], v[78:79]
	v_pk_mul_f32 v[90:91], v[14:15], v[72:73]
	v_pk_mul_f32 v[8:9], v[8:9], v[36:37]
	v_pk_mul_f32 v[10:11], v[10:11], v[38:39]
	v_pk_mul_f32 v[12:13], v[12:13], v[32:33]
	v_pk_mul_f32 v[14:15], v[14:15], v[34:35]
	v_pk_fma_f32 v[32:33], v[6:7], v[76:77], v[80:81]
	v_pk_fma_f32 v[36:37], v[2:3], v[72:73], v[82:83]
	v_pk_fma_f32 v[4:5], v[6:7], v[38:39], v[4:5]
	v_pk_fma_f32 v[0:1], v[2:3], v[34:35], v[0:1]
	v_pk_fma_f32 v[2:3], v[42:43], v[76:77], v[84:85]
	v_pk_fma_f32 v[6:7], v[46:47], v[72:73], v[86:87]
	v_pk_fma_f32 v[38:39], v[42:43], v[38:39], v[40:41]
	v_pk_fma_f32 v[34:35], v[46:47], v[34:35], v[44:45]
	s_waitcnt lgkmcnt(0)
	v_mov_b32_e32 v94, v93
	v_pk_add_f32 v[0:1], v[4:5], v[0:1]
	v_pk_add_f32 v[2:3], v[2:3], v[6:7]
	v_pk_add_f32 v[4:5], v[38:39], v[34:35]
	v_pk_fma_f32 v[80:81], v[56:57], v[94:95], v[8:9] op_sel_hi:[1,0,1]
	v_pk_add_f32 v[8:9], v[32:33], v[36:37]
	v_add_f32_e32 v0, v0, v1
	v_add_f32_e32 v1, v2, v3
	v_add_f32_e32 v2, v4, v5
	v_pk_fma_f32 v[76:77], v[60:61], v[92:93], v[78:79] op_sel_hi:[1,0,1]
	v_pk_fma_f32 v[78:79], v[62:63], v[92:93], v[90:91] op_sel_hi:[1,0,1]
	v_add_f32_e32 v6, v8, v9
	v_add_f32_dpp v31, v1, v1 quad_perm:[1,0,3,2] row_mask:0xf bank_mask:0xf bound_ctrl:1
	v_add_f32_dpp v90, v2, v2 quad_perm:[1,0,3,2] row_mask:0xf bank_mask:0xf bound_ctrl:1
	ds_write2st64_b32 v29, v6, v0 offset0:208 offset1:212
	v_add_f32_dpp v31, v31, v31 quad_perm:[2,3,0,1] row_mask:0xf bank_mask:0xf bound_ctrl:1
	v_add_f32_dpp v91, v90, v90 quad_perm:[2,3,0,1] row_mask:0xf bank_mask:0xf bound_ctrl:1
	v_pk_fma_f32 v[72:73], v[56:57], v[92:93], v[74:75] op_sel_hi:[1,0,1]
	v_pk_fma_f32 v[74:75], v[58:59], v[92:93], v[88:89] op_sel_hi:[1,0,1]
	v_pk_fma_f32 v[82:83], v[58:59], v[94:95], v[10:11] op_sel_hi:[1,0,1]
	v_pk_fma_f32 v[84:85], v[60:61], v[94:95], v[12:13] op_sel_hi:[1,0,1]
	v_pk_fma_f32 v[86:87], v[62:63], v[94:95], v[14:15] op_sel_hi:[1,0,1]
	ds_read2_b32 v[88:89], v130 offset0:64 offset1:72
	ds_read_b128 v[0:3], v22 offset:7184
	ds_read_b128 v[4:7], v22 offset:7168
	ds_read_b128 v[8:11], v22 offset:6928
	ds_read_b128 v[12:15], v22 offset:6912
	ds_read_b128 v[32:35], v22 offset:6672
	ds_read_b128 v[36:39], v22 offset:6656
	ds_read_b128 v[40:43], v22 offset:6416
	ds_read_b128 v[44:47], v22 offset:6400
	ds_read_b128 v[56:59], v22 offset:6144
	ds_read_b128 v[60:63], v22 offset:6160
	v_add_f32_dpp v90, v31, v31 row_half_mirror row_mask:0xf bank_mask:0xf bound_ctrl:1
	v_add_f32_dpp v92, v91, v91 row_half_mirror row_mask:0xf bank_mask:0xf bound_ctrl:1
	v_pk_fma_f32 v[72:73], v[48:49], v[90:91], v[72:73] op_sel_hi:[1,0,1]
	v_pk_fma_f32 v[76:77], v[52:53], v[90:91], v[76:77] op_sel_hi:[1,0,1]
	v_pk_fma_f32 v[48:49], v[48:49], v[92:93], v[80:81] op_sel_hi:[1,0,1]
	v_pk_fma_f32 v[52:53], v[52:53], v[92:93], v[84:85] op_sel_hi:[1,0,1]
	v_pk_fma_f32 v[74:75], v[50:51], v[90:91], v[74:75] op_sel_hi:[1,0,1]
	v_pk_fma_f32 v[78:79], v[54:55], v[90:91], v[78:79] op_sel_hi:[1,0,1]
	v_pk_fma_f32 v[50:51], v[50:51], v[92:93], v[82:83] op_sel_hi:[1,0,1]
	v_pk_fma_f32 v[54:55], v[54:55], v[92:93], v[86:87] op_sel_hi:[1,0,1]
	v_pk_mul_f32 v[80:81], v[64:65], v[72:73]
	v_pk_mul_f32 v[82:83], v[68:69], v[76:77]
	v_pk_mul_f32 v[64:65], v[64:65], v[48:49]
	v_pk_mul_f32 v[68:69], v[68:69], v[52:53]
	v_pk_fma_f32 v[80:81], v[66:67], v[74:75], v[80:81]
	v_pk_fma_f32 v[64:65], v[66:67], v[50:51], v[64:65]
	v_pk_fma_f32 v[66:67], v[70:71], v[54:55], v[68:69]
	v_pk_fma_f32 v[82:83], v[70:71], v[78:79], v[82:83]
	v_pk_add_f32 v[64:65], v[64:65], v[66:67]
	s_waitcnt lgkmcnt(2)
	v_pk_mul_f32 v[66:67], v[44:45], v[72:73]
	v_pk_mul_f32 v[70:71], v[40:41], v[76:77]
	v_pk_mul_f32 v[44:45], v[44:45], v[48:49]
	v_pk_mul_f32 v[40:41], v[40:41], v[52:53]
	v_pk_add_f32 v[68:69], v[80:81], v[82:83]
	s_waitcnt lgkmcnt(1)
; #define SCAN_STEP(w0, w1, a0, a1, b0, b1, k0, k1, r0, r1, vi, vj, t) do { \
;                 SCAN_ROW(S0, S1, S2, S3, w0, w1, a0, a1, b0, b1, k0, k1, r0, r1, vi, (t) * 512); \
;                 SCAN_ROW(T0, T1, T2, T3, w0, w1, a0, a1, b0, b1, k0, k1, r0, r1, vj, (t) * 512 + 256); } while (0)
;     ...
;             SCAN_LOAD(w0, w1, a0, a1, b0, b1, k0, k1, r0, r1, vi, vj, 0);
; #pragma unroll
;             for (int t = 0; t < 16; t += 2) {
;                 SCAN_LOAD(W0, W1, A0, A1, B0, B1, K0, K1, R0, R1, VI, VJ, t + 1);
;                 SCAN_STEP(w0, w1, a0, a1, b0, b1, k0, k1, r0, r1, vi, vj, t);
;                 if (t + 2 < 16) SCAN_LOAD(w0, w1, a0, a1, b0, b1, k0, k1, r0, r1, vi, vj, t + 2);
;                 SCAN_STEP(W0, W1, A0, A1, B0, B1, K0, K1, R0, R1, VI, VJ, t + 1);
	v_pk_mul_f32 v[72:73], v[56:57], v[72:73]
	v_pk_mul_f32 v[80:81], v[58:59], v[74:75]
	s_waitcnt lgkmcnt(0)
	v_pk_mul_f32 v[76:77], v[60:61], v[76:77]
	v_pk_mul_f32 v[82:83], v[62:63], v[78:79]
	v_pk_mul_f32 v[48:49], v[56:57], v[48:49]
	v_pk_mul_f32 v[56:57], v[58:59], v[50:51]
	v_pk_mul_f32 v[52:53], v[60:61], v[52:53]
	v_pk_mul_f32 v[58:59], v[62:63], v[54:55]
	v_pk_fma_f32 v[60:61], v[46:47], v[74:75], v[66:67]
	v_pk_fma_f32 v[62:63], v[42:43], v[78:79], v[70:71]
	v_pk_fma_f32 v[44:45], v[46:47], v[50:51], v[44:45]
	v_pk_fma_f32 v[40:41], v[42:43], v[54:55], v[40:41]
	v_mov_b32_e32 v84, v89
	v_add_f32_e32 v31, v68, v69
	v_add_f32_e32 v64, v64, v65
	v_pk_fma_f32 v[72:73], v[88:89], v[12:13], v[72:73] op_sel_hi:[0,1,1]
	v_pk_fma_f32 v[74:75], v[88:89], v[14:15], v[80:81] op_sel_hi:[0,1,1]
	v_pk_fma_f32 v[76:77], v[88:89], v[8:9], v[76:77] op_sel_hi:[0,1,1]
	v_pk_fma_f32 v[78:79], v[88:89], v[10:11], v[82:83] op_sel_hi:[0,1,1]
	v_pk_add_f32 v[88:89], v[62:63], v[60:61]
	v_pk_add_f32 v[90:91], v[40:41], v[44:45]
	ds_write2st64_b32 v29, v31, v64 offset0:216 offset1:220
	v_add_f32_e32 v31, v88, v89
	v_add_f32_e32 v88, v90, v91
	v_add_u32_e32 v131, 0x2000, v23
	v_add_f32_dpp v31, v31, v31 quad_perm:[1,0,3,2] row_mask:0xf bank_mask:0xf bound_ctrl:1
	v_add_f32_dpp v88, v88, v88 quad_perm:[1,0,3,2] row_mask:0xf bank_mask:0xf bound_ctrl:1
	v_pk_fma_f32 v[80:81], v[84:85], v[12:13], v[48:49] op_sel_hi:[0,1,1]
	v_pk_fma_f32 v[82:83], v[84:85], v[14:15], v[56:57] op_sel_hi:[0,1,1]
	v_pk_fma_f32 v[86:87], v[84:85], v[8:9], v[52:53] op_sel_hi:[0,1,1]
	v_pk_fma_f32 v[84:85], v[84:85], v[10:11], v[58:59] op_sel_hi:[0,1,1]
	ds_read_b128 v[8:11], v22 offset:7680
	ds_read_b128 v[12:15], v22 offset:7696
	ds_read_b128 v[40:43], v22 offset:7936
	ds_read_b128 v[44:47], v22 offset:7952
	ds_read_b128 v[48:51], v22 offset:8192
	ds_read_b128 v[52:55], v22 offset:8208
	ds_read_b128 v[56:59], v22 offset:8448
	ds_read_b128 v[60:63], v22 offset:8464
	ds_read_b128 v[64:67], v22 offset:8704
	ds_read_b128 v[68:71], v22 offset:8720
	ds_read2_b32 v[92:93], v131 offset0:192 offset1:200
	v_add_f32_dpp v31, v31, v31 quad_perm:[2,3,0,1] row_mask:0xf bank_mask:0xf bound_ctrl:1
	v_add_f32_dpp v89, v88, v88 quad_perm:[2,3,0,1] row_mask:0xf bank_mask:0xf bound_ctrl:1
	v_add_u32_e32 v132, 0x2800, v23
	v_add_f32_dpp v88, v31, v31 row_half_mirror row_mask:0xf bank_mask:0xf bound_ctrl:1
	v_add_f32_dpp v90, v89, v89 row_half_mirror row_mask:0xf bank_mask:0xf bound_ctrl:1
	v_pk_fma_f32 v[72:73], v[36:37], v[88:89], v[72:73] op_sel_hi:[1,0,1]
	v_pk_fma_f32 v[76:77], v[32:33], v[88:89], v[76:77] op_sel_hi:[1,0,1]
	v_pk_fma_f32 v[36:37], v[36:37], v[90:91], v[80:81] op_sel_hi:[1,0,1]
	v_pk_fma_f32 v[32:33], v[32:33], v[90:91], v[86:87] op_sel_hi:[1,0,1]
	v_pk_fma_f32 v[74:75], v[38:39], v[88:89], v[74:75] op_sel_hi:[1,0,1]
	v_pk_fma_f32 v[78:79], v[34:35], v[88:89], v[78:79] op_sel_hi:[1,0,1]
	v_pk_fma_f32 v[38:39], v[38:39], v[90:91], v[82:83] op_sel_hi:[1,0,1]
	v_pk_fma_f32 v[34:35], v[34:35], v[90:91], v[84:85] op_sel_hi:[1,0,1]
	v_pk_mul_f32 v[80:81], v[4:5], v[72:73]
	v_pk_mul_f32 v[82:83], v[0:1], v[76:77]
	v_pk_mul_f32 v[4:5], v[4:5], v[36:37]
	v_pk_mul_f32 v[0:1], v[0:1], v[32:33]
	s_waitcnt lgkmcnt(8)
	v_pk_mul_f32 v[84:85], v[40:41], v[72:73]
	s_waitcnt lgkmcnt(7)
	v_pk_mul_f32 v[86:87], v[44:45], v[76:77]
	v_pk_mul_f32 v[40:41], v[40:41], v[36:37]
	v_pk_mul_f32 v[44:45], v[44:45], v[32:33]
	v_pk_mul_f32 v[72:73], v[8:9], v[72:73]
	v_pk_mul_f32 v[88:89], v[10:11], v[74:75]
	v_pk_mul_f32 v[76:77], v[12:13], v[76:77]
	v_pk_mul_f32 v[90:91], v[14:15], v[78:79]
	v_pk_mul_f32 v[8:9], v[8:9], v[36:37]
	v_pk_mul_f32 v[10:11], v[10:11], v[38:39]
	v_pk_mul_f32 v[12:13], v[12:13], v[32:33]
	v_pk_mul_f32 v[14:15], v[14:15], v[34:35]
	v_pk_fma_f32 v[32:33], v[6:7], v[74:75], v[80:81]
	v_pk_fma_f32 v[36:37], v[2:3], v[78:79], v[82:83]
	v_pk_fma_f32 v[4:5], v[6:7], v[38:39], v[4:5]
	v_pk_fma_f32 v[0:1], v[2:3], v[34:35], v[0:1]
	v_pk_fma_f32 v[2:3], v[42:43], v[74:75], v[84:85]
	v_pk_fma_f32 v[6:7], v[46:47], v[78:79], v[86:87]
	v_pk_fma_f32 v[38:39], v[42:43], v[38:39], v[40:41]
	v_pk_fma_f32 v[34:35], v[46:47], v[34:35], v[44:45]
	s_waitcnt lgkmcnt(0)
	v_mov_b32_e32 v94, v93
	v_pk_add_f32 v[0:1], v[4:5], v[0:1]
	v_pk_add_f32 v[2:3], v[2:3], v[6:7]
	v_pk_add_f32 v[4:5], v[38:39], v[34:35]
	v_pk_fma_f32 v[80:81], v[56:57], v[94:95], v[8:9] op_sel_hi:[1,0,1]
	v_pk_add_f32 v[8:9], v[32:33], v[36:37]
	v_add_f32_e32 v0, v0, v1
	v_add_f32_e32 v1, v2, v3
	v_add_f32_e32 v2, v4, v5
	v_pk_fma_f32 v[78:79], v[62:63], v[92:93], v[90:91] op_sel_hi:[1,0,1]
	v_add_f32_e32 v6, v8, v9
	v_add_f32_dpp v31, v1, v1 quad_perm:[1,0,3,2] row_mask:0xf bank_mask:0xf bound_ctrl:1
	v_add_f32_dpp v90, v2, v2 quad_perm:[1,0,3,2] row_mask:0xf bank_mask:0xf bound_ctrl:1
	ds_write2st64_b32 v29, v6, v0 offset0:224 offset1:228
	v_add_f32_dpp v31, v31, v31 quad_perm:[2,3,0,1] row_mask:0xf bank_mask:0xf bound_ctrl:1
	v_add_f32_dpp v91, v90, v90 quad_perm:[2,3,0,1] row_mask:0xf bank_mask:0xf bound_ctrl:1
	v_pk_fma_f32 v[72:73], v[56:57], v[92:93], v[72:73] op_sel_hi:[1,0,1]
	v_pk_fma_f32 v[74:75], v[58:59], v[92:93], v[88:89] op_sel_hi:[1,0,1]
	v_pk_fma_f32 v[76:77], v[60:61], v[92:93], v[76:77] op_sel_hi:[1,0,1]
	v_pk_fma_f32 v[82:83], v[58:59], v[94:95], v[10:11] op_sel_hi:[1,0,1]
	v_pk_fma_f32 v[84:85], v[60:61], v[94:95], v[12:13] op_sel_hi:[1,0,1]
	v_pk_fma_f32 v[86:87], v[62:63], v[94:95], v[14:15] op_sel_hi:[1,0,1]
	ds_read2_b32 v[88:89], v132 offset0:64 offset1:72
	ds_read_b128 v[0:3], v22 offset:10256
	ds_read_b128 v[4:7], v22 offset:10240
	ds_read_b128 v[8:11], v22 offset:10000
	ds_read_b128 v[12:15], v22 offset:9984
; #define SCAN_STEP(w0, w1, a0, a1, b0, b1, k0, k1, r0, r1, vi, vj, t) do { \
;                 SCAN_ROW(S0, S1, S2, S3, w0, w1, a0, a1, b0, b1, k0, k1, r0, r1, vi, (t) * 512); \
;                 SCAN_ROW(T0, T1, T2, T3, w0, w1, a0, a1, b0, b1, k0, k1, r0, r1, vj, (t) * 512 + 256); } while (0)
;     ...
;             SCAN_LOAD(w0, w1, a0, a1, b0, b1, k0, k1, r0, r1, vi, vj, 0);
; #pragma unroll
;             for (int t = 0; t < 16; t += 2) {
;                 SCAN_LOAD(W0, W1, A0, A1, B0, B1, K0, K1, R0, R1, VI, VJ, t + 1);
;                 SCAN_STEP(w0, w1, a0, a1, b0, b1, k0, k1, r0, r1, vi, vj, t);
;                 if (t + 2 < 16) SCAN_LOAD(w0, w1, a0, a1, b0, b1, k0, k1, r0, r1, vi, vj, t + 2);
;                 SCAN_STEP(W0, W1, A0, A1, B0, B1, K0, K1, R0, R1, VI, VJ, t + 1);
	ds_read_b128 v[32:35], v22 offset:9744
	ds_read_b128 v[36:39], v22 offset:9728
	ds_read_b128 v[40:43], v22 offset:9488
	ds_read_b128 v[44:47], v22 offset:9472
	ds_read_b128 v[56:59], v22 offset:9216
	ds_read_b128 v[60:63], v22 offset:9232
	v_add_f32_dpp v90, v31, v31 row_half_mirror row_mask:0xf bank_mask:0xf bound_ctrl:1
	v_add_f32_dpp v92, v91, v91 row_half_mirror row_mask:0xf bank_mask:0xf bound_ctrl:1
	v_pk_fma_f32 v[72:73], v[48:49], v[90:91], v[72:73] op_sel_hi:[1,0,1]
	v_pk_fma_f32 v[76:77], v[52:53], v[90:91], v[76:77] op_sel_hi:[1,0,1]
	v_pk_fma_f32 v[48:49], v[48:49], v[92:93], v[80:81] op_sel_hi:[1,0,1]
	v_pk_fma_f32 v[52:53], v[52:53], v[92:93], v[84:85] op_sel_hi:[1,0,1]
	v_pk_fma_f32 v[74:75], v[50:51], v[90:91], v[74:75] op_sel_hi:[1,0,1]
	v_pk_fma_f32 v[78:79], v[54:55], v[90:91], v[78:79] op_sel_hi:[1,0,1]
	v_pk_fma_f32 v[50:51], v[50:51], v[92:93], v[82:83] op_sel_hi:[1,0,1]
	v_pk_fma_f32 v[54:55], v[54:55], v[92:93], v[86:87] op_sel_hi:[1,0,1]
	v_pk_mul_f32 v[80:81], v[64:65], v[72:73]
	v_pk_mul_f32 v[82:83], v[68:69], v[76:77]
	v_pk_mul_f32 v[64:65], v[64:65], v[48:49]
	v_pk_mul_f32 v[68:69], v[68:69], v[52:53]
	v_pk_fma_f32 v[80:81], v[66:67], v[74:75], v[80:81]
	v_pk_fma_f32 v[64:65], v[66:67], v[50:51], v[64:65]
	v_pk_fma_f32 v[66:67], v[70:71], v[54:55], v[68:69]
	v_pk_fma_f32 v[82:83], v[70:71], v[78:79], v[82:83]
	v_pk_add_f32 v[64:65], v[64:65], v[66:67]
	s_waitcnt lgkmcnt(2)
	v_pk_mul_f32 v[66:67], v[44:45], v[72:73]
	v_pk_mul_f32 v[70:71], v[40:41], v[76:77]
	v_pk_mul_f32 v[44:45], v[44:45], v[48:49]
	v_pk_mul_f32 v[40:41], v[40:41], v[52:53]
	v_pk_add_f32 v[68:69], v[80:81], v[82:83]
	s_waitcnt lgkmcnt(1)
	v_pk_mul_f32 v[72:73], v[56:57], v[72:73]
	v_pk_mul_f32 v[80:81], v[58:59], v[74:75]
	s_waitcnt lgkmcnt(0)
	v_pk_mul_f32 v[76:77], v[60:61], v[76:77]
	v_pk_mul_f32 v[82:83], v[62:63], v[78:79]
	v_pk_mul_f32 v[48:49], v[56:57], v[48:49]
	v_pk_mul_f32 v[56:57], v[58:59], v[50:51]
	v_pk_mul_f32 v[52:53], v[60:61], v[52:53]
	v_pk_mul_f32 v[58:59], v[62:63], v[54:55]
	v_pk_fma_f32 v[60:61], v[46:47], v[74:75], v[66:67]
	v_pk_fma_f32 v[62:63], v[42:43], v[78:79], v[70:71]
	v_pk_fma_f32 v[44:45], v[46:47], v[50:51], v[44:45]
	v_pk_fma_f32 v[40:41], v[42:43], v[54:55], v[40:41]
	v_mov_b32_e32 v84, v89
	v_add_f32_e32 v31, v68, v69
	v_add_f32_e32 v64, v64, v65
	v_pk_fma_f32 v[72:73], v[88:89], v[12:13], v[72:73] op_sel_hi:[0,1,1]
	v_pk_fma_f32 v[74:75], v[88:89], v[14:15], v[80:81] op_sel_hi:[0,1,1]
	v_pk_fma_f32 v[76:77], v[88:89], v[8:9], v[76:77] op_sel_hi:[0,1,1]
	v_pk_fma_f32 v[78:79], v[88:89], v[10:11], v[82:83] op_sel_hi:[0,1,1]
	v_pk_add_f32 v[88:89], v[62:63], v[60:61]
	v_pk_add_f32 v[90:91], v[40:41], v[44:45]
	ds_write2st64_b32 v29, v31, v64 offset0:232 offset1:236
	v_add_f32_e32 v31, v88, v89
	v_add_f32_e32 v88, v90, v91
	v_add_u32_e32 v133, 0x2c00, v23
	v_add_f32_dpp v31, v31, v31 quad_perm:[1,0,3,2] row_mask:0xf bank_mask:0xf bound_ctrl:1
	v_add_f32_dpp v88, v88, v88 quad_perm:[1,0,3,2] row_mask:0xf bank_mask:0xf bound_ctrl:1
	v_pk_fma_f32 v[80:81], v[84:85], v[12:13], v[48:49] op_sel_hi:[0,1,1]
	v_pk_fma_f32 v[82:83], v[84:85], v[14:15], v[56:57] op_sel_hi:[0,1,1]
	v_pk_fma_f32 v[86:87], v[84:85], v[8:9], v[52:53] op_sel_hi:[0,1,1]
	v_pk_fma_f32 v[84:85], v[84:85], v[10:11], v[58:59] op_sel_hi:[0,1,1]
	ds_read_b128 v[8:11], v22 offset:10752
	ds_read_b128 v[12:15], v22 offset:10768
	ds_read_b128 v[40:43], v22 offset:11008
	ds_read_b128 v[44:47], v22 offset:11024
	ds_read_b128 v[48:51], v22 offset:11264
	ds_read_b128 v[52:55], v22 offset:11280
	ds_read_b128 v[56:59], v22 offset:11520
	ds_read_b128 v[60:63], v22 offset:11536
	ds_read_b128 v[64:67], v22 offset:11776
	ds_read_b128 v[68:71], v22 offset:11792
	ds_read2_b32 v[92:93], v133 offset0:192 offset1:200
	v_add_f32_dpp v31, v31, v31 quad_perm:[2,3,0,1] row_mask:0xf bank_mask:0xf bound_ctrl:1
	v_add_f32_dpp v89, v88, v88 quad_perm:[2,3,0,1] row_mask:0xf bank_mask:0xf bound_ctrl:1
	v_add_u32_e32 v134, 0x3400, v23
	v_add_f32_dpp v88, v31, v31 row_half_mirror row_mask:0xf bank_mask:0xf bound_ctrl:1
	v_add_f32_dpp v90, v89, v89 row_half_mirror row_mask:0xf bank_mask:0xf bound_ctrl:1
	v_pk_fma_f32 v[72:73], v[36:37], v[88:89], v[72:73] op_sel_hi:[1,0,1]
	v_pk_fma_f32 v[76:77], v[32:33], v[88:89], v[76:77] op_sel_hi:[1,0,1]
	v_pk_fma_f32 v[36:37], v[36:37], v[90:91], v[80:81] op_sel_hi:[1,0,1]
	v_pk_fma_f32 v[32:33], v[32:33], v[90:91], v[86:87] op_sel_hi:[1,0,1]
	v_pk_fma_f32 v[74:75], v[38:39], v[88:89], v[74:75] op_sel_hi:[1,0,1]
	v_pk_fma_f32 v[78:79], v[34:35], v[88:89], v[78:79] op_sel_hi:[1,0,1]
	v_pk_fma_f32 v[38:39], v[38:39], v[90:91], v[82:83] op_sel_hi:[1,0,1]
	v_pk_fma_f32 v[34:35], v[34:35], v[90:91], v[84:85] op_sel_hi:[1,0,1]
	v_pk_mul_f32 v[80:81], v[4:5], v[72:73]
	v_pk_mul_f32 v[82:83], v[0:1], v[76:77]
	v_pk_mul_f32 v[4:5], v[4:5], v[36:37]
	v_pk_mul_f32 v[0:1], v[0:1], v[32:33]
	s_waitcnt lgkmcnt(8)
	v_pk_mul_f32 v[84:85], v[40:41], v[72:73]
	s_waitcnt lgkmcnt(7)
	v_pk_mul_f32 v[86:87], v[44:45], v[76:77]
	v_pk_mul_f32 v[40:41], v[40:41], v[36:37]
	v_pk_mul_f32 v[44:45], v[44:45], v[32:33]
	v_pk_mul_f32 v[72:73], v[8:9], v[72:73]
	v_pk_mul_f32 v[88:89], v[10:11], v[74:75]
	v_pk_mul_f32 v[76:77], v[12:13], v[76:77]
	v_pk_mul_f32 v[90:91], v[14:15], v[78:79]
	v_pk_mul_f32 v[8:9], v[8:9], v[36:37]
	v_pk_mul_f32 v[10:11], v[10:11], v[38:39]
	v_pk_mul_f32 v[12:13], v[12:13], v[32:33]
	v_pk_mul_f32 v[14:15], v[14:15], v[34:35]
	v_pk_fma_f32 v[32:33], v[6:7], v[74:75], v[80:81]
	v_pk_fma_f32 v[36:37], v[2:3], v[78:79], v[82:83]
	v_pk_fma_f32 v[4:5], v[6:7], v[38:39], v[4:5]
	v_pk_fma_f32 v[0:1], v[2:3], v[34:35], v[0:1]
	v_pk_fma_f32 v[2:3], v[42:43], v[74:75], v[84:85]
	v_pk_fma_f32 v[6:7], v[46:47], v[78:79], v[86:87]
	v_pk_fma_f32 v[38:39], v[42:43], v[38:39], v[40:41]
	v_pk_fma_f32 v[34:35], v[46:47], v[34:35], v[44:45]
	s_waitcnt lgkmcnt(0)
; #define SCAN_STEP(w0, w1, a0, a1, b0, b1, k0, k1, r0, r1, vi, vj, t) do { \
;                 SCAN_ROW(S0, S1, S2, S3, w0, w1, a0, a1, b0, b1, k0, k1, r0, r1, vi, (t) * 512); \
;                 SCAN_ROW(T0, T1, T2, T3, w0, w1, a0, a1, b0, b1, k0, k1, r0, r1, vj, (t) * 512 + 256); } while (0)
;     ...
;             SCAN_LOAD(w0, w1, a0, a1, b0, b1, k0, k1, r0, r1, vi, vj, 0);
; #pragma unroll
;             for (int t = 0; t < 16; t += 2) {
;                 SCAN_LOAD(W0, W1, A0, A1, B0, B1, K0, K1, R0, R1, VI, VJ, t + 1);
;                 SCAN_STEP(w0, w1, a0, a1, b0, b1, k0, k1, r0, r1, vi, vj, t);
;                 if (t + 2 < 16) SCAN_LOAD(w0, w1, a0, a1, b0, b1, k0, k1, r0, r1, vi, vj, t + 2);
;                 SCAN_STEP(W0, W1, A0, A1, B0, B1, K0, K1, R0, R1, VI, VJ, t + 1);
	v_mov_b32_e32 v94, v93
	v_pk_add_f32 v[0:1], v[4:5], v[0:1]
	v_pk_add_f32 v[2:3], v[2:3], v[6:7]
	v_pk_add_f32 v[4:5], v[38:39], v[34:35]
	v_pk_fma_f32 v[80:81], v[56:57], v[94:95], v[8:9] op_sel_hi:[1,0,1]
	v_pk_add_f32 v[8:9], v[32:33], v[36:37]
	v_add_f32_e32 v0, v0, v1
	v_add_f32_e32 v1, v2, v3
	v_add_f32_e32 v2, v4, v5
	v_pk_fma_f32 v[78:79], v[62:63], v[92:93], v[90:91] op_sel_hi:[1,0,1]
	v_add_f32_e32 v6, v8, v9
	v_add_f32_dpp v31, v1, v1 quad_perm:[1,0,3,2] row_mask:0xf bank_mask:0xf bound_ctrl:1
	v_add_f32_dpp v90, v2, v2 quad_perm:[1,0,3,2] row_mask:0xf bank_mask:0xf bound_ctrl:1
	ds_write2st64_b32 v29, v6, v0 offset0:240 offset1:244
	v_add_f32_dpp v31, v31, v31 quad_perm:[2,3,0,1] row_mask:0xf bank_mask:0xf bound_ctrl:1
	v_add_f32_dpp v91, v90, v90 quad_perm:[2,3,0,1] row_mask:0xf bank_mask:0xf bound_ctrl:1
	v_pk_fma_f32 v[72:73], v[56:57], v[92:93], v[72:73] op_sel_hi:[1,0,1]
	v_pk_fma_f32 v[74:75], v[58:59], v[92:93], v[88:89] op_sel_hi:[1,0,1]
	v_pk_fma_f32 v[76:77], v[60:61], v[92:93], v[76:77] op_sel_hi:[1,0,1]
	v_pk_fma_f32 v[82:83], v[58:59], v[94:95], v[10:11] op_sel_hi:[1,0,1]
	v_pk_fma_f32 v[84:85], v[60:61], v[94:95], v[12:13] op_sel_hi:[1,0,1]
	v_pk_fma_f32 v[86:87], v[62:63], v[94:95], v[14:15] op_sel_hi:[1,0,1]
	ds_read2_b32 v[88:89], v134 offset0:64 offset1:72
	ds_read_b128 v[0:3], v22 offset:13328
	ds_read_b128 v[4:7], v22 offset:13312
	ds_read_b128 v[8:11], v22 offset:13072
	ds_read_b128 v[12:15], v22 offset:13056
	ds_read_b128 v[32:35], v22 offset:12816
	ds_read_b128 v[36:39], v22 offset:12800
	ds_read_b128 v[40:43], v22 offset:12560
	ds_read_b128 v[44:47], v22 offset:12544
	ds_read_b128 v[56:59], v22 offset:12288
	ds_read_b128 v[60:63], v22 offset:12304
	v_add_f32_dpp v90, v31, v31 row_half_mirror row_mask:0xf bank_mask:0xf bound_ctrl:1
	v_add_f32_dpp v92, v91, v91 row_half_mirror row_mask:0xf bank_mask:0xf bound_ctrl:1
	v_pk_fma_f32 v[72:73], v[48:49], v[90:91], v[72:73] op_sel_hi:[1,0,1]
	v_pk_fma_f32 v[76:77], v[52:53], v[90:91], v[76:77] op_sel_hi:[1,0,1]
	v_pk_fma_f32 v[48:49], v[48:49], v[92:93], v[80:81] op_sel_hi:[1,0,1]
	v_pk_fma_f32 v[52:53], v[52:53], v[92:93], v[84:85] op_sel_hi:[1,0,1]
	v_pk_fma_f32 v[74:75], v[50:51], v[90:91], v[74:75] op_sel_hi:[1,0,1]
	v_pk_fma_f32 v[78:79], v[54:55], v[90:91], v[78:79] op_sel_hi:[1,0,1]
	v_pk_fma_f32 v[50:51], v[50:51], v[92:93], v[82:83] op_sel_hi:[1,0,1]
	v_pk_fma_f32 v[54:55], v[54:55], v[92:93], v[86:87] op_sel_hi:[1,0,1]
	v_pk_mul_f32 v[80:81], v[64:65], v[72:73]
	v_pk_mul_f32 v[82:83], v[68:69], v[76:77]
	v_pk_mul_f32 v[64:65], v[64:65], v[48:49]
	v_pk_mul_f32 v[68:69], v[68:69], v[52:53]
	v_pk_fma_f32 v[80:81], v[66:67], v[74:75], v[80:81]
	v_pk_fma_f32 v[64:65], v[66:67], v[50:51], v[64:65]
	v_pk_fma_f32 v[66:67], v[70:71], v[54:55], v[68:69]
	v_pk_fma_f32 v[82:83], v[70:71], v[78:79], v[82:83]
	v_pk_add_f32 v[64:65], v[64:65], v[66:67]
	s_waitcnt lgkmcnt(2)
	v_pk_mul_f32 v[66:67], v[44:45], v[72:73]
	v_pk_mul_f32 v[70:71], v[40:41], v[76:77]
	v_pk_mul_f32 v[44:45], v[44:45], v[48:49]
	v_pk_mul_f32 v[40:41], v[40:41], v[52:53]
	v_pk_add_f32 v[68:69], v[80:81], v[82:83]
	s_waitcnt lgkmcnt(1)
	v_pk_mul_f32 v[72:73], v[56:57], v[72:73]
	v_pk_mul_f32 v[80:81], v[58:59], v[74:75]
	s_waitcnt lgkmcnt(0)
	v_pk_mul_f32 v[76:77], v[60:61], v[76:77]
	v_pk_mul_f32 v[82:83], v[62:63], v[78:79]
	v_pk_mul_f32 v[48:49], v[56:57], v[48:49]
	v_pk_mul_f32 v[56:57], v[58:59], v[50:51]
	v_pk_mul_f32 v[52:53], v[60:61], v[52:53]
	v_pk_mul_f32 v[58:59], v[62:63], v[54:55]
	v_pk_fma_f32 v[60:61], v[46:47], v[74:75], v[66:67]
	v_pk_fma_f32 v[62:63], v[42:43], v[78:79], v[70:71]
	v_pk_fma_f32 v[44:45], v[46:47], v[50:51], v[44:45]
	v_pk_fma_f32 v[40:41], v[42:43], v[54:55], v[40:41]
	v_mov_b32_e32 v84, v89
	v_add_f32_e32 v31, v68, v69
	v_add_f32_e32 v64, v64, v65
	v_pk_fma_f32 v[72:73], v[88:89], v[12:13], v[72:73] op_sel_hi:[0,1,1]
	v_pk_fma_f32 v[74:75], v[88:89], v[14:15], v[80:81] op_sel_hi:[0,1,1]
	v_pk_fma_f32 v[76:77], v[88:89], v[8:9], v[76:77] op_sel_hi:[0,1,1]
	v_pk_fma_f32 v[78:79], v[88:89], v[10:11], v[82:83] op_sel_hi:[0,1,1]
	v_pk_add_f32 v[88:89], v[62:63], v[60:61]
	v_pk_add_f32 v[90:91], v[40:41], v[44:45]
	v_add_u32_e32 v21, 0xc000, v29
	v_add_u32_e32 v30, 0x3800, v23
	ds_write2st64_b32 v29, v31, v64 offset0:248 offset1:252
	v_add_f32_e32 v29, v88, v89
	v_add_f32_e32 v88, v90, v91
	v_pk_fma_f32 v[80:81], v[84:85], v[12:13], v[48:49] op_sel_hi:[0,1,1]
	v_pk_fma_f32 v[82:83], v[84:85], v[14:15], v[56:57] op_sel_hi:[0,1,1]
	v_pk_fma_f32 v[86:87], v[84:85], v[8:9], v[52:53] op_sel_hi:[0,1,1]
	v_pk_fma_f32 v[84:85], v[84:85], v[10:11], v[58:59] op_sel_hi:[0,1,1]
	ds_read_b128 v[8:11], v22 offset:13824
	ds_read_b128 v[12:15], v22 offset:13840
	ds_read_b128 v[40:43], v22 offset:14080
	ds_read_b128 v[44:47], v22 offset:14096
	ds_read_b128 v[48:51], v22 offset:14336
	ds_read_b128 v[52:55], v22 offset:14352
	ds_read_b128 v[56:59], v22 offset:14592
	ds_read_b128 v[60:63], v22 offset:14608
	ds_read_b128 v[64:67], v22 offset:14848
	ds_read_b128 v[68:71], v22 offset:14864
	ds_read2_b32 v[30:31], v30 offset0:192 offset1:200
	v_add_f32_dpp v29, v29, v29 quad_perm:[1,0,3,2] row_mask:0xf bank_mask:0xf bound_ctrl:1
	v_add_f32_dpp v88, v88, v88 quad_perm:[1,0,3,2] row_mask:0xf bank_mask:0xf bound_ctrl:1
	v_add_u32_e32 v28, 0x4000, v23
	v_add_f32_dpp v29, v29, v29 quad_perm:[2,3,0,1] row_mask:0xf bank_mask:0xf bound_ctrl:1
	v_add_f32_dpp v89, v88, v88 quad_perm:[2,3,0,1] row_mask:0xf bank_mask:0xf bound_ctrl:1
	s_waitcnt lgkmcnt(0)
; #define SCAN_STEP(w0, w1, a0, a1, b0, b1, k0, k1, r0, r1, vi, vj, t) do { \
;                 SCAN_ROW(S0, S1, S2, S3, w0, w1, a0, a1, b0, b1, k0, k1, r0, r1, vi, (t) * 512); \
;                 SCAN_ROW(T0, T1, T2, T3, w0, w1, a0, a1, b0, b1, k0, k1, r0, r1, vj, (t) * 512 + 256); } while (0)
;     ...
;             SCAN_LOAD(w0, w1, a0, a1, b0, b1, k0, k1, r0, r1, vi, vj, 0);
; #pragma unroll
;             for (int t = 0; t < 16; t += 2) {
;                 SCAN_LOAD(W0, W1, A0, A1, B0, B1, K0, K1, R0, R1, VI, VJ, t + 1);
;                 SCAN_STEP(w0, w1, a0, a1, b0, b1, k0, k1, r0, r1, vi, vj, t);
;                 if (t + 2 < 16) SCAN_LOAD(w0, w1, a0, a1, b0, b1, k0, k1, r0, r1, vi, vj, t + 2);
;                 SCAN_STEP(W0, W1, A0, A1, B0, B1, K0, K1, R0, R1, VI, VJ, t + 1);
	v_mov_b32_e32 v92, v31
	v_add_f32_dpp v88, v29, v29 row_half_mirror row_mask:0xf bank_mask:0xf bound_ctrl:1
	v_add_f32_dpp v90, v89, v89 row_half_mirror row_mask:0xf bank_mask:0xf bound_ctrl:1
	v_pk_fma_f32 v[72:73], v[36:37], v[88:89], v[72:73] op_sel_hi:[1,0,1]
	v_pk_fma_f32 v[74:75], v[38:39], v[88:89], v[74:75] op_sel_hi:[1,0,1]
	v_pk_fma_f32 v[76:77], v[32:33], v[88:89], v[76:77] op_sel_hi:[1,0,1]
	v_pk_fma_f32 v[78:79], v[34:35], v[88:89], v[78:79] op_sel_hi:[1,0,1]
	v_pk_fma_f32 v[36:37], v[36:37], v[90:91], v[80:81] op_sel_hi:[1,0,1]
	v_pk_fma_f32 v[32:33], v[32:33], v[90:91], v[86:87] op_sel_hi:[1,0,1]
	v_pk_fma_f32 v[38:39], v[38:39], v[90:91], v[82:83] op_sel_hi:[1,0,1]
	v_pk_fma_f32 v[34:35], v[34:35], v[90:91], v[84:85] op_sel_hi:[1,0,1]
	v_pk_mul_f32 v[80:81], v[4:5], v[72:73]
	v_pk_mul_f32 v[82:83], v[0:1], v[76:77]
	v_pk_mul_f32 v[4:5], v[4:5], v[36:37]
	v_pk_mul_f32 v[0:1], v[0:1], v[32:33]
	v_pk_mul_f32 v[84:85], v[40:41], v[72:73]
	v_pk_mul_f32 v[86:87], v[44:45], v[76:77]
	v_pk_mul_f32 v[72:73], v[8:9], v[72:73]
	v_pk_mul_f32 v[88:89], v[10:11], v[74:75]
	v_pk_mul_f32 v[76:77], v[12:13], v[76:77]
	v_pk_mul_f32 v[90:91], v[14:15], v[78:79]
	v_pk_mul_f32 v[40:41], v[40:41], v[36:37]
	v_pk_mul_f32 v[44:45], v[44:45], v[32:33]
	v_pk_mul_f32 v[8:9], v[8:9], v[36:37]
	v_pk_mul_f32 v[12:13], v[12:13], v[32:33]
	v_pk_mul_f32 v[14:15], v[14:15], v[34:35]
	v_pk_fma_f32 v[32:33], v[6:7], v[74:75], v[80:81]
	v_pk_fma_f32 v[36:37], v[2:3], v[78:79], v[82:83]
	v_pk_fma_f32 v[4:5], v[6:7], v[38:39], v[4:5]
	v_pk_fma_f32 v[0:1], v[2:3], v[34:35], v[0:1]
	v_pk_fma_f32 v[2:3], v[42:43], v[74:75], v[84:85]
	v_pk_fma_f32 v[6:7], v[46:47], v[78:79], v[86:87]
	v_pk_fma_f32 v[72:73], v[56:57], v[30:31], v[72:73] op_sel_hi:[1,0,1]
	v_pk_fma_f32 v[74:75], v[58:59], v[30:31], v[88:89] op_sel_hi:[1,0,1]
	v_pk_fma_f32 v[76:77], v[60:61], v[30:31], v[76:77] op_sel_hi:[1,0,1]
	v_pk_fma_f32 v[78:79], v[62:63], v[30:31], v[90:91] op_sel_hi:[1,0,1]
	v_pk_fma_f32 v[30:31], v[42:43], v[38:39], v[40:41]
	v_pk_fma_f32 v[34:35], v[46:47], v[34:35], v[44:45]
	v_pk_add_f32 v[0:1], v[4:5], v[0:1]
	v_pk_add_f32 v[2:3], v[2:3], v[6:7]
	v_pk_add_f32 v[4:5], v[30:31], v[34:35]
	v_pk_fma_f32 v[80:81], v[56:57], v[92:93], v[8:9] op_sel_hi:[1,0,1]
	v_pk_add_f32 v[8:9], v[32:33], v[36:37]
	v_add_f32_e32 v0, v0, v1
	v_add_f32_e32 v1, v2, v3
	v_add_f32_e32 v2, v4, v5
	v_add_f32_e32 v6, v8, v9
	v_add_f32_dpp v86, v1, v1 quad_perm:[1,0,3,2] row_mask:0xf bank_mask:0xf bound_ctrl:1
	v_add_f32_dpp v87, v2, v2 quad_perm:[1,0,3,2] row_mask:0xf bank_mask:0xf bound_ctrl:1
	v_pk_mul_f32 v[10:11], v[10:11], v[38:39]
	ds_write2st64_b32 v21, v6, v0 offset0:64 offset1:68
	v_add_f32_dpp v86, v86, v86 quad_perm:[2,3,0,1] row_mask:0xf bank_mask:0xf bound_ctrl:1
	v_add_f32_dpp v87, v87, v87 quad_perm:[2,3,0,1] row_mask:0xf bank_mask:0xf bound_ctrl:1
	v_pk_fma_f32 v[82:83], v[58:59], v[92:93], v[10:11] op_sel_hi:[1,0,1]
	v_pk_fma_f32 v[60:61], v[60:61], v[92:93], v[12:13] op_sel_hi:[1,0,1]
	v_pk_fma_f32 v[62:63], v[62:63], v[92:93], v[14:15] op_sel_hi:[1,0,1]
	ds_read2_b32 v[84:85], v28 offset0:64 offset1:72
	ds_read_b128 v[0:3], v22 offset:16400
	ds_read_b128 v[4:7], v22 offset:16384
	ds_read_b128 v[8:11], v22 offset:16144
	ds_read_b128 v[12:15], v22 offset:16128
	ds_read_b128 v[28:31], v22 offset:15888
	ds_read_b128 v[32:35], v22 offset:15872
	ds_read_b128 v[36:39], v22 offset:15632
	ds_read_b128 v[40:43], v22 offset:15616
	ds_read_b128 v[44:47], v22 offset:15360
	ds_read_b128 v[56:59], v22 offset:15376
	v_add_f32_dpp v86, v86, v86 row_half_mirror row_mask:0xf bank_mask:0xf bound_ctrl:1
	v_add_f32_dpp v88, v87, v87 row_half_mirror row_mask:0xf bank_mask:0xf bound_ctrl:1
	v_pk_fma_f32 v[72:73], v[48:49], v[86:87], v[72:73] op_sel_hi:[1,0,1]
	v_pk_fma_f32 v[76:77], v[52:53], v[86:87], v[76:77] op_sel_hi:[1,0,1]
	v_pk_fma_f32 v[48:49], v[48:49], v[88:89], v[80:81] op_sel_hi:[1,0,1]
	v_pk_fma_f32 v[52:53], v[52:53], v[88:89], v[60:61] op_sel_hi:[1,0,1]
	v_pk_fma_f32 v[74:75], v[50:51], v[86:87], v[74:75] op_sel_hi:[1,0,1]
	v_pk_fma_f32 v[78:79], v[54:55], v[86:87], v[78:79] op_sel_hi:[1,0,1]
	v_pk_fma_f32 v[50:51], v[50:51], v[88:89], v[82:83] op_sel_hi:[1,0,1]
	v_pk_fma_f32 v[54:55], v[54:55], v[88:89], v[62:63] op_sel_hi:[1,0,1]
	v_pk_mul_f32 v[60:61], v[64:65], v[72:73]
	v_pk_mul_f32 v[62:63], v[68:69], v[76:77]
	v_pk_mul_f32 v[64:65], v[64:65], v[48:49]
	v_pk_mul_f32 v[68:69], v[68:69], v[52:53]
	v_pk_fma_f32 v[60:61], v[66:67], v[74:75], v[60:61]
	v_pk_fma_f32 v[62:63], v[70:71], v[78:79], v[62:63]
	v_pk_fma_f32 v[64:65], v[66:67], v[50:51], v[64:65]
	v_pk_fma_f32 v[66:67], v[70:71], v[54:55], v[68:69]
	v_pk_add_f32 v[60:61], v[60:61], v[62:63]
	v_pk_add_f32 v[62:63], v[64:65], v[66:67]
	s_waitcnt lgkmcnt(2)
	v_pk_mul_f32 v[64:65], v[40:41], v[72:73]
	v_pk_mul_f32 v[66:67], v[36:37], v[76:77]
	v_pk_mul_f32 v[40:41], v[40:41], v[48:49]
	v_pk_mul_f32 v[36:37], v[36:37], v[52:53]
	s_waitcnt lgkmcnt(1)
	v_pk_mul_f32 v[68:69], v[44:45], v[72:73]
	v_pk_mul_f32 v[70:71], v[46:47], v[74:75]
	s_waitcnt lgkmcnt(0)
; #define SCAN_STEP(w0, w1, a0, a1, b0, b1, k0, k1, r0, r1, vi, vj, t) do { \
;                 SCAN_ROW(S0, S1, S2, S3, w0, w1, a0, a1, b0, b1, k0, k1, r0, r1, vi, (t) * 512); \
;                 SCAN_ROW(T0, T1, T2, T3, w0, w1, a0, a1, b0, b1, k0, k1, r0, r1, vj, (t) * 512 + 256); } while (0)
;     ...
;             SCAN_LOAD(w0, w1, a0, a1, b0, b1, k0, k1, r0, r1, vi, vj, 0);
; #pragma unroll
;             for (int t = 0; t < 16; t += 2) {
;                 SCAN_LOAD(W0, W1, A0, A1, B0, B1, K0, K1, R0, R1, VI, VJ, t + 1);
;                 SCAN_STEP(w0, w1, a0, a1, b0, b1, k0, k1, r0, r1, vi, vj, t);
;                 if (t + 2 < 16) SCAN_LOAD(w0, w1, a0, a1, b0, b1, k0, k1, r0, r1, vi, vj, t + 2);
;                 SCAN_STEP(W0, W1, A0, A1, B0, B1, K0, K1, R0, R1, VI, VJ, t + 1);
	v_pk_mul_f32 v[72:73], v[56:57], v[76:77]
	v_pk_mul_f32 v[76:77], v[58:59], v[78:79]
	v_pk_mul_f32 v[44:45], v[44:45], v[48:49]
	v_pk_mul_f32 v[48:49], v[56:57], v[52:53]
	v_pk_mul_f32 v[52:53], v[58:59], v[54:55]
	v_add_f32_e32 v60, v60, v61
	v_add_f32_e32 v61, v62, v63
	v_pk_fma_f32 v[56:57], v[42:43], v[74:75], v[64:65]
	v_pk_fma_f32 v[58:59], v[38:39], v[78:79], v[66:67]
	v_pk_fma_f32 v[40:41], v[42:43], v[50:51], v[40:41]
	v_pk_fma_f32 v[36:37], v[38:39], v[54:55], v[36:37]
	v_add_u32_e32 v27, 0x4400, v23
	v_mov_b32_e32 v80, v85
	v_pk_mul_f32 v[46:47], v[46:47], v[50:51]
	v_pk_fma_f32 v[68:69], v[84:85], v[12:13], v[68:69] op_sel_hi:[0,1,1]
	v_pk_fma_f32 v[70:71], v[84:85], v[14:15], v[70:71] op_sel_hi:[0,1,1]
	v_pk_fma_f32 v[72:73], v[84:85], v[8:9], v[72:73] op_sel_hi:[0,1,1]
	v_pk_fma_f32 v[74:75], v[84:85], v[10:11], v[76:77] op_sel_hi:[0,1,1]
	ds_write2st64_b32 v21, v60, v61 offset0:72 offset1:76
	v_pk_add_f32 v[84:85], v[58:59], v[56:57]
	v_pk_add_f32 v[86:87], v[36:37], v[40:41]
	v_pk_fma_f32 v[76:77], v[80:81], v[12:13], v[44:45] op_sel_hi:[0,1,1]
	v_pk_fma_f32 v[78:79], v[80:81], v[14:15], v[46:47] op_sel_hi:[0,1,1]
	v_pk_fma_f32 v[82:83], v[80:81], v[8:9], v[48:49] op_sel_hi:[0,1,1]
	v_pk_fma_f32 v[80:81], v[80:81], v[10:11], v[52:53] op_sel_hi:[0,1,1]
	ds_read_b128 v[8:11], v22 offset:16896
	ds_read_b128 v[12:15], v22 offset:16912
	ds_read_b128 v[36:39], v22 offset:17152
	ds_read_b128 v[40:43], v22 offset:17168
	ds_read_b128 v[44:47], v22 offset:17408
	ds_read_b128 v[48:51], v22 offset:17424
	ds_read_b128 v[52:55], v22 offset:17664
	ds_read_b128 v[56:59], v22 offset:17680
	ds_read_b128 v[60:63], v22 offset:17920
	ds_read_b128 v[64:67], v22 offset:17936
	ds_read2_b32 v[88:89], v27 offset0:192 offset1:200
	v_add_f32_e32 v27, v84, v85
	v_add_f32_e32 v84, v86, v87
	v_add_u32_e32 v26, 0x4c00, v23
	v_add_f32_dpp v27, v27, v27 quad_perm:[1,0,3,2] row_mask:0xf bank_mask:0xf bound_ctrl:1
	v_add_f32_dpp v84, v84, v84 quad_perm:[1,0,3,2] row_mask:0xf bank_mask:0xf bound_ctrl:1
	s_waitcnt lgkmcnt(0)
	v_mov_b32_e32 v90, v89
	v_add_f32_dpp v27, v27, v27 quad_perm:[2,3,0,1] row_mask:0xf bank_mask:0xf bound_ctrl:1
	v_add_f32_dpp v85, v84, v84 quad_perm:[2,3,0,1] row_mask:0xf bank_mask:0xf bound_ctrl:1
	v_add_u32_e32 v25, 0x5000, v23
	v_add_f32_dpp v84, v27, v27 row_half_mirror row_mask:0xf bank_mask:0xf bound_ctrl:1
	v_add_f32_dpp v86, v85, v85 row_half_mirror row_mask:0xf bank_mask:0xf bound_ctrl:1
	v_pk_fma_f32 v[68:69], v[32:33], v[84:85], v[68:69] op_sel_hi:[1,0,1]
	v_pk_fma_f32 v[72:73], v[28:29], v[84:85], v[72:73] op_sel_hi:[1,0,1]
	v_pk_fma_f32 v[32:33], v[32:33], v[86:87], v[76:77] op_sel_hi:[1,0,1]
	v_pk_fma_f32 v[28:29], v[28:29], v[86:87], v[82:83] op_sel_hi:[1,0,1]
	v_pk_fma_f32 v[70:71], v[34:35], v[84:85], v[70:71] op_sel_hi:[1,0,1]
	v_pk_fma_f32 v[74:75], v[30:31], v[84:85], v[74:75] op_sel_hi:[1,0,1]
	v_pk_fma_f32 v[34:35], v[34:35], v[86:87], v[78:79] op_sel_hi:[1,0,1]
	v_pk_fma_f32 v[30:31], v[30:31], v[86:87], v[80:81] op_sel_hi:[1,0,1]
	v_pk_mul_f32 v[76:77], v[4:5], v[68:69]
	v_pk_mul_f32 v[78:79], v[0:1], v[72:73]
	v_pk_mul_f32 v[4:5], v[4:5], v[32:33]
	v_pk_mul_f32 v[0:1], v[0:1], v[28:29]
	v_pk_mul_f32 v[80:81], v[36:37], v[68:69]
	v_pk_mul_f32 v[82:83], v[40:41], v[72:73]
	v_pk_mul_f32 v[36:37], v[36:37], v[32:33]
	v_pk_mul_f32 v[40:41], v[40:41], v[28:29]
	v_pk_mul_f32 v[68:69], v[8:9], v[68:69]
	v_pk_mul_f32 v[84:85], v[10:11], v[70:71]
	v_pk_mul_f32 v[72:73], v[12:13], v[72:73]
	v_pk_mul_f32 v[86:87], v[14:15], v[74:75]
	v_pk_mul_f32 v[8:9], v[8:9], v[32:33]
	v_pk_mul_f32 v[10:11], v[10:11], v[34:35]
	v_pk_mul_f32 v[12:13], v[12:13], v[28:29]
	v_pk_mul_f32 v[14:15], v[14:15], v[30:31]
	v_pk_fma_f32 v[28:29], v[6:7], v[70:71], v[76:77]
	v_pk_fma_f32 v[32:33], v[2:3], v[74:75], v[78:79]
	v_pk_fma_f32 v[4:5], v[6:7], v[34:35], v[4:5]
	v_pk_fma_f32 v[0:1], v[2:3], v[30:31], v[0:1]
	v_pk_fma_f32 v[2:3], v[38:39], v[70:71], v[80:81]
	v_pk_fma_f32 v[6:7], v[42:43], v[74:75], v[82:83]
	v_pk_fma_f32 v[34:35], v[38:39], v[34:35], v[36:37]
	v_pk_fma_f32 v[30:31], v[42:43], v[30:31], v[40:41]
	v_pk_add_f32 v[0:1], v[4:5], v[0:1]
	v_pk_add_f32 v[2:3], v[2:3], v[6:7]
	v_pk_add_f32 v[4:5], v[34:35], v[30:31]
	v_pk_fma_f32 v[42:43], v[52:53], v[90:91], v[8:9] op_sel_hi:[1,0,1]
	v_pk_add_f32 v[8:9], v[28:29], v[32:33]
	v_add_f32_e32 v0, v0, v1
	v_add_f32_e32 v1, v2, v3
	v_add_f32_e32 v2, v4, v5
	v_pk_fma_f32 v[70:71], v[54:55], v[88:89], v[84:85] op_sel_hi:[1,0,1]
	v_add_f32_e32 v6, v8, v9
	v_add_f32_dpp v84, v1, v1 quad_perm:[1,0,3,2] row_mask:0xf bank_mask:0xf bound_ctrl:1
	v_add_f32_dpp v85, v2, v2 quad_perm:[1,0,3,2] row_mask:0xf bank_mask:0xf bound_ctrl:1
	ds_write2st64_b32 v21, v6, v0 offset0:80 offset1:84
	v_add_f32_dpp v84, v84, v84 quad_perm:[2,3,0,1] row_mask:0xf bank_mask:0xf bound_ctrl:1
	v_add_f32_dpp v85, v85, v85 quad_perm:[2,3,0,1] row_mask:0xf bank_mask:0xf bound_ctrl:1
	v_pk_fma_f32 v[68:69], v[52:53], v[88:89], v[68:69] op_sel_hi:[1,0,1]
	v_pk_fma_f32 v[72:73], v[56:57], v[88:89], v[72:73] op_sel_hi:[1,0,1]
	v_pk_fma_f32 v[74:75], v[58:59], v[88:89], v[86:87] op_sel_hi:[1,0,1]
	v_pk_fma_f32 v[76:77], v[54:55], v[90:91], v[10:11] op_sel_hi:[1,0,1]
	v_pk_fma_f32 v[78:79], v[56:57], v[90:91], v[12:13] op_sel_hi:[1,0,1]
	v_pk_fma_f32 v[80:81], v[58:59], v[90:91], v[14:15] op_sel_hi:[1,0,1]
	ds_read2_b32 v[82:83], v26 offset0:64 offset1:72
	ds_read_b128 v[0:3], v22 offset:19472
	ds_read_b128 v[4:7], v22 offset:19456
	ds_read_b128 v[8:11], v22 offset:19216
	ds_read_b128 v[12:15], v22 offset:19200
	ds_read_b128 v[26:29], v22 offset:18960
	ds_read_b128 v[30:33], v22 offset:18944
	ds_read_b128 v[34:37], v22 offset:18704
	ds_read_b128 v[38:41], v22 offset:18688
	ds_read_b128 v[52:55], v22 offset:18432
	ds_read_b128 v[56:59], v22 offset:18448
	v_add_f32_dpp v84, v84, v84 row_half_mirror row_mask:0xf bank_mask:0xf bound_ctrl:1
	v_add_f32_dpp v86, v85, v85 row_half_mirror row_mask:0xf bank_mask:0xf bound_ctrl:1
	v_pk_fma_f32 v[68:69], v[44:45], v[84:85], v[68:69] op_sel_hi:[1,0,1]
	v_pk_fma_f32 v[70:71], v[46:47], v[84:85], v[70:71] op_sel_hi:[1,0,1]
	v_pk_fma_f32 v[72:73], v[48:49], v[84:85], v[72:73] op_sel_hi:[1,0,1]
	v_pk_fma_f32 v[42:43], v[44:45], v[86:87], v[42:43] op_sel_hi:[1,0,1]
	v_pk_fma_f32 v[44:45], v[46:47], v[86:87], v[76:77] op_sel_hi:[1,0,1]
	v_pk_fma_f32 v[46:47], v[48:49], v[86:87], v[78:79] op_sel_hi:[1,0,1]
	v_pk_fma_f32 v[74:75], v[50:51], v[84:85], v[74:75] op_sel_hi:[1,0,1]
	v_pk_fma_f32 v[48:49], v[50:51], v[86:87], v[80:81] op_sel_hi:[1,0,1]
	v_pk_mul_f32 v[50:51], v[60:61], v[68:69]
	v_pk_mul_f32 v[76:77], v[64:65], v[72:73]
	v_pk_mul_f32 v[60:61], v[60:61], v[42:43]
	v_pk_mul_f32 v[64:65], v[64:65], v[46:47]
	v_pk_fma_f32 v[50:51], v[62:63], v[70:71], v[50:51]
	v_pk_fma_f32 v[76:77], v[66:67], v[74:75], v[76:77]
	v_pk_fma_f32 v[60:61], v[62:63], v[44:45], v[60:61]
	v_pk_fma_f32 v[62:63], v[66:67], v[48:49], v[64:65]
	v_pk_add_f32 v[50:51], v[50:51], v[76:77]
	v_pk_add_f32 v[60:61], v[60:61], v[62:63]
	s_waitcnt lgkmcnt(2)
; #define SCAN_STEP(w0, w1, a0, a1, b0, b1, k0, k1, r0, r1, vi, vj, t) do { \
;                 SCAN_ROW(S0, S1, S2, S3, w0, w1, a0, a1, b0, b1, k0, k1, r0, r1, vi, (t) * 512); \
;                 SCAN_ROW(T0, T1, T2, T3, w0, w1, a0, a1, b0, b1, k0, k1, r0, r1, vj, (t) * 512 + 256); } while (0)
;     ...
;             SCAN_LOAD(w0, w1, a0, a1, b0, b1, k0, k1, r0, r1, vi, vj, 0);
; #pragma unroll
;             for (int t = 0; t < 16; t += 2) {
;                 SCAN_LOAD(W0, W1, A0, A1, B0, B1, K0, K1, R0, R1, VI, VJ, t + 1);
;                 SCAN_STEP(w0, w1, a0, a1, b0, b1, k0, k1, r0, r1, vi, vj, t);
;                 if (t + 2 < 16) SCAN_LOAD(w0, w1, a0, a1, b0, b1, k0, k1, r0, r1, vi, vj, t + 2);
;                 SCAN_STEP(W0, W1, A0, A1, B0, B1, K0, K1, R0, R1, VI, VJ, t + 1);
	v_pk_mul_f32 v[62:63], v[38:39], v[68:69]
	v_pk_mul_f32 v[64:65], v[34:35], v[72:73]
	v_pk_mul_f32 v[38:39], v[38:39], v[42:43]
	v_pk_mul_f32 v[34:35], v[34:35], v[46:47]
	s_waitcnt lgkmcnt(1)
	v_pk_mul_f32 v[66:67], v[52:53], v[68:69]
	v_pk_mul_f32 v[68:69], v[54:55], v[70:71]
	s_waitcnt lgkmcnt(0)
	v_pk_mul_f32 v[72:73], v[56:57], v[72:73]
	v_pk_mul_f32 v[76:77], v[58:59], v[74:75]
	v_pk_mul_f32 v[42:43], v[52:53], v[42:43]
	v_pk_mul_f32 v[52:53], v[54:55], v[44:45]
	v_pk_mul_f32 v[46:47], v[56:57], v[46:47]
	v_pk_mul_f32 v[54:55], v[58:59], v[48:49]
	v_add_f32_e32 v58, v50, v51
	v_add_f32_e32 v59, v60, v61
	v_pk_fma_f32 v[50:51], v[40:41], v[70:71], v[62:63]
	v_pk_fma_f32 v[56:57], v[36:37], v[74:75], v[64:65]
	v_pk_fma_f32 v[38:39], v[40:41], v[44:45], v[38:39]
	v_pk_fma_f32 v[34:35], v[36:37], v[48:49], v[34:35]
	v_mov_b32_e32 v78, v83
	v_pk_fma_f32 v[66:67], v[82:83], v[12:13], v[66:67] op_sel_hi:[0,1,1]
	v_pk_fma_f32 v[68:69], v[82:83], v[14:15], v[68:69] op_sel_hi:[0,1,1]
	v_pk_fma_f32 v[70:71], v[82:83], v[8:9], v[72:73] op_sel_hi:[0,1,1]
	v_pk_fma_f32 v[72:73], v[82:83], v[10:11], v[76:77] op_sel_hi:[0,1,1]
	ds_write2st64_b32 v21, v58, v59 offset0:88 offset1:92
	v_pk_add_f32 v[82:83], v[56:57], v[50:51]
	v_pk_add_f32 v[84:85], v[34:35], v[38:39]
	v_pk_fma_f32 v[74:75], v[78:79], v[12:13], v[42:43] op_sel_hi:[0,1,1]
	v_pk_fma_f32 v[76:77], v[78:79], v[14:15], v[52:53] op_sel_hi:[0,1,1]
	v_pk_fma_f32 v[80:81], v[78:79], v[8:9], v[46:47] op_sel_hi:[0,1,1]
	v_pk_fma_f32 v[78:79], v[78:79], v[10:11], v[54:55] op_sel_hi:[0,1,1]
	ds_read_b128 v[8:11], v22 offset:19968
	ds_read_b128 v[12:15], v22 offset:19984
	ds_read_b128 v[34:37], v22 offset:20224
	ds_read_b128 v[38:41], v22 offset:20240
	ds_read_b128 v[42:45], v22 offset:20480
	ds_read_b128 v[46:49], v22 offset:20496
	ds_read_b128 v[50:53], v22 offset:20736
	ds_read_b128 v[54:57], v22 offset:20752
	ds_read_b128 v[58:61], v22 offset:20992
	ds_read_b128 v[62:65], v22 offset:21008
	ds_read2_b32 v[86:87], v25 offset0:192 offset1:200
	v_add_f32_e32 v25, v82, v83
	v_add_f32_e32 v82, v84, v85
	v_add_u32_e32 v24, 0x5800, v23
	v_add_f32_dpp v25, v25, v25 quad_perm:[1,0,3,2] row_mask:0xf bank_mask:0xf bound_ctrl:1
	v_add_f32_dpp v82, v82, v82 quad_perm:[1,0,3,2] row_mask:0xf bank_mask:0xf bound_ctrl:1
	s_waitcnt lgkmcnt(0)
	v_mov_b32_e32 v88, v87
	v_add_f32_dpp v25, v25, v25 quad_perm:[2,3,0,1] row_mask:0xf bank_mask:0xf bound_ctrl:1
	v_add_f32_dpp v83, v82, v82 quad_perm:[2,3,0,1] row_mask:0xf bank_mask:0xf bound_ctrl:1
	v_add_u32_e32 v23, 0x5c00, v23
	v_add_f32_dpp v82, v25, v25 row_half_mirror row_mask:0xf bank_mask:0xf bound_ctrl:1
	v_add_f32_dpp v84, v83, v83 row_half_mirror row_mask:0xf bank_mask:0xf bound_ctrl:1
	v_pk_fma_f32 v[66:67], v[30:31], v[82:83], v[66:67] op_sel_hi:[1,0,1]
	v_pk_fma_f32 v[70:71], v[26:27], v[82:83], v[70:71] op_sel_hi:[1,0,1]
	v_pk_fma_f32 v[30:31], v[30:31], v[84:85], v[74:75] op_sel_hi:[1,0,1]
	v_pk_fma_f32 v[26:27], v[26:27], v[84:85], v[80:81] op_sel_hi:[1,0,1]
	v_pk_fma_f32 v[68:69], v[32:33], v[82:83], v[68:69] op_sel_hi:[1,0,1]
	v_pk_fma_f32 v[72:73], v[28:29], v[82:83], v[72:73] op_sel_hi:[1,0,1]
	v_pk_fma_f32 v[32:33], v[32:33], v[84:85], v[76:77] op_sel_hi:[1,0,1]
	v_pk_fma_f32 v[28:29], v[28:29], v[84:85], v[78:79] op_sel_hi:[1,0,1]
	v_pk_mul_f32 v[74:75], v[4:5], v[66:67]
	v_pk_mul_f32 v[76:77], v[0:1], v[70:71]
	v_pk_mul_f32 v[4:5], v[4:5], v[30:31]
	v_pk_mul_f32 v[0:1], v[0:1], v[26:27]
	v_pk_mul_f32 v[78:79], v[34:35], v[66:67]
	v_pk_mul_f32 v[80:81], v[38:39], v[70:71]
	v_pk_mul_f32 v[34:35], v[34:35], v[30:31]
	v_pk_mul_f32 v[38:39], v[38:39], v[26:27]
	v_pk_mul_f32 v[66:67], v[8:9], v[66:67]
	v_pk_mul_f32 v[82:83], v[10:11], v[68:69]
	v_pk_mul_f32 v[70:71], v[12:13], v[70:71]
	v_pk_mul_f32 v[84:85], v[14:15], v[72:73]
	v_pk_mul_f32 v[8:9], v[8:9], v[30:31]
	v_pk_mul_f32 v[10:11], v[10:11], v[32:33]
	v_pk_mul_f32 v[12:13], v[12:13], v[26:27]
	v_pk_mul_f32 v[14:15], v[14:15], v[28:29]
	v_pk_fma_f32 v[26:27], v[6:7], v[68:69], v[74:75]
	v_pk_fma_f32 v[30:31], v[2:3], v[72:73], v[76:77]
	v_pk_fma_f32 v[4:5], v[6:7], v[32:33], v[4:5]
	v_pk_fma_f32 v[0:1], v[2:3], v[28:29], v[0:1]
	v_pk_fma_f32 v[2:3], v[36:37], v[68:69], v[78:79]
	v_pk_fma_f32 v[6:7], v[40:41], v[72:73], v[80:81]
	v_pk_fma_f32 v[32:33], v[36:37], v[32:33], v[34:35]
	v_pk_fma_f32 v[28:29], v[40:41], v[28:29], v[38:39]
	v_pk_add_f32 v[0:1], v[4:5], v[0:1]
	v_pk_add_f32 v[2:3], v[2:3], v[6:7]
	v_pk_add_f32 v[4:5], v[32:33], v[28:29]
	v_pk_fma_f32 v[40:41], v[50:51], v[88:89], v[8:9] op_sel_hi:[1,0,1]
	v_pk_add_f32 v[8:9], v[26:27], v[30:31]
	v_add_f32_e32 v0, v0, v1
	v_add_f32_e32 v1, v2, v3
	v_add_f32_e32 v2, v4, v5
	v_pk_fma_f32 v[68:69], v[52:53], v[86:87], v[82:83] op_sel_hi:[1,0,1]
	v_add_f32_e32 v6, v8, v9
	v_add_f32_dpp v82, v1, v1 quad_perm:[1,0,3,2] row_mask:0xf bank_mask:0xf bound_ctrl:1
	v_add_f32_dpp v83, v2, v2 quad_perm:[1,0,3,2] row_mask:0xf bank_mask:0xf bound_ctrl:1
	ds_write2st64_b32 v21, v6, v0 offset0:96 offset1:100
	v_add_f32_dpp v82, v82, v82 quad_perm:[2,3,0,1] row_mask:0xf bank_mask:0xf bound_ctrl:1
	v_add_f32_dpp v83, v83, v83 quad_perm:[2,3,0,1] row_mask:0xf bank_mask:0xf bound_ctrl:1
	v_pk_fma_f32 v[66:67], v[50:51], v[86:87], v[66:67] op_sel_hi:[1,0,1]
	v_pk_fma_f32 v[70:71], v[54:55], v[86:87], v[70:71] op_sel_hi:[1,0,1]
	v_pk_fma_f32 v[72:73], v[56:57], v[86:87], v[84:85] op_sel_hi:[1,0,1]
	v_pk_fma_f32 v[74:75], v[52:53], v[88:89], v[10:11] op_sel_hi:[1,0,1]
	v_pk_fma_f32 v[76:77], v[54:55], v[88:89], v[12:13] op_sel_hi:[1,0,1]
	v_pk_fma_f32 v[78:79], v[56:57], v[88:89], v[14:15] op_sel_hi:[1,0,1]
	ds_read2_b32 v[80:81], v24 offset0:64 offset1:72
; #define SCAN_STEP(w0, w1, a0, a1, b0, b1, k0, k1, r0, r1, vi, vj, t) do { \
;                 SCAN_ROW(S0, S1, S2, S3, w0, w1, a0, a1, b0, b1, k0, k1, r0, r1, vi, (t) * 512); \
;                 SCAN_ROW(T0, T1, T2, T3, w0, w1, a0, a1, b0, b1, k0, k1, r0, r1, vj, (t) * 512 + 256); } while (0)
;     ...
;             SCAN_LOAD(w0, w1, a0, a1, b0, b1, k0, k1, r0, r1, vi, vj, 0);
; #pragma unroll
;             for (int t = 0; t < 16; t += 2) {
;                 SCAN_LOAD(W0, W1, A0, A1, B0, B1, K0, K1, R0, R1, VI, VJ, t + 1);
;                 SCAN_STEP(w0, w1, a0, a1, b0, b1, k0, k1, r0, r1, vi, vj, t);
;                 if (t + 2 < 16) SCAN_LOAD(w0, w1, a0, a1, b0, b1, k0, k1, r0, r1, vi, vj, t + 2);
;                 SCAN_STEP(W0, W1, A0, A1, B0, B1, K0, K1, R0, R1, VI, VJ, t + 1);
	ds_read_b128 v[0:3], v22 offset:22544
	ds_read_b128 v[4:7], v22 offset:22528
	ds_read_b128 v[8:11], v22 offset:22288
	ds_read_b128 v[12:15], v22 offset:22272
	ds_read_b128 v[24:27], v22 offset:22032
	ds_read_b128 v[28:31], v22 offset:22016
	ds_read_b128 v[32:35], v22 offset:21776
	ds_read_b128 v[36:39], v22 offset:21760
	ds_read_b128 v[50:53], v22 offset:21504
	ds_read_b128 v[54:57], v22 offset:21520
	v_add_f32_dpp v82, v82, v82 row_half_mirror row_mask:0xf bank_mask:0xf bound_ctrl:1
	v_add_f32_dpp v84, v83, v83 row_half_mirror row_mask:0xf bank_mask:0xf bound_ctrl:1
	v_pk_fma_f32 v[66:67], v[42:43], v[82:83], v[66:67] op_sel_hi:[1,0,1]
	v_pk_fma_f32 v[68:69], v[44:45], v[82:83], v[68:69] op_sel_hi:[1,0,1]
	v_pk_fma_f32 v[70:71], v[46:47], v[82:83], v[70:71] op_sel_hi:[1,0,1]
	v_pk_fma_f32 v[40:41], v[42:43], v[84:85], v[40:41] op_sel_hi:[1,0,1]
	v_pk_fma_f32 v[42:43], v[44:45], v[84:85], v[74:75] op_sel_hi:[1,0,1]
	v_pk_fma_f32 v[44:45], v[46:47], v[84:85], v[76:77] op_sel_hi:[1,0,1]
	v_pk_fma_f32 v[72:73], v[48:49], v[82:83], v[72:73] op_sel_hi:[1,0,1]
	v_pk_fma_f32 v[46:47], v[48:49], v[84:85], v[78:79] op_sel_hi:[1,0,1]
	v_pk_mul_f32 v[48:49], v[58:59], v[66:67]
	v_pk_mul_f32 v[74:75], v[62:63], v[70:71]
	v_pk_mul_f32 v[58:59], v[58:59], v[40:41]
	v_pk_mul_f32 v[62:63], v[62:63], v[44:45]
	v_pk_fma_f32 v[48:49], v[60:61], v[68:69], v[48:49]
	v_pk_fma_f32 v[74:75], v[64:65], v[72:73], v[74:75]
	v_pk_fma_f32 v[58:59], v[60:61], v[42:43], v[58:59]
	v_pk_fma_f32 v[60:61], v[64:65], v[46:47], v[62:63]
	v_pk_add_f32 v[48:49], v[48:49], v[74:75]
	v_pk_add_f32 v[58:59], v[58:59], v[60:61]
	s_waitcnt lgkmcnt(2)
	v_pk_mul_f32 v[60:61], v[36:37], v[66:67]
	v_pk_mul_f32 v[62:63], v[32:33], v[70:71]
	v_pk_mul_f32 v[36:37], v[36:37], v[40:41]
	v_pk_mul_f32 v[32:33], v[32:33], v[44:45]
	s_waitcnt lgkmcnt(1)
	v_pk_mul_f32 v[64:65], v[50:51], v[66:67]
	v_pk_mul_f32 v[66:67], v[52:53], v[68:69]
	s_waitcnt lgkmcnt(0)
	v_pk_mul_f32 v[70:71], v[54:55], v[70:71]
	v_pk_mul_f32 v[74:75], v[56:57], v[72:73]
	v_pk_mul_f32 v[40:41], v[50:51], v[40:41]
	v_pk_mul_f32 v[50:51], v[52:53], v[42:43]
	v_pk_mul_f32 v[44:45], v[54:55], v[44:45]
	v_pk_mul_f32 v[52:53], v[56:57], v[46:47]
	v_add_f32_e32 v56, v48, v49
	v_pk_fma_f32 v[48:49], v[38:39], v[68:69], v[60:61]
	v_pk_fma_f32 v[54:55], v[34:35], v[72:73], v[62:63]
	v_pk_fma_f32 v[36:37], v[38:39], v[42:43], v[36:37]
	v_pk_fma_f32 v[32:33], v[34:35], v[46:47], v[32:33]
	v_mov_b32_e32 v76, v81
	v_add_f32_e32 v57, v58, v59
	v_pk_fma_f32 v[64:65], v[80:81], v[12:13], v[64:65] op_sel_hi:[0,1,1]
	v_pk_fma_f32 v[66:67], v[80:81], v[14:15], v[66:67] op_sel_hi:[0,1,1]
	v_pk_fma_f32 v[68:69], v[80:81], v[8:9], v[70:71] op_sel_hi:[0,1,1]
	v_pk_fma_f32 v[70:71], v[80:81], v[10:11], v[74:75] op_sel_hi:[0,1,1]
	v_pk_add_f32 v[80:81], v[54:55], v[48:49]
	v_pk_add_f32 v[82:83], v[32:33], v[36:37]
	ds_write2st64_b32 v21, v56, v57 offset0:104 offset1:108
	v_add_f32_e32 v80, v80, v81
	v_add_f32_e32 v81, v82, v83
	v_pk_fma_f32 v[72:73], v[76:77], v[12:13], v[40:41] op_sel_hi:[0,1,1]
	v_pk_fma_f32 v[74:75], v[76:77], v[14:15], v[50:51] op_sel_hi:[0,1,1]
	v_pk_fma_f32 v[78:79], v[76:77], v[8:9], v[44:45] op_sel_hi:[0,1,1]
	v_pk_fma_f32 v[76:77], v[76:77], v[10:11], v[52:53] op_sel_hi:[0,1,1]
	ds_read_b128 v[8:11], v22 offset:23040
	ds_read_b128 v[12:15], v22 offset:23056
	ds_read_b128 v[32:35], v22 offset:23296
	ds_read_b128 v[36:39], v22 offset:23312
	ds_read_b128 v[40:43], v22 offset:23552
	ds_read_b128 v[44:47], v22 offset:23568
	ds_read_b128 v[48:51], v22 offset:23808
	ds_read_b128 v[52:55], v22 offset:23824
	ds_read_b128 v[56:59], v22 offset:24064
	ds_read_b128 v[60:63], v22 offset:24080
	ds_read2_b32 v[22:23], v23 offset0:192 offset1:200
	v_add_f32_dpp v80, v80, v80 quad_perm:[1,0,3,2] row_mask:0xf bank_mask:0xf bound_ctrl:1
	v_add_f32_dpp v81, v81, v81 quad_perm:[1,0,3,2] row_mask:0xf bank_mask:0xf bound_ctrl:1
	s_add_i32 s7, s7, 1
	v_add_f32_dpp v80, v80, v80 quad_perm:[2,3,0,1] row_mask:0xf bank_mask:0xf bound_ctrl:1
	v_add_f32_dpp v81, v81, v81 quad_perm:[2,3,0,1] row_mask:0xf bank_mask:0xf bound_ctrl:1
	s_waitcnt lgkmcnt(0)
; #define SCAN_STEP(w0, w1, a0, a1, b0, b1, k0, k1, r0, r1, vi, vj, t) do { \
;                 SCAN_ROW(S0, S1, S2, S3, w0, w1, a0, a1, b0, b1, k0, k1, r0, r1, vi, (t) * 512); \
;                 SCAN_ROW(T0, T1, T2, T3, w0, w1, a0, a1, b0, b1, k0, k1, r0, r1, vj, (t) * 512 + 256); } while (0)
;     ...
;             SCAN_LOAD(w0, w1, a0, a1, b0, b1, k0, k1, r0, r1, vi, vj, 0);
; #pragma unroll
;             for (int t = 0; t < 16; t += 2) {
;                 SCAN_LOAD(W0, W1, A0, A1, B0, B1, K0, K1, R0, R1, VI, VJ, t + 1);
;                 SCAN_STEP(w0, w1, a0, a1, b0, b1, k0, k1, r0, r1, vi, vj, t);
;                 if (t + 2 < 16) SCAN_LOAD(w0, w1, a0, a1, b0, b1, k0, k1, r0, r1, vi, vj, t + 2);
;                 SCAN_STEP(W0, W1, A0, A1, B0, B1, K0, K1, R0, R1, VI, VJ, t + 1);
;             }
;     ...
;             __syncthreads();
;         }
;         float* so = P.out + (samp ? O_RS + ((size_t)(l * 16 + b) * 16 + h) * 4096 : O_RP + ((size_t)(l * 4 + b) * 16 + h) * 4096) + js;
;         f32x4 o0, o1; o0.xy = S0; o0.zw = S1; o1.xy = S2; o1.zw = S3;
;         *(f32x4*)(so + i0 * 64) = o0; *(f32x4*)(so + i0 * 64 + 4) = o1;
;         o0.xy = T0; o0.zw = T1; o1.xy = T2; o1.zw = T3;
;         *(f32x4*)(so + i1 * 64) = o0; *(f32x4*)(so + i1 * 64 + 4) = o1;
	v_mov_b32_e32 v84, v23
	v_add_f32_dpp v80, v80, v80 row_half_mirror row_mask:0xf bank_mask:0xf bound_ctrl:1
	v_add_f32_dpp v82, v81, v81 row_half_mirror row_mask:0xf bank_mask:0xf bound_ctrl:1
	v_pk_fma_f32 v[64:65], v[28:29], v[80:81], v[64:65] op_sel_hi:[1,0,1]
	v_pk_fma_f32 v[68:69], v[24:25], v[80:81], v[68:69] op_sel_hi:[1,0,1]
	v_pk_fma_f32 v[28:29], v[28:29], v[82:83], v[72:73] op_sel_hi:[1,0,1]
	v_pk_fma_f32 v[24:25], v[24:25], v[82:83], v[78:79] op_sel_hi:[1,0,1]
	v_pk_fma_f32 v[66:67], v[30:31], v[80:81], v[66:67] op_sel_hi:[1,0,1]
	v_pk_fma_f32 v[70:71], v[26:27], v[80:81], v[70:71] op_sel_hi:[1,0,1]
	v_pk_fma_f32 v[30:31], v[30:31], v[82:83], v[74:75] op_sel_hi:[1,0,1]
	v_pk_fma_f32 v[26:27], v[26:27], v[82:83], v[76:77] op_sel_hi:[1,0,1]
	v_pk_mul_f32 v[72:73], v[4:5], v[64:65]
	v_pk_mul_f32 v[74:75], v[0:1], v[68:69]
	v_pk_mul_f32 v[4:5], v[4:5], v[28:29]
	v_pk_mul_f32 v[0:1], v[0:1], v[24:25]
	v_pk_mul_f32 v[76:77], v[32:33], v[64:65]
	v_pk_mul_f32 v[78:79], v[36:37], v[68:69]
	v_pk_mul_f32 v[32:33], v[32:33], v[28:29]
	v_pk_mul_f32 v[36:37], v[36:37], v[24:25]
	v_pk_mul_f32 v[64:65], v[8:9], v[64:65]
	v_pk_mul_f32 v[80:81], v[10:11], v[66:67]
	v_pk_mul_f32 v[68:69], v[12:13], v[68:69]
	v_pk_mul_f32 v[82:83], v[14:15], v[70:71]
	v_pk_mul_f32 v[8:9], v[8:9], v[28:29]
	v_pk_mul_f32 v[10:11], v[10:11], v[30:31]
	v_pk_mul_f32 v[12:13], v[12:13], v[24:25]
	v_pk_mul_f32 v[14:15], v[14:15], v[26:27]
	v_pk_fma_f32 v[24:25], v[6:7], v[66:67], v[72:73]
	v_pk_fma_f32 v[28:29], v[2:3], v[70:71], v[74:75]
	v_pk_fma_f32 v[4:5], v[6:7], v[30:31], v[4:5]
	v_pk_fma_f32 v[0:1], v[2:3], v[26:27], v[0:1]
	v_pk_fma_f32 v[2:3], v[34:35], v[66:67], v[76:77]
	v_pk_fma_f32 v[6:7], v[38:39], v[70:71], v[78:79]
	v_pk_fma_f32 v[30:31], v[34:35], v[30:31], v[32:33]
	v_pk_fma_f32 v[26:27], v[38:39], v[26:27], v[36:37]
	v_pk_fma_f32 v[32:33], v[48:49], v[84:85], v[8:9] op_sel_hi:[1,0,1]
	v_pk_add_f32 v[8:9], v[24:25], v[28:29]
	v_pk_add_f32 v[0:1], v[4:5], v[0:1]
	v_pk_add_f32 v[2:3], v[2:3], v[6:7]
	v_pk_add_f32 v[4:5], v[30:31], v[26:27]
	v_add_f32_e32 v6, v8, v9
	v_add_f32_e32 v0, v0, v1
	v_add_f32_e32 v1, v2, v3
	v_add_f32_e32 v2, v4, v5
	ds_write2st64_b32 v21, v6, v0 offset0:112 offset1:116
	v_add_f32_dpp v0, v1, v1 quad_perm:[1,0,3,2] row_mask:0xf bank_mask:0xf bound_ctrl:1
	v_add_f32_dpp v1, v2, v2 quad_perm:[1,0,3,2] row_mask:0xf bank_mask:0xf bound_ctrl:1
	v_pk_fma_f32 v[64:65], v[48:49], v[22:23], v[64:65] op_sel_hi:[1,0,1]
	v_add_f32_dpp v0, v0, v0 quad_perm:[2,3,0,1] row_mask:0xf bank_mask:0xf bound_ctrl:1
	v_add_f32_dpp v1, v1, v1 quad_perm:[2,3,0,1] row_mask:0xf bank_mask:0xf bound_ctrl:1
	v_pk_fma_f32 v[66:67], v[50:51], v[22:23], v[80:81] op_sel_hi:[1,0,1]
	v_pk_fma_f32 v[68:69], v[52:53], v[22:23], v[68:69] op_sel_hi:[1,0,1]
	v_pk_fma_f32 v[22:23], v[54:55], v[22:23], v[82:83] op_sel_hi:[1,0,1]
	v_pk_fma_f32 v[36:37], v[52:53], v[84:85], v[12:13] op_sel_hi:[1,0,1]
	v_add_f32_dpp v0, v0, v0 row_half_mirror row_mask:0xf bank_mask:0xf bound_ctrl:1
	v_add_f32_dpp v6, v1, v1 row_half_mirror row_mask:0xf bank_mask:0xf bound_ctrl:1
	v_pk_fma_f32 v[34:35], v[50:51], v[84:85], v[10:11] op_sel_hi:[1,0,1]
	v_pk_fma_f32 v[38:39], v[54:55], v[84:85], v[14:15] op_sel_hi:[1,0,1]
	v_pk_fma_f32 v[12:13], v[40:41], v[0:1], v[64:65] op_sel_hi:[1,0,1]
	v_pk_fma_f32 v[14:15], v[42:43], v[0:1], v[66:67] op_sel_hi:[1,0,1]
	v_pk_fma_f32 v[8:9], v[44:45], v[0:1], v[68:69] op_sel_hi:[1,0,1]
	v_pk_fma_f32 v[10:11], v[46:47], v[0:1], v[22:23] op_sel_hi:[1,0,1]
	v_pk_fma_f32 v[0:1], v[40:41], v[6:7], v[32:33] op_sel_hi:[1,0,1]
	v_pk_fma_f32 v[4:5], v[44:45], v[6:7], v[36:37] op_sel_hi:[1,0,1]
	v_pk_fma_f32 v[2:3], v[42:43], v[6:7], v[34:35] op_sel_hi:[1,0,1]
	v_pk_fma_f32 v[6:7], v[46:47], v[6:7], v[38:39] op_sel_hi:[1,0,1]
	v_pk_mul_f32 v[22:23], v[56:57], v[12:13]
	v_pk_mul_f32 v[24:25], v[60:61], v[8:9]
	v_pk_mul_f32 v[26:27], v[56:57], v[0:1]
	v_pk_mul_f32 v[28:29], v[60:61], v[4:5]
	v_pk_fma_f32 v[22:23], v[58:59], v[14:15], v[22:23]
	v_pk_fma_f32 v[24:25], v[62:63], v[10:11], v[24:25]
	v_pk_fma_f32 v[26:27], v[58:59], v[2:3], v[26:27]
	v_pk_fma_f32 v[28:29], v[62:63], v[6:7], v[28:29]
	v_pk_add_f32 v[22:23], v[22:23], v[24:25]
	v_pk_add_f32 v[24:25], v[26:27], v[28:29]
	s_cmpk_eq_i32 s7, 0x100
	v_add_f32_e32 v22, v22, v23
	v_add_f32_e32 v23, v24, v25
	ds_write2st64_b32 v21, v22, v23 offset0:120 offset1:124
	s_waitcnt lgkmcnt(0)
	s_barrier
	s_cbranch_scc0 .LBB0_4119
	s_setprio 0
	s_add_u32 s3, s72, s3
	s_addc_u32 s4, s73, s6
	s_add_u32 s2, s3, s2
	s_addc_u32 s3, s4, 0
	v_lshlrev_b32_e32 v16, 2, v16
	v_mov_b32_e32 v17, 0
	v_lshl_add_u64 v[16:17], s[2:3], 0, v[16:17]
	v_lshl_add_u64 v[16:17], v[18:19], 2, v[16:17]
	s_mov_b64 s[2:3], 0x8500000
	v_lshl_add_u64 v[18:19], v[16:17], 0, s[2:3]
	v_add_co_u32_e32 v16, vcc, 0x8500000, v16
	s_nop 1
	v_addc_co_u32_e32 v17, vcc, 0, v17, vcc
	global_store_dwordx4 v[16:17], v[12:15], off
	global_store_dwordx4 v[18:19], v[8:11], off offset:16
	global_store_dwordx4 v[18:19], v[0:3], off offset:2048
	global_store_dwordx4 v[18:19], v[4:7], off offset:2064
